# 4 double-phase GEMM loops (8 barriers per 128 MFMA) + prologue vmcnt(0) so the first load segment may read all buffer-0 half-tiles
# speedup vs baseline: 1.0136x; 1.0076x over previous
_Z4mega6Params:
	s_mov_b32 s100, 0
	s_load_dwordx2 s[56:57], s[0:1], 0x100
	s_add_u32 s4, s0, 0x100
	s_addc_u32 s5, s1, 0
	v_and_b32_e32 v186, 0x3ff, v0
	v_writelane_b32 v252, s4, 0
	v_cmp_gt_u32_e32 vcc, 2, v186
	s_nop 0
	v_writelane_b32 v252, s5, 1
	s_and_saveexec_b64 s[4:5], vcc
	v_lshl_add_u32 v1, v186, 2, 0
	v_add_u32_e32 v1, 0x25ff0, v1
	v_mov_b32_e32 v2, 0
	ds_write_b32 v1, v2
	s_or_b64 exec, exec, s[4:5]
	s_mov_b64 s[4:5], s[0:1]
	s_waitcnt lgkmcnt(0)
	s_barrier
	s_load_dwordx2 s[24:25], s[4:5], 0xf8
	s_getreg_b32 s3, hwreg(HW_REG_XCC_ID, 0, 4)
	s_mov_b32 s61, 0
	v_cmp_eq_u32_e64 s[6:7], 0, v186
	s_waitcnt lgkmcnt(0)
	s_add_u32 s26, s24, 0x1df10000
	s_addc_u32 s27, s25, 0
	s_and_b32 s12, s3, 15
	s_lshl_b32 s13, s12, 6
	s_mov_b64 s[4:5], exec
	v_writelane_b32 v252, s6, 2
	s_nop 1
	v_writelane_b32 v252, s7, 3
	s_and_b64 s[6:7], s[4:5], s[6:7]
	s_mov_b64 exec, s[6:7]
	s_cbranch_execz .LBB0_5
	s_mov_b64 s[6:7], exec
	v_mbcnt_lo_u32_b32 v1, s6, 0
	v_mbcnt_hi_u32_b32 v1, s7, v1
	v_cmp_eq_u32_e32 vcc, 0, v1
	s_and_b64 s[8:9], exec, vcc
	s_mov_b64 exec, s[8:9]
	s_cbranch_execz .LBB0_5
	s_lshl_b32 s3, s13, 2
	s_bcnt1_i32_b64 s6, s[6:7]
	v_mov_b32_e32 v1, s3
	v_mov_b32_e32 v2, s6
	global_atomic_add v1, v2, s[26:27] offset:1024

.LBB0_18:
	s_waitcnt lgkmcnt(0)
	s_add_u32 s4, s4, 0x12290000
	s_addc_u32 s5, s5, 0
	s_add_u32 s28, s28, 0x12290000
	s_addc_u32 s29, s29, 0
	s_and_b32 s12, s10, 3
	s_add_i32 m0, s58, 0x18000
	v_lshl_add_u64 v[6:7], v[6:7], 0, s[36:37]
	s_lshl_b32 s19, s6, 6
	s_lshl_b32 s6, s6, 13
	s_lshl_b32 s23, s12, 12
	s_waitcnt vmcnt(0)
	s_barrier
	global_load_lds_dwordx4 v[6:7], off
	v_lshl_add_u64 v[4:5], v[4:5], 0, s[36:37]
	s_add_i32 m0, s58, 0x1a000
	s_add_i32 s70, s58, 0x8000
	s_add_i32 s71, s58, 0xa000
	global_load_lds_dwordx4 v[4:5], off
	v_lshl_add_u64 v[2:3], v[2:3], 0, s[36:37]
	s_mov_b32 m0, s70
	s_add_u32 s10, s52, 0xb0080
	global_load_lds_dwordx4 v[2:3], off
	v_lshl_add_u64 v[0:1], v[0:1], 0, s[36:37]
	s_mov_b32 m0, s71
	s_addc_u32 s11, s53, 0
	global_load_lds_dwordx4 v[0:1], off
	s_add_i32 m0, s58, 0x1c000
	v_lshl_add_u64 v[0:1], s[10:11], 0, v[140:141]
	global_load_lds_dwordx4 v[0:1], off
	v_lshl_add_u64 v[0:1], s[10:11], 0, v[150:151]
	s_add_i32 m0, s58, 0x1e000
	v_lshlrev_b32_e32 v4, 2, v8
	global_load_lds_dwordx4 v[0:1], off
	v_bfe_u32 v1, v8, 4, 2
	v_and_b32_e32 v0, 15, v8
	v_lshlrev_b32_e32 v3, 4, v1
	v_lshl_or_b32 v3, v0, 6, v3
	v_and_b32_e32 v4, 32, v4
	v_bitop3_b32 v5, v3, s6, v4 bitop3:0xde
	s_ashr_i32 s6, s19, 31
	v_mov_b32_e32 v157, s6
	s_lshl_b32 s6, s12, 2
	s_add_u32 s6, s34, s6
	s_addc_u32 s10, s35, 0
	v_lshlrev_b32_e32 v2, 3, v1
	s_add_u32 s73, s6, 0x1df14000
	s_movk_i32 s6, 0xb00
	v_lshl_or_b32 v207, s12, 5, v2
	v_or_b32_e32 v156, s19, v0
	v_cmp_eq_u32_e64 s[42:43], 0, v1
	v_lshrrev_b32_e32 v1, 1, v14
	v_mul_lo_u32 v0, v13, s6
	s_mov_b32 s12, 0xb000
	s_addc_u32 s74, s10, 0
	v_mad_u64_u32 v[0:1], s[10:11], v1, s12, v[0:1]
	v_or_b32_e32 v0, v0, v15
	v_add_lshl_u32 v0, v0, v16, 1
	v_mov_b32_e32 v1, v141
	s_mov_b64 s[30:31], 0xb0080
	v_lshl_add_u64 v[158:159], v[0:1], 0, s[30:31]
	v_lshrrev_b32_e32 v1, 1, v9
	v_mul_lo_u32 v0, v10, s6
	v_mad_u64_u32 v[0:1], s[10:11], v1, s12, v[0:1]
	s_waitcnt vmcnt(6)
	v_or_b32_e32 v0, v0, v11
	v_add_lshl_u32 v0, v0, v12, 1
	v_mov_b32_e32 v1, v141
	v_bitop3_b32 v206, v3, s23, v4 bitop3:0xde
	s_mov_b32 s72, 0
	v_lshl_add_u64 v[160:161], v[0:1], 0, s[30:31]
	v_add_u32_e32 v208, 0, v5
	v_readlane_b32 s81, v254, 52
	v_readlane_b32 s38, v254, 55
	s_barrier
	v_readlane_b32 s39, v254, 56
	s_mov_b32 s100, 0
	s_branch .LBB0_20

.LBB0_31:
	s_add_u32 s46, s50, 0x100
	s_addc_u32 s47, s51, 0
	s_add_i32 s6, 0, 0x10000
	v_add_u32_e32 v146, s6, v206
	ds_read_b128 v[128:131], v146
	ds_read_b128 v[132:135], v146 offset:1024
	ds_read_b128 v[136:139], v146 offset:2048
	ds_read_b128 v[146:149], v146 offset:3072
	s_cmp_eq_u32 s12, 40
	s_cselect_b32 s53, s31, s47
	s_cselect_b32 s52, s30, s46
	s_cselect_b32 s49, s35, s11
	s_cselect_b32 s48, s34, s10
	v_lshl_add_u64 v[214:215], s[50:51], 0, v[158:159]
	s_add_i32 m0, s58, 0xc000
	ds_read_b128 v[162:165], v208
	ds_read_b128 v[166:169], v208 offset:1024
	ds_read_b128 v[170:173], v208 offset:2048
	ds_read_b128 v[174:177], v208 offset:3072
	ds_read_b128 v[178:181], v208 offset:4096
	ds_read_b128 v[182:185], v208 offset:5120
	ds_read_b128 v[194:197], v208 offset:6144
	ds_read_b128 v[210:213], v208 offset:7168
	global_load_lds_dwordx4 v[214:215], off
	v_lshl_add_u64 v[214:215], s[50:51], 0, v[160:161]
	s_add_i32 m0, s58, 0xe000
	s_nop 0
	global_load_lds_dwordx4 v[214:215], off
	s_add_i32 s19, 0, 0x14000
	v_add_u32_e32 v192, s19, v206
	ds_read_b128 v[214:217], v192
	ds_read_b128 v[218:221], v192 offset:1024
	ds_read_b128 v[222:225], v192 offset:2048
	ds_read_b128 v[226:229], v192 offset:3072
	s_waitcnt vmcnt(40)
	s_cmp_lg_u32 s100, 0
	s_cbranch_scc1 .Lm4a_31
	s_waitcnt vmcnt(8)
.Lm4a_31:
	s_waitcnt lgkmcnt(0)
	s_barrier
	s_setprio 1
	v_mfma_f32_16x16x32_bf16 v[124:127], v[128:131], v[162:165], v[124:127]
	v_mfma_f32_16x16x32_bf16 v[120:123], v[136:139], v[162:165], v[120:123]
	v_mfma_f32_16x16x32_bf16 v[108:111], v[128:131], v[170:173], v[108:111]
	v_mfma_f32_16x16x32_bf16 v[104:107], v[136:139], v[170:173], v[104:107]
	v_mfma_f32_16x16x32_bf16 v[96:99], v[128:131], v[178:181], v[96:99]
	v_mfma_f32_16x16x32_bf16 v[88:91], v[136:139], v[178:181], v[88:91]
	v_mfma_f32_16x16x32_bf16 v[84:87], v[128:131], v[194:197], v[84:87]
	v_mfma_f32_16x16x32_bf16 v[80:83], v[136:139], v[194:197], v[80:83]
	v_mfma_f32_16x16x32_bf16 v[124:127], v[132:135], v[166:169], v[124:127]
	v_mfma_f32_16x16x32_bf16 v[120:123], v[146:149], v[166:169], v[120:123]
	v_mfma_f32_16x16x32_bf16 v[108:111], v[132:135], v[174:177], v[108:111]
	v_mfma_f32_16x16x32_bf16 v[104:107], v[146:149], v[174:177], v[104:107]
	v_mfma_f32_16x16x32_bf16 v[96:99], v[132:135], v[182:185], v[96:99]
	v_mfma_f32_16x16x32_bf16 v[88:91], v[146:149], v[182:185], v[88:91]
	v_mfma_f32_16x16x32_bf16 v[84:87], v[132:135], v[210:213], v[84:87]
	v_mfma_f32_16x16x32_bf16 v[80:83], v[146:149], v[210:213], v[80:83]
	v_mfma_f32_16x16x32_bf16 v[116:119], v[214:217], v[162:165], v[116:119]
	v_mfma_f32_16x16x32_bf16 v[112:115], v[222:225], v[162:165], v[112:115]
	v_mfma_f32_16x16x32_bf16 v[100:103], v[214:217], v[170:173], v[100:103]
	v_mfma_f32_16x16x32_bf16 v[92:95], v[222:225], v[170:173], v[92:95]
	v_mfma_f32_16x16x32_bf16 v[76:79], v[214:217], v[178:181], v[76:79]
	v_mfma_f32_16x16x32_bf16 v[72:75], v[222:225], v[178:181], v[72:75]
	v_mfma_f32_16x16x32_bf16 v[68:71], v[214:217], v[194:197], v[68:71]
	v_mfma_f32_16x16x32_bf16 v[64:67], v[222:225], v[194:197], v[64:67]
	v_mfma_f32_16x16x32_bf16 v[116:119], v[218:221], v[166:169], v[116:119]
	v_mfma_f32_16x16x32_bf16 v[112:115], v[226:229], v[166:169], v[112:115]
	v_mfma_f32_16x16x32_bf16 v[100:103], v[218:221], v[174:177], v[100:103]
	v_mfma_f32_16x16x32_bf16 v[92:95], v[226:229], v[174:177], v[92:95]
	v_mfma_f32_16x16x32_bf16 v[76:79], v[218:221], v[182:185], v[76:79]
	v_mfma_f32_16x16x32_bf16 v[72:75], v[226:229], v[182:185], v[72:75]
	v_mfma_f32_16x16x32_bf16 v[68:71], v[218:221], v[210:213], v[68:71]
	v_mfma_f32_16x16x32_bf16 v[64:67], v[226:229], v[210:213], v[64:67]
	s_setprio 0
	s_barrier
	s_add_i32 s6, s6, s57
	v_lshl_add_u64 v[230:231], s[48:49], 0, v[140:141]
	s_mov_b32 m0, s6
	s_nop 0
	global_load_lds_dwordx4 v[230:231], off
	v_lshl_add_u64 v[232:233], s[48:49], 0, v[150:151]
	s_add_i32 m0, s6, 0x2000
	s_nop 0
	global_load_lds_dwordx4 v[232:233], off
	s_mov_b32 m0, s58
	v_lshl_add_u64 v[234:235], s[52:53], 0, v[154:155]
	ds_read_b128 v[162:165], v208 offset:16384
	ds_read_b128 v[166:169], v208 offset:17408
	ds_read_b128 v[170:173], v208 offset:18432
	ds_read_b128 v[174:177], v208 offset:19456
	ds_read_b128 v[178:181], v208 offset:20480
	ds_read_b128 v[182:185], v208 offset:21504
	ds_read_b128 v[194:197], v208 offset:22528
	ds_read_b128 v[210:213], v208 offset:23552
	global_load_lds_dwordx4 v[234:235], off
	v_lshl_add_u64 v[236:237], s[52:53], 0, v[152:153]
	s_mov_b32 m0, s59
	s_nop 0
	global_load_lds_dwordx4 v[236:237], off
	s_add_u32 s50, s48, 0xb0000
	s_addc_u32 s51, s49, 0
	s_add_i32 s6, s19, s57
	v_lshl_add_u64 v[250:251], s[50:51], 0, v[140:141]
	s_mov_b32 m0, s6
	s_nop 0
	global_load_lds_dwordx4 v[250:251], off
	v_lshl_add_u64 v[250:251], s[50:51], 0, v[150:151]
	s_add_i32 m0, s6, 0x2000
	s_nop 0
	global_load_lds_dwordx4 v[250:251], off
	s_waitcnt vmcnt(40)
	s_cmp_lg_u32 s100, 0
	s_cbranch_scc1 .Lm4b_31
	s_waitcnt vmcnt(8)
.Lm4b_31:
	s_waitcnt lgkmcnt(0)
	s_mov_b32 s100, 0
	s_barrier
	s_setprio 1
	v_mfma_f32_16x16x32_bf16 v[60:63], v[128:131], v[162:165], v[60:63]
	v_mfma_f32_16x16x32_bf16 v[56:59], v[136:139], v[162:165], v[56:59]
	v_mfma_f32_16x16x32_bf16 v[48:51], v[128:131], v[170:173], v[48:51]
	v_mfma_f32_16x16x32_bf16 v[40:43], v[136:139], v[170:173], v[40:43]
	v_mfma_f32_16x16x32_bf16 v[32:35], v[128:131], v[178:181], v[32:35]
	v_mfma_f32_16x16x32_bf16 v[24:27], v[136:139], v[178:181], v[24:27]
	v_mfma_f32_16x16x32_bf16 v[16:19], v[128:131], v[194:197], v[16:19]
	v_mfma_f32_16x16x32_bf16 v[8:11], v[136:139], v[194:197], v[8:11]
	v_mfma_f32_16x16x32_bf16 v[60:63], v[132:135], v[166:169], v[60:63]
	v_mfma_f32_16x16x32_bf16 v[56:59], v[146:149], v[166:169], v[56:59]
	v_mfma_f32_16x16x32_bf16 v[48:51], v[132:135], v[174:177], v[48:51]
	v_mfma_f32_16x16x32_bf16 v[40:43], v[146:149], v[174:177], v[40:43]
	v_mfma_f32_16x16x32_bf16 v[32:35], v[132:135], v[182:185], v[32:35]
	v_mfma_f32_16x16x32_bf16 v[24:27], v[146:149], v[182:185], v[24:27]
	v_mfma_f32_16x16x32_bf16 v[16:19], v[132:135], v[210:213], v[16:19]
	v_mfma_f32_16x16x32_bf16 v[8:11], v[146:149], v[210:213], v[8:11]
	v_mfma_f32_16x16x32_bf16 v[52:55], v[214:217], v[162:165], v[52:55]
	v_mfma_f32_16x16x32_bf16 v[44:47], v[222:225], v[162:165], v[44:47]
	v_mfma_f32_16x16x32_bf16 v[36:39], v[214:217], v[170:173], v[36:39]
	v_mfma_f32_16x16x32_bf16 v[28:31], v[222:225], v[170:173], v[28:31]
	v_mfma_f32_16x16x32_bf16 v[20:23], v[214:217], v[178:181], v[20:23]
	v_mfma_f32_16x16x32_bf16 v[12:15], v[222:225], v[178:181], v[12:15]
	v_mfma_f32_16x16x32_bf16 v[4:7], v[214:217], v[194:197], v[4:7]
	v_mfma_f32_16x16x32_bf16 v[0:3], v[222:225], v[194:197], v[0:3]
	v_mfma_f32_16x16x32_bf16 v[52:55], v[218:221], v[166:169], v[52:55]
	v_mfma_f32_16x16x32_bf16 v[44:47], v[226:229], v[166:169], v[44:47]
	v_mfma_f32_16x16x32_bf16 v[36:39], v[218:221], v[174:177], v[36:39]
	v_mfma_f32_16x16x32_bf16 v[28:31], v[226:229], v[174:177], v[28:31]
	v_mfma_f32_16x16x32_bf16 v[20:23], v[218:221], v[182:185], v[20:23]
	v_mfma_f32_16x16x32_bf16 v[12:15], v[226:229], v[182:185], v[12:15]
	v_mfma_f32_16x16x32_bf16 v[4:7], v[218:221], v[210:213], v[4:7]
	v_mfma_f32_16x16x32_bf16 v[0:3], v[226:229], v[210:213], v[0:3]
	s_setprio 0
	s_barrier
	s_add_i32 s6, 0, 0x18000
	v_add_u32_e32 v146, s6, v206
	ds_read_b128 v[128:131], v146
	ds_read_b128 v[132:135], v146 offset:1024
	ds_read_b128 v[136:139], v146 offset:2048
	ds_read_b128 v[146:149], v146 offset:3072
	s_add_u32 s50, s52, 0xb0000
	s_addc_u32 s51, s53, 0
	s_mov_b32 m0, s68
	v_lshl_add_u64 v[214:215], s[50:51], 0, v[154:155]
	ds_read_b128 v[162:165], v208 offset:32768
	ds_read_b128 v[166:169], v208 offset:33792
	ds_read_b128 v[170:173], v208 offset:34816
	ds_read_b128 v[174:177], v208 offset:35840
	ds_read_b128 v[178:181], v208 offset:36864
	ds_read_b128 v[182:185], v208 offset:37888
	ds_read_b128 v[194:197], v208 offset:38912
	ds_read_b128 v[210:213], v208 offset:39936
	global_load_lds_dwordx4 v[214:215], off
	v_lshl_add_u64 v[214:215], s[50:51], 0, v[152:153]
	s_mov_b32 m0, s69
	s_nop 0
	global_load_lds_dwordx4 v[214:215], off
	s_add_i32 s19, 0, 0x1c000
	v_add_u32_e32 v192, s19, v206
	ds_read_b128 v[214:217], v192
	ds_read_b128 v[218:221], v192 offset:1024
	ds_read_b128 v[222:225], v192 offset:2048
	ds_read_b128 v[226:229], v192 offset:3072
	s_waitcnt vmcnt(8)
	s_waitcnt lgkmcnt(0)
	s_barrier
	s_setprio 1
	v_mfma_f32_16x16x32_bf16 v[124:127], v[128:131], v[162:165], v[124:127]
	v_mfma_f32_16x16x32_bf16 v[120:123], v[136:139], v[162:165], v[120:123]
	v_mfma_f32_16x16x32_bf16 v[108:111], v[128:131], v[170:173], v[108:111]
	v_mfma_f32_16x16x32_bf16 v[104:107], v[136:139], v[170:173], v[104:107]
	v_mfma_f32_16x16x32_bf16 v[96:99], v[128:131], v[178:181], v[96:99]
	v_mfma_f32_16x16x32_bf16 v[88:91], v[136:139], v[178:181], v[88:91]
	v_mfma_f32_16x16x32_bf16 v[84:87], v[128:131], v[194:197], v[84:87]
	v_mfma_f32_16x16x32_bf16 v[80:83], v[136:139], v[194:197], v[80:83]
	v_mfma_f32_16x16x32_bf16 v[124:127], v[132:135], v[166:169], v[124:127]
	v_mfma_f32_16x16x32_bf16 v[120:123], v[146:149], v[166:169], v[120:123]
	v_mfma_f32_16x16x32_bf16 v[108:111], v[132:135], v[174:177], v[108:111]
	v_mfma_f32_16x16x32_bf16 v[104:107], v[146:149], v[174:177], v[104:107]
	v_mfma_f32_16x16x32_bf16 v[96:99], v[132:135], v[182:185], v[96:99]
	v_mfma_f32_16x16x32_bf16 v[88:91], v[146:149], v[182:185], v[88:91]
	v_mfma_f32_16x16x32_bf16 v[84:87], v[132:135], v[210:213], v[84:87]
	v_mfma_f32_16x16x32_bf16 v[80:83], v[146:149], v[210:213], v[80:83]
	v_mfma_f32_16x16x32_bf16 v[116:119], v[214:217], v[162:165], v[116:119]
	v_mfma_f32_16x16x32_bf16 v[112:115], v[222:225], v[162:165], v[112:115]
	v_mfma_f32_16x16x32_bf16 v[100:103], v[214:217], v[170:173], v[100:103]
	v_mfma_f32_16x16x32_bf16 v[92:95], v[222:225], v[170:173], v[92:95]
	v_mfma_f32_16x16x32_bf16 v[76:79], v[214:217], v[178:181], v[76:79]
	v_mfma_f32_16x16x32_bf16 v[72:75], v[222:225], v[178:181], v[72:75]
	v_mfma_f32_16x16x32_bf16 v[68:71], v[214:217], v[194:197], v[68:71]
	v_mfma_f32_16x16x32_bf16 v[64:67], v[222:225], v[194:197], v[64:67]
	v_mfma_f32_16x16x32_bf16 v[116:119], v[218:221], v[166:169], v[116:119]
	v_mfma_f32_16x16x32_bf16 v[112:115], v[226:229], v[166:169], v[112:115]
	v_mfma_f32_16x16x32_bf16 v[100:103], v[218:221], v[174:177], v[100:103]
	v_mfma_f32_16x16x32_bf16 v[92:95], v[226:229], v[174:177], v[92:95]
	v_mfma_f32_16x16x32_bf16 v[76:79], v[218:221], v[182:185], v[76:79]
	v_mfma_f32_16x16x32_bf16 v[72:75], v[226:229], v[182:185], v[72:75]
	v_mfma_f32_16x16x32_bf16 v[68:71], v[218:221], v[210:213], v[68:71]
	v_mfma_f32_16x16x32_bf16 v[64:67], v[226:229], v[210:213], v[64:67]
	s_setprio 0
	s_barrier
	s_add_i32 s6, s6, s57
	v_lshl_add_u64 v[230:231], v[230:231], 0, s[36:37]
	s_mov_b32 m0, s6
	s_nop 0
	global_load_lds_dwordx4 v[230:231], off
	v_lshl_add_u64 v[230:231], v[232:233], 0, s[36:37]
	s_add_i32 m0, s6, 0x2000
	s_nop 0
	global_load_lds_dwordx4 v[230:231], off
	s_mov_b32 m0, s70
	v_lshl_add_u64 v[230:231], v[234:235], 0, s[36:37]
	ds_read_b128 v[162:165], v208 offset:49152
	ds_read_b128 v[166:169], v208 offset:50176
	ds_read_b128 v[170:173], v208 offset:51200
	ds_read_b128 v[174:177], v208 offset:52224
	ds_read_b128 v[178:181], v208 offset:53248
	ds_read_b128 v[182:185], v208 offset:54272
	ds_read_b128 v[194:197], v208 offset:55296
	ds_read_b128 v[210:213], v208 offset:56320
	global_load_lds_dwordx4 v[230:231], off
	v_lshl_add_u64 v[230:231], v[236:237], 0, s[36:37]
	s_mov_b32 m0, s71
	s_nop 0
	global_load_lds_dwordx4 v[230:231], off
	s_add_u32 s48, s48, 0xb0080
	s_addc_u32 s49, s49, 0
	s_add_i32 s6, s19, s57
	v_lshl_add_u64 v[250:251], s[48:49], 0, v[140:141]
	s_mov_b32 m0, s6
	s_nop 0
	global_load_lds_dwordx4 v[250:251], off
	v_lshl_add_u64 v[250:251], s[48:49], 0, v[150:151]
	s_add_i32 m0, s6, 0x2000
	s_nop 0
	global_load_lds_dwordx4 v[250:251], off
	s_waitcnt vmcnt(8)
	s_waitcnt lgkmcnt(0)
	s_barrier
	s_setprio 1
	v_mfma_f32_16x16x32_bf16 v[60:63], v[128:131], v[162:165], v[60:63]
	v_mfma_f32_16x16x32_bf16 v[56:59], v[136:139], v[162:165], v[56:59]
	v_mfma_f32_16x16x32_bf16 v[48:51], v[128:131], v[170:173], v[48:51]
	v_mfma_f32_16x16x32_bf16 v[40:43], v[136:139], v[170:173], v[40:43]
	v_mfma_f32_16x16x32_bf16 v[32:35], v[128:131], v[178:181], v[32:35]
	v_mfma_f32_16x16x32_bf16 v[24:27], v[136:139], v[178:181], v[24:27]
	v_mfma_f32_16x16x32_bf16 v[16:19], v[128:131], v[194:197], v[16:19]
	v_mfma_f32_16x16x32_bf16 v[8:11], v[136:139], v[194:197], v[8:11]
	v_mfma_f32_16x16x32_bf16 v[60:63], v[132:135], v[166:169], v[60:63]
	v_mfma_f32_16x16x32_bf16 v[56:59], v[146:149], v[166:169], v[56:59]
	v_mfma_f32_16x16x32_bf16 v[48:51], v[132:135], v[174:177], v[48:51]
	v_mfma_f32_16x16x32_bf16 v[40:43], v[146:149], v[174:177], v[40:43]
	v_mfma_f32_16x16x32_bf16 v[32:35], v[132:135], v[182:185], v[32:35]
	v_mfma_f32_16x16x32_bf16 v[24:27], v[146:149], v[182:185], v[24:27]
	v_mfma_f32_16x16x32_bf16 v[16:19], v[132:135], v[210:213], v[16:19]
	v_mfma_f32_16x16x32_bf16 v[8:11], v[146:149], v[210:213], v[8:11]
	v_mfma_f32_16x16x32_bf16 v[52:55], v[214:217], v[162:165], v[52:55]
	v_mfma_f32_16x16x32_bf16 v[44:47], v[222:225], v[162:165], v[44:47]
	v_mfma_f32_16x16x32_bf16 v[36:39], v[214:217], v[170:173], v[36:39]
	v_mfma_f32_16x16x32_bf16 v[28:31], v[222:225], v[170:173], v[28:31]
	v_mfma_f32_16x16x32_bf16 v[20:23], v[214:217], v[178:181], v[20:23]
	v_mfma_f32_16x16x32_bf16 v[12:15], v[222:225], v[178:181], v[12:15]
	v_mfma_f32_16x16x32_bf16 v[4:7], v[214:217], v[194:197], v[4:7]
	v_mfma_f32_16x16x32_bf16 v[0:3], v[222:225], v[194:197], v[0:3]
	v_mfma_f32_16x16x32_bf16 v[52:55], v[218:221], v[166:169], v[52:55]
	v_mfma_f32_16x16x32_bf16 v[44:47], v[226:229], v[166:169], v[44:47]
	v_mfma_f32_16x16x32_bf16 v[36:39], v[218:221], v[174:177], v[36:39]
	v_mfma_f32_16x16x32_bf16 v[28:31], v[226:229], v[174:177], v[28:31]
	v_mfma_f32_16x16x32_bf16 v[20:23], v[218:221], v[182:185], v[20:23]
	v_mfma_f32_16x16x32_bf16 v[12:15], v[226:229], v[182:185], v[12:15]
	v_mfma_f32_16x16x32_bf16 v[4:7], v[218:221], v[210:213], v[4:7]
	v_mfma_f32_16x16x32_bf16 v[0:3], v[226:229], v[210:213], v[0:3]
	s_setprio 0
	s_add_i32 s12, s12, 2
	s_add_u32 s10, s10, 0x100
	s_addc_u32 s11, s11, 0
	s_cmp_gt_u32 s12, 41
	s_mov_b64 s[50:51], s[46:47]
	s_barrier
	s_cbranch_scc0 .LBB0_31
	s_mov_b32 s100, 1
	s_ashr_i32 s39, s38, 31
	v_lshl_or_b32 v128, s81, 8, v207
	s_lshl_b64 s[10:11], s[38:39], 8
	v_ashrrev_i32_e32 v129, 31, v128
	v_lshl_add_u64 v[168:169], s[10:11], 0, v[156:157]
	v_lshlrev_b64 v[170:171], 1, v[128:129]
	v_lshl_add_u64 v[174:175], s[4:5], 0, v[170:171]
	v_lshlrev_b64 v[172:173], 11, v[168:169]
	v_lshl_add_u64 v[128:129], v[174:175], 0, v[172:173]
	global_load_dwordx4 v[146:149], v[128:129], off
	global_load_dwordx4 v[182:185], v[128:129], off offset:256
	v_or_b32_e32 v166, 16, v168
	v_mov_b32_e32 v167, v169
	v_lshlrev_b64 v[176:177], 11, v[166:167]
	v_lshl_add_u64 v[128:129], v[174:175], 0, v[176:177]
	global_load_dwordx4 v[194:197], v[128:129], off
	global_load_dwordx4 v[210:213], v[128:129], off offset:256
	v_or_b32_e32 v164, 32, v168
	v_mov_b32_e32 v165, v169
	v_or_b32_e32 v162, 48, v168
	v_mov_b32_e32 v163, v169
	v_lshlrev_b64 v[180:181], 11, v[164:165]
	v_lshlrev_b64 v[178:179], 11, v[162:163]
	v_lshl_add_u64 v[128:129], v[174:175], 0, v[180:181]
	v_lshl_add_u64 v[130:131], v[174:175], 0, v[178:179]
	global_load_dwordx4 v[214:217], v[128:129], off
	global_load_dwordx4 v[136:139], v[128:129], off offset:256
	global_load_dwordx4 v[132:135], v[130:131], off
	s_nop 0
	global_load_dwordx4 v[128:131], v[130:131], off offset:256
	s_mov_b64 s[10:11], 0x90
	v_lshl_add_u64 v[172:173], s[28:29], 0, v[172:173]
	v_lshl_add_u64 v[172:173], v[172:173], 0, v[170:171]
	s_waitcnt vmcnt(0)
	v_lshlrev_b32_e32 v218, 16, v146
	v_and_b32_e32 v219, 0xffff0000, v146
	v_lshlrev_b32_e32 v220, 16, v148
	v_and_b32_e32 v221, 0xffff0000, v148
	v_lshlrev_b32_e32 v146, 16, v147
	v_and_b32_e32 v147, 0xffff0000, v147
	v_lshlrev_b32_e32 v222, 16, v182
	v_and_b32_e32 v223, 0xffff0000, v182
	v_lshlrev_b32_e32 v224, 16, v184
	v_and_b32_e32 v225, 0xffff0000, v184
	v_lshlrev_b32_e32 v182, 16, v183
	v_and_b32_e32 v183, 0xffff0000, v183
	v_pk_fma_f32 v[124:125], v[124:125], 0.5, v[218:219] op_sel_hi:[1,0,1]
	v_pk_fma_f32 v[120:121], v[120:121], 0.5, v[220:221] op_sel_hi:[1,0,1]
	v_pk_fma_f32 v[126:127], v[126:127], 0.5, v[146:147] op_sel_hi:[1,0,1]
	v_pk_fma_f32 v[116:117], v[116:117], 0.5, v[222:223] op_sel_hi:[1,0,1]
	v_pk_fma_f32 v[146:147], v[112:113], 0.5, v[224:225] op_sel_hi:[1,0,1]
	v_pk_fma_f32 v[118:119], v[118:119], 0.5, v[182:183] op_sel_hi:[1,0,1]
	v_pk_mul_f32 v[220:221], v[124:125], v[124:125]
	v_pk_mul_f32 v[222:223], v[126:127], v[126:127]
	v_cvt_pk_bf16_f32 v112, v124, v125
	v_cvt_pk_bf16_f32 v113, v126, v127
	v_pk_mul_f32 v[124:125], v[116:117], v[116:117]
	v_pk_mul_f32 v[126:127], v[118:119], v[118:119]
	v_pk_mul_f32 v[228:229], v[146:147], v[146:147]
	v_cvt_pk_bf16_f32 v116, v116, v117
	v_cvt_pk_bf16_f32 v117, v118, v119
	v_cvt_pk_bf16_f32 v118, v146, v147
	v_add_f32_e32 v146, v220, v221
	v_add_f32_e32 v146, v222, v146
	v_lshlrev_b32_e32 v148, 16, v149
	v_and_b32_e32 v149, 0xffff0000, v149
	v_pk_mul_f32 v[224:225], v[120:121], v[120:121]
	v_add_f32_e32 v146, v223, v146
	v_pk_fma_f32 v[122:123], v[122:123], 0.5, v[148:149] op_sel_hi:[1,0,1]
	v_add_f32_e32 v146, v224, v146
	v_pk_mul_f32 v[226:227], v[122:123], v[122:123]
	v_add_f32_e32 v146, v225, v146
	v_add_f32_e32 v146, v226, v146
	v_add_f32_e32 v146, v227, v146
	v_add_f32_e32 v124, v124, v146
	v_add_f32_e32 v124, v125, v124
	v_add_f32_e32 v124, v126, v124
	v_lshlrev_b32_e32 v184, 16, v185
	v_and_b32_e32 v185, 0xffff0000, v185
	v_add_f32_e32 v124, v127, v124
	v_pk_fma_f32 v[148:149], v[114:115], 0.5, v[184:185] op_sel_hi:[1,0,1]
	v_add_f32_e32 v124, v228, v124
	v_pk_mul_f32 v[230:231], v[148:149], v[148:149]
	v_add_f32_e32 v124, v229, v124
	v_add_f32_e32 v124, v230, v124
	v_add_f32_e32 v209, v231, v124
	v_lshlrev_b32_e32 v124, 16, v212
	v_and_b32_e32 v125, 0xffff0000, v212
	v_pk_fma_f32 v[124:125], v[92:93], 0.5, v[124:125] op_sel_hi:[1,0,1]
	v_lshlrev_b32_e32 v92, 16, v211
	v_and_b32_e32 v93, 0xffff0000, v211
	v_pk_fma_f32 v[102:103], v[102:103], 0.5, v[92:93] op_sel_hi:[1,0,1]
	v_lshlrev_b32_e32 v92, 16, v213
	v_and_b32_e32 v93, 0xffff0000, v213
	v_pk_fma_f32 v[126:127], v[94:95], 0.5, v[92:93] op_sel_hi:[1,0,1]
	v_lshlrev_b32_e32 v92, 16, v214
	v_and_b32_e32 v93, 0xffff0000, v214
	v_pk_fma_f32 v[92:93], v[96:97], 0.5, v[92:93] op_sel_hi:[1,0,1]
	v_lshlrev_b32_e32 v96, 16, v217
	v_and_b32_e32 v97, 0xffff0000, v217
	v_lshlrev_b32_e32 v94, 16, v216
	v_and_b32_e32 v95, 0xffff0000, v216
	v_pk_fma_f32 v[90:91], v[90:91], 0.5, v[96:97] op_sel_hi:[1,0,1]
	v_lshlrev_b32_e32 v96, 16, v136
	v_and_b32_e32 v97, 0xffff0000, v136
	v_lshlrev_b32_e32 v182, 16, v194
	v_and_b32_e32 v183, 0xffff0000, v194
	v_pk_fma_f32 v[88:89], v[88:89], 0.5, v[94:95] op_sel_hi:[1,0,1]
	v_lshlrev_b32_e32 v94, 16, v215
	v_and_b32_e32 v95, 0xffff0000, v215
	v_pk_fma_f32 v[96:97], v[76:77], 0.5, v[96:97] op_sel_hi:[1,0,1]
	v_lshl_add_u64 v[76:77], v[168:169], 0, s[36:37]
	v_lshlrev_b32_e32 v184, 16, v196
	v_and_b32_e32 v185, 0xffff0000, v196
	v_cvt_pk_bf16_f32 v114, v120, v121
	v_pk_fma_f32 v[120:121], v[108:109], 0.5, v[182:183] op_sel_hi:[1,0,1]
	v_pk_fma_f32 v[94:95], v[98:99], 0.5, v[94:95] op_sel_hi:[1,0,1]
	v_lshlrev_b64 v[182:183], 11, v[76:77]
	v_lshlrev_b32_e32 v98, 16, v138
	v_and_b32_e32 v99, 0xffff0000, v138
	v_pk_fma_f32 v[108:109], v[104:105], 0.5, v[184:185] op_sel_hi:[1,0,1]
	v_lshl_add_u64 v[184:185], v[174:175], 0, v[182:183]
	v_pk_fma_f32 v[98:99], v[72:73], 0.5, v[98:99] op_sel_hi:[1,0,1]
	v_lshlrev_b32_e32 v72, 16, v137
	v_and_b32_e32 v73, 0xffff0000, v137
	v_lshlrev_b32_e32 v218, 16, v210
	v_and_b32_e32 v219, 0xffff0000, v210
	global_load_dwordx4 v[210:213], v[184:185], off
	v_pk_fma_f32 v[136:137], v[78:79], 0.5, v[72:73] op_sel_hi:[1,0,1]
	v_lshlrev_b32_e32 v72, 16, v139
	v_and_b32_e32 v73, 0xffff0000, v139
	v_pk_fma_f32 v[138:139], v[74:75], 0.5, v[72:73] op_sel_hi:[1,0,1]
	v_lshlrev_b32_e32 v72, 16, v132
	v_and_b32_e32 v73, 0xffff0000, v132
	v_pk_fma_f32 v[74:75], v[84:85], 0.5, v[72:73] op_sel_hi:[1,0,1]
	v_lshlrev_b32_e32 v72, 16, v134
	v_and_b32_e32 v73, 0xffff0000, v134
	v_pk_fma_f32 v[78:79], v[80:81], 0.5, v[72:73] op_sel_hi:[1,0,1]
	v_lshlrev_b32_e32 v72, 16, v133
	v_and_b32_e32 v73, 0xffff0000, v133
	v_pk_fma_f32 v[100:101], v[100:101], 0.5, v[218:219] op_sel_hi:[1,0,1]
	global_load_dwordx4 v[218:221], v[184:185], off offset:256
	v_pk_fma_f32 v[80:81], v[86:87], 0.5, v[72:73] op_sel_hi:[1,0,1]
	v_lshlrev_b32_e32 v72, 16, v135
	v_and_b32_e32 v73, 0xffff0000, v135
	v_pk_fma_f32 v[82:83], v[82:83], 0.5, v[72:73] op_sel_hi:[1,0,1]
	v_lshl_add_u64 v[72:73], v[168:169], 0, s[10:11]
	v_lshlrev_b64 v[132:133], 11, v[72:73]
	v_lshl_add_u64 v[134:135], v[174:175], 0, v[132:133]
	v_lshlrev_b32_e32 v84, 16, v128
	v_and_b32_e32 v85, 0xffff0000, v128
	global_load_dwordx4 v[226:229], v[134:135], off
	global_load_dwordx4 v[234:237], v[134:135], off offset:256
	v_pk_fma_f32 v[84:85], v[68:69], 0.5, v[84:85] op_sel_hi:[1,0,1]
	v_lshlrev_b32_e32 v68, 16, v130
	v_and_b32_e32 v69, 0xffff0000, v130
	v_pk_fma_f32 v[86:87], v[64:65], 0.5, v[68:69] op_sel_hi:[1,0,1]
	v_lshlrev_b32_e32 v64, 16, v129
	v_and_b32_e32 v65, 0xffff0000, v129
	s_mov_b64 s[10:11], 0xa0
	v_pk_fma_f32 v[128:129], v[70:71], 0.5, v[64:65] op_sel_hi:[1,0,1]
	v_lshl_add_u64 v[70:71], v[168:169], 0, s[10:11]
	s_mov_b64 s[10:11], 0xb0
	v_lshlrev_b32_e32 v64, 16, v131
	v_and_b32_e32 v65, 0xffff0000, v131
	v_lshlrev_b64 v[134:135], 11, v[70:71]
	v_lshl_add_u64 v[68:69], v[168:169], 0, s[10:11]
	v_pk_fma_f32 v[130:131], v[66:67], 0.5, v[64:65] op_sel_hi:[1,0,1]
	v_lshl_add_u64 v[64:65], v[174:175], 0, v[134:135]
	v_lshlrev_b64 v[184:185], 11, v[68:69]
	global_load_dwordx4 v[238:241], v[64:65], off
	global_load_dwordx4 v[242:245], v[64:65], off offset:256
	v_lshl_add_u64 v[64:65], v[174:175], 0, v[184:185]
	global_load_dwordx4 v[246:249], v[64:65], off
	s_nop 0
	global_load_dwordx4 v[64:67], v[64:65], off offset:256
	v_lshlrev_b32_e32 v194, 16, v195
	v_and_b32_e32 v195, 0xffff0000, v195
	v_lshlrev_b32_e32 v196, 16, v197
	v_and_b32_e32 v197, 0xffff0000, v197
	v_cvt_pk_bf16_f32 v115, v122, v123
	v_cvt_pk_bf16_f32 v119, v148, v149
	v_pk_fma_f32 v[122:123], v[110:111], 0.5, v[194:195] op_sel_hi:[1,0,1]
	v_pk_fma_f32 v[110:111], v[106:107], 0.5, v[196:197] op_sel_hi:[1,0,1]
	global_store_dwordx4 v[172:173], v[112:115], off
	global_store_dwordx4 v[172:173], v[116:119], off offset:256
	v_cvt_pk_bf16_f32 v104, v120, v121
	v_lshl_add_u64 v[112:113], s[28:29], 0, v[176:177]
	v_cvt_pk_bf16_f32 v105, v122, v123
	v_cvt_pk_bf16_f32 v106, v108, v109
	v_cvt_pk_bf16_f32 v107, v110, v111
	v_lshl_add_u64 v[112:113], v[112:113], 0, v[170:171]
	v_cvt_pk_bf16_f32 v146, v100, v101
	v_cvt_pk_bf16_f32 v147, v102, v103
	v_cvt_pk_bf16_f32 v148, v124, v125
	v_cvt_pk_bf16_f32 v149, v126, v127
	global_store_dwordx4 v[112:113], v[104:107], off
	global_store_dwordx4 v[112:113], v[146:149], off offset:256
	v_cvt_pk_bf16_f32 v194, v92, v93
	v_lshl_add_u64 v[104:105], s[28:29], 0, v[180:181]
	v_cvt_pk_bf16_f32 v195, v94, v95
	v_cvt_pk_bf16_f32 v196, v88, v89
	v_cvt_pk_bf16_f32 v197, v90, v91
	v_lshl_add_u64 v[104:105], v[104:105], 0, v[170:171]
	v_cvt_pk_bf16_f32 v214, v96, v97
	v_cvt_pk_bf16_f32 v215, v136, v137
	v_cvt_pk_bf16_f32 v216, v98, v99
	v_cvt_pk_bf16_f32 v217, v138, v139
	global_store_dwordx4 v[104:105], v[194:197], off
	global_store_dwordx4 v[104:105], v[214:217], off offset:256
	v_lshl_add_u64 v[104:105], s[28:29], 0, v[178:179]
	v_cvt_pk_bf16_f32 v222, v74, v75
	v_cvt_pk_bf16_f32 v223, v80, v81
	v_cvt_pk_bf16_f32 v224, v78, v79
	v_cvt_pk_bf16_f32 v225, v82, v83
	v_lshl_add_u64 v[104:105], v[104:105], 0, v[170:171]
	v_cvt_pk_bf16_f32 v230, v84, v85
	v_cvt_pk_bf16_f32 v231, v128, v129
	v_cvt_pk_bf16_f32 v232, v86, v87
	v_cvt_pk_bf16_f32 v233, v130, v131
	global_store_dwordx4 v[104:105], v[222:225], off
	global_store_dwordx4 v[104:105], v[230:233], off offset:256
	s_waitcnt vmcnt(0)
	v_lshlrev_b32_e32 v104, 16, v210
	v_and_b32_e32 v105, 0xffff0000, v210
	v_pk_fma_f32 v[60:61], v[60:61], 0.5, v[104:105] op_sel_hi:[1,0,1]
	v_lshlrev_b32_e32 v104, 16, v212
	v_and_b32_e32 v105, 0xffff0000, v212
	v_pk_fma_f32 v[56:57], v[56:57], 0.5, v[104:105] op_sel_hi:[1,0,1]
	v_lshlrev_b32_e32 v104, 16, v211
	v_and_b32_e32 v105, 0xffff0000, v211
	v_pk_fma_f32 v[62:63], v[62:63], 0.5, v[104:105] op_sel_hi:[1,0,1]
	v_lshlrev_b32_e32 v104, 16, v213
	v_and_b32_e32 v105, 0xffff0000, v213
	v_pk_fma_f32 v[58:59], v[58:59], 0.5, v[104:105] op_sel_hi:[1,0,1]
	v_lshlrev_b32_e32 v104, 16, v218
	v_and_b32_e32 v105, 0xffff0000, v218
	v_pk_fma_f32 v[52:53], v[52:53], 0.5, v[104:105] op_sel_hi:[1,0,1]
	v_lshlrev_b32_e32 v104, 16, v220
	v_and_b32_e32 v105, 0xffff0000, v220
	v_pk_fma_f32 v[104:105], v[44:45], 0.5, v[104:105] op_sel_hi:[1,0,1]
	v_lshlrev_b32_e32 v44, 16, v219
	v_and_b32_e32 v45, 0xffff0000, v219
	v_pk_fma_f32 v[54:55], v[54:55], 0.5, v[44:45] op_sel_hi:[1,0,1]
	v_lshlrev_b32_e32 v44, 16, v221
	v_and_b32_e32 v45, 0xffff0000, v221
	v_pk_fma_f32 v[106:107], v[46:47], 0.5, v[44:45] op_sel_hi:[1,0,1]
	v_lshlrev_b32_e32 v44, 16, v226
	v_and_b32_e32 v45, 0xffff0000, v226
	v_pk_fma_f32 v[44:45], v[48:49], 0.5, v[44:45] op_sel_hi:[1,0,1]
	v_lshlrev_b32_e32 v48, 16, v229
	v_and_b32_e32 v49, 0xffff0000, v229
	v_pk_fma_f32 v[42:43], v[42:43], 0.5, v[48:49] op_sel_hi:[1,0,1]
	v_lshlrev_b32_e32 v48, 16, v234
	v_and_b32_e32 v49, 0xffff0000, v234
	v_pk_fma_f32 v[36:37], v[36:37], 0.5, v[48:49] op_sel_hi:[1,0,1]
	v_lshlrev_b32_e32 v48, 16, v236
	v_and_b32_e32 v49, 0xffff0000, v236
	v_lshlrev_b32_e32 v46, 16, v228
	v_and_b32_e32 v47, 0xffff0000, v228
	v_pk_fma_f32 v[48:49], v[28:29], 0.5, v[48:49] op_sel_hi:[1,0,1]
	v_lshlrev_b32_e32 v28, 16, v235
	v_and_b32_e32 v29, 0xffff0000, v235
	v_pk_fma_f32 v[40:41], v[40:41], 0.5, v[46:47] op_sel_hi:[1,0,1]
	v_lshlrev_b32_e32 v46, 16, v227
	v_and_b32_e32 v47, 0xffff0000, v227
	v_pk_fma_f32 v[38:39], v[38:39], 0.5, v[28:29] op_sel_hi:[1,0,1]
	v_lshlrev_b32_e32 v28, 16, v237
	v_and_b32_e32 v29, 0xffff0000, v237
	v_pk_fma_f32 v[46:47], v[50:51], 0.5, v[46:47] op_sel_hi:[1,0,1]
	v_pk_fma_f32 v[50:51], v[30:31], 0.5, v[28:29] op_sel_hi:[1,0,1]
	v_lshlrev_b32_e32 v28, 16, v238
	v_and_b32_e32 v29, 0xffff0000, v238
	v_lshlrev_b32_e32 v180, 16, v64
	v_and_b32_e32 v181, 0xffff0000, v64
	v_pk_fma_f32 v[28:29], v[32:33], 0.5, v[28:29] op_sel_hi:[1,0,1]
	v_lshlrev_b32_e32 v32, 16, v241
	v_and_b32_e32 v33, 0xffff0000, v241
	v_pk_fma_f32 v[4:5], v[4:5], 0.5, v[180:181] op_sel_hi:[1,0,1]
	v_lshlrev_b32_e32 v180, 16, v66
	v_and_b32_e32 v181, 0xffff0000, v66
	v_pk_fma_f32 v[26:27], v[26:27], 0.5, v[32:33] op_sel_hi:[1,0,1]
	v_lshlrev_b32_e32 v32, 16, v242
	v_and_b32_e32 v33, 0xffff0000, v242
	v_pk_fma_f32 v[0:1], v[0:1], 0.5, v[180:181] op_sel_hi:[1,0,1]
	v_lshl_add_u64 v[180:181], s[28:29], 0, v[182:183]
	v_cvt_pk_bf16_f32 v112, v60, v61
	v_cvt_pk_bf16_f32 v113, v62, v63
	v_cvt_pk_bf16_f32 v114, v56, v57
	v_cvt_pk_bf16_f32 v115, v58, v59
	v_pk_fma_f32 v[20:21], v[20:21], 0.5, v[32:33] op_sel_hi:[1,0,1]
	v_lshlrev_b32_e32 v32, 16, v244
	v_and_b32_e32 v33, 0xffff0000, v244
	v_lshl_add_u64 v[180:181], v[180:181], 0, v[170:171]
	v_cvt_pk_bf16_f32 v116, v52, v53
	v_cvt_pk_bf16_f32 v117, v54, v55
	v_cvt_pk_bf16_f32 v118, v104, v105
	v_cvt_pk_bf16_f32 v119, v106, v107
	v_lshlrev_b32_e32 v30, 16, v240
	v_and_b32_e32 v31, 0xffff0000, v240
	v_pk_fma_f32 v[32:33], v[12:13], 0.5, v[32:33] op_sel_hi:[1,0,1]
	v_lshlrev_b32_e32 v12, 16, v243
	v_and_b32_e32 v13, 0xffff0000, v243
	global_store_dwordx4 v[180:181], v[112:115], off
	global_store_dwordx4 v[180:181], v[116:119], off offset:256
	v_cvt_pk_bf16_f32 v146, v44, v45
	v_lshl_add_u64 v[112:113], s[28:29], 0, v[132:133]
	v_cvt_pk_bf16_f32 v147, v46, v47
	v_cvt_pk_bf16_f32 v148, v40, v41
	v_cvt_pk_bf16_f32 v149, v42, v43
	v_pk_fma_f32 v[24:25], v[24:25], 0.5, v[30:31] op_sel_hi:[1,0,1]
	v_lshlrev_b32_e32 v30, 16, v239
	v_and_b32_e32 v31, 0xffff0000, v239
	v_pk_fma_f32 v[22:23], v[22:23], 0.5, v[12:13] op_sel_hi:[1,0,1]
	v_lshlrev_b32_e32 v12, 16, v245
	v_and_b32_e32 v13, 0xffff0000, v245
	v_lshl_add_u64 v[112:113], v[112:113], 0, v[170:171]
	v_cvt_pk_bf16_f32 v172, v36, v37
	v_cvt_pk_bf16_f32 v173, v38, v39
	v_cvt_pk_bf16_f32 v174, v48, v49
	v_cvt_pk_bf16_f32 v175, v50, v51
	v_pk_fma_f32 v[30:31], v[34:35], 0.5, v[30:31] op_sel_hi:[1,0,1]
	v_pk_fma_f32 v[34:35], v[14:15], 0.5, v[12:13] op_sel_hi:[1,0,1]
	v_lshlrev_b32_e32 v12, 16, v246
	v_and_b32_e32 v13, 0xffff0000, v246
	v_lshlrev_b32_e32 v14, 16, v248
	v_and_b32_e32 v15, 0xffff0000, v248
	global_store_dwordx4 v[112:113], v[146:149], off
	global_store_dwordx4 v[112:113], v[172:175], off offset:256
	v_lshl_add_u64 v[112:113], s[28:29], 0, v[134:135]
	v_cvt_pk_bf16_f32 v176, v28, v29
	v_cvt_pk_bf16_f32 v177, v30, v31
	v_cvt_pk_bf16_f32 v178, v24, v25
	v_cvt_pk_bf16_f32 v179, v26, v27
	v_pk_fma_f32 v[12:13], v[16:17], 0.5, v[12:13] op_sel_hi:[1,0,1]
	v_pk_fma_f32 v[8:9], v[8:9], 0.5, v[14:15] op_sel_hi:[1,0,1]
	v_lshlrev_b32_e32 v14, 16, v247
	v_and_b32_e32 v15, 0xffff0000, v247
	v_lshlrev_b32_e32 v16, 16, v249
	v_and_b32_e32 v17, 0xffff0000, v249
	v_lshlrev_b32_e32 v64, 16, v65
	v_and_b32_e32 v65, 0xffff0000, v65
	v_lshl_add_u64 v[112:113], v[112:113], 0, v[170:171]
	v_cvt_pk_bf16_f32 v194, v20, v21
	v_cvt_pk_bf16_f32 v195, v22, v23
	v_cvt_pk_bf16_f32 v196, v32, v33
	v_cvt_pk_bf16_f32 v197, v34, v35
	v_pk_fma_f32 v[14:15], v[18:19], 0.5, v[14:15] op_sel_hi:[1,0,1]
	v_pk_fma_f32 v[10:11], v[10:11], 0.5, v[16:17] op_sel_hi:[1,0,1]
	v_pk_fma_f32 v[6:7], v[6:7], 0.5, v[64:65] op_sel_hi:[1,0,1]
	v_lshlrev_b32_e32 v64, 16, v67
	v_and_b32_e32 v65, 0xffff0000, v67
	global_store_dwordx4 v[112:113], v[176:179], off
	global_store_dwordx4 v[112:113], v[194:197], off offset:256
	v_lshl_add_u64 v[112:113], s[28:29], 0, v[184:185]
	v_cvt_pk_bf16_f32 v16, v12, v13
	v_cvt_pk_bf16_f32 v17, v14, v15
	v_cvt_pk_bf16_f32 v18, v8, v9
	v_cvt_pk_bf16_f32 v19, v10, v11
	v_pk_fma_f32 v[2:3], v[2:3], 0.5, v[64:65] op_sel_hi:[1,0,1]
	v_lshl_add_u64 v[112:113], v[112:113], 0, v[170:171]
	v_cvt_pk_bf16_f32 v64, v4, v5
	v_cvt_pk_bf16_f32 v65, v6, v7
	v_cvt_pk_bf16_f32 v66, v0, v1
	v_cvt_pk_bf16_f32 v67, v2, v3
	global_store_dwordx4 v[112:113], v[16:19], off
	global_store_dwordx4 v[112:113], v[64:67], off offset:256
	s_lshl_b32 s10, s81, 2
	v_and_b32_e32 v17, 64, v188
	v_xor_b32_e32 v16, 16, v188
	v_add_u32_e32 v17, 64, v17
	v_cmp_lt_i32_e32 vcc, v16, v17
	v_xor_b32_e32 v18, 32, v188
	s_ashr_i32 s11, s10, 31
	v_cndmask_b32_e32 v16, v188, v16, vcc
	v_lshlrev_b32_e32 v16, 2, v16
	ds_bpermute_b32 v19, v16, v209
	v_cmp_lt_i32_e32 vcc, v18, v17
	s_lshl_b64 s[10:11], s[10:11], 2
	s_add_u32 s38, s73, s10
	v_cndmask_b32_e32 v17, v188, v18, vcc
	v_lshlrev_b32_e32 v17, 2, v17
	s_waitcnt lgkmcnt(0)
	v_add_f32_e32 v18, v209, v19
	ds_bpermute_b32 v19, v17, v18
	s_addc_u32 s39, s74, s11
	s_and_saveexec_b64 s[46:47], s[42:43]
	s_cbranch_execz .LBB0_34
	s_waitcnt lgkmcnt(0)
	v_add_f32_e32 v64, v18, v19
	v_lshlrev_b64 v[18:19], 6, v[168:169]
	v_lshl_add_u64 v[18:19], s[38:39], 0, v[18:19]
	global_store_dword v[18:19], v64, off

.LBB0_72:
	s_add_u32 s28, s28, 0x3290000
	v_and_b32_e32 v15, 15, v8
	v_lshrrev_b32_e32 v8, 1, v8
	s_addc_u32 s29, s29, 0
	v_and_b32_e32 v8, 24, v8
	s_lshl_b32 s10, s10, 5
	v_lshlrev_b32_e32 v16, 1, v8
	v_lshlrev_b32_e32 v17, 2, v15
	s_and_b32 s19, s10, 0x60
	s_add_i32 m0, s68, 0x18000
	v_lshl_add_u64 v[6:7], v[6:7], 0, s[36:37]
	s_lshl_b32 s12, s6, 6
	v_lshl_or_b32 v16, v15, 6, v16
	s_lshl_b32 s11, s6, 13
	v_and_b32_e32 v18, 32, v17
	s_lshl_b32 s10, s19, 7
	s_waitcnt vmcnt(0)
	s_barrier
	global_load_lds_dwordx4 v[6:7], off
	v_lshl_add_u64 v[4:5], v[4:5], 0, s[36:37]
	s_add_i32 m0, s68, 0x1a000
	s_add_i32 s72, s68, 0x8000
	s_add_i32 s73, s68, 0xa000
	v_bitop3_b32 v154, v16, s10, v18 bitop3:0xde
	global_load_lds_dwordx4 v[4:5], off
	v_lshl_add_u64 v[2:3], v[2:3], 0, s[36:37]
	s_mov_b32 m0, s72
	s_add_u32 s10, s50, 0x40080
	v_bitop3_b32 v19, v16, s11, v18 bitop3:0xde
	global_load_lds_dwordx4 v[2:3], off
	v_lshl_add_u64 v[0:1], v[0:1], 0, s[36:37]
	s_mov_b32 m0, s73
	s_addc_u32 s11, s51, 0
	global_load_lds_dwordx4 v[0:1], off
	s_add_i32 m0, s68, 0x1c000
	v_lshl_add_u64 v[0:1], s[10:11], 0, v[140:141]
	global_load_lds_dwordx4 v[0:1], off
	v_lshl_add_u64 v[0:1], s[10:11], 0, v[132:133]
	s_add_i32 m0, s68, 0x1e000
	s_lshl_b32 s6, s6, 8
	global_load_lds_dwordx4 v[0:1], off
	v_lshlrev_b32_e32 v0, 14, v9
	v_and_b32_e32 v0, 0xffff8000, v0
	v_lshl_add_u32 v0, v10, 11, v0
	v_and_b32_e32 v1, 1, v9
	v_lshl_or_b32 v0, v1, 6, v0
	v_lshl_add_u32 v136, v11, 1, v0
	v_lshlrev_b32_e32 v0, 14, v12
	v_and_b32_e32 v0, 0xffff8000, v0
	s_add_i32 s6, s6, 0
	v_lshl_add_u32 v0, v13, 11, v0
	v_and_b32_e32 v1, 1, v12
	s_waitcnt vmcnt(6)
	s_add_i32 s6, s6, 0x22000
	v_lshl_or_b32 v0, v1, 6, v0
	v_add_u32_e32 v155, s6, v17
	s_ashr_i32 s6, s12, 31
	v_lshl_add_u32 v138, v14, 1, v0
	v_mov_b32_e32 v0, 0
	v_or_b32_e32 v134, s12, v15
	v_mov_b32_e32 v135, s6
	v_or_b32_e32 v156, s19, v8
	v_mov_b32_e32 v137, v141
	v_mov_b32_e32 v139, v141
	s_mov_b32 s75, 0
	v_add_u32_e32 v157, 0, v19
	v_readlane_b32 s74, v253, 49
	v_readlane_b32 s30, v254, 0
	v_mov_b32_e32 v1, v0
	v_mov_b32_e32 v2, v0
	v_mov_b32_e32 v3, v0
	v_mov_b32_e32 v4, v0
	v_mov_b32_e32 v5, v0
	v_mov_b32_e32 v6, v0
	v_mov_b32_e32 v7, v0
	v_mov_b32_e32 v8, v0
	v_mov_b32_e32 v9, v0
	v_mov_b32_e32 v10, v0
	v_mov_b32_e32 v11, v0
	v_mov_b32_e32 v12, v0
	v_mov_b32_e32 v13, v0
	v_mov_b32_e32 v14, v0
	v_mov_b32_e32 v15, v0
	v_mov_b32_e32 v16, v0
	v_mov_b32_e32 v17, v0
	v_mov_b32_e32 v18, v0
	v_mov_b32_e32 v19, v0
	v_mov_b32_e32 v20, v0
	v_mov_b32_e32 v21, v0
	v_mov_b32_e32 v22, v0
	v_mov_b32_e32 v23, v0
	v_mov_b32_e32 v24, v0
	v_mov_b32_e32 v25, v0
	v_mov_b32_e32 v26, v0
	v_mov_b32_e32 v27, v0
	v_mov_b32_e32 v28, v0
	v_mov_b32_e32 v29, v0
	v_mov_b32_e32 v30, v0
	v_mov_b32_e32 v31, v0
	v_mov_b32_e32 v32, v0
	v_mov_b32_e32 v33, v0
	v_mov_b32_e32 v34, v0
	v_mov_b32_e32 v35, v0
	v_mov_b32_e32 v36, v0
	v_mov_b32_e32 v37, v0
	v_mov_b32_e32 v38, v0
	v_mov_b32_e32 v39, v0
	v_mov_b32_e32 v40, v0
	v_mov_b32_e32 v41, v0
	v_mov_b32_e32 v42, v0
	v_mov_b32_e32 v43, v0
	v_mov_b32_e32 v44, v0
	v_mov_b32_e32 v45, v0
	v_mov_b32_e32 v46, v0
	v_mov_b32_e32 v47, v0
	v_mov_b32_e32 v48, v0
	v_mov_b32_e32 v49, v0
	v_mov_b32_e32 v50, v0
	v_mov_b32_e32 v51, v0
	v_mov_b32_e32 v52, v0
	v_mov_b32_e32 v53, v0
	v_mov_b32_e32 v54, v0
	v_mov_b32_e32 v55, v0
	v_mov_b32_e32 v56, v0
	v_mov_b32_e32 v57, v0
	v_mov_b32_e32 v58, v0
	v_mov_b32_e32 v59, v0
	v_mov_b32_e32 v60, v0
	v_mov_b32_e32 v61, v0
	v_mov_b32_e32 v62, v0
	v_mov_b32_e32 v63, v0
	v_mov_b32_e32 v64, v0
	v_mov_b32_e32 v65, v0
	v_mov_b32_e32 v66, v0
	v_mov_b32_e32 v67, v0
	v_mov_b32_e32 v68, v0
	v_mov_b32_e32 v69, v0
	v_mov_b32_e32 v70, v0
	v_mov_b32_e32 v71, v0
	v_mov_b32_e32 v72, v0
	v_mov_b32_e32 v73, v0
	v_mov_b32_e32 v74, v0
	v_mov_b32_e32 v75, v0
	v_mov_b32_e32 v76, v0
	v_mov_b32_e32 v77, v0
	v_mov_b32_e32 v78, v0
	v_mov_b32_e32 v79, v0
	v_mov_b32_e32 v80, v0
	v_mov_b32_e32 v81, v0
	v_mov_b32_e32 v82, v0
	v_mov_b32_e32 v83, v0
	v_mov_b32_e32 v84, v0
	v_mov_b32_e32 v85, v0
	v_mov_b32_e32 v86, v0
	v_mov_b32_e32 v87, v0
	v_mov_b32_e32 v88, v0
	v_mov_b32_e32 v89, v0
	v_mov_b32_e32 v90, v0
	v_mov_b32_e32 v91, v0
	v_mov_b32_e32 v92, v0
	v_mov_b32_e32 v93, v0
	v_mov_b32_e32 v94, v0
	v_mov_b32_e32 v95, v0
	v_mov_b32_e32 v96, v0
	v_mov_b32_e32 v97, v0
	v_mov_b32_e32 v98, v0
	v_mov_b32_e32 v99, v0
	v_mov_b32_e32 v100, v0
	v_mov_b32_e32 v101, v0
	v_mov_b32_e32 v102, v0
	v_mov_b32_e32 v103, v0
	v_mov_b32_e32 v104, v0
	v_mov_b32_e32 v105, v0
	v_mov_b32_e32 v106, v0
	v_mov_b32_e32 v107, v0
	v_mov_b32_e32 v108, v0
	v_mov_b32_e32 v109, v0
	v_mov_b32_e32 v110, v0
	v_mov_b32_e32 v111, v0
	v_mov_b32_e32 v112, v0
	v_mov_b32_e32 v113, v0
	v_mov_b32_e32 v114, v0
	v_mov_b32_e32 v115, v0
	v_mov_b32_e32 v116, v0
	v_mov_b32_e32 v117, v0
	v_mov_b32_e32 v118, v0
	v_mov_b32_e32 v119, v0
	v_mov_b32_e32 v120, v0
	v_mov_b32_e32 v121, v0
	v_mov_b32_e32 v122, v0
	v_mov_b32_e32 v123, v0
	v_mov_b32_e32 v124, v0
	v_mov_b32_e32 v125, v0
	v_mov_b32_e32 v126, v0
	v_mov_b32_e32 v127, v0
	s_barrier
	v_readlane_b32 s31, v254, 1
	s_mov_b32 s100, 0
	s_branch .LBB0_74

.LBB0_77:
	s_add_u32 s6, s26, s50
	s_addc_u32 s19, s27, s51
	s_add_u32 s6, s6, 0x100
	s_addc_u32 s19, s19, 0
	s_add_u32 s23, s10, s50
	s_addc_u32 s52, s11, s51
	s_add_i32 s82, 0, 0x10000
	v_add_u32_e32 v146, s82, v154
	ds_read_b128 v[158:161], v146
	ds_read_b128 v[162:165], v146 offset:1024
	ds_read_b128 v[166:169], v146 offset:2048
	ds_read_b128 v[170:173], v146 offset:3072
	s_cmpk_eq_i32 s50, 0x700
	s_cselect_b32 s55, s12, s19
	s_cselect_b32 s54, s31, s6
	s_cselect_b32 s53, s35, s52
	s_cselect_b32 s52, s39, s23
	v_lshl_add_u64 v[146:147], v[150:151], 0, s[50:51]
	s_add_i32 m0, s68, 0xc000
	ds_read_b128 v[174:177], v157
	ds_read_b128 v[178:181], v157 offset:1024
	ds_read_b128 v[182:185], v157 offset:2048
	ds_read_b128 v[206:209], v157 offset:3072
	ds_read_b128 v[210:213], v157 offset:4096
	ds_read_b128 v[214:217], v157 offset:5120
	ds_read_b128 v[218:221], v157 offset:6144
	ds_read_b128 v[222:225], v157 offset:7168
	global_load_lds_dwordx4 v[146:147], off
	v_lshl_add_u64 v[146:147], v[152:153], 0, s[50:51]
	s_add_i32 m0, s68, 0xe000
	s_nop 0
	global_load_lds_dwordx4 v[146:147], off
	s_add_i32 s6, 0, 0x14000
	v_add_u32_e32 v146, s6, v154
	ds_read_b128 v[226:229], v146
	ds_read_b128 v[230:233], v146 offset:1024
	ds_read_b128 v[234:237], v146 offset:2048
	ds_read_b128 v[238:241], v146 offset:3072
	s_waitcnt vmcnt(16)
	s_cmp_lg_u32 s100, 0
	s_cbranch_scc1 .Lm4a_77
	s_waitcnt vmcnt(8)
.Lm4a_77:
	s_waitcnt lgkmcnt(0)
	s_barrier
	s_setprio 1
	v_mfma_f32_16x16x32_bf16 v[124:127], v[158:161], v[174:177], v[124:127]
	v_mfma_f32_16x16x32_bf16 v[120:123], v[166:169], v[174:177], v[120:123]
	v_mfma_f32_16x16x32_bf16 v[116:119], v[158:161], v[182:185], v[116:119]
	v_mfma_f32_16x16x32_bf16 v[112:115], v[166:169], v[182:185], v[112:115]
	v_mfma_f32_16x16x32_bf16 v[108:111], v[158:161], v[210:213], v[108:111]
	v_mfma_f32_16x16x32_bf16 v[104:107], v[166:169], v[210:213], v[104:107]
	v_mfma_f32_16x16x32_bf16 v[100:103], v[158:161], v[218:221], v[100:103]
	v_mfma_f32_16x16x32_bf16 v[96:99], v[166:169], v[218:221], v[96:99]
	v_mfma_f32_16x16x32_bf16 v[124:127], v[162:165], v[178:181], v[124:127]
	v_mfma_f32_16x16x32_bf16 v[120:123], v[170:173], v[178:181], v[120:123]
	v_mfma_f32_16x16x32_bf16 v[116:119], v[162:165], v[206:209], v[116:119]
	v_mfma_f32_16x16x32_bf16 v[112:115], v[170:173], v[206:209], v[112:115]
	v_mfma_f32_16x16x32_bf16 v[108:111], v[162:165], v[214:217], v[108:111]
	v_mfma_f32_16x16x32_bf16 v[104:107], v[170:173], v[214:217], v[104:107]
	v_mfma_f32_16x16x32_bf16 v[100:103], v[162:165], v[222:225], v[100:103]
	v_mfma_f32_16x16x32_bf16 v[96:99], v[170:173], v[222:225], v[96:99]
	v_mfma_f32_16x16x32_bf16 v[92:95], v[226:229], v[174:177], v[92:95]
	v_mfma_f32_16x16x32_bf16 v[88:91], v[234:237], v[174:177], v[88:91]
	v_mfma_f32_16x16x32_bf16 v[84:87], v[226:229], v[182:185], v[84:87]
	v_mfma_f32_16x16x32_bf16 v[80:83], v[234:237], v[182:185], v[80:83]
	v_mfma_f32_16x16x32_bf16 v[76:79], v[226:229], v[210:213], v[76:79]
	v_mfma_f32_16x16x32_bf16 v[72:75], v[234:237], v[210:213], v[72:75]
	v_mfma_f32_16x16x32_bf16 v[68:71], v[226:229], v[218:221], v[68:71]
	v_mfma_f32_16x16x32_bf16 v[64:67], v[234:237], v[218:221], v[64:67]
	v_mfma_f32_16x16x32_bf16 v[92:95], v[230:233], v[178:181], v[92:95]
	v_mfma_f32_16x16x32_bf16 v[88:91], v[238:241], v[178:181], v[88:91]
	v_mfma_f32_16x16x32_bf16 v[84:87], v[230:233], v[206:209], v[84:87]
	v_mfma_f32_16x16x32_bf16 v[80:83], v[238:241], v[206:209], v[80:83]
	v_mfma_f32_16x16x32_bf16 v[76:79], v[230:233], v[214:217], v[76:79]
	v_mfma_f32_16x16x32_bf16 v[72:75], v[238:241], v[214:217], v[72:75]
	v_mfma_f32_16x16x32_bf16 v[68:71], v[230:233], v[222:225], v[68:71]
	v_mfma_f32_16x16x32_bf16 v[64:67], v[238:241], v[222:225], v[64:67]
	s_setprio 0
	s_barrier
	s_add_i32 s19, s82, s59
	v_lshl_add_u64 v[146:147], s[52:53], 0, v[140:141]
	s_mov_b32 m0, s19
	v_lshl_add_u64 v[148:149], s[52:53], 0, v[132:133]
	global_load_lds_dwordx4 v[146:147], off
	s_add_i32 m0, s19, 0x2000
	s_nop 0
	global_load_lds_dwordx4 v[148:149], off
	s_mov_b32 m0, s68
	v_lshl_add_u64 v[194:195], s[54:55], 0, v[128:129]
	ds_read_b128 v[174:177], v157 offset:16384
	ds_read_b128 v[178:181], v157 offset:17408
	ds_read_b128 v[182:185], v157 offset:18432
	ds_read_b128 v[206:209], v157 offset:19456
	ds_read_b128 v[210:213], v157 offset:20480
	ds_read_b128 v[214:217], v157 offset:21504
	ds_read_b128 v[218:221], v157 offset:22528
	ds_read_b128 v[222:225], v157 offset:23552
	global_load_lds_dwordx4 v[194:195], off
	v_lshl_add_u64 v[196:197], s[54:55], 0, v[130:131]
	s_mov_b32 m0, s69
	s_nop 0
	global_load_lds_dwordx4 v[196:197], off
	s_add_u32 s82, s52, 0x40000
	s_addc_u32 s83, s53, 0
	s_add_i32 s6, s6, s59
	v_lshl_add_u64 v[250:251], s[82:83], 0, v[140:141]
	s_mov_b32 m0, s6
	s_nop 0
	global_load_lds_dwordx4 v[250:251], off
	v_lshl_add_u64 v[250:251], s[82:83], 0, v[132:133]
	s_add_i32 m0, s6, 0x2000
	s_nop 0
	global_load_lds_dwordx4 v[250:251], off
	s_waitcnt vmcnt(16)
	s_cmp_lg_u32 s100, 0
	s_cbranch_scc1 .Lm4b_77
	s_waitcnt vmcnt(8)
.Lm4b_77:
	s_waitcnt lgkmcnt(0)
	s_mov_b32 s100, 0
	s_barrier
	s_setprio 1
	v_mfma_f32_16x16x32_bf16 v[60:63], v[158:161], v[174:177], v[60:63]
	v_mfma_f32_16x16x32_bf16 v[56:59], v[166:169], v[174:177], v[56:59]
	v_mfma_f32_16x16x32_bf16 v[52:55], v[158:161], v[182:185], v[52:55]
	v_mfma_f32_16x16x32_bf16 v[48:51], v[166:169], v[182:185], v[48:51]
	v_mfma_f32_16x16x32_bf16 v[44:47], v[158:161], v[210:213], v[44:47]
	v_mfma_f32_16x16x32_bf16 v[40:43], v[166:169], v[210:213], v[40:43]
	v_mfma_f32_16x16x32_bf16 v[36:39], v[158:161], v[218:221], v[36:39]
	v_mfma_f32_16x16x32_bf16 v[32:35], v[166:169], v[218:221], v[32:35]
	v_mfma_f32_16x16x32_bf16 v[60:63], v[162:165], v[178:181], v[60:63]
	v_mfma_f32_16x16x32_bf16 v[56:59], v[170:173], v[178:181], v[56:59]
	v_mfma_f32_16x16x32_bf16 v[52:55], v[162:165], v[206:209], v[52:55]
	v_mfma_f32_16x16x32_bf16 v[48:51], v[170:173], v[206:209], v[48:51]
	v_mfma_f32_16x16x32_bf16 v[44:47], v[162:165], v[214:217], v[44:47]
	v_mfma_f32_16x16x32_bf16 v[40:43], v[170:173], v[214:217], v[40:43]
	v_mfma_f32_16x16x32_bf16 v[36:39], v[162:165], v[222:225], v[36:39]
	v_mfma_f32_16x16x32_bf16 v[32:35], v[170:173], v[222:225], v[32:35]
	v_mfma_f32_16x16x32_bf16 v[28:31], v[226:229], v[174:177], v[28:31]
	v_mfma_f32_16x16x32_bf16 v[24:27], v[234:237], v[174:177], v[24:27]
	v_mfma_f32_16x16x32_bf16 v[20:23], v[226:229], v[182:185], v[20:23]
	v_mfma_f32_16x16x32_bf16 v[16:19], v[234:237], v[182:185], v[16:19]
	v_mfma_f32_16x16x32_bf16 v[12:15], v[226:229], v[210:213], v[12:15]
	v_mfma_f32_16x16x32_bf16 v[8:11], v[234:237], v[210:213], v[8:11]
	v_mfma_f32_16x16x32_bf16 v[4:7], v[226:229], v[218:221], v[4:7]
	v_mfma_f32_16x16x32_bf16 v[0:3], v[234:237], v[218:221], v[0:3]
	v_mfma_f32_16x16x32_bf16 v[28:31], v[230:233], v[178:181], v[28:31]
	v_mfma_f32_16x16x32_bf16 v[24:27], v[238:241], v[178:181], v[24:27]
	v_mfma_f32_16x16x32_bf16 v[20:23], v[230:233], v[206:209], v[20:23]
	v_mfma_f32_16x16x32_bf16 v[16:19], v[238:241], v[206:209], v[16:19]
	v_mfma_f32_16x16x32_bf16 v[12:15], v[230:233], v[214:217], v[12:15]
	v_mfma_f32_16x16x32_bf16 v[8:11], v[238:241], v[214:217], v[8:11]
	v_mfma_f32_16x16x32_bf16 v[4:7], v[230:233], v[222:225], v[4:7]
	v_mfma_f32_16x16x32_bf16 v[0:3], v[238:241], v[222:225], v[0:3]
	s_setprio 0
	s_barrier
	s_add_i32 s6, 0, 0x18000
	v_add_u32_e32 v170, s6, v154
	ds_read_b128 v[158:161], v170
	ds_read_b128 v[162:165], v170 offset:1024
	ds_read_b128 v[166:169], v170 offset:2048
	ds_read_b128 v[170:173], v170 offset:3072
	s_add_u32 s54, s54, 0x40000
	s_addc_u32 s55, s55, 0
	s_mov_b32 m0, s70
	v_lshl_add_u64 v[226:227], s[54:55], 0, v[128:129]
	ds_read_b128 v[174:177], v157 offset:32768
	ds_read_b128 v[178:181], v157 offset:33792
	ds_read_b128 v[182:185], v157 offset:34816
	ds_read_b128 v[206:209], v157 offset:35840
	ds_read_b128 v[210:213], v157 offset:36864
	ds_read_b128 v[214:217], v157 offset:37888
	ds_read_b128 v[218:221], v157 offset:38912
	ds_read_b128 v[222:225], v157 offset:39936
	global_load_lds_dwordx4 v[226:227], off
	v_lshl_add_u64 v[226:227], s[54:55], 0, v[130:131]
	s_mov_b32 m0, s71
	s_nop 0
	global_load_lds_dwordx4 v[226:227], off
	s_add_i32 s19, 0, 0x1c000
	v_add_u32_e32 v192, s19, v154
	ds_read_b128 v[226:229], v192
	ds_read_b128 v[230:233], v192 offset:1024
	ds_read_b128 v[234:237], v192 offset:2048
	ds_read_b128 v[238:241], v192 offset:3072
	s_waitcnt vmcnt(8)
	s_waitcnt lgkmcnt(0)
	s_barrier
	s_setprio 1
	v_mfma_f32_16x16x32_bf16 v[124:127], v[158:161], v[174:177], v[124:127]
	v_mfma_f32_16x16x32_bf16 v[120:123], v[166:169], v[174:177], v[120:123]
	v_mfma_f32_16x16x32_bf16 v[116:119], v[158:161], v[182:185], v[116:119]
	v_mfma_f32_16x16x32_bf16 v[112:115], v[166:169], v[182:185], v[112:115]
	v_mfma_f32_16x16x32_bf16 v[108:111], v[158:161], v[210:213], v[108:111]
	v_mfma_f32_16x16x32_bf16 v[104:107], v[166:169], v[210:213], v[104:107]
	v_mfma_f32_16x16x32_bf16 v[100:103], v[158:161], v[218:221], v[100:103]
	v_mfma_f32_16x16x32_bf16 v[96:99], v[166:169], v[218:221], v[96:99]
	v_mfma_f32_16x16x32_bf16 v[124:127], v[162:165], v[178:181], v[124:127]
	v_mfma_f32_16x16x32_bf16 v[120:123], v[170:173], v[178:181], v[120:123]
	v_mfma_f32_16x16x32_bf16 v[116:119], v[162:165], v[206:209], v[116:119]
	v_mfma_f32_16x16x32_bf16 v[112:115], v[170:173], v[206:209], v[112:115]
	v_mfma_f32_16x16x32_bf16 v[108:111], v[162:165], v[214:217], v[108:111]
	v_mfma_f32_16x16x32_bf16 v[104:107], v[170:173], v[214:217], v[104:107]
	v_mfma_f32_16x16x32_bf16 v[100:103], v[162:165], v[222:225], v[100:103]
	v_mfma_f32_16x16x32_bf16 v[96:99], v[170:173], v[222:225], v[96:99]
	v_mfma_f32_16x16x32_bf16 v[92:95], v[226:229], v[174:177], v[92:95]
	v_mfma_f32_16x16x32_bf16 v[88:91], v[234:237], v[174:177], v[88:91]
	v_mfma_f32_16x16x32_bf16 v[84:87], v[226:229], v[182:185], v[84:87]
	v_mfma_f32_16x16x32_bf16 v[80:83], v[234:237], v[182:185], v[80:83]
	v_mfma_f32_16x16x32_bf16 v[76:79], v[226:229], v[210:213], v[76:79]
	v_mfma_f32_16x16x32_bf16 v[72:75], v[234:237], v[210:213], v[72:75]
	v_mfma_f32_16x16x32_bf16 v[68:71], v[226:229], v[218:221], v[68:71]
	v_mfma_f32_16x16x32_bf16 v[64:67], v[234:237], v[218:221], v[64:67]
	v_mfma_f32_16x16x32_bf16 v[92:95], v[230:233], v[178:181], v[92:95]
	v_mfma_f32_16x16x32_bf16 v[88:91], v[238:241], v[178:181], v[88:91]
	v_mfma_f32_16x16x32_bf16 v[84:87], v[230:233], v[206:209], v[84:87]
	v_mfma_f32_16x16x32_bf16 v[80:83], v[238:241], v[206:209], v[80:83]
	v_mfma_f32_16x16x32_bf16 v[76:79], v[230:233], v[214:217], v[76:79]
	v_mfma_f32_16x16x32_bf16 v[72:75], v[238:241], v[214:217], v[72:75]
	v_mfma_f32_16x16x32_bf16 v[68:71], v[230:233], v[222:225], v[68:71]
	v_mfma_f32_16x16x32_bf16 v[64:67], v[238:241], v[222:225], v[64:67]
	s_setprio 0
	s_barrier
	s_add_i32 s6, s6, s59
	v_lshl_add_u64 v[146:147], v[146:147], 0, s[36:37]
	s_mov_b32 m0, s6
	s_nop 0
	global_load_lds_dwordx4 v[146:147], off
	v_lshl_add_u64 v[146:147], v[148:149], 0, s[36:37]
	s_add_i32 m0, s6, 0x2000
	s_nop 0
	global_load_lds_dwordx4 v[146:147], off
	s_mov_b32 m0, s72
	v_lshl_add_u64 v[146:147], v[194:195], 0, s[36:37]
	ds_read_b128 v[174:177], v157 offset:49152
	ds_read_b128 v[178:181], v157 offset:50176
	ds_read_b128 v[182:185], v157 offset:51200
	ds_read_b128 v[206:209], v157 offset:52224
	ds_read_b128 v[210:213], v157 offset:53248
	ds_read_b128 v[214:217], v157 offset:54272
	ds_read_b128 v[218:221], v157 offset:55296
	ds_read_b128 v[222:225], v157 offset:56320
	global_load_lds_dwordx4 v[146:147], off
	v_lshl_add_u64 v[146:147], v[196:197], 0, s[36:37]
	s_mov_b32 m0, s73
	s_nop 0
	global_load_lds_dwordx4 v[146:147], off
	s_add_u32 s52, s52, 0x40080
	s_addc_u32 s53, s53, 0
	s_add_i32 s6, s19, s59
	v_lshl_add_u64 v[146:147], s[52:53], 0, v[140:141]
	s_mov_b32 m0, s6
	s_nop 0
	global_load_lds_dwordx4 v[146:147], off
	v_lshl_add_u64 v[146:147], s[52:53], 0, v[132:133]
	s_add_i32 m0, s6, 0x2000
	s_nop 0
	global_load_lds_dwordx4 v[146:147], off
	s_waitcnt vmcnt(8)
	s_waitcnt lgkmcnt(0)
	s_barrier
	s_setprio 1
	v_mfma_f32_16x16x32_bf16 v[60:63], v[158:161], v[174:177], v[60:63]
	v_mfma_f32_16x16x32_bf16 v[56:59], v[166:169], v[174:177], v[56:59]
	v_mfma_f32_16x16x32_bf16 v[52:55], v[158:161], v[182:185], v[52:55]
	v_mfma_f32_16x16x32_bf16 v[48:51], v[166:169], v[182:185], v[48:51]
	v_mfma_f32_16x16x32_bf16 v[44:47], v[158:161], v[210:213], v[44:47]
	v_mfma_f32_16x16x32_bf16 v[40:43], v[166:169], v[210:213], v[40:43]
	v_mfma_f32_16x16x32_bf16 v[36:39], v[158:161], v[218:221], v[36:39]
	v_mfma_f32_16x16x32_bf16 v[32:35], v[166:169], v[218:221], v[32:35]
	v_mfma_f32_16x16x32_bf16 v[60:63], v[162:165], v[178:181], v[60:63]
	v_mfma_f32_16x16x32_bf16 v[56:59], v[170:173], v[178:181], v[56:59]
	v_mfma_f32_16x16x32_bf16 v[52:55], v[162:165], v[206:209], v[52:55]
	v_mfma_f32_16x16x32_bf16 v[48:51], v[170:173], v[206:209], v[48:51]
	v_mfma_f32_16x16x32_bf16 v[44:47], v[162:165], v[214:217], v[44:47]
	v_mfma_f32_16x16x32_bf16 v[40:43], v[170:173], v[214:217], v[40:43]
	v_mfma_f32_16x16x32_bf16 v[36:39], v[162:165], v[222:225], v[36:39]
	v_mfma_f32_16x16x32_bf16 v[32:35], v[170:173], v[222:225], v[32:35]
	v_mfma_f32_16x16x32_bf16 v[28:31], v[226:229], v[174:177], v[28:31]
	v_mfma_f32_16x16x32_bf16 v[24:27], v[234:237], v[174:177], v[24:27]
	v_mfma_f32_16x16x32_bf16 v[20:23], v[226:229], v[182:185], v[20:23]
	v_mfma_f32_16x16x32_bf16 v[16:19], v[234:237], v[182:185], v[16:19]
	v_mfma_f32_16x16x32_bf16 v[12:15], v[226:229], v[210:213], v[12:15]
	v_mfma_f32_16x16x32_bf16 v[8:11], v[234:237], v[210:213], v[8:11]
	v_mfma_f32_16x16x32_bf16 v[4:7], v[226:229], v[218:221], v[4:7]
	v_mfma_f32_16x16x32_bf16 v[0:3], v[234:237], v[218:221], v[0:3]
	v_mfma_f32_16x16x32_bf16 v[28:31], v[230:233], v[178:181], v[28:31]
	v_mfma_f32_16x16x32_bf16 v[24:27], v[238:241], v[178:181], v[24:27]
	v_mfma_f32_16x16x32_bf16 v[20:23], v[230:233], v[206:209], v[20:23]
	v_mfma_f32_16x16x32_bf16 v[16:19], v[238:241], v[206:209], v[16:19]
	v_mfma_f32_16x16x32_bf16 v[12:15], v[230:233], v[214:217], v[12:15]
	v_mfma_f32_16x16x32_bf16 v[8:11], v[238:241], v[214:217], v[8:11]
	v_mfma_f32_16x16x32_bf16 v[4:7], v[230:233], v[222:225], v[4:7]
	v_mfma_f32_16x16x32_bf16 v[0:3], v[238:241], v[222:225], v[0:3]
	s_setprio 0
	s_add_i32 s81, s81, 2
	s_add_u32 s50, s50, 0x100
	s_addc_u32 s51, s51, 0
	s_cmp_gt_u32 s81, 13
	s_barrier
	s_cbranch_scc0 .LBB0_77
	s_mov_b32 s100, 1
	v_lshl_add_u32 v158, s75, 10, v155
	ds_read2_b32 v[146:147], v158 offset1:16
	s_add_u32 s50, s10, 0xffffff00
	s_addc_u32 s51, s11, -1
	s_ashr_i32 s31, s30, 31
	s_lshl_b64 s[10:11], s[30:31], 8
	s_waitcnt lgkmcnt(0)
	v_pk_mul_f32 v[148:149], v[124:125], v[146:147] op_sel_hi:[1,0]
	v_lshl_add_u64 v[152:153], v[134:135], 0, s[10:11]
	v_mul_f32_e32 v159, 0xbfb8aa3b, v148
	v_exp_f32_e32 v159, v159
	s_movk_i32 s6, 0x1600
	v_lshl_or_b32 v150, s74, 7, v156
	v_ashrrev_i32_e32 v151, 31, v150
	v_add_f32_e32 v159, 1.0, v159
	v_rcp_f32_e32 v160, v159
	v_mul_f32_e32 v159, 0xbfb8aa3b, v149
	v_exp_f32_e32 v159, v159
	s_nop 0
	v_add_f32_e32 v159, 1.0, v159
	v_rcp_f32_e32 v161, v159
	s_nop 0
	v_pk_mul_f32 v[148:149], v[148:149], v[160:161]
	v_pk_mul_f32 v[160:161], v[92:93], v[146:147] op_sel_hi:[1,0]
	s_nop 0
	v_pk_mul_f32 v[148:149], v[160:161], v[148:149]
	v_pk_mul_f32 v[160:161], v[126:127], v[146:147] op_sel_hi:[1,0]
	s_nop 0
	v_mul_f32_e32 v159, 0xbfb8aa3b, v160
	v_exp_f32_e32 v159, v159
	s_nop 0
	v_add_f32_e32 v159, 1.0, v159
	v_rcp_f32_e32 v162, v159
	v_mul_f32_e32 v159, 0xbfb8aa3b, v161
	v_exp_f32_e32 v159, v159
	s_nop 0
	v_add_f32_e32 v159, 1.0, v159
	v_rcp_f32_e32 v163, v159
	s_nop 0
	v_pk_mul_f32 v[160:161], v[160:161], v[162:163]
	v_pk_mul_f32 v[162:163], v[94:95], v[146:147] op_sel_hi:[1,0]
	s_nop 0
	v_pk_mul_f32 v[162:163], v[162:163], v[160:161]
	v_pk_mul_f32 v[160:161], v[120:121], v[146:147] op_sel_hi:[1,0]
	s_nop 0
	v_mul_f32_e32 v159, 0xbfb8aa3b, v160
	v_exp_f32_e32 v159, v159
	s_nop 0
	v_add_f32_e32 v159, 1.0, v159
	v_rcp_f32_e32 v164, v159
	v_mul_f32_e32 v159, 0xbfb8aa3b, v161
	v_exp_f32_e32 v159, v159
	s_nop 0
	v_add_f32_e32 v159, 1.0, v159
	v_rcp_f32_e32 v165, v159
	s_nop 0
	v_pk_mul_f32 v[160:161], v[160:161], v[164:165]
	v_pk_mul_f32 v[164:165], v[88:89], v[146:147] op_sel_hi:[1,0]
	s_nop 0
	v_pk_mul_f32 v[164:165], v[164:165], v[160:161]
	v_pk_mul_f32 v[160:161], v[122:123], v[146:147] op_sel_hi:[1,0]
	s_nop 0
	v_mul_f32_e32 v159, 0xbfb8aa3b, v160
	v_exp_f32_e32 v159, v159
	s_nop 0
	v_add_f32_e32 v159, 1.0, v159
	v_rcp_f32_e32 v166, v159
	v_mul_f32_e32 v159, 0xbfb8aa3b, v161
	v_exp_f32_e32 v159, v159
	s_nop 0
	v_add_f32_e32 v159, 1.0, v159
	v_rcp_f32_e32 v167, v159
	s_nop 0
	v_pk_mul_f32 v[160:161], v[160:161], v[166:167]
	v_pk_mul_f32 v[166:167], v[90:91], v[146:147] op_sel_hi:[1,0]
	s_nop 0
	v_pk_mul_f32 v[166:167], v[166:167], v[160:161]
	v_cvt_pk_bf16_f32 v160, v148, v149
	v_mov_b64_e32 v[148:149], s[28:29]
	v_mad_u64_u32 v[148:149], s[10:11], v152, s6, v[148:149]
	v_mov_b32_e32 v146, v149
	v_mad_u64_u32 v[152:153], s[10:11], v153, s6, v[146:147]
	v_mov_b32_e32 v149, v152
	v_mov_b32_e32 v146, v147
	v_lshl_add_u64 v[150:151], v[150:151], 1, v[148:149]
	v_pk_mul_f32 v[148:149], v[116:117], v[146:147] op_sel_hi:[1,0]
	v_cvt_pk_bf16_f32 v161, v162, v163
	v_mul_f32_e32 v147, 0xbfb8aa3b, v148
	v_exp_f32_e32 v147, v147
	v_cvt_pk_bf16_f32 v162, v164, v165
	v_cvt_pk_bf16_f32 v163, v166, v167
	global_store_dwordx4 v[150:151], v[160:163], off
	v_add_f32_e32 v147, 1.0, v147
	v_rcp_f32_e32 v152, v147
	v_mul_f32_e32 v147, 0xbfb8aa3b, v149
	v_exp_f32_e32 v147, v147
	s_mov_b32 s6, 0x16000
	v_add_f32_e32 v147, 1.0, v147
	v_rcp_f32_e32 v153, v147
	s_nop 0
	v_pk_mul_f32 v[148:149], v[148:149], v[152:153]
	v_pk_mul_f32 v[152:153], v[84:85], v[146:147] op_sel_hi:[1,0]
	s_nop 0
	v_pk_mul_f32 v[148:149], v[152:153], v[148:149]
	v_pk_mul_f32 v[152:153], v[118:119], v[146:147] op_sel_hi:[1,0]
	s_nop 0
	v_mul_f32_e32 v147, 0xbfb8aa3b, v152
	v_exp_f32_e32 v147, v147
	s_nop 0
	v_add_f32_e32 v147, 1.0, v147
	v_rcp_f32_e32 v160, v147
	v_mul_f32_e32 v147, 0xbfb8aa3b, v153
	v_exp_f32_e32 v147, v147
	s_nop 0
	v_add_f32_e32 v147, 1.0, v147
	v_rcp_f32_e32 v161, v147
	s_nop 0
	v_pk_mul_f32 v[152:153], v[152:153], v[160:161]
	v_pk_mul_f32 v[160:161], v[86:87], v[146:147] op_sel_hi:[1,0]
	s_nop 0
	v_pk_mul_f32 v[152:153], v[160:161], v[152:153]
	v_pk_mul_f32 v[160:161], v[112:113], v[146:147] op_sel_hi:[1,0]
	s_nop 0
	v_mul_f32_e32 v147, 0xbfb8aa3b, v160
	v_exp_f32_e32 v147, v147
	s_nop 0
	v_add_f32_e32 v147, 1.0, v147
	v_rcp_f32_e32 v162, v147
	v_mul_f32_e32 v147, 0xbfb8aa3b, v161
	v_exp_f32_e32 v147, v147
	s_nop 0
	v_add_f32_e32 v147, 1.0, v147
	v_rcp_f32_e32 v163, v147
	s_nop 0
	v_pk_mul_f32 v[160:161], v[160:161], v[162:163]
	v_pk_mul_f32 v[162:163], v[80:81], v[146:147] op_sel_hi:[1,0]
	s_nop 0
	v_pk_mul_f32 v[162:163], v[162:163], v[160:161]
	v_pk_mul_f32 v[160:161], v[114:115], v[146:147] op_sel_hi:[1,0]
	v_cvt_pk_bf16_f32 v162, v162, v163
	v_mul_f32_e32 v147, 0xbfb8aa3b, v160
	v_exp_f32_e32 v147, v147
	s_nop 0
	v_add_f32_e32 v147, 1.0, v147
	v_rcp_f32_e32 v164, v147
	v_mul_f32_e32 v147, 0xbfb8aa3b, v161
	v_exp_f32_e32 v147, v147
	s_nop 0
	v_add_f32_e32 v147, 1.0, v147
	v_rcp_f32_e32 v165, v147
	v_pk_mul_f32 v[146:147], v[82:83], v[146:147] op_sel_hi:[1,0]
	v_pk_mul_f32 v[160:161], v[160:161], v[164:165]
	s_nop 0
	v_pk_mul_f32 v[146:147], v[146:147], v[160:161]
	v_cvt_pk_bf16_f32 v160, v148, v149
	v_cvt_pk_bf16_f32 v163, v146, v147
	v_add_co_u32_e32 v146, vcc, s6, v150
	v_cvt_pk_bf16_f32 v161, v152, v153
	s_nop 0
	v_addc_co_u32_e32 v147, vcc, 0, v151, vcc
	global_store_dwordx4 v[146:147], v[160:163], off
	ds_read2_b32 v[146:147], v158 offset0:32 offset1:48
	s_mov_b32 s6, 0x2c000
	s_waitcnt lgkmcnt(0)
	v_pk_mul_f32 v[148:149], v[108:109], v[146:147] op_sel_hi:[1,0]
	s_nop 0
	v_mul_f32_e32 v152, 0xbfb8aa3b, v148
	v_mul_f32_e32 v153, 0xbfb8aa3b, v149
	v_exp_f32_e32 v152, v152
	v_exp_f32_e32 v153, v153
	v_add_f32_e32 v152, 1.0, v152
	v_add_f32_e32 v153, 1.0, v153
	v_rcp_f32_e32 v152, v152
	v_rcp_f32_e32 v153, v153
	s_nop 0
	v_pk_mul_f32 v[148:149], v[148:149], v[152:153]
	v_pk_mul_f32 v[152:153], v[76:77], v[146:147] op_sel_hi:[1,0]
	s_nop 0
	v_pk_mul_f32 v[148:149], v[152:153], v[148:149]
	v_pk_mul_f32 v[152:153], v[110:111], v[146:147] op_sel_hi:[1,0]
	s_nop 0
	v_mul_f32_e32 v159, 0xbfb8aa3b, v152
	v_exp_f32_e32 v159, v159
	s_nop 0
	v_add_f32_e32 v159, 1.0, v159
	v_rcp_f32_e32 v160, v159
	v_mul_f32_e32 v159, 0xbfb8aa3b, v153
	v_exp_f32_e32 v159, v159
	s_nop 0
	v_add_f32_e32 v159, 1.0, v159
	v_rcp_f32_e32 v161, v159
	s_nop 0
	v_pk_mul_f32 v[152:153], v[152:153], v[160:161]
	v_pk_mul_f32 v[160:161], v[78:79], v[146:147] op_sel_hi:[1,0]
	s_nop 0
	v_pk_mul_f32 v[152:153], v[160:161], v[152:153]
	v_pk_mul_f32 v[160:161], v[104:105], v[146:147] op_sel_hi:[1,0]
	s_nop 0
	v_mul_f32_e32 v159, 0xbfb8aa3b, v160
	v_exp_f32_e32 v159, v159
	s_nop 0
	v_add_f32_e32 v159, 1.0, v159
	v_rcp_f32_e32 v162, v159
	v_mul_f32_e32 v159, 0xbfb8aa3b, v161
	v_exp_f32_e32 v159, v159
	s_nop 0
	v_add_f32_e32 v159, 1.0, v159
	v_rcp_f32_e32 v163, v159
	s_nop 0
	v_pk_mul_f32 v[160:161], v[160:161], v[162:163]
	v_pk_mul_f32 v[162:163], v[72:73], v[146:147] op_sel_hi:[1,0]
	s_nop 0
	v_pk_mul_f32 v[162:163], v[162:163], v[160:161]
	v_pk_mul_f32 v[160:161], v[106:107], v[146:147] op_sel_hi:[1,0]
	v_cvt_pk_bf16_f32 v162, v162, v163
	v_mul_f32_e32 v159, 0xbfb8aa3b, v160
	v_exp_f32_e32 v159, v159
	s_nop 0
	v_add_f32_e32 v159, 1.0, v159
	v_rcp_f32_e32 v164, v159
	v_mul_f32_e32 v159, 0xbfb8aa3b, v161
	v_exp_f32_e32 v159, v159
	s_nop 0
	v_add_f32_e32 v159, 1.0, v159
	v_rcp_f32_e32 v165, v159
	s_nop 0
	v_pk_mul_f32 v[160:161], v[160:161], v[164:165]
	v_pk_mul_f32 v[164:165], v[74:75], v[146:147] op_sel_hi:[1,0]
	v_mov_b32_e32 v146, v147
	v_pk_mul_f32 v[164:165], v[164:165], v[160:161]
	v_cvt_pk_bf16_f32 v160, v148, v149
	v_add_co_u32_e32 v148, vcc, s6, v150
	v_cvt_pk_bf16_f32 v161, v152, v153
	v_cvt_pk_bf16_f32 v163, v164, v165
	v_addc_co_u32_e32 v149, vcc, 0, v151, vcc
	global_store_dwordx4 v[148:149], v[160:163], off
	v_pk_mul_f32 v[148:149], v[100:101], v[146:147] op_sel_hi:[1,0]
	s_mov_b32 s6, 0x42000
	v_mul_f32_e32 v147, 0xbfb8aa3b, v148
	v_exp_f32_e32 v147, v147
	s_nop 0
	v_add_f32_e32 v147, 1.0, v147
	v_rcp_f32_e32 v152, v147
	v_mul_f32_e32 v147, 0xbfb8aa3b, v149
	v_exp_f32_e32 v147, v147
	s_nop 0
	v_add_f32_e32 v147, 1.0, v147
	v_rcp_f32_e32 v153, v147
	s_nop 0
	v_pk_mul_f32 v[148:149], v[148:149], v[152:153]
	v_pk_mul_f32 v[152:153], v[68:69], v[146:147] op_sel_hi:[1,0]
	s_nop 0
	v_pk_mul_f32 v[148:149], v[152:153], v[148:149]
	v_pk_mul_f32 v[152:153], v[102:103], v[146:147] op_sel_hi:[1,0]
	s_nop 0
	v_mul_f32_e32 v147, 0xbfb8aa3b, v152
	v_exp_f32_e32 v147, v147
	s_nop 0
	v_add_f32_e32 v147, 1.0, v147
	v_rcp_f32_e32 v160, v147
	v_mul_f32_e32 v147, 0xbfb8aa3b, v153
	v_exp_f32_e32 v147, v147
	s_nop 0
	v_add_f32_e32 v147, 1.0, v147
	v_rcp_f32_e32 v161, v147
	s_nop 0
	v_pk_mul_f32 v[152:153], v[152:153], v[160:161]
	v_pk_mul_f32 v[160:161], v[70:71], v[146:147] op_sel_hi:[1,0]
	s_nop 0
	v_pk_mul_f32 v[152:153], v[160:161], v[152:153]
	v_pk_mul_f32 v[160:161], v[96:97], v[146:147] op_sel_hi:[1,0]
	s_nop 0
	v_mul_f32_e32 v147, 0xbfb8aa3b, v160
	v_exp_f32_e32 v147, v147
	s_nop 0
	v_add_f32_e32 v147, 1.0, v147
	v_rcp_f32_e32 v162, v147
	v_mul_f32_e32 v147, 0xbfb8aa3b, v161
	v_exp_f32_e32 v147, v147
	s_nop 0
	v_add_f32_e32 v147, 1.0, v147
	v_rcp_f32_e32 v163, v147
	s_nop 0
	v_pk_mul_f32 v[160:161], v[160:161], v[162:163]
	v_pk_mul_f32 v[162:163], v[64:65], v[146:147] op_sel_hi:[1,0]
	s_nop 0
	v_pk_mul_f32 v[162:163], v[162:163], v[160:161]
	v_pk_mul_f32 v[160:161], v[98:99], v[146:147] op_sel_hi:[1,0]
	v_cvt_pk_bf16_f32 v162, v162, v163
	v_mul_f32_e32 v147, 0xbfb8aa3b, v160
	v_exp_f32_e32 v147, v147
	s_nop 0
	v_add_f32_e32 v147, 1.0, v147
	v_rcp_f32_e32 v164, v147
	v_mul_f32_e32 v147, 0xbfb8aa3b, v161
	v_exp_f32_e32 v147, v147
	s_nop 0
	v_add_f32_e32 v147, 1.0, v147
	v_rcp_f32_e32 v165, v147
	v_pk_mul_f32 v[146:147], v[66:67], v[146:147] op_sel_hi:[1,0]
	v_pk_mul_f32 v[160:161], v[160:161], v[164:165]
	s_nop 0
	v_pk_mul_f32 v[146:147], v[146:147], v[160:161]
	v_cvt_pk_bf16_f32 v160, v148, v149
	v_cvt_pk_bf16_f32 v163, v146, v147
	v_add_co_u32_e32 v146, vcc, s6, v150
	v_cvt_pk_bf16_f32 v161, v152, v153
	s_nop 0
	v_addc_co_u32_e32 v147, vcc, 0, v151, vcc
	global_store_dwordx4 v[146:147], v[160:163], off
	ds_read2_b32 v[146:147], v158 offset0:128 offset1:144
	s_mov_b32 s6, 0xb0000
	s_waitcnt lgkmcnt(0)
	v_pk_mul_f32 v[148:149], v[60:61], v[146:147] op_sel_hi:[1,0]
	s_nop 0
	v_mul_f32_e32 v152, 0xbfb8aa3b, v148
	v_mul_f32_e32 v153, 0xbfb8aa3b, v149
	v_exp_f32_e32 v152, v152
	v_exp_f32_e32 v153, v153
	v_add_f32_e32 v152, 1.0, v152
	v_add_f32_e32 v153, 1.0, v153
	v_rcp_f32_e32 v152, v152
	v_rcp_f32_e32 v153, v153
	s_nop 0
	v_pk_mul_f32 v[148:149], v[148:149], v[152:153]
	v_pk_mul_f32 v[152:153], v[28:29], v[146:147] op_sel_hi:[1,0]
	s_nop 0
	v_pk_mul_f32 v[148:149], v[152:153], v[148:149]
	v_pk_mul_f32 v[152:153], v[62:63], v[146:147] op_sel_hi:[1,0]
	s_nop 0
	v_mul_f32_e32 v159, 0xbfb8aa3b, v152
	v_exp_f32_e32 v159, v159
	s_nop 0
	v_add_f32_e32 v159, 1.0, v159
	v_rcp_f32_e32 v160, v159
	v_mul_f32_e32 v159, 0xbfb8aa3b, v153
	v_exp_f32_e32 v159, v159
	s_nop 0
	v_add_f32_e32 v159, 1.0, v159
	v_rcp_f32_e32 v161, v159
	s_nop 0
	v_pk_mul_f32 v[152:153], v[152:153], v[160:161]
	v_pk_mul_f32 v[160:161], v[30:31], v[146:147] op_sel_hi:[1,0]
	s_nop 0
	v_pk_mul_f32 v[152:153], v[160:161], v[152:153]
	v_pk_mul_f32 v[160:161], v[56:57], v[146:147] op_sel_hi:[1,0]
	s_nop 0
	v_mul_f32_e32 v159, 0xbfb8aa3b, v160
	v_exp_f32_e32 v159, v159
	s_nop 0
	v_add_f32_e32 v159, 1.0, v159
	v_rcp_f32_e32 v162, v159
	v_mul_f32_e32 v159, 0xbfb8aa3b, v161
	v_exp_f32_e32 v159, v159
	s_nop 0
	v_add_f32_e32 v159, 1.0, v159
	v_rcp_f32_e32 v163, v159
	s_nop 0
	v_pk_mul_f32 v[160:161], v[160:161], v[162:163]
	v_pk_mul_f32 v[162:163], v[24:25], v[146:147] op_sel_hi:[1,0]
	s_nop 0
	v_pk_mul_f32 v[162:163], v[162:163], v[160:161]
	v_pk_mul_f32 v[160:161], v[58:59], v[146:147] op_sel_hi:[1,0]
	v_cvt_pk_bf16_f32 v162, v162, v163
	v_mul_f32_e32 v159, 0xbfb8aa3b, v160
	v_exp_f32_e32 v159, v159
	s_nop 0
	v_add_f32_e32 v159, 1.0, v159
	v_rcp_f32_e32 v164, v159
	v_mul_f32_e32 v159, 0xbfb8aa3b, v161
	v_exp_f32_e32 v159, v159
	s_nop 0
	v_add_f32_e32 v159, 1.0, v159
	v_rcp_f32_e32 v165, v159
	s_nop 0
	v_pk_mul_f32 v[160:161], v[160:161], v[164:165]
	v_pk_mul_f32 v[164:165], v[26:27], v[146:147] op_sel_hi:[1,0]
	v_mov_b32_e32 v146, v147
	v_pk_mul_f32 v[164:165], v[164:165], v[160:161]
	v_cvt_pk_bf16_f32 v160, v148, v149
	v_add_co_u32_e32 v148, vcc, s6, v150
	v_cvt_pk_bf16_f32 v161, v152, v153
	v_cvt_pk_bf16_f32 v163, v164, v165
	v_addc_co_u32_e32 v149, vcc, 0, v151, vcc
	global_store_dwordx4 v[148:149], v[160:163], off
	v_pk_mul_f32 v[148:149], v[52:53], v[146:147] op_sel_hi:[1,0]
	s_mov_b32 s6, 0xc6000
	v_mul_f32_e32 v147, 0xbfb8aa3b, v148
	v_exp_f32_e32 v147, v147
	s_nop 0
	v_add_f32_e32 v147, 1.0, v147
	v_rcp_f32_e32 v152, v147
	v_mul_f32_e32 v147, 0xbfb8aa3b, v149
	v_exp_f32_e32 v147, v147
	s_nop 0
	v_add_f32_e32 v147, 1.0, v147
	v_rcp_f32_e32 v153, v147
	s_nop 0
	v_pk_mul_f32 v[148:149], v[148:149], v[152:153]
	v_pk_mul_f32 v[152:153], v[20:21], v[146:147] op_sel_hi:[1,0]
	s_nop 0
	v_pk_mul_f32 v[148:149], v[152:153], v[148:149]
	v_pk_mul_f32 v[152:153], v[54:55], v[146:147] op_sel_hi:[1,0]
	s_nop 0
	v_mul_f32_e32 v147, 0xbfb8aa3b, v152
	v_exp_f32_e32 v147, v147
	s_nop 0
	v_add_f32_e32 v147, 1.0, v147
	v_rcp_f32_e32 v160, v147
	v_mul_f32_e32 v147, 0xbfb8aa3b, v153
	v_exp_f32_e32 v147, v147
	s_nop 0
	v_add_f32_e32 v147, 1.0, v147
	v_rcp_f32_e32 v161, v147
	s_nop 0
	v_pk_mul_f32 v[152:153], v[152:153], v[160:161]
	v_pk_mul_f32 v[160:161], v[22:23], v[146:147] op_sel_hi:[1,0]
	s_nop 0
	v_pk_mul_f32 v[152:153], v[160:161], v[152:153]
	v_pk_mul_f32 v[160:161], v[48:49], v[146:147] op_sel_hi:[1,0]
	s_nop 0
	v_mul_f32_e32 v147, 0xbfb8aa3b, v160
	v_exp_f32_e32 v147, v147
	s_nop 0
	v_add_f32_e32 v147, 1.0, v147
	v_rcp_f32_e32 v162, v147
	v_mul_f32_e32 v147, 0xbfb8aa3b, v161
	v_exp_f32_e32 v147, v147
	s_nop 0
	v_add_f32_e32 v147, 1.0, v147
	v_rcp_f32_e32 v163, v147
	s_nop 0
	v_pk_mul_f32 v[160:161], v[160:161], v[162:163]
	v_pk_mul_f32 v[162:163], v[16:17], v[146:147] op_sel_hi:[1,0]
	s_nop 0
	v_pk_mul_f32 v[162:163], v[162:163], v[160:161]
	v_pk_mul_f32 v[160:161], v[50:51], v[146:147] op_sel_hi:[1,0]
	v_cvt_pk_bf16_f32 v162, v162, v163
	v_mul_f32_e32 v147, 0xbfb8aa3b, v160
	v_exp_f32_e32 v147, v147
	s_nop 0
	v_add_f32_e32 v147, 1.0, v147
	v_rcp_f32_e32 v164, v147
	v_mul_f32_e32 v147, 0xbfb8aa3b, v161
	v_exp_f32_e32 v147, v147
	s_nop 0
	v_add_f32_e32 v147, 1.0, v147
	v_rcp_f32_e32 v165, v147
	v_pk_mul_f32 v[146:147], v[18:19], v[146:147] op_sel_hi:[1,0]
	v_pk_mul_f32 v[160:161], v[160:161], v[164:165]
	s_nop 0
	v_pk_mul_f32 v[146:147], v[146:147], v[160:161]
	v_cvt_pk_bf16_f32 v160, v148, v149
	v_cvt_pk_bf16_f32 v163, v146, v147
	v_add_co_u32_e32 v146, vcc, s6, v150
	v_cvt_pk_bf16_f32 v161, v152, v153
	s_nop 0
	v_addc_co_u32_e32 v147, vcc, 0, v151, vcc
	global_store_dwordx4 v[146:147], v[160:163], off
	ds_read2_b32 v[146:147], v158 offset0:160 offset1:176
	s_mov_b32 s6, 0xdc000
	s_waitcnt lgkmcnt(0)
	v_pk_mul_f32 v[148:149], v[44:45], v[146:147] op_sel_hi:[1,0]
	s_nop 0
	v_mul_f32_e32 v152, 0xbfb8aa3b, v148
	v_mul_f32_e32 v153, 0xbfb8aa3b, v149
	v_exp_f32_e32 v152, v152
	v_exp_f32_e32 v153, v153
	v_add_f32_e32 v152, 1.0, v152
	v_add_f32_e32 v153, 1.0, v153
	v_rcp_f32_e32 v152, v152
	v_rcp_f32_e32 v153, v153
	s_nop 0
	v_pk_mul_f32 v[148:149], v[148:149], v[152:153]
	v_pk_mul_f32 v[152:153], v[12:13], v[146:147] op_sel_hi:[1,0]
	s_nop 0
	v_pk_mul_f32 v[148:149], v[152:153], v[148:149]
	v_pk_mul_f32 v[152:153], v[46:47], v[146:147] op_sel_hi:[1,0]
	s_nop 0
	v_mul_f32_e32 v158, 0xbfb8aa3b, v152
	v_mul_f32_e32 v159, 0xbfb8aa3b, v153
	v_exp_f32_e32 v158, v158
	v_exp_f32_e32 v159, v159
	v_add_f32_e32 v158, 1.0, v158
	v_add_f32_e32 v159, 1.0, v159
	v_rcp_f32_e32 v158, v158
	v_rcp_f32_e32 v159, v159
	s_nop 0
	v_pk_mul_f32 v[152:153], v[152:153], v[158:159]
	v_pk_mul_f32 v[158:159], v[14:15], v[146:147] op_sel_hi:[1,0]
	s_nop 0
	v_pk_mul_f32 v[152:153], v[158:159], v[152:153]
	v_pk_mul_f32 v[158:159], v[40:41], v[146:147] op_sel_hi:[1,0]
	s_nop 0
	v_mul_f32_e32 v160, 0xbfb8aa3b, v158
	v_mul_f32_e32 v161, 0xbfb8aa3b, v159
	v_exp_f32_e32 v160, v160
	v_exp_f32_e32 v161, v161
	v_add_f32_e32 v160, 1.0, v160
	v_add_f32_e32 v161, 1.0, v161
	v_rcp_f32_e32 v160, v160
	v_rcp_f32_e32 v161, v161
	s_nop 0
	v_pk_mul_f32 v[158:159], v[158:159], v[160:161]
	v_pk_mul_f32 v[160:161], v[8:9], v[146:147] op_sel_hi:[1,0]
	s_nop 0
	v_pk_mul_f32 v[160:161], v[160:161], v[158:159]
	v_pk_mul_f32 v[158:159], v[42:43], v[146:147] op_sel_hi:[1,0]
	v_cvt_pk_bf16_f32 v160, v160, v161
	v_mul_f32_e32 v162, 0xbfb8aa3b, v158
	v_mul_f32_e32 v163, 0xbfb8aa3b, v159
	v_exp_f32_e32 v162, v162
	v_exp_f32_e32 v163, v163
	v_add_f32_e32 v162, 1.0, v162
	v_add_f32_e32 v163, 1.0, v163
	v_rcp_f32_e32 v162, v162
	v_rcp_f32_e32 v163, v163
	s_nop 0
	v_pk_mul_f32 v[158:159], v[158:159], v[162:163]
	v_pk_mul_f32 v[162:163], v[10:11], v[146:147] op_sel_hi:[1,0]
	v_mov_b32_e32 v146, v147
	v_pk_mul_f32 v[162:163], v[162:163], v[158:159]
	v_cvt_pk_bf16_f32 v158, v148, v149
	v_add_co_u32_e32 v148, vcc, s6, v150
	v_cvt_pk_bf16_f32 v159, v152, v153
	v_cvt_pk_bf16_f32 v161, v162, v163
	v_addc_co_u32_e32 v149, vcc, 0, v151, vcc
	global_store_dwordx4 v[148:149], v[158:161], off
	v_pk_mul_f32 v[148:149], v[36:37], v[146:147] op_sel_hi:[1,0]
	s_nop 0
	v_mul_f32_e32 v147, 0xbfb8aa3b, v148
	v_exp_f32_e32 v147, v147
	s_nop 0
	v_add_f32_e32 v147, 1.0, v147
	v_rcp_f32_e32 v152, v147
	v_mul_f32_e32 v147, 0xbfb8aa3b, v149
	v_exp_f32_e32 v147, v147
	s_nop 0
	v_add_f32_e32 v147, 1.0, v147
	v_rcp_f32_e32 v153, v147
	s_nop 0
	v_pk_mul_f32 v[148:149], v[148:149], v[152:153]
	v_pk_mul_f32 v[152:153], v[4:5], v[146:147] op_sel_hi:[1,0]
	s_nop 0
	v_pk_mul_f32 v[148:149], v[152:153], v[148:149]
	v_pk_mul_f32 v[152:153], v[38:39], v[146:147] op_sel_hi:[1,0]
	s_nop 0
	v_mul_f32_e32 v147, 0xbfb8aa3b, v152
	v_exp_f32_e32 v147, v147
	s_nop 0
	v_add_f32_e32 v147, 1.0, v147
	v_rcp_f32_e32 v158, v147
	v_mul_f32_e32 v147, 0xbfb8aa3b, v153
	v_exp_f32_e32 v147, v147
	s_nop 0
	v_add_f32_e32 v147, 1.0, v147
	v_rcp_f32_e32 v159, v147
	s_nop 0
	v_pk_mul_f32 v[152:153], v[152:153], v[158:159]
	v_pk_mul_f32 v[158:159], v[6:7], v[146:147] op_sel_hi:[1,0]
	s_nop 0
	v_pk_mul_f32 v[152:153], v[158:159], v[152:153]
	v_pk_mul_f32 v[158:159], v[32:33], v[146:147] op_sel_hi:[1,0]
	s_nop 0
	v_mul_f32_e32 v147, 0xbfb8aa3b, v158
	v_exp_f32_e32 v147, v147
	s_nop 0
	v_add_f32_e32 v147, 1.0, v147
	v_rcp_f32_e32 v160, v147
	v_mul_f32_e32 v147, 0xbfb8aa3b, v159
	v_exp_f32_e32 v147, v147
	s_nop 0
	v_add_f32_e32 v147, 1.0, v147
	v_rcp_f32_e32 v161, v147
	s_nop 0
	v_pk_mul_f32 v[158:159], v[158:159], v[160:161]
	v_pk_mul_f32 v[160:161], v[0:1], v[146:147] op_sel_hi:[1,0]
	s_nop 0
	v_pk_mul_f32 v[160:161], v[160:161], v[158:159]
	v_pk_mul_f32 v[158:159], v[34:35], v[146:147] op_sel_hi:[1,0]
	v_cvt_pk_bf16_f32 v160, v160, v161
	v_mul_f32_e32 v147, 0xbfb8aa3b, v158
	v_exp_f32_e32 v147, v147
	s_nop 0
	v_add_f32_e32 v147, 1.0, v147
	v_rcp_f32_e32 v162, v147
	v_mul_f32_e32 v147, 0xbfb8aa3b, v159
	v_exp_f32_e32 v147, v147
	s_nop 0
	v_add_f32_e32 v147, 1.0, v147
	v_rcp_f32_e32 v163, v147
	v_pk_mul_f32 v[146:147], v[2:3], v[146:147] op_sel_hi:[1,0]
	v_pk_mul_f32 v[158:159], v[158:159], v[162:163]
	s_nop 0
	v_pk_mul_f32 v[146:147], v[146:147], v[158:159]
	v_cvt_pk_bf16_f32 v158, v148, v149
	v_cvt_pk_bf16_f32 v161, v146, v147
	v_add_co_u32_e32 v146, vcc, 0xf2000, v150
	v_cvt_pk_bf16_f32 v159, v152, v153
	s_nop 0
	v_addc_co_u32_e32 v147, vcc, 0, v151, vcc
	s_andn2_b64 vcc, exec, s[44:45]
	global_store_dwordx4 v[146:147], v[158:161], off
	s_cbranch_vccz .LBB0_73
	s_mov_b64 s[46:47], s[50:51]
	s_andn2_b64 vcc, exec, s[42:43]
	s_mov_b64 s[50:51], s[46:47]
	s_cbranch_vccnz .LBB0_74

.LBB0_90:
	s_waitcnt lgkmcnt(0)
	s_add_u32 s26, s26, 0x12290000
	s_addc_u32 s27, s27, 0
	s_add_u32 s28, s28, 0x12290000
	s_addc_u32 s29, s29, 0
	s_and_b32 s12, s10, 3
	s_add_i32 m0, s72, 0x18000
	v_lshl_add_u64 v[6:7], v[6:7], 0, s[36:37]
	s_lshl_b32 s19, s6, 6
	s_lshl_b32 s6, s6, 13
	s_lshl_b32 s23, s12, 12
	s_waitcnt vmcnt(0)
	s_barrier
	global_load_lds_dwordx4 v[6:7], off
	v_lshl_add_u64 v[4:5], v[4:5], 0, s[36:37]
	s_add_i32 m0, s72, 0x1a000
	s_add_i32 s80, s72, 0x8000
	s_add_i32 s81, s72, 0xa000
	global_load_lds_dwordx4 v[4:5], off
	v_lshl_add_u64 v[2:3], v[2:3], 0, s[36:37]
	s_mov_b32 m0, s80
	s_add_u32 s10, s58, 0x40080
	global_load_lds_dwordx4 v[2:3], off
	v_lshl_add_u64 v[0:1], v[0:1], 0, s[36:37]
	s_mov_b32 m0, s81
	s_addc_u32 s11, s59, 0
	global_load_lds_dwordx4 v[0:1], off
	s_add_i32 m0, s72, 0x1c000
	v_lshl_add_u64 v[0:1], s[10:11], 0, v[140:141]
	global_load_lds_dwordx4 v[0:1], off
	v_lshl_add_u64 v[0:1], s[10:11], 0, v[150:151]
	s_add_i32 m0, s72, 0x1e000
	v_lshlrev_b32_e32 v4, 2, v8
	global_load_lds_dwordx4 v[0:1], off
	v_bfe_u32 v1, v8, 4, 2
	v_and_b32_e32 v0, 15, v8
	v_lshlrev_b32_e32 v3, 4, v1
	v_lshl_or_b32 v3, v0, 6, v3
	v_or_b32_e32 v156, s19, v0
	v_lshlrev_b32_e32 v0, 14, v13
	v_and_b32_e32 v0, 0xffff8000, v0
	v_lshlrev_b32_e32 v2, 3, v1
	v_and_b32_e32 v4, 32, v4
	v_cmp_eq_u32_e64 s[42:43], 0, v1
	v_lshl_add_u32 v0, v12, 11, v0
	v_and_b32_e32 v1, 1, v13
	v_bitop3_b32 v5, v3, s6, v4 bitop3:0xde
	s_ashr_i32 s6, s19, 31
	v_lshl_or_b32 v0, v1, 6, v0
	v_mov_b32_e32 v157, s6
	s_lshl_b32 s6, s12, 2
	v_lshl_add_u32 v158, v14, 1, v0
	v_lshlrev_b32_e32 v0, 14, v9
	s_add_u32 s6, s34, s6
	v_and_b32_e32 v0, 0xffff8000, v0
	s_waitcnt vmcnt(6)
	s_addc_u32 s10, s35, 0
	v_lshl_add_u32 v0, v10, 11, v0
	v_and_b32_e32 v1, 1, v9
	s_add_u32 s83, s6, 0x1e114000
	v_lshl_or_b32 v0, v1, 6, v0
	v_bitop3_b32 v206, v3, s23, v4 bitop3:0xde
	v_lshl_or_b32 v207, s12, 5, v2
	s_mov_b32 s82, 0
	s_addc_u32 s84, s10, 0
	v_mov_b32_e32 v159, v141
	v_lshl_add_u32 v160, v11, 1, v0
	v_mov_b32_e32 v161, v141
	v_add_u32_e32 v208, 0, v5
	v_readlane_b32 s50, v254, 10
	v_readlane_b32 s85, v253, 55
	v_readlane_b32 s52, v254, 14
	s_barrier
	v_readlane_b32 s51, v254, 11
	v_readlane_b32 s53, v254, 15
	s_mov_b32 s100, 0
	s_branch .LBB0_92

.LBB0_103:
	s_add_u32 s6, s54, 0xfffc0080
	s_addc_u32 s19, s55, -1
	s_add_i32 s23, 0, 0x10000
	v_add_u32_e32 v146, s23, v206
	ds_read_b128 v[128:131], v146
	ds_read_b128 v[132:135], v146 offset:1024
	ds_read_b128 v[136:139], v146 offset:2048
	ds_read_b128 v[146:149], v146 offset:3072
	s_cmp_eq_u32 s12, 12
	s_cselect_b32 s69, s47, s19
	s_cselect_b32 s68, s46, s6
	s_cselect_b32 s59, s49, s11
	s_cselect_b32 s58, s48, s10
	v_lshl_add_u64 v[192:193], s[54:55], 0, v[158:159]
	s_add_i32 m0, s72, 0xc000
	ds_read_b128 v[162:165], v208
	ds_read_b128 v[166:169], v208 offset:1024
	ds_read_b128 v[170:173], v208 offset:2048
	ds_read_b128 v[174:177], v208 offset:3072
	ds_read_b128 v[178:181], v208 offset:4096
	ds_read_b128 v[182:185], v208 offset:5120
	ds_read_b128 v[194:197], v208 offset:6144
	ds_read_b128 v[210:213], v208 offset:7168
	global_load_lds_dwordx4 v[192:193], off
	v_lshl_add_u64 v[192:193], s[54:55], 0, v[160:161]
	s_add_i32 m0, s72, 0xe000
	s_nop 0
	global_load_lds_dwordx4 v[192:193], off
	s_add_i32 s6, 0, 0x14000
	v_add_u32_e32 v192, s6, v206
	ds_read_b128 v[214:217], v192
	ds_read_b128 v[218:221], v192 offset:1024
	ds_read_b128 v[222:225], v192 offset:2048
	ds_read_b128 v[226:229], v192 offset:3072
	s_waitcnt vmcnt(40)
	s_cmp_lg_u32 s100, 0
	s_cbranch_scc1 .Lm4a_103
	s_waitcnt vmcnt(8)
.Lm4a_103:
	s_waitcnt lgkmcnt(0)
	s_barrier
	s_setprio 1
	v_mfma_f32_16x16x32_bf16 v[124:127], v[128:131], v[162:165], v[124:127]
	v_mfma_f32_16x16x32_bf16 v[120:123], v[136:139], v[162:165], v[120:123]
	v_mfma_f32_16x16x32_bf16 v[108:111], v[128:131], v[170:173], v[108:111]
	v_mfma_f32_16x16x32_bf16 v[104:107], v[136:139], v[170:173], v[104:107]
	v_mfma_f32_16x16x32_bf16 v[96:99], v[128:131], v[178:181], v[96:99]
	v_mfma_f32_16x16x32_bf16 v[88:91], v[136:139], v[178:181], v[88:91]
	v_mfma_f32_16x16x32_bf16 v[84:87], v[128:131], v[194:197], v[84:87]
	v_mfma_f32_16x16x32_bf16 v[80:83], v[136:139], v[194:197], v[80:83]
	v_mfma_f32_16x16x32_bf16 v[124:127], v[132:135], v[166:169], v[124:127]
	v_mfma_f32_16x16x32_bf16 v[120:123], v[146:149], v[166:169], v[120:123]
	v_mfma_f32_16x16x32_bf16 v[108:111], v[132:135], v[174:177], v[108:111]
	v_mfma_f32_16x16x32_bf16 v[104:107], v[146:149], v[174:177], v[104:107]
	v_mfma_f32_16x16x32_bf16 v[96:99], v[132:135], v[182:185], v[96:99]
	v_mfma_f32_16x16x32_bf16 v[88:91], v[146:149], v[182:185], v[88:91]
	v_mfma_f32_16x16x32_bf16 v[84:87], v[132:135], v[210:213], v[84:87]
	v_mfma_f32_16x16x32_bf16 v[80:83], v[146:149], v[210:213], v[80:83]
	v_mfma_f32_16x16x32_bf16 v[116:119], v[214:217], v[162:165], v[116:119]
	v_mfma_f32_16x16x32_bf16 v[112:115], v[222:225], v[162:165], v[112:115]
	v_mfma_f32_16x16x32_bf16 v[100:103], v[214:217], v[170:173], v[100:103]
	v_mfma_f32_16x16x32_bf16 v[92:95], v[222:225], v[170:173], v[92:95]
	v_mfma_f32_16x16x32_bf16 v[76:79], v[214:217], v[178:181], v[76:79]
	v_mfma_f32_16x16x32_bf16 v[72:75], v[222:225], v[178:181], v[72:75]
	v_mfma_f32_16x16x32_bf16 v[68:71], v[214:217], v[194:197], v[68:71]
	v_mfma_f32_16x16x32_bf16 v[64:67], v[222:225], v[194:197], v[64:67]
	v_mfma_f32_16x16x32_bf16 v[116:119], v[218:221], v[166:169], v[116:119]
	v_mfma_f32_16x16x32_bf16 v[112:115], v[226:229], v[166:169], v[112:115]
	v_mfma_f32_16x16x32_bf16 v[100:103], v[218:221], v[174:177], v[100:103]
	v_mfma_f32_16x16x32_bf16 v[92:95], v[226:229], v[174:177], v[92:95]
	v_mfma_f32_16x16x32_bf16 v[76:79], v[218:221], v[182:185], v[76:79]
	v_mfma_f32_16x16x32_bf16 v[72:75], v[226:229], v[182:185], v[72:75]
	v_mfma_f32_16x16x32_bf16 v[68:71], v[218:221], v[210:213], v[68:71]
	v_mfma_f32_16x16x32_bf16 v[64:67], v[226:229], v[210:213], v[64:67]
	s_setprio 0
	s_barrier
	s_add_i32 s19, s23, s71
	v_lshl_add_u64 v[192:193], s[58:59], 0, v[140:141]
	s_mov_b32 m0, s19
	v_lshl_add_u64 v[230:231], s[58:59], 0, v[150:151]
	global_load_lds_dwordx4 v[192:193], off
	s_add_i32 m0, s19, 0x2000
	s_nop 0
	global_load_lds_dwordx4 v[230:231], off
	s_mov_b32 m0, s72
	v_lshl_add_u64 v[232:233], s[68:69], 0, v[154:155]
	ds_read_b128 v[162:165], v208 offset:16384
	ds_read_b128 v[166:169], v208 offset:17408
	ds_read_b128 v[170:173], v208 offset:18432
	ds_read_b128 v[174:177], v208 offset:19456
	ds_read_b128 v[178:181], v208 offset:20480
	ds_read_b128 v[182:185], v208 offset:21504
	ds_read_b128 v[194:197], v208 offset:22528
	ds_read_b128 v[210:213], v208 offset:23552
	global_load_lds_dwordx4 v[232:233], off
	v_lshl_add_u64 v[234:235], s[68:69], 0, v[152:153]
	s_mov_b32 m0, s73
	s_nop 0
	global_load_lds_dwordx4 v[234:235], off
	s_add_u32 s86, s58, 0x40000
	s_addc_u32 s87, s59, 0
	s_add_i32 s6, s6, s71
	v_lshl_add_u64 v[250:251], s[86:87], 0, v[140:141]
	s_mov_b32 m0, s6
	s_nop 0
	global_load_lds_dwordx4 v[250:251], off
	v_lshl_add_u64 v[250:251], s[86:87], 0, v[150:151]
	s_add_i32 m0, s6, 0x2000
	s_nop 0
	global_load_lds_dwordx4 v[250:251], off
	s_waitcnt vmcnt(40)
	s_cmp_lg_u32 s100, 0
	s_cbranch_scc1 .Lm4b_103
	s_waitcnt vmcnt(8)
.Lm4b_103:
	s_waitcnt lgkmcnt(0)
	s_mov_b32 s100, 0
	s_barrier
	s_setprio 1
	v_mfma_f32_16x16x32_bf16 v[60:63], v[128:131], v[162:165], v[60:63]
	v_mfma_f32_16x16x32_bf16 v[56:59], v[136:139], v[162:165], v[56:59]
	v_mfma_f32_16x16x32_bf16 v[48:51], v[128:131], v[170:173], v[48:51]
	v_mfma_f32_16x16x32_bf16 v[40:43], v[136:139], v[170:173], v[40:43]
	v_mfma_f32_16x16x32_bf16 v[32:35], v[128:131], v[178:181], v[32:35]
	v_mfma_f32_16x16x32_bf16 v[24:27], v[136:139], v[178:181], v[24:27]
	v_mfma_f32_16x16x32_bf16 v[16:19], v[128:131], v[194:197], v[16:19]
	v_mfma_f32_16x16x32_bf16 v[8:11], v[136:139], v[194:197], v[8:11]
	v_mfma_f32_16x16x32_bf16 v[60:63], v[132:135], v[166:169], v[60:63]
	v_mfma_f32_16x16x32_bf16 v[56:59], v[146:149], v[166:169], v[56:59]
	v_mfma_f32_16x16x32_bf16 v[48:51], v[132:135], v[174:177], v[48:51]
	v_mfma_f32_16x16x32_bf16 v[40:43], v[146:149], v[174:177], v[40:43]
	v_mfma_f32_16x16x32_bf16 v[32:35], v[132:135], v[182:185], v[32:35]
	v_mfma_f32_16x16x32_bf16 v[24:27], v[146:149], v[182:185], v[24:27]
	v_mfma_f32_16x16x32_bf16 v[16:19], v[132:135], v[210:213], v[16:19]
	v_mfma_f32_16x16x32_bf16 v[8:11], v[146:149], v[210:213], v[8:11]
	v_mfma_f32_16x16x32_bf16 v[52:55], v[214:217], v[162:165], v[52:55]
	v_mfma_f32_16x16x32_bf16 v[44:47], v[222:225], v[162:165], v[44:47]
	v_mfma_f32_16x16x32_bf16 v[36:39], v[214:217], v[170:173], v[36:39]
	v_mfma_f32_16x16x32_bf16 v[28:31], v[222:225], v[170:173], v[28:31]
	v_mfma_f32_16x16x32_bf16 v[20:23], v[214:217], v[178:181], v[20:23]
	v_mfma_f32_16x16x32_bf16 v[12:15], v[222:225], v[178:181], v[12:15]
	v_mfma_f32_16x16x32_bf16 v[4:7], v[214:217], v[194:197], v[4:7]
	v_mfma_f32_16x16x32_bf16 v[0:3], v[222:225], v[194:197], v[0:3]
	v_mfma_f32_16x16x32_bf16 v[52:55], v[218:221], v[166:169], v[52:55]
	v_mfma_f32_16x16x32_bf16 v[44:47], v[226:229], v[166:169], v[44:47]
	v_mfma_f32_16x16x32_bf16 v[36:39], v[218:221], v[174:177], v[36:39]
	v_mfma_f32_16x16x32_bf16 v[28:31], v[226:229], v[174:177], v[28:31]
	v_mfma_f32_16x16x32_bf16 v[20:23], v[218:221], v[182:185], v[20:23]
	v_mfma_f32_16x16x32_bf16 v[12:15], v[226:229], v[182:185], v[12:15]
	v_mfma_f32_16x16x32_bf16 v[4:7], v[218:221], v[210:213], v[4:7]
	v_mfma_f32_16x16x32_bf16 v[0:3], v[226:229], v[210:213], v[0:3]
	s_setprio 0
	s_barrier
	s_add_i32 s6, 0, 0x18000
	v_add_u32_e32 v146, s6, v206
	ds_read_b128 v[128:131], v146
	ds_read_b128 v[132:135], v146 offset:1024
	ds_read_b128 v[136:139], v146 offset:2048
	ds_read_b128 v[146:149], v146 offset:3072
	s_add_u32 s68, s68, 0x40000
	s_addc_u32 s69, s69, 0
	s_mov_b32 m0, s74
	v_lshl_add_u64 v[214:215], s[68:69], 0, v[154:155]
	ds_read_b128 v[162:165], v208 offset:32768
	ds_read_b128 v[166:169], v208 offset:33792
	ds_read_b128 v[170:173], v208 offset:34816
	ds_read_b128 v[174:177], v208 offset:35840
	ds_read_b128 v[178:181], v208 offset:36864
	ds_read_b128 v[182:185], v208 offset:37888
	ds_read_b128 v[194:197], v208 offset:38912
	ds_read_b128 v[210:213], v208 offset:39936
	global_load_lds_dwordx4 v[214:215], off
	v_lshl_add_u64 v[214:215], s[68:69], 0, v[152:153]
	s_mov_b32 m0, s75
	s_nop 0
	global_load_lds_dwordx4 v[214:215], off
	s_add_i32 s19, 0, 0x1c000
	v_add_u32_e32 v209, s19, v206
	ds_read_b128 v[214:217], v209
	ds_read_b128 v[218:221], v209 offset:1024
	ds_read_b128 v[222:225], v209 offset:2048
	ds_read_b128 v[226:229], v209 offset:3072
	s_waitcnt vmcnt(8)
	s_waitcnt lgkmcnt(0)
	s_barrier
	s_setprio 1
	v_mfma_f32_16x16x32_bf16 v[124:127], v[128:131], v[162:165], v[124:127]
	v_mfma_f32_16x16x32_bf16 v[120:123], v[136:139], v[162:165], v[120:123]
	v_mfma_f32_16x16x32_bf16 v[108:111], v[128:131], v[170:173], v[108:111]
	v_mfma_f32_16x16x32_bf16 v[104:107], v[136:139], v[170:173], v[104:107]
	v_mfma_f32_16x16x32_bf16 v[96:99], v[128:131], v[178:181], v[96:99]
	v_mfma_f32_16x16x32_bf16 v[88:91], v[136:139], v[178:181], v[88:91]
	v_mfma_f32_16x16x32_bf16 v[84:87], v[128:131], v[194:197], v[84:87]
	v_mfma_f32_16x16x32_bf16 v[80:83], v[136:139], v[194:197], v[80:83]
	v_mfma_f32_16x16x32_bf16 v[124:127], v[132:135], v[166:169], v[124:127]
	v_mfma_f32_16x16x32_bf16 v[120:123], v[146:149], v[166:169], v[120:123]
	v_mfma_f32_16x16x32_bf16 v[108:111], v[132:135], v[174:177], v[108:111]
	v_mfma_f32_16x16x32_bf16 v[104:107], v[146:149], v[174:177], v[104:107]
	v_mfma_f32_16x16x32_bf16 v[96:99], v[132:135], v[182:185], v[96:99]
	v_mfma_f32_16x16x32_bf16 v[88:91], v[146:149], v[182:185], v[88:91]
	v_mfma_f32_16x16x32_bf16 v[84:87], v[132:135], v[210:213], v[84:87]
	v_mfma_f32_16x16x32_bf16 v[80:83], v[146:149], v[210:213], v[80:83]
	v_mfma_f32_16x16x32_bf16 v[116:119], v[214:217], v[162:165], v[116:119]
	v_mfma_f32_16x16x32_bf16 v[112:115], v[222:225], v[162:165], v[112:115]
	v_mfma_f32_16x16x32_bf16 v[100:103], v[214:217], v[170:173], v[100:103]
	v_mfma_f32_16x16x32_bf16 v[92:95], v[222:225], v[170:173], v[92:95]
	v_mfma_f32_16x16x32_bf16 v[76:79], v[214:217], v[178:181], v[76:79]
	v_mfma_f32_16x16x32_bf16 v[72:75], v[222:225], v[178:181], v[72:75]
	v_mfma_f32_16x16x32_bf16 v[68:71], v[214:217], v[194:197], v[68:71]
	v_mfma_f32_16x16x32_bf16 v[64:67], v[222:225], v[194:197], v[64:67]
	v_mfma_f32_16x16x32_bf16 v[116:119], v[218:221], v[166:169], v[116:119]
	v_mfma_f32_16x16x32_bf16 v[112:115], v[226:229], v[166:169], v[112:115]
	v_mfma_f32_16x16x32_bf16 v[100:103], v[218:221], v[174:177], v[100:103]
	v_mfma_f32_16x16x32_bf16 v[92:95], v[226:229], v[174:177], v[92:95]
	v_mfma_f32_16x16x32_bf16 v[76:79], v[218:221], v[182:185], v[76:79]
	v_mfma_f32_16x16x32_bf16 v[72:75], v[226:229], v[182:185], v[72:75]
	v_mfma_f32_16x16x32_bf16 v[68:71], v[218:221], v[210:213], v[68:71]
	v_mfma_f32_16x16x32_bf16 v[64:67], v[226:229], v[210:213], v[64:67]
	s_setprio 0
	s_barrier
	s_add_i32 s6, s6, s71
	v_lshl_add_u64 v[192:193], v[192:193], 0, s[36:37]
	s_mov_b32 m0, s6
	s_nop 0
	global_load_lds_dwordx4 v[192:193], off
	v_lshl_add_u64 v[192:193], v[230:231], 0, s[36:37]
	s_add_i32 m0, s6, 0x2000
	s_nop 0
	global_load_lds_dwordx4 v[192:193], off
	s_mov_b32 m0, s80
	v_lshl_add_u64 v[192:193], v[232:233], 0, s[36:37]
	ds_read_b128 v[162:165], v208 offset:49152
	ds_read_b128 v[166:169], v208 offset:50176
	ds_read_b128 v[170:173], v208 offset:51200
	ds_read_b128 v[174:177], v208 offset:52224
	ds_read_b128 v[178:181], v208 offset:53248
	ds_read_b128 v[182:185], v208 offset:54272
	ds_read_b128 v[194:197], v208 offset:55296
	ds_read_b128 v[210:213], v208 offset:56320
	global_load_lds_dwordx4 v[192:193], off
	v_lshl_add_u64 v[192:193], v[234:235], 0, s[36:37]
	s_mov_b32 m0, s81
	s_nop 0
	global_load_lds_dwordx4 v[192:193], off
	s_add_u32 s58, s58, 0x40080
	s_addc_u32 s59, s59, 0
	s_add_i32 s6, s19, s71
	v_lshl_add_u64 v[250:251], s[58:59], 0, v[140:141]
	s_mov_b32 m0, s6
	s_nop 0
	global_load_lds_dwordx4 v[250:251], off
	v_lshl_add_u64 v[250:251], s[58:59], 0, v[150:151]
	s_add_i32 m0, s6, 0x2000
	s_nop 0
	global_load_lds_dwordx4 v[250:251], off
	s_waitcnt vmcnt(8)
	s_waitcnt lgkmcnt(0)
	s_barrier
	s_setprio 1
	v_mfma_f32_16x16x32_bf16 v[60:63], v[128:131], v[162:165], v[60:63]
	v_mfma_f32_16x16x32_bf16 v[56:59], v[136:139], v[162:165], v[56:59]
	v_mfma_f32_16x16x32_bf16 v[48:51], v[128:131], v[170:173], v[48:51]
	v_mfma_f32_16x16x32_bf16 v[40:43], v[136:139], v[170:173], v[40:43]
	v_mfma_f32_16x16x32_bf16 v[32:35], v[128:131], v[178:181], v[32:35]
	v_mfma_f32_16x16x32_bf16 v[24:27], v[136:139], v[178:181], v[24:27]
	v_mfma_f32_16x16x32_bf16 v[16:19], v[128:131], v[194:197], v[16:19]
	v_mfma_f32_16x16x32_bf16 v[8:11], v[136:139], v[194:197], v[8:11]
	v_mfma_f32_16x16x32_bf16 v[60:63], v[132:135], v[166:169], v[60:63]
	v_mfma_f32_16x16x32_bf16 v[56:59], v[146:149], v[166:169], v[56:59]
	v_mfma_f32_16x16x32_bf16 v[48:51], v[132:135], v[174:177], v[48:51]
	v_mfma_f32_16x16x32_bf16 v[40:43], v[146:149], v[174:177], v[40:43]
	v_mfma_f32_16x16x32_bf16 v[32:35], v[132:135], v[182:185], v[32:35]
	v_mfma_f32_16x16x32_bf16 v[24:27], v[146:149], v[182:185], v[24:27]
	v_mfma_f32_16x16x32_bf16 v[16:19], v[132:135], v[210:213], v[16:19]
	v_mfma_f32_16x16x32_bf16 v[8:11], v[146:149], v[210:213], v[8:11]
	v_mfma_f32_16x16x32_bf16 v[52:55], v[214:217], v[162:165], v[52:55]
	v_mfma_f32_16x16x32_bf16 v[44:47], v[222:225], v[162:165], v[44:47]
	v_mfma_f32_16x16x32_bf16 v[36:39], v[214:217], v[170:173], v[36:39]
	v_mfma_f32_16x16x32_bf16 v[28:31], v[222:225], v[170:173], v[28:31]
	v_mfma_f32_16x16x32_bf16 v[20:23], v[214:217], v[178:181], v[20:23]
	v_mfma_f32_16x16x32_bf16 v[12:15], v[222:225], v[178:181], v[12:15]
	v_mfma_f32_16x16x32_bf16 v[4:7], v[214:217], v[194:197], v[4:7]
	v_mfma_f32_16x16x32_bf16 v[0:3], v[222:225], v[194:197], v[0:3]
	v_mfma_f32_16x16x32_bf16 v[52:55], v[218:221], v[166:169], v[52:55]
	v_mfma_f32_16x16x32_bf16 v[44:47], v[226:229], v[166:169], v[44:47]
	v_mfma_f32_16x16x32_bf16 v[36:39], v[218:221], v[174:177], v[36:39]
	v_mfma_f32_16x16x32_bf16 v[28:31], v[226:229], v[174:177], v[28:31]
	v_mfma_f32_16x16x32_bf16 v[20:23], v[218:221], v[182:185], v[20:23]
	v_mfma_f32_16x16x32_bf16 v[12:15], v[226:229], v[182:185], v[12:15]
	v_mfma_f32_16x16x32_bf16 v[4:7], v[218:221], v[210:213], v[4:7]
	v_mfma_f32_16x16x32_bf16 v[0:3], v[226:229], v[210:213], v[0:3]
	s_setprio 0
	s_add_i32 s12, s12, 2
	s_add_u32 s54, s54, 0x100
	s_addc_u32 s55, s55, 0
	s_add_u32 s10, s10, 0x100
	s_addc_u32 s11, s11, 0
	s_cmp_gt_u32 s12, 13
	s_barrier
	s_cbranch_scc0 .LBB0_103
	s_mov_b32 s100, 1
	s_ashr_i32 s51, s50, 31
	s_ashr_i32 s53, s52, 31
	s_lshl_b64 s[10:11], s[50:51], 13
	s_lshl_b64 s[50:51], s[52:53], 8
	s_add_u32 s10, s50, s10
	v_lshl_or_b32 v128, s85, 8, v207
	s_addc_u32 s11, s51, s11
	v_ashrrev_i32_e32 v129, 31, v128
	v_lshl_add_u64 v[168:169], s[10:11], 0, v[156:157]
	v_lshlrev_b64 v[170:171], 1, v[128:129]
	v_lshl_add_u64 v[174:175], s[26:27], 0, v[170:171]
	v_lshlrev_b64 v[172:173], 11, v[168:169]
	v_or_b32_e32 v166, 16, v168
	v_mov_b32_e32 v167, v169
	v_lshl_add_u64 v[128:129], v[174:175], 0, v[172:173]
	v_lshlrev_b64 v[176:177], 11, v[166:167]
	global_load_dwordx4 v[146:149], v[128:129], off
	global_load_dwordx4 v[182:185], v[128:129], off offset:256
	v_lshl_add_u64 v[128:129], v[174:175], 0, v[176:177]
	global_load_dwordx4 v[194:197], v[128:129], off
	global_load_dwordx4 v[210:213], v[128:129], off offset:256
	v_or_b32_e32 v164, 32, v168
	v_mov_b32_e32 v165, v169
	v_or_b32_e32 v162, 48, v168
	v_mov_b32_e32 v163, v169
	v_lshlrev_b64 v[180:181], 11, v[164:165]
	v_lshlrev_b64 v[178:179], 11, v[162:163]
	v_lshl_add_u64 v[128:129], v[174:175], 0, v[180:181]
	v_lshl_add_u64 v[130:131], v[174:175], 0, v[178:179]
	global_load_dwordx4 v[214:217], v[128:129], off
	global_load_dwordx4 v[136:139], v[128:129], off offset:256
	global_load_dwordx4 v[132:135], v[130:131], off
	s_nop 0
	global_load_dwordx4 v[128:131], v[130:131], off offset:256
	s_mov_b64 s[10:11], 0x90
	v_lshl_add_u64 v[172:173], s[28:29], 0, v[172:173]
	v_lshl_add_u64 v[172:173], v[172:173], 0, v[170:171]
	s_waitcnt vmcnt(0)
	v_lshlrev_b32_e32 v192, 16, v146
	v_and_b32_e32 v193, 0xffff0000, v146
	v_lshlrev_b32_e32 v218, 16, v148
	v_and_b32_e32 v219, 0xffff0000, v148
	v_lshlrev_b32_e32 v146, 16, v147
	v_and_b32_e32 v147, 0xffff0000, v147
	v_lshlrev_b32_e32 v148, 16, v149
	v_and_b32_e32 v149, 0xffff0000, v149
	v_lshlrev_b32_e32 v220, 16, v182
	v_and_b32_e32 v221, 0xffff0000, v182
	v_lshlrev_b32_e32 v222, 16, v184
	v_and_b32_e32 v223, 0xffff0000, v184
	v_lshlrev_b32_e32 v182, 16, v183
	v_and_b32_e32 v183, 0xffff0000, v183
	v_lshlrev_b32_e32 v184, 16, v185
	v_and_b32_e32 v185, 0xffff0000, v185
	v_pk_add_f32 v[124:125], v[124:125], v[192:193]
	v_pk_add_f32 v[126:127], v[126:127], v[146:147]
	v_pk_add_f32 v[122:123], v[122:123], v[148:149]
	v_pk_add_f32 v[116:117], v[116:117], v[220:221]
	v_pk_add_f32 v[146:147], v[112:113], v[222:223]
	v_pk_add_f32 v[118:119], v[118:119], v[182:183]
	v_pk_add_f32 v[148:149], v[114:115], v[184:185]
	v_lshlrev_b32_e32 v182, 16, v194
	v_and_b32_e32 v183, 0xffff0000, v194
	v_lshlrev_b32_e32 v184, 16, v196
	v_and_b32_e32 v185, 0xffff0000, v196
	v_lshlrev_b32_e32 v192, 16, v195
	v_and_b32_e32 v193, 0xffff0000, v195
	v_lshlrev_b32_e32 v194, 16, v197
	v_and_b32_e32 v195, 0xffff0000, v197
	v_pk_mul_f32 v[196:197], v[124:125], v[124:125]
	v_pk_add_f32 v[120:121], v[120:121], v[218:219]
	v_pk_mul_f32 v[218:219], v[126:127], v[126:127]
	v_cvt_pk_bf16_f32 v112, v124, v125
	v_cvt_pk_bf16_f32 v113, v126, v127
	v_pk_mul_f32 v[124:125], v[116:117], v[116:117]
	v_pk_mul_f32 v[126:127], v[118:119], v[118:119]
	v_pk_mul_f32 v[224:225], v[146:147], v[146:147]
	v_cvt_pk_bf16_f32 v116, v116, v117
	v_cvt_pk_bf16_f32 v117, v118, v119
	v_cvt_pk_bf16_f32 v118, v146, v147
	v_add_f32_e32 v146, v196, v197
	v_add_f32_e32 v146, v218, v146
	v_pk_mul_f32 v[220:221], v[120:121], v[120:121]
	v_add_f32_e32 v146, v219, v146
	v_add_f32_e32 v146, v220, v146
	v_pk_mul_f32 v[222:223], v[122:123], v[122:123]
	v_add_f32_e32 v146, v221, v146
	v_add_f32_e32 v146, v222, v146
	v_add_f32_e32 v146, v223, v146
	v_add_f32_e32 v124, v124, v146
	v_add_f32_e32 v124, v125, v124
	v_add_f32_e32 v124, v126, v124
	v_add_f32_e32 v124, v127, v124
	v_add_f32_e32 v124, v224, v124
	v_pk_mul_f32 v[226:227], v[148:149], v[148:149]
	v_add_f32_e32 v124, v225, v124
	v_add_f32_e32 v124, v226, v124
	v_add_f32_e32 v209, v227, v124
	v_lshlrev_b32_e32 v124, 16, v210
	v_and_b32_e32 v125, 0xffff0000, v210
	v_pk_add_f32 v[100:101], v[100:101], v[124:125]
	v_lshlrev_b32_e32 v124, 16, v212
	v_and_b32_e32 v125, 0xffff0000, v212
	v_pk_add_f32 v[124:125], v[92:93], v[124:125]
	v_lshlrev_b32_e32 v92, 16, v211
	v_and_b32_e32 v93, 0xffff0000, v211
	v_pk_add_f32 v[102:103], v[102:103], v[92:93]
	v_lshlrev_b32_e32 v92, 16, v213
	v_and_b32_e32 v93, 0xffff0000, v213
	v_pk_add_f32 v[126:127], v[94:95], v[92:93]
	v_lshlrev_b32_e32 v92, 16, v214
	v_and_b32_e32 v93, 0xffff0000, v214
	v_pk_add_f32 v[92:93], v[96:97], v[92:93]
	v_lshlrev_b32_e32 v96, 16, v217
	v_and_b32_e32 v97, 0xffff0000, v217
	v_lshlrev_b32_e32 v94, 16, v216
	v_and_b32_e32 v95, 0xffff0000, v216
	v_pk_add_f32 v[90:91], v[90:91], v[96:97]
	v_lshlrev_b32_e32 v96, 16, v136
	v_and_b32_e32 v97, 0xffff0000, v136
	v_pk_add_f32 v[88:89], v[88:89], v[94:95]
	v_lshlrev_b32_e32 v94, 16, v215
	v_and_b32_e32 v95, 0xffff0000, v215
	v_pk_add_f32 v[96:97], v[76:77], v[96:97]
	v_lshl_add_u64 v[76:77], v[168:169], 0, s[36:37]
	v_cvt_pk_bf16_f32 v114, v120, v121
	v_pk_add_f32 v[120:121], v[108:109], v[182:183]
	v_pk_add_f32 v[94:95], v[98:99], v[94:95]
	v_lshlrev_b64 v[182:183], 11, v[76:77]
	v_lshlrev_b32_e32 v98, 16, v138
	v_and_b32_e32 v99, 0xffff0000, v138
	v_pk_add_f32 v[108:109], v[104:105], v[184:185]
	v_lshl_add_u64 v[184:185], v[174:175], 0, v[182:183]
	v_pk_add_f32 v[98:99], v[72:73], v[98:99]
	v_lshlrev_b32_e32 v72, 16, v137
	v_and_b32_e32 v73, 0xffff0000, v137
	global_load_dwordx4 v[210:213], v[184:185], off
	global_load_dwordx4 v[218:221], v[184:185], off offset:256
	v_pk_add_f32 v[136:137], v[78:79], v[72:73]
	v_lshlrev_b32_e32 v72, 16, v139
	v_and_b32_e32 v73, 0xffff0000, v139
	v_pk_add_f32 v[138:139], v[74:75], v[72:73]
	v_lshlrev_b32_e32 v72, 16, v132
	v_and_b32_e32 v73, 0xffff0000, v132
	v_pk_add_f32 v[74:75], v[84:85], v[72:73]
	v_lshlrev_b32_e32 v72, 16, v134
	v_and_b32_e32 v73, 0xffff0000, v134
	v_pk_add_f32 v[78:79], v[80:81], v[72:73]
	v_lshlrev_b32_e32 v72, 16, v133
	v_and_b32_e32 v73, 0xffff0000, v133
	v_pk_add_f32 v[80:81], v[86:87], v[72:73]
	v_lshlrev_b32_e32 v72, 16, v135
	v_and_b32_e32 v73, 0xffff0000, v135
	v_pk_add_f32 v[82:83], v[82:83], v[72:73]
	v_lshl_add_u64 v[72:73], v[168:169], 0, s[10:11]
	v_lshlrev_b64 v[132:133], 11, v[72:73]
	v_lshl_add_u64 v[134:135], v[174:175], 0, v[132:133]
	v_lshlrev_b32_e32 v84, 16, v128
	v_and_b32_e32 v85, 0xffff0000, v128
	global_load_dwordx4 v[226:229], v[134:135], off
	global_load_dwordx4 v[234:237], v[134:135], off offset:256
	v_pk_add_f32 v[84:85], v[68:69], v[84:85]
	v_lshlrev_b32_e32 v68, 16, v130
	v_and_b32_e32 v69, 0xffff0000, v130
	v_pk_add_f32 v[86:87], v[64:65], v[68:69]
	v_lshlrev_b32_e32 v64, 16, v129
	v_and_b32_e32 v65, 0xffff0000, v129
	s_mov_b64 s[10:11], 0xa0
	v_pk_add_f32 v[128:129], v[70:71], v[64:65]
	v_lshl_add_u64 v[70:71], v[168:169], 0, s[10:11]
	s_mov_b64 s[10:11], 0xb0
	v_lshlrev_b32_e32 v64, 16, v131
	v_and_b32_e32 v65, 0xffff0000, v131
	v_lshlrev_b64 v[134:135], 11, v[70:71]
	v_lshl_add_u64 v[68:69], v[168:169], 0, s[10:11]
	v_pk_add_f32 v[130:131], v[66:67], v[64:65]
	v_lshl_add_u64 v[64:65], v[174:175], 0, v[134:135]
	v_lshlrev_b64 v[184:185], 11, v[68:69]
	global_load_dwordx4 v[238:241], v[64:65], off
	global_load_dwordx4 v[242:245], v[64:65], off offset:256
	v_lshl_add_u64 v[64:65], v[174:175], 0, v[184:185]
	global_load_dwordx4 v[246:249], v[64:65], off
	s_nop 0
	global_load_dwordx4 v[64:67], v[64:65], off offset:256
	v_cvt_pk_bf16_f32 v115, v122, v123
	v_cvt_pk_bf16_f32 v119, v148, v149
	v_pk_add_f32 v[110:111], v[110:111], v[192:193]
	v_pk_add_f32 v[122:123], v[106:107], v[194:195]
	global_store_dwordx4 v[172:173], v[112:115], off
	global_store_dwordx4 v[172:173], v[116:119], off offset:256
	v_cvt_pk_bf16_f32 v104, v120, v121
	v_lshl_add_u64 v[112:113], s[28:29], 0, v[176:177]
	v_cvt_pk_bf16_f32 v105, v110, v111
	v_cvt_pk_bf16_f32 v106, v108, v109
	v_cvt_pk_bf16_f32 v107, v122, v123
	v_lshl_add_u64 v[112:113], v[112:113], 0, v[170:171]
	v_cvt_pk_bf16_f32 v146, v100, v101
	v_cvt_pk_bf16_f32 v147, v102, v103
	v_cvt_pk_bf16_f32 v148, v124, v125
	v_cvt_pk_bf16_f32 v149, v126, v127
	global_store_dwordx4 v[112:113], v[104:107], off
	global_store_dwordx4 v[112:113], v[146:149], off offset:256
	v_cvt_pk_bf16_f32 v194, v92, v93
	v_lshl_add_u64 v[104:105], s[28:29], 0, v[180:181]
	v_cvt_pk_bf16_f32 v195, v94, v95
	v_cvt_pk_bf16_f32 v196, v88, v89
	v_cvt_pk_bf16_f32 v197, v90, v91
	v_lshl_add_u64 v[104:105], v[104:105], 0, v[170:171]
	v_cvt_pk_bf16_f32 v214, v96, v97
	v_cvt_pk_bf16_f32 v215, v136, v137
	v_cvt_pk_bf16_f32 v216, v98, v99
	v_cvt_pk_bf16_f32 v217, v138, v139
	global_store_dwordx4 v[104:105], v[194:197], off
	global_store_dwordx4 v[104:105], v[214:217], off offset:256
	v_lshl_add_u64 v[104:105], s[28:29], 0, v[178:179]
	v_cvt_pk_bf16_f32 v222, v74, v75
	v_cvt_pk_bf16_f32 v223, v80, v81
	v_cvt_pk_bf16_f32 v224, v78, v79
	v_cvt_pk_bf16_f32 v225, v82, v83
	v_lshl_add_u64 v[104:105], v[104:105], 0, v[170:171]
	v_cvt_pk_bf16_f32 v230, v84, v85
	v_cvt_pk_bf16_f32 v231, v128, v129
	v_cvt_pk_bf16_f32 v232, v86, v87
	v_cvt_pk_bf16_f32 v233, v130, v131
	global_store_dwordx4 v[104:105], v[222:225], off
	global_store_dwordx4 v[104:105], v[230:233], off offset:256
	s_waitcnt vmcnt(0)
	v_lshlrev_b32_e32 v104, 16, v210
	v_and_b32_e32 v105, 0xffff0000, v210
	v_pk_add_f32 v[60:61], v[60:61], v[104:105]
	v_lshlrev_b32_e32 v104, 16, v212
	v_and_b32_e32 v105, 0xffff0000, v212
	v_pk_add_f32 v[56:57], v[56:57], v[104:105]
	v_lshlrev_b32_e32 v104, 16, v211
	v_and_b32_e32 v105, 0xffff0000, v211
	v_pk_add_f32 v[62:63], v[62:63], v[104:105]
	v_lshlrev_b32_e32 v104, 16, v213
	v_and_b32_e32 v105, 0xffff0000, v213
	v_pk_add_f32 v[58:59], v[58:59], v[104:105]
	v_lshlrev_b32_e32 v104, 16, v218
	v_and_b32_e32 v105, 0xffff0000, v218
	v_pk_add_f32 v[52:53], v[52:53], v[104:105]
	v_lshlrev_b32_e32 v104, 16, v220
	v_and_b32_e32 v105, 0xffff0000, v220
	v_pk_add_f32 v[104:105], v[44:45], v[104:105]
	v_lshlrev_b32_e32 v44, 16, v219
	v_and_b32_e32 v45, 0xffff0000, v219
	v_pk_add_f32 v[54:55], v[54:55], v[44:45]
	v_lshlrev_b32_e32 v44, 16, v221
	v_and_b32_e32 v45, 0xffff0000, v221
	v_pk_add_f32 v[106:107], v[46:47], v[44:45]
	v_lshlrev_b32_e32 v44, 16, v226
	v_and_b32_e32 v45, 0xffff0000, v226
	v_pk_add_f32 v[44:45], v[48:49], v[44:45]
	v_lshlrev_b32_e32 v48, 16, v229
	v_and_b32_e32 v49, 0xffff0000, v229
	v_pk_add_f32 v[42:43], v[42:43], v[48:49]
	v_lshlrev_b32_e32 v48, 16, v234
	v_and_b32_e32 v49, 0xffff0000, v234
	v_pk_add_f32 v[36:37], v[36:37], v[48:49]
	v_lshlrev_b32_e32 v48, 16, v236
	v_and_b32_e32 v49, 0xffff0000, v236
	v_lshlrev_b32_e32 v46, 16, v228
	v_and_b32_e32 v47, 0xffff0000, v228
	v_pk_add_f32 v[48:49], v[28:29], v[48:49]
	v_lshlrev_b32_e32 v28, 16, v235
	v_and_b32_e32 v29, 0xffff0000, v235
	v_pk_add_f32 v[40:41], v[40:41], v[46:47]
	v_lshlrev_b32_e32 v46, 16, v227
	v_and_b32_e32 v47, 0xffff0000, v227
	v_pk_add_f32 v[38:39], v[38:39], v[28:29]
	v_lshlrev_b32_e32 v28, 16, v237
	v_and_b32_e32 v29, 0xffff0000, v237
	v_pk_add_f32 v[46:47], v[50:51], v[46:47]
	v_pk_add_f32 v[50:51], v[30:31], v[28:29]
	v_lshlrev_b32_e32 v28, 16, v238
	v_and_b32_e32 v29, 0xffff0000, v238
	v_lshlrev_b32_e32 v180, 16, v64
	v_and_b32_e32 v181, 0xffff0000, v64
	v_pk_add_f32 v[28:29], v[32:33], v[28:29]
	v_lshlrev_b32_e32 v32, 16, v241
	v_and_b32_e32 v33, 0xffff0000, v241
	v_pk_add_f32 v[4:5], v[4:5], v[180:181]
	v_lshlrev_b32_e32 v180, 16, v66
	v_and_b32_e32 v181, 0xffff0000, v66
	v_pk_add_f32 v[26:27], v[26:27], v[32:33]
	v_lshlrev_b32_e32 v32, 16, v242
	v_and_b32_e32 v33, 0xffff0000, v242
	v_pk_add_f32 v[0:1], v[0:1], v[180:181]
	v_lshl_add_u64 v[180:181], s[28:29], 0, v[182:183]
	v_cvt_pk_bf16_f32 v112, v60, v61
	v_cvt_pk_bf16_f32 v113, v62, v63
	v_cvt_pk_bf16_f32 v114, v56, v57
	v_cvt_pk_bf16_f32 v115, v58, v59
	v_pk_add_f32 v[20:21], v[20:21], v[32:33]
	v_lshlrev_b32_e32 v32, 16, v244
	v_and_b32_e32 v33, 0xffff0000, v244
	v_lshl_add_u64 v[180:181], v[180:181], 0, v[170:171]
	v_cvt_pk_bf16_f32 v116, v52, v53
	v_cvt_pk_bf16_f32 v117, v54, v55
	v_cvt_pk_bf16_f32 v118, v104, v105
	v_cvt_pk_bf16_f32 v119, v106, v107
	v_lshlrev_b32_e32 v30, 16, v240
	v_and_b32_e32 v31, 0xffff0000, v240
	v_pk_add_f32 v[32:33], v[12:13], v[32:33]
	v_lshlrev_b32_e32 v12, 16, v243
	v_and_b32_e32 v13, 0xffff0000, v243
	global_store_dwordx4 v[180:181], v[112:115], off
	global_store_dwordx4 v[180:181], v[116:119], off offset:256
	v_cvt_pk_bf16_f32 v146, v44, v45
	v_lshl_add_u64 v[112:113], s[28:29], 0, v[132:133]
	v_cvt_pk_bf16_f32 v147, v46, v47
	v_cvt_pk_bf16_f32 v148, v40, v41
	v_cvt_pk_bf16_f32 v149, v42, v43
	v_pk_add_f32 v[24:25], v[24:25], v[30:31]
	v_lshlrev_b32_e32 v30, 16, v239
	v_and_b32_e32 v31, 0xffff0000, v239
	v_pk_add_f32 v[22:23], v[22:23], v[12:13]
	v_lshlrev_b32_e32 v12, 16, v245
	v_and_b32_e32 v13, 0xffff0000, v245
	v_lshl_add_u64 v[112:113], v[112:113], 0, v[170:171]
	v_cvt_pk_bf16_f32 v172, v36, v37
	v_cvt_pk_bf16_f32 v173, v38, v39
	v_cvt_pk_bf16_f32 v174, v48, v49
	v_cvt_pk_bf16_f32 v175, v50, v51
	v_pk_add_f32 v[30:31], v[34:35], v[30:31]
	v_pk_add_f32 v[34:35], v[14:15], v[12:13]
	v_lshlrev_b32_e32 v12, 16, v246
	v_and_b32_e32 v13, 0xffff0000, v246
	v_lshlrev_b32_e32 v14, 16, v248
	v_and_b32_e32 v15, 0xffff0000, v248
	global_store_dwordx4 v[112:113], v[146:149], off
	global_store_dwordx4 v[112:113], v[172:175], off offset:256
	v_lshl_add_u64 v[112:113], s[28:29], 0, v[134:135]
	v_cvt_pk_bf16_f32 v176, v28, v29
	v_cvt_pk_bf16_f32 v177, v30, v31
	v_cvt_pk_bf16_f32 v178, v24, v25
	v_cvt_pk_bf16_f32 v179, v26, v27
	v_pk_add_f32 v[12:13], v[16:17], v[12:13]
	v_pk_add_f32 v[8:9], v[8:9], v[14:15]
	v_lshlrev_b32_e32 v14, 16, v247
	v_and_b32_e32 v15, 0xffff0000, v247
	v_lshlrev_b32_e32 v16, 16, v249
	v_and_b32_e32 v17, 0xffff0000, v249
	v_lshlrev_b32_e32 v64, 16, v65
	v_and_b32_e32 v65, 0xffff0000, v65
	v_lshl_add_u64 v[112:113], v[112:113], 0, v[170:171]
	v_cvt_pk_bf16_f32 v194, v20, v21
	v_cvt_pk_bf16_f32 v195, v22, v23
	v_cvt_pk_bf16_f32 v196, v32, v33
	v_cvt_pk_bf16_f32 v197, v34, v35
	v_pk_add_f32 v[14:15], v[18:19], v[14:15]
	v_pk_add_f32 v[10:11], v[10:11], v[16:17]
	v_pk_add_f32 v[6:7], v[6:7], v[64:65]
	v_lshlrev_b32_e32 v64, 16, v67
	v_and_b32_e32 v65, 0xffff0000, v67
	global_store_dwordx4 v[112:113], v[176:179], off
	global_store_dwordx4 v[112:113], v[194:197], off offset:256
	v_lshl_add_u64 v[112:113], s[28:29], 0, v[184:185]
	v_cvt_pk_bf16_f32 v16, v12, v13
	v_cvt_pk_bf16_f32 v17, v14, v15
	v_cvt_pk_bf16_f32 v18, v8, v9
	v_cvt_pk_bf16_f32 v19, v10, v11
	v_pk_add_f32 v[2:3], v[2:3], v[64:65]
	v_lshl_add_u64 v[112:113], v[112:113], 0, v[170:171]
	v_cvt_pk_bf16_f32 v64, v4, v5
	v_cvt_pk_bf16_f32 v65, v6, v7
	v_cvt_pk_bf16_f32 v66, v0, v1
	v_cvt_pk_bf16_f32 v67, v2, v3
	global_store_dwordx4 v[112:113], v[16:19], off
	global_store_dwordx4 v[112:113], v[64:67], off offset:256
	s_lshl_b32 s10, s85, 2
	v_and_b32_e32 v17, 64, v188
	v_xor_b32_e32 v16, 16, v188
	v_add_u32_e32 v17, 64, v17
	v_cmp_lt_i32_e32 vcc, v16, v17
	v_xor_b32_e32 v18, 32, v188
	s_ashr_i32 s11, s10, 31
	v_cndmask_b32_e32 v16, v188, v16, vcc
	v_lshlrev_b32_e32 v16, 2, v16
	ds_bpermute_b32 v19, v16, v209
	v_cmp_lt_i32_e32 vcc, v18, v17
	s_lshl_b64 s[10:11], s[10:11], 2
	s_add_u32 s50, s83, s10
	v_cndmask_b32_e32 v17, v188, v18, vcc
	v_lshlrev_b32_e32 v17, 2, v17
	s_waitcnt lgkmcnt(0)
	v_add_f32_e32 v18, v209, v19
	ds_bpermute_b32 v19, v17, v18
	s_addc_u32 s51, s84, s11
	s_and_saveexec_b64 s[52:53], s[42:43]
	s_cbranch_execz .LBB0_106
	s_waitcnt lgkmcnt(0)
	v_add_f32_e32 v64, v18, v19
	v_lshlrev_b64 v[18:19], 6, v[168:169]
	v_lshl_add_u64 v[18:19], s[50:51], 0, v[18:19]
	global_store_dword v[18:19], v64, off

.LBB0_239:
	s_waitcnt lgkmcnt(0)
	s_add_u32 s28, s28, 0x12290000
	s_addc_u32 s29, s29, 0
	s_add_u32 s30, s30, 0x12290000
	s_addc_u32 s31, s31, 0
	s_and_b32 s12, s10, 3
	s_add_i32 m0, s68, 0x18000
	v_lshl_add_u64 v[6:7], v[6:7], 0, s[36:37]
	s_lshl_b32 s19, s6, 6
	s_lshl_b32 s6, s6, 13
	s_lshl_b32 s23, s12, 12
	s_waitcnt vmcnt(0)
	s_barrier
	global_load_lds_dwordx4 v[6:7], off
	v_lshl_add_u64 v[4:5], v[4:5], 0, s[36:37]
	s_add_i32 m0, s68, 0x1a000
	s_add_i32 s72, s68, 0x8000
	s_add_i32 s73, s68, 0xa000
	global_load_lds_dwordx4 v[4:5], off
	v_lshl_add_u64 v[2:3], v[2:3], 0, s[36:37]
	s_mov_b32 m0, s72
	s_add_u32 s10, s54, 0x40080
	global_load_lds_dwordx4 v[2:3], off
	v_lshl_add_u64 v[0:1], v[0:1], 0, s[36:37]
	s_mov_b32 m0, s73
	s_addc_u32 s11, s55, 0
	global_load_lds_dwordx4 v[0:1], off
	s_add_i32 m0, s68, 0x1c000
	v_lshl_add_u64 v[0:1], s[10:11], 0, v[140:141]
	global_load_lds_dwordx4 v[0:1], off
	v_lshl_add_u64 v[0:1], s[10:11], 0, v[150:151]
	s_add_i32 m0, s68, 0x1e000
	v_lshlrev_b32_e32 v4, 2, v8
	global_load_lds_dwordx4 v[0:1], off
	v_bfe_u32 v1, v8, 4, 2
	v_and_b32_e32 v0, 15, v8
	v_lshlrev_b32_e32 v3, 4, v1
	v_lshl_or_b32 v3, v0, 6, v3
	v_or_b32_e32 v156, s19, v0
	v_lshlrev_b32_e32 v0, 14, v13
	v_and_b32_e32 v0, 0xffff8000, v0
	v_lshlrev_b32_e32 v2, 3, v1
	v_and_b32_e32 v4, 32, v4
	v_cmp_eq_u32_e64 s[42:43], 0, v1
	v_lshl_add_u32 v0, v12, 11, v0
	v_and_b32_e32 v1, 1, v13
	v_bitop3_b32 v5, v3, s6, v4 bitop3:0xde
	s_ashr_i32 s6, s19, 31
	v_lshl_or_b32 v0, v1, 6, v0
	v_mov_b32_e32 v157, s6
	s_lshl_b32 s6, s12, 2
	v_lshl_add_u32 v158, v14, 1, v0
	v_lshlrev_b32_e32 v0, 14, v9
	s_add_u32 s6, s38, s6
	v_and_b32_e32 v0, 0xffff8000, v0
	s_waitcnt vmcnt(6)
	s_addc_u32 s10, s39, 0
	v_lshl_add_u32 v0, v10, 11, v0
	v_and_b32_e32 v1, 1, v9
	s_add_u32 s75, s6, 0x1df14000
	v_lshl_or_b32 v0, v1, 6, v0
	v_bitop3_b32 v206, v3, s23, v4 bitop3:0xde
	v_lshl_or_b32 v207, s12, 5, v2
	s_mov_b32 s74, 0
	s_addc_u32 s80, s10, 0
	v_mov_b32_e32 v159, v141
	v_lshl_add_u32 v160, v11, 1, v0
	v_mov_b32_e32 v161, v141
	v_add_u32_e32 v208, 0, v5
	v_readlane_b32 s81, v254, 52
	v_readlane_b32 s50, v254, 55
	s_barrier
	v_readlane_b32 s51, v254, 56
	s_mov_b32 s100, 0
	s_branch .LBB0_241

.LBB0_248:
	s_add_u32 s6, s52, 0xfffc0080
	s_addc_u32 s19, s53, -1
	s_add_i32 s23, 0, 0x10000
	v_add_u32_e32 v146, s23, v206
	ds_read_b128 v[128:131], v146
	ds_read_b128 v[132:135], v146 offset:1024
	ds_read_b128 v[136:139], v146 offset:2048
	ds_read_b128 v[146:149], v146 offset:3072
	s_cmp_eq_u32 s82, 12
	s_cselect_b32 s59, s10, s19
	s_cselect_b32 s58, s11, s6
	s_cselect_b32 s55, s12, s51
	s_cselect_b32 s54, s35, s39
	v_lshl_add_u64 v[214:215], s[52:53], 0, v[158:159]
	s_add_i32 m0, s68, 0xc000
	ds_read_b128 v[162:165], v208
	ds_read_b128 v[166:169], v208 offset:1024
	ds_read_b128 v[170:173], v208 offset:2048
	ds_read_b128 v[174:177], v208 offset:3072
	ds_read_b128 v[178:181], v208 offset:4096
	ds_read_b128 v[182:185], v208 offset:5120
	ds_read_b128 v[194:197], v208 offset:6144
	ds_read_b128 v[210:213], v208 offset:7168
	global_load_lds_dwordx4 v[214:215], off
	v_lshl_add_u64 v[214:215], s[52:53], 0, v[160:161]
	s_add_i32 m0, s68, 0xe000
	s_nop 0
	global_load_lds_dwordx4 v[214:215], off
	s_add_i32 s6, 0, 0x14000
	v_add_u32_e32 v192, s6, v206
	ds_read_b128 v[214:217], v192
	ds_read_b128 v[218:221], v192 offset:1024
	ds_read_b128 v[222:225], v192 offset:2048
	ds_read_b128 v[226:229], v192 offset:3072
	s_waitcnt vmcnt(40)
	s_cmp_lg_u32 s100, 0
	s_cbranch_scc1 .Lm4a_248
	s_waitcnt vmcnt(8)
.Lm4a_248:
	s_waitcnt lgkmcnt(0)
	s_barrier
	s_setprio 1
	v_mfma_f32_16x16x32_bf16 v[124:127], v[128:131], v[162:165], v[124:127]
	v_mfma_f32_16x16x32_bf16 v[120:123], v[136:139], v[162:165], v[120:123]
	v_mfma_f32_16x16x32_bf16 v[108:111], v[128:131], v[170:173], v[108:111]
	v_mfma_f32_16x16x32_bf16 v[104:107], v[136:139], v[170:173], v[104:107]
	v_mfma_f32_16x16x32_bf16 v[96:99], v[128:131], v[178:181], v[96:99]
	v_mfma_f32_16x16x32_bf16 v[88:91], v[136:139], v[178:181], v[88:91]
	v_mfma_f32_16x16x32_bf16 v[84:87], v[128:131], v[194:197], v[84:87]
	v_mfma_f32_16x16x32_bf16 v[80:83], v[136:139], v[194:197], v[80:83]
	v_mfma_f32_16x16x32_bf16 v[124:127], v[132:135], v[166:169], v[124:127]
	v_mfma_f32_16x16x32_bf16 v[120:123], v[146:149], v[166:169], v[120:123]
	v_mfma_f32_16x16x32_bf16 v[108:111], v[132:135], v[174:177], v[108:111]
	v_mfma_f32_16x16x32_bf16 v[104:107], v[146:149], v[174:177], v[104:107]
	v_mfma_f32_16x16x32_bf16 v[96:99], v[132:135], v[182:185], v[96:99]
	v_mfma_f32_16x16x32_bf16 v[88:91], v[146:149], v[182:185], v[88:91]
	v_mfma_f32_16x16x32_bf16 v[84:87], v[132:135], v[210:213], v[84:87]
	v_mfma_f32_16x16x32_bf16 v[80:83], v[146:149], v[210:213], v[80:83]
	v_mfma_f32_16x16x32_bf16 v[116:119], v[214:217], v[162:165], v[116:119]
	v_mfma_f32_16x16x32_bf16 v[112:115], v[222:225], v[162:165], v[112:115]
	v_mfma_f32_16x16x32_bf16 v[100:103], v[214:217], v[170:173], v[100:103]
	v_mfma_f32_16x16x32_bf16 v[92:95], v[222:225], v[170:173], v[92:95]
	v_mfma_f32_16x16x32_bf16 v[76:79], v[214:217], v[178:181], v[76:79]
	v_mfma_f32_16x16x32_bf16 v[72:75], v[222:225], v[178:181], v[72:75]
	v_mfma_f32_16x16x32_bf16 v[68:71], v[214:217], v[194:197], v[68:71]
	v_mfma_f32_16x16x32_bf16 v[64:67], v[222:225], v[194:197], v[64:67]
	v_mfma_f32_16x16x32_bf16 v[116:119], v[218:221], v[166:169], v[116:119]
	v_mfma_f32_16x16x32_bf16 v[112:115], v[226:229], v[166:169], v[112:115]
	v_mfma_f32_16x16x32_bf16 v[100:103], v[218:221], v[174:177], v[100:103]
	v_mfma_f32_16x16x32_bf16 v[92:95], v[226:229], v[174:177], v[92:95]
	v_mfma_f32_16x16x32_bf16 v[76:79], v[218:221], v[182:185], v[76:79]
	v_mfma_f32_16x16x32_bf16 v[72:75], v[226:229], v[182:185], v[72:75]
	v_mfma_f32_16x16x32_bf16 v[68:71], v[218:221], v[210:213], v[68:71]
	v_mfma_f32_16x16x32_bf16 v[64:67], v[226:229], v[210:213], v[64:67]
	s_setprio 0
	s_barrier
	s_add_i32 s19, s23, s57
	v_lshl_add_u64 v[230:231], s[54:55], 0, v[140:141]
	s_mov_b32 m0, s19
	s_nop 0
	global_load_lds_dwordx4 v[230:231], off
	v_lshl_add_u64 v[232:233], s[54:55], 0, v[150:151]
	s_add_i32 m0, s19, 0x2000
	s_nop 0
	global_load_lds_dwordx4 v[232:233], off
	s_mov_b32 m0, s68
	v_lshl_add_u64 v[234:235], s[58:59], 0, v[154:155]
	ds_read_b128 v[162:165], v208 offset:16384
	ds_read_b128 v[166:169], v208 offset:17408
	ds_read_b128 v[170:173], v208 offset:18432
	ds_read_b128 v[174:177], v208 offset:19456
	ds_read_b128 v[178:181], v208 offset:20480
	ds_read_b128 v[182:185], v208 offset:21504
	ds_read_b128 v[194:197], v208 offset:22528
	ds_read_b128 v[210:213], v208 offset:23552
	global_load_lds_dwordx4 v[234:235], off
	v_lshl_add_u64 v[236:237], s[58:59], 0, v[152:153]
	s_mov_b32 m0, s69
	s_nop 0
	global_load_lds_dwordx4 v[236:237], off
	s_add_u32 s84, s54, 0x40000
	s_addc_u32 s85, s55, 0
	s_add_i32 s6, s6, s57
	v_lshl_add_u64 v[250:251], s[84:85], 0, v[140:141]
	s_mov_b32 m0, s6
	s_nop 0
	global_load_lds_dwordx4 v[250:251], off
	v_lshl_add_u64 v[250:251], s[84:85], 0, v[150:151]
	s_add_i32 m0, s6, 0x2000
	s_nop 0
	global_load_lds_dwordx4 v[250:251], off
	s_waitcnt vmcnt(40)
	s_cmp_lg_u32 s100, 0
	s_cbranch_scc1 .Lm4b_248
	s_waitcnt vmcnt(8)
.Lm4b_248:
	s_waitcnt lgkmcnt(0)
	s_mov_b32 s100, 0
	s_barrier
	s_setprio 1
	v_mfma_f32_16x16x32_bf16 v[60:63], v[128:131], v[162:165], v[60:63]
	v_mfma_f32_16x16x32_bf16 v[56:59], v[136:139], v[162:165], v[56:59]
	v_mfma_f32_16x16x32_bf16 v[48:51], v[128:131], v[170:173], v[48:51]
	v_mfma_f32_16x16x32_bf16 v[40:43], v[136:139], v[170:173], v[40:43]
	v_mfma_f32_16x16x32_bf16 v[32:35], v[128:131], v[178:181], v[32:35]
	v_mfma_f32_16x16x32_bf16 v[24:27], v[136:139], v[178:181], v[24:27]
	v_mfma_f32_16x16x32_bf16 v[16:19], v[128:131], v[194:197], v[16:19]
	v_mfma_f32_16x16x32_bf16 v[8:11], v[136:139], v[194:197], v[8:11]
	v_mfma_f32_16x16x32_bf16 v[60:63], v[132:135], v[166:169], v[60:63]
	v_mfma_f32_16x16x32_bf16 v[56:59], v[146:149], v[166:169], v[56:59]
	v_mfma_f32_16x16x32_bf16 v[48:51], v[132:135], v[174:177], v[48:51]
	v_mfma_f32_16x16x32_bf16 v[40:43], v[146:149], v[174:177], v[40:43]
	v_mfma_f32_16x16x32_bf16 v[32:35], v[132:135], v[182:185], v[32:35]
	v_mfma_f32_16x16x32_bf16 v[24:27], v[146:149], v[182:185], v[24:27]
	v_mfma_f32_16x16x32_bf16 v[16:19], v[132:135], v[210:213], v[16:19]
	v_mfma_f32_16x16x32_bf16 v[8:11], v[146:149], v[210:213], v[8:11]
	v_mfma_f32_16x16x32_bf16 v[52:55], v[214:217], v[162:165], v[52:55]
	v_mfma_f32_16x16x32_bf16 v[44:47], v[222:225], v[162:165], v[44:47]
	v_mfma_f32_16x16x32_bf16 v[36:39], v[214:217], v[170:173], v[36:39]
	v_mfma_f32_16x16x32_bf16 v[28:31], v[222:225], v[170:173], v[28:31]
	v_mfma_f32_16x16x32_bf16 v[20:23], v[214:217], v[178:181], v[20:23]
	v_mfma_f32_16x16x32_bf16 v[12:15], v[222:225], v[178:181], v[12:15]
	v_mfma_f32_16x16x32_bf16 v[4:7], v[214:217], v[194:197], v[4:7]
	v_mfma_f32_16x16x32_bf16 v[0:3], v[222:225], v[194:197], v[0:3]
	v_mfma_f32_16x16x32_bf16 v[52:55], v[218:221], v[166:169], v[52:55]
	v_mfma_f32_16x16x32_bf16 v[44:47], v[226:229], v[166:169], v[44:47]
	v_mfma_f32_16x16x32_bf16 v[36:39], v[218:221], v[174:177], v[36:39]
	v_mfma_f32_16x16x32_bf16 v[28:31], v[226:229], v[174:177], v[28:31]
	v_mfma_f32_16x16x32_bf16 v[20:23], v[218:221], v[182:185], v[20:23]
	v_mfma_f32_16x16x32_bf16 v[12:15], v[226:229], v[182:185], v[12:15]
	v_mfma_f32_16x16x32_bf16 v[4:7], v[218:221], v[210:213], v[4:7]
	v_mfma_f32_16x16x32_bf16 v[0:3], v[226:229], v[210:213], v[0:3]
	s_setprio 0
	s_barrier
	s_add_i32 s6, 0, 0x18000
	v_add_u32_e32 v146, s6, v206
	ds_read_b128 v[128:131], v146
	ds_read_b128 v[132:135], v146 offset:1024
	ds_read_b128 v[136:139], v146 offset:2048
	ds_read_b128 v[146:149], v146 offset:3072
	s_add_u32 s58, s58, 0x40000
	s_addc_u32 s59, s59, 0
	s_mov_b32 m0, s70
	v_lshl_add_u64 v[214:215], s[58:59], 0, v[154:155]
	ds_read_b128 v[162:165], v208 offset:32768
	ds_read_b128 v[166:169], v208 offset:33792
	ds_read_b128 v[170:173], v208 offset:34816
	ds_read_b128 v[174:177], v208 offset:35840
	ds_read_b128 v[178:181], v208 offset:36864
	ds_read_b128 v[182:185], v208 offset:37888
	ds_read_b128 v[194:197], v208 offset:38912
	ds_read_b128 v[210:213], v208 offset:39936
	global_load_lds_dwordx4 v[214:215], off
	v_lshl_add_u64 v[214:215], s[58:59], 0, v[152:153]
	s_mov_b32 m0, s71
	s_nop 0
	global_load_lds_dwordx4 v[214:215], off
	s_add_i32 s19, 0, 0x1c000
	v_add_u32_e32 v192, s19, v206
	ds_read_b128 v[214:217], v192
	ds_read_b128 v[218:221], v192 offset:1024
	ds_read_b128 v[222:225], v192 offset:2048
	ds_read_b128 v[226:229], v192 offset:3072
	s_waitcnt vmcnt(8)
	s_waitcnt lgkmcnt(0)
	s_barrier
	s_setprio 1
	v_mfma_f32_16x16x32_bf16 v[124:127], v[128:131], v[162:165], v[124:127]
	v_mfma_f32_16x16x32_bf16 v[120:123], v[136:139], v[162:165], v[120:123]
	v_mfma_f32_16x16x32_bf16 v[108:111], v[128:131], v[170:173], v[108:111]
	v_mfma_f32_16x16x32_bf16 v[104:107], v[136:139], v[170:173], v[104:107]
	v_mfma_f32_16x16x32_bf16 v[96:99], v[128:131], v[178:181], v[96:99]
	v_mfma_f32_16x16x32_bf16 v[88:91], v[136:139], v[178:181], v[88:91]
	v_mfma_f32_16x16x32_bf16 v[84:87], v[128:131], v[194:197], v[84:87]
	v_mfma_f32_16x16x32_bf16 v[80:83], v[136:139], v[194:197], v[80:83]
	v_mfma_f32_16x16x32_bf16 v[124:127], v[132:135], v[166:169], v[124:127]
	v_mfma_f32_16x16x32_bf16 v[120:123], v[146:149], v[166:169], v[120:123]
	v_mfma_f32_16x16x32_bf16 v[108:111], v[132:135], v[174:177], v[108:111]
	v_mfma_f32_16x16x32_bf16 v[104:107], v[146:149], v[174:177], v[104:107]
	v_mfma_f32_16x16x32_bf16 v[96:99], v[132:135], v[182:185], v[96:99]
	v_mfma_f32_16x16x32_bf16 v[88:91], v[146:149], v[182:185], v[88:91]
	v_mfma_f32_16x16x32_bf16 v[84:87], v[132:135], v[210:213], v[84:87]
	v_mfma_f32_16x16x32_bf16 v[80:83], v[146:149], v[210:213], v[80:83]
	v_mfma_f32_16x16x32_bf16 v[116:119], v[214:217], v[162:165], v[116:119]
	v_mfma_f32_16x16x32_bf16 v[112:115], v[222:225], v[162:165], v[112:115]
	v_mfma_f32_16x16x32_bf16 v[100:103], v[214:217], v[170:173], v[100:103]
	v_mfma_f32_16x16x32_bf16 v[92:95], v[222:225], v[170:173], v[92:95]
	v_mfma_f32_16x16x32_bf16 v[76:79], v[214:217], v[178:181], v[76:79]
	v_mfma_f32_16x16x32_bf16 v[72:75], v[222:225], v[178:181], v[72:75]
	v_mfma_f32_16x16x32_bf16 v[68:71], v[214:217], v[194:197], v[68:71]
	v_mfma_f32_16x16x32_bf16 v[64:67], v[222:225], v[194:197], v[64:67]
	v_mfma_f32_16x16x32_bf16 v[116:119], v[218:221], v[166:169], v[116:119]
	v_mfma_f32_16x16x32_bf16 v[112:115], v[226:229], v[166:169], v[112:115]
	v_mfma_f32_16x16x32_bf16 v[100:103], v[218:221], v[174:177], v[100:103]
	v_mfma_f32_16x16x32_bf16 v[92:95], v[226:229], v[174:177], v[92:95]
	v_mfma_f32_16x16x32_bf16 v[76:79], v[218:221], v[182:185], v[76:79]
	v_mfma_f32_16x16x32_bf16 v[72:75], v[226:229], v[182:185], v[72:75]
	v_mfma_f32_16x16x32_bf16 v[68:71], v[218:221], v[210:213], v[68:71]
	v_mfma_f32_16x16x32_bf16 v[64:67], v[226:229], v[210:213], v[64:67]
	s_setprio 0
	s_barrier
	s_add_i32 s6, s6, s57
	v_lshl_add_u64 v[230:231], v[230:231], 0, s[36:37]
	s_mov_b32 m0, s6
	s_nop 0
	global_load_lds_dwordx4 v[230:231], off
	v_lshl_add_u64 v[230:231], v[232:233], 0, s[36:37]
	s_add_i32 m0, s6, 0x2000
	s_nop 0
	global_load_lds_dwordx4 v[230:231], off
	s_mov_b32 m0, s72
	v_lshl_add_u64 v[230:231], v[234:235], 0, s[36:37]
	ds_read_b128 v[162:165], v208 offset:49152
	ds_read_b128 v[166:169], v208 offset:50176
	ds_read_b128 v[170:173], v208 offset:51200
	ds_read_b128 v[174:177], v208 offset:52224
	ds_read_b128 v[178:181], v208 offset:53248
	ds_read_b128 v[182:185], v208 offset:54272
	ds_read_b128 v[194:197], v208 offset:55296
	ds_read_b128 v[210:213], v208 offset:56320
	global_load_lds_dwordx4 v[230:231], off
	v_lshl_add_u64 v[230:231], v[236:237], 0, s[36:37]
	s_mov_b32 m0, s73
	s_nop 0
	global_load_lds_dwordx4 v[230:231], off
	s_add_u32 s54, s54, 0x40080
	s_addc_u32 s55, s55, 0
	s_add_i32 s6, s19, s57
	v_lshl_add_u64 v[250:251], s[54:55], 0, v[140:141]
	s_mov_b32 m0, s6
	s_nop 0
	global_load_lds_dwordx4 v[250:251], off
	v_lshl_add_u64 v[250:251], s[54:55], 0, v[150:151]
	s_add_i32 m0, s6, 0x2000
	s_nop 0
	global_load_lds_dwordx4 v[250:251], off
	s_waitcnt vmcnt(8)
	s_waitcnt lgkmcnt(0)
	s_barrier
	s_setprio 1
	v_mfma_f32_16x16x32_bf16 v[60:63], v[128:131], v[162:165], v[60:63]
	v_mfma_f32_16x16x32_bf16 v[56:59], v[136:139], v[162:165], v[56:59]
	v_mfma_f32_16x16x32_bf16 v[48:51], v[128:131], v[170:173], v[48:51]
	v_mfma_f32_16x16x32_bf16 v[40:43], v[136:139], v[170:173], v[40:43]
	v_mfma_f32_16x16x32_bf16 v[32:35], v[128:131], v[178:181], v[32:35]
	v_mfma_f32_16x16x32_bf16 v[24:27], v[136:139], v[178:181], v[24:27]
	v_mfma_f32_16x16x32_bf16 v[16:19], v[128:131], v[194:197], v[16:19]
	v_mfma_f32_16x16x32_bf16 v[8:11], v[136:139], v[194:197], v[8:11]
	v_mfma_f32_16x16x32_bf16 v[60:63], v[132:135], v[166:169], v[60:63]
	v_mfma_f32_16x16x32_bf16 v[56:59], v[146:149], v[166:169], v[56:59]
	v_mfma_f32_16x16x32_bf16 v[48:51], v[132:135], v[174:177], v[48:51]
	v_mfma_f32_16x16x32_bf16 v[40:43], v[146:149], v[174:177], v[40:43]
	v_mfma_f32_16x16x32_bf16 v[32:35], v[132:135], v[182:185], v[32:35]
	v_mfma_f32_16x16x32_bf16 v[24:27], v[146:149], v[182:185], v[24:27]
	v_mfma_f32_16x16x32_bf16 v[16:19], v[132:135], v[210:213], v[16:19]
	v_mfma_f32_16x16x32_bf16 v[8:11], v[146:149], v[210:213], v[8:11]
	v_mfma_f32_16x16x32_bf16 v[52:55], v[214:217], v[162:165], v[52:55]
	v_mfma_f32_16x16x32_bf16 v[44:47], v[222:225], v[162:165], v[44:47]
	v_mfma_f32_16x16x32_bf16 v[36:39], v[214:217], v[170:173], v[36:39]
	v_mfma_f32_16x16x32_bf16 v[28:31], v[222:225], v[170:173], v[28:31]
	v_mfma_f32_16x16x32_bf16 v[20:23], v[214:217], v[178:181], v[20:23]
	v_mfma_f32_16x16x32_bf16 v[12:15], v[222:225], v[178:181], v[12:15]
	v_mfma_f32_16x16x32_bf16 v[4:7], v[214:217], v[194:197], v[4:7]
	v_mfma_f32_16x16x32_bf16 v[0:3], v[222:225], v[194:197], v[0:3]
	v_mfma_f32_16x16x32_bf16 v[52:55], v[218:221], v[166:169], v[52:55]
	v_mfma_f32_16x16x32_bf16 v[44:47], v[226:229], v[166:169], v[44:47]
	v_mfma_f32_16x16x32_bf16 v[36:39], v[218:221], v[174:177], v[36:39]
	v_mfma_f32_16x16x32_bf16 v[28:31], v[226:229], v[174:177], v[28:31]
	v_mfma_f32_16x16x32_bf16 v[20:23], v[218:221], v[182:185], v[20:23]
	v_mfma_f32_16x16x32_bf16 v[12:15], v[226:229], v[182:185], v[12:15]
	v_mfma_f32_16x16x32_bf16 v[4:7], v[218:221], v[210:213], v[4:7]
	v_mfma_f32_16x16x32_bf16 v[0:3], v[226:229], v[210:213], v[0:3]
	s_setprio 0
	s_add_i32 s82, s82, 2
	s_add_u32 s52, s52, 0x100
	s_addc_u32 s53, s53, 0
	s_add_u32 s39, s39, 0x100
	s_addc_u32 s51, s51, 0
	s_cmp_gt_u32 s82, 13
	s_barrier
	s_cbranch_scc0 .LBB0_248
	s_mov_b32 s100, 1
	s_ashr_i32 s51, s50, 31
	v_lshl_or_b32 v128, s81, 8, v207
	s_lshl_b64 s[10:11], s[50:51], 8
	v_ashrrev_i32_e32 v129, 31, v128
	v_lshl_add_u64 v[168:169], s[10:11], 0, v[156:157]
	v_lshlrev_b64 v[170:171], 1, v[128:129]
	v_lshl_add_u64 v[174:175], s[28:29], 0, v[170:171]
	v_lshlrev_b64 v[172:173], 11, v[168:169]
	v_lshl_add_u64 v[128:129], v[174:175], 0, v[172:173]
	global_load_dwordx4 v[146:149], v[128:129], off
	global_load_dwordx4 v[182:185], v[128:129], off offset:256
	v_or_b32_e32 v166, 16, v168
	v_mov_b32_e32 v167, v169
	v_lshlrev_b64 v[176:177], 11, v[166:167]
	v_lshl_add_u64 v[128:129], v[174:175], 0, v[176:177]
	global_load_dwordx4 v[194:197], v[128:129], off
	global_load_dwordx4 v[210:213], v[128:129], off offset:256
	v_or_b32_e32 v164, 32, v168
	v_mov_b32_e32 v165, v169
	v_or_b32_e32 v162, 48, v168
	v_mov_b32_e32 v163, v169
	v_lshlrev_b64 v[180:181], 11, v[164:165]
	v_lshlrev_b64 v[178:179], 11, v[162:163]
	v_lshl_add_u64 v[128:129], v[174:175], 0, v[180:181]
	v_lshl_add_u64 v[130:131], v[174:175], 0, v[178:179]
	global_load_dwordx4 v[214:217], v[128:129], off
	global_load_dwordx4 v[136:139], v[128:129], off offset:256
	global_load_dwordx4 v[132:135], v[130:131], off
	s_nop 0
	global_load_dwordx4 v[128:131], v[130:131], off offset:256
	s_mov_b64 s[10:11], 0x90
	v_lshl_add_u64 v[172:173], s[30:31], 0, v[172:173]
	v_lshl_add_u64 v[172:173], v[172:173], 0, v[170:171]
	s_waitcnt vmcnt(0)
	v_lshlrev_b32_e32 v218, 16, v146
	v_and_b32_e32 v219, 0xffff0000, v146
	v_lshlrev_b32_e32 v220, 16, v148
	v_and_b32_e32 v221, 0xffff0000, v148
	v_lshlrev_b32_e32 v146, 16, v147
	v_and_b32_e32 v147, 0xffff0000, v147
	v_lshlrev_b32_e32 v222, 16, v182
	v_and_b32_e32 v223, 0xffff0000, v182
	v_lshlrev_b32_e32 v224, 16, v184
	v_and_b32_e32 v225, 0xffff0000, v184
	v_lshlrev_b32_e32 v182, 16, v183
	v_and_b32_e32 v183, 0xffff0000, v183
	v_pk_add_f32 v[124:125], v[124:125], v[218:219]
	v_pk_add_f32 v[120:121], v[120:121], v[220:221]
	v_pk_add_f32 v[126:127], v[126:127], v[146:147]
	v_pk_add_f32 v[116:117], v[116:117], v[222:223]
	v_pk_add_f32 v[146:147], v[112:113], v[224:225]
	v_pk_add_f32 v[118:119], v[118:119], v[182:183]
	v_pk_mul_f32 v[220:221], v[124:125], v[124:125]
	v_pk_mul_f32 v[222:223], v[126:127], v[126:127]
	v_cvt_pk_bf16_f32 v112, v124, v125
	v_cvt_pk_bf16_f32 v113, v126, v127
	v_pk_mul_f32 v[124:125], v[116:117], v[116:117]
	v_pk_mul_f32 v[126:127], v[118:119], v[118:119]
	v_pk_mul_f32 v[228:229], v[146:147], v[146:147]
	v_cvt_pk_bf16_f32 v116, v116, v117
	v_cvt_pk_bf16_f32 v117, v118, v119
	v_cvt_pk_bf16_f32 v118, v146, v147
	v_add_f32_e32 v146, v220, v221
	v_add_f32_e32 v146, v222, v146
	v_lshlrev_b32_e32 v148, 16, v149
	v_and_b32_e32 v149, 0xffff0000, v149
	v_pk_mul_f32 v[224:225], v[120:121], v[120:121]
	v_add_f32_e32 v146, v223, v146
	v_pk_add_f32 v[122:123], v[122:123], v[148:149]
	v_add_f32_e32 v146, v224, v146
	v_pk_mul_f32 v[226:227], v[122:123], v[122:123]
	v_add_f32_e32 v146, v225, v146
	v_add_f32_e32 v146, v226, v146
	v_add_f32_e32 v146, v227, v146
	v_add_f32_e32 v124, v124, v146
	v_add_f32_e32 v124, v125, v124
	v_add_f32_e32 v124, v126, v124
	v_lshlrev_b32_e32 v184, 16, v185
	v_and_b32_e32 v185, 0xffff0000, v185
	v_add_f32_e32 v124, v127, v124
	v_pk_add_f32 v[148:149], v[114:115], v[184:185]
	v_add_f32_e32 v124, v228, v124
	v_pk_mul_f32 v[230:231], v[148:149], v[148:149]
	v_add_f32_e32 v124, v229, v124
	v_add_f32_e32 v124, v230, v124
	v_add_f32_e32 v209, v231, v124
	v_lshlrev_b32_e32 v124, 16, v212
	v_and_b32_e32 v125, 0xffff0000, v212
	v_pk_add_f32 v[124:125], v[92:93], v[124:125]
	v_lshlrev_b32_e32 v92, 16, v211
	v_and_b32_e32 v93, 0xffff0000, v211
	v_pk_add_f32 v[102:103], v[102:103], v[92:93]
	v_lshlrev_b32_e32 v92, 16, v213
	v_and_b32_e32 v93, 0xffff0000, v213
	v_pk_add_f32 v[126:127], v[94:95], v[92:93]
	v_lshlrev_b32_e32 v92, 16, v214
	v_and_b32_e32 v93, 0xffff0000, v214
	v_pk_add_f32 v[92:93], v[96:97], v[92:93]
	v_lshlrev_b32_e32 v96, 16, v217
	v_and_b32_e32 v97, 0xffff0000, v217
	v_lshlrev_b32_e32 v94, 16, v216
	v_and_b32_e32 v95, 0xffff0000, v216
	v_pk_add_f32 v[90:91], v[90:91], v[96:97]
	v_lshlrev_b32_e32 v96, 16, v136
	v_and_b32_e32 v97, 0xffff0000, v136
	v_lshlrev_b32_e32 v182, 16, v194
	v_and_b32_e32 v183, 0xffff0000, v194
	v_pk_add_f32 v[88:89], v[88:89], v[94:95]
	v_lshlrev_b32_e32 v94, 16, v215
	v_and_b32_e32 v95, 0xffff0000, v215
	v_pk_add_f32 v[96:97], v[76:77], v[96:97]
	v_lshl_add_u64 v[76:77], v[168:169], 0, s[36:37]
	v_lshlrev_b32_e32 v184, 16, v196
	v_and_b32_e32 v185, 0xffff0000, v196
	v_cvt_pk_bf16_f32 v114, v120, v121
	v_pk_add_f32 v[120:121], v[108:109], v[182:183]
	v_pk_add_f32 v[94:95], v[98:99], v[94:95]
	v_lshlrev_b64 v[182:183], 11, v[76:77]
	v_lshlrev_b32_e32 v98, 16, v138
	v_and_b32_e32 v99, 0xffff0000, v138
	v_pk_add_f32 v[108:109], v[104:105], v[184:185]
	v_lshl_add_u64 v[184:185], v[174:175], 0, v[182:183]
	v_pk_add_f32 v[98:99], v[72:73], v[98:99]
	v_lshlrev_b32_e32 v72, 16, v137
	v_and_b32_e32 v73, 0xffff0000, v137
	v_lshlrev_b32_e32 v218, 16, v210
	v_and_b32_e32 v219, 0xffff0000, v210
	global_load_dwordx4 v[210:213], v[184:185], off
	v_pk_add_f32 v[136:137], v[78:79], v[72:73]
	v_lshlrev_b32_e32 v72, 16, v139
	v_and_b32_e32 v73, 0xffff0000, v139
	v_pk_add_f32 v[138:139], v[74:75], v[72:73]
	v_lshlrev_b32_e32 v72, 16, v132
	v_and_b32_e32 v73, 0xffff0000, v132
	v_pk_add_f32 v[74:75], v[84:85], v[72:73]
	v_lshlrev_b32_e32 v72, 16, v134
	v_and_b32_e32 v73, 0xffff0000, v134
	v_pk_add_f32 v[78:79], v[80:81], v[72:73]
	v_lshlrev_b32_e32 v72, 16, v133
	v_and_b32_e32 v73, 0xffff0000, v133
	v_pk_add_f32 v[100:101], v[100:101], v[218:219]
	global_load_dwordx4 v[218:221], v[184:185], off offset:256
	v_pk_add_f32 v[80:81], v[86:87], v[72:73]
	v_lshlrev_b32_e32 v72, 16, v135
	v_and_b32_e32 v73, 0xffff0000, v135
	v_pk_add_f32 v[82:83], v[82:83], v[72:73]
	v_lshl_add_u64 v[72:73], v[168:169], 0, s[10:11]
	v_lshlrev_b64 v[132:133], 11, v[72:73]
	v_lshl_add_u64 v[134:135], v[174:175], 0, v[132:133]
	v_lshlrev_b32_e32 v84, 16, v128
	v_and_b32_e32 v85, 0xffff0000, v128
	global_load_dwordx4 v[226:229], v[134:135], off
	global_load_dwordx4 v[234:237], v[134:135], off offset:256
	v_pk_add_f32 v[84:85], v[68:69], v[84:85]
	v_lshlrev_b32_e32 v68, 16, v130
	v_and_b32_e32 v69, 0xffff0000, v130
	v_pk_add_f32 v[86:87], v[64:65], v[68:69]
	v_lshlrev_b32_e32 v64, 16, v129
	v_and_b32_e32 v65, 0xffff0000, v129
	s_mov_b64 s[10:11], 0xa0
	v_pk_add_f32 v[128:129], v[70:71], v[64:65]
	v_lshl_add_u64 v[70:71], v[168:169], 0, s[10:11]
	s_mov_b64 s[10:11], 0xb0
	v_lshlrev_b32_e32 v64, 16, v131
	v_and_b32_e32 v65, 0xffff0000, v131
	v_lshlrev_b64 v[134:135], 11, v[70:71]
	v_lshl_add_u64 v[68:69], v[168:169], 0, s[10:11]
	v_pk_add_f32 v[130:131], v[66:67], v[64:65]
	v_lshl_add_u64 v[64:65], v[174:175], 0, v[134:135]
	v_lshlrev_b64 v[184:185], 11, v[68:69]
	global_load_dwordx4 v[238:241], v[64:65], off
	global_load_dwordx4 v[242:245], v[64:65], off offset:256
	v_lshl_add_u64 v[64:65], v[174:175], 0, v[184:185]
	global_load_dwordx4 v[246:249], v[64:65], off
	s_nop 0
	global_load_dwordx4 v[64:67], v[64:65], off offset:256
	v_lshlrev_b32_e32 v194, 16, v195
	v_and_b32_e32 v195, 0xffff0000, v195
	v_lshlrev_b32_e32 v196, 16, v197
	v_and_b32_e32 v197, 0xffff0000, v197
	v_cvt_pk_bf16_f32 v115, v122, v123
	v_cvt_pk_bf16_f32 v119, v148, v149
	v_pk_add_f32 v[122:123], v[110:111], v[194:195]
	v_pk_add_f32 v[110:111], v[106:107], v[196:197]
	global_store_dwordx4 v[172:173], v[112:115], off
	global_store_dwordx4 v[172:173], v[116:119], off offset:256
	v_cvt_pk_bf16_f32 v104, v120, v121
	v_lshl_add_u64 v[112:113], s[30:31], 0, v[176:177]
	v_cvt_pk_bf16_f32 v105, v122, v123
	v_cvt_pk_bf16_f32 v106, v108, v109
	v_cvt_pk_bf16_f32 v107, v110, v111
	v_lshl_add_u64 v[112:113], v[112:113], 0, v[170:171]
	v_cvt_pk_bf16_f32 v146, v100, v101
	v_cvt_pk_bf16_f32 v147, v102, v103
	v_cvt_pk_bf16_f32 v148, v124, v125
	v_cvt_pk_bf16_f32 v149, v126, v127
	global_store_dwordx4 v[112:113], v[104:107], off
	global_store_dwordx4 v[112:113], v[146:149], off offset:256
	v_cvt_pk_bf16_f32 v194, v92, v93
	v_lshl_add_u64 v[104:105], s[30:31], 0, v[180:181]
	v_cvt_pk_bf16_f32 v195, v94, v95
	v_cvt_pk_bf16_f32 v196, v88, v89
	v_cvt_pk_bf16_f32 v197, v90, v91
	v_lshl_add_u64 v[104:105], v[104:105], 0, v[170:171]
	v_cvt_pk_bf16_f32 v214, v96, v97
	v_cvt_pk_bf16_f32 v215, v136, v137
	v_cvt_pk_bf16_f32 v216, v98, v99
	v_cvt_pk_bf16_f32 v217, v138, v139
	global_store_dwordx4 v[104:105], v[194:197], off
	global_store_dwordx4 v[104:105], v[214:217], off offset:256
	v_lshl_add_u64 v[104:105], s[30:31], 0, v[178:179]
	v_cvt_pk_bf16_f32 v222, v74, v75
	v_cvt_pk_bf16_f32 v223, v80, v81
	v_cvt_pk_bf16_f32 v224, v78, v79
	v_cvt_pk_bf16_f32 v225, v82, v83
	v_lshl_add_u64 v[104:105], v[104:105], 0, v[170:171]
	v_cvt_pk_bf16_f32 v230, v84, v85
	v_cvt_pk_bf16_f32 v231, v128, v129
	v_cvt_pk_bf16_f32 v232, v86, v87
	v_cvt_pk_bf16_f32 v233, v130, v131
	global_store_dwordx4 v[104:105], v[222:225], off
	global_store_dwordx4 v[104:105], v[230:233], off offset:256
	s_waitcnt vmcnt(0)
	v_lshlrev_b32_e32 v104, 16, v210
	v_and_b32_e32 v105, 0xffff0000, v210
	v_pk_add_f32 v[60:61], v[60:61], v[104:105]
	v_lshlrev_b32_e32 v104, 16, v212
	v_and_b32_e32 v105, 0xffff0000, v212
	v_pk_add_f32 v[56:57], v[56:57], v[104:105]
	v_lshlrev_b32_e32 v104, 16, v211
	v_and_b32_e32 v105, 0xffff0000, v211
	v_pk_add_f32 v[62:63], v[62:63], v[104:105]
	v_lshlrev_b32_e32 v104, 16, v213
	v_and_b32_e32 v105, 0xffff0000, v213
	v_pk_add_f32 v[58:59], v[58:59], v[104:105]
	v_lshlrev_b32_e32 v104, 16, v218
	v_and_b32_e32 v105, 0xffff0000, v218
	v_pk_add_f32 v[52:53], v[52:53], v[104:105]
	v_lshlrev_b32_e32 v104, 16, v220
	v_and_b32_e32 v105, 0xffff0000, v220
	v_pk_add_f32 v[104:105], v[44:45], v[104:105]
	v_lshlrev_b32_e32 v44, 16, v219
	v_and_b32_e32 v45, 0xffff0000, v219
	v_pk_add_f32 v[54:55], v[54:55], v[44:45]
	v_lshlrev_b32_e32 v44, 16, v221
	v_and_b32_e32 v45, 0xffff0000, v221
	v_pk_add_f32 v[106:107], v[46:47], v[44:45]
	v_lshlrev_b32_e32 v44, 16, v226
	v_and_b32_e32 v45, 0xffff0000, v226
	v_pk_add_f32 v[44:45], v[48:49], v[44:45]
	v_lshlrev_b32_e32 v48, 16, v229
	v_and_b32_e32 v49, 0xffff0000, v229
	v_pk_add_f32 v[42:43], v[42:43], v[48:49]
	v_lshlrev_b32_e32 v48, 16, v234
	v_and_b32_e32 v49, 0xffff0000, v234
	v_pk_add_f32 v[36:37], v[36:37], v[48:49]
	v_lshlrev_b32_e32 v48, 16, v236
	v_and_b32_e32 v49, 0xffff0000, v236
	v_lshlrev_b32_e32 v46, 16, v228
	v_and_b32_e32 v47, 0xffff0000, v228
	v_pk_add_f32 v[48:49], v[28:29], v[48:49]
	v_lshlrev_b32_e32 v28, 16, v235
	v_and_b32_e32 v29, 0xffff0000, v235
	v_pk_add_f32 v[40:41], v[40:41], v[46:47]
	v_lshlrev_b32_e32 v46, 16, v227
	v_and_b32_e32 v47, 0xffff0000, v227
	v_pk_add_f32 v[38:39], v[38:39], v[28:29]
	v_lshlrev_b32_e32 v28, 16, v237
	v_and_b32_e32 v29, 0xffff0000, v237
	v_pk_add_f32 v[46:47], v[50:51], v[46:47]
	v_pk_add_f32 v[50:51], v[30:31], v[28:29]
	v_lshlrev_b32_e32 v28, 16, v238
	v_and_b32_e32 v29, 0xffff0000, v238
	v_lshlrev_b32_e32 v180, 16, v64
	v_and_b32_e32 v181, 0xffff0000, v64
	v_pk_add_f32 v[28:29], v[32:33], v[28:29]
	v_lshlrev_b32_e32 v32, 16, v241
	v_and_b32_e32 v33, 0xffff0000, v241
	v_pk_add_f32 v[4:5], v[4:5], v[180:181]
	v_lshlrev_b32_e32 v180, 16, v66
	v_and_b32_e32 v181, 0xffff0000, v66
	v_pk_add_f32 v[26:27], v[26:27], v[32:33]
	v_lshlrev_b32_e32 v32, 16, v242
	v_and_b32_e32 v33, 0xffff0000, v242
	v_pk_add_f32 v[0:1], v[0:1], v[180:181]
	v_lshl_add_u64 v[180:181], s[30:31], 0, v[182:183]
	v_cvt_pk_bf16_f32 v112, v60, v61
	v_cvt_pk_bf16_f32 v113, v62, v63
	v_cvt_pk_bf16_f32 v114, v56, v57
	v_cvt_pk_bf16_f32 v115, v58, v59
	v_pk_add_f32 v[20:21], v[20:21], v[32:33]
	v_lshlrev_b32_e32 v32, 16, v244
	v_and_b32_e32 v33, 0xffff0000, v244
	v_lshl_add_u64 v[180:181], v[180:181], 0, v[170:171]
	v_cvt_pk_bf16_f32 v116, v52, v53
	v_cvt_pk_bf16_f32 v117, v54, v55
	v_cvt_pk_bf16_f32 v118, v104, v105
	v_cvt_pk_bf16_f32 v119, v106, v107
	v_lshlrev_b32_e32 v30, 16, v240
	v_and_b32_e32 v31, 0xffff0000, v240
	v_pk_add_f32 v[32:33], v[12:13], v[32:33]
	v_lshlrev_b32_e32 v12, 16, v243
	v_and_b32_e32 v13, 0xffff0000, v243
	global_store_dwordx4 v[180:181], v[112:115], off
	global_store_dwordx4 v[180:181], v[116:119], off offset:256
	v_cvt_pk_bf16_f32 v146, v44, v45
	v_lshl_add_u64 v[112:113], s[30:31], 0, v[132:133]
	v_cvt_pk_bf16_f32 v147, v46, v47
	v_cvt_pk_bf16_f32 v148, v40, v41
	v_cvt_pk_bf16_f32 v149, v42, v43
	v_pk_add_f32 v[24:25], v[24:25], v[30:31]
	v_lshlrev_b32_e32 v30, 16, v239
	v_and_b32_e32 v31, 0xffff0000, v239
	v_pk_add_f32 v[22:23], v[22:23], v[12:13]
	v_lshlrev_b32_e32 v12, 16, v245
	v_and_b32_e32 v13, 0xffff0000, v245
	v_lshl_add_u64 v[112:113], v[112:113], 0, v[170:171]
	v_cvt_pk_bf16_f32 v172, v36, v37
	v_cvt_pk_bf16_f32 v173, v38, v39
	v_cvt_pk_bf16_f32 v174, v48, v49
	v_cvt_pk_bf16_f32 v175, v50, v51
	v_pk_add_f32 v[30:31], v[34:35], v[30:31]
	v_pk_add_f32 v[34:35], v[14:15], v[12:13]
	v_lshlrev_b32_e32 v12, 16, v246
	v_and_b32_e32 v13, 0xffff0000, v246
	v_lshlrev_b32_e32 v14, 16, v248
	v_and_b32_e32 v15, 0xffff0000, v248
	global_store_dwordx4 v[112:113], v[146:149], off
	global_store_dwordx4 v[112:113], v[172:175], off offset:256
	v_lshl_add_u64 v[112:113], s[30:31], 0, v[134:135]
	v_cvt_pk_bf16_f32 v176, v28, v29
	v_cvt_pk_bf16_f32 v177, v30, v31
	v_cvt_pk_bf16_f32 v178, v24, v25
	v_cvt_pk_bf16_f32 v179, v26, v27
	v_pk_add_f32 v[12:13], v[16:17], v[12:13]
	v_pk_add_f32 v[8:9], v[8:9], v[14:15]
	v_lshlrev_b32_e32 v14, 16, v247
	v_and_b32_e32 v15, 0xffff0000, v247
	v_lshlrev_b32_e32 v16, 16, v249
	v_and_b32_e32 v17, 0xffff0000, v249
	v_lshlrev_b32_e32 v64, 16, v65
	v_and_b32_e32 v65, 0xffff0000, v65
	v_lshl_add_u64 v[112:113], v[112:113], 0, v[170:171]
	v_cvt_pk_bf16_f32 v194, v20, v21
	v_cvt_pk_bf16_f32 v195, v22, v23
	v_cvt_pk_bf16_f32 v196, v32, v33
	v_cvt_pk_bf16_f32 v197, v34, v35
	v_pk_add_f32 v[14:15], v[18:19], v[14:15]
	v_pk_add_f32 v[10:11], v[10:11], v[16:17]
	v_pk_add_f32 v[6:7], v[6:7], v[64:65]
	v_lshlrev_b32_e32 v64, 16, v67
	v_and_b32_e32 v65, 0xffff0000, v67
	global_store_dwordx4 v[112:113], v[176:179], off
	global_store_dwordx4 v[112:113], v[194:197], off offset:256
	v_lshl_add_u64 v[112:113], s[30:31], 0, v[184:185]
	v_cvt_pk_bf16_f32 v16, v12, v13
	v_cvt_pk_bf16_f32 v17, v14, v15
	v_cvt_pk_bf16_f32 v18, v8, v9
	v_cvt_pk_bf16_f32 v19, v10, v11
	v_pk_add_f32 v[2:3], v[2:3], v[64:65]
	v_lshl_add_u64 v[112:113], v[112:113], 0, v[170:171]
	v_cvt_pk_bf16_f32 v64, v4, v5
	v_cvt_pk_bf16_f32 v65, v6, v7
	v_cvt_pk_bf16_f32 v66, v0, v1
	v_cvt_pk_bf16_f32 v67, v2, v3
	global_store_dwordx4 v[112:113], v[16:19], off
	global_store_dwordx4 v[112:113], v[64:67], off offset:256
	s_lshl_b32 s10, s81, 2
	v_and_b32_e32 v17, 64, v188
	v_xor_b32_e32 v16, 16, v188
	v_add_u32_e32 v17, 64, v17
	v_cmp_lt_i32_e32 vcc, v16, v17
	v_xor_b32_e32 v18, 32, v188
	s_ashr_i32 s11, s10, 31
	v_cndmask_b32_e32 v16, v188, v16, vcc
	v_lshlrev_b32_e32 v16, 2, v16
	ds_bpermute_b32 v19, v16, v209
	v_cmp_lt_i32_e32 vcc, v18, v17
	s_lshl_b64 s[10:11], s[10:11], 2
	s_add_u32 s50, s75, s10
	v_cndmask_b32_e32 v17, v188, v18, vcc
	v_lshlrev_b32_e32 v17, 2, v17
	s_waitcnt lgkmcnt(0)
	v_add_f32_e32 v18, v209, v19
	ds_bpermute_b32 v19, v17, v18
	s_addc_u32 s51, s80, s11
	s_and_saveexec_b64 s[52:53], s[42:43]
	s_cbranch_execz .LBB0_251
	s_waitcnt lgkmcnt(0)
	v_add_f32_e32 v64, v18, v19
	v_lshlrev_b64 v[18:19], 6, v[168:169]
	v_lshl_add_u64 v[18:19], s[50:51], 0, v[18:19]
	global_store_dword v[18:19], v64, off

.LBB0_290:
	s_add_u32 s26, s26, 0x3290000
	v_and_b32_e32 v15, 15, v8
	v_lshrrev_b32_e32 v8, 1, v8
	s_addc_u32 s27, s27, 0
	v_and_b32_e32 v8, 24, v8
	s_lshl_b32 s10, s10, 5
	v_lshlrev_b32_e32 v16, 1, v8
	v_lshlrev_b32_e32 v17, 2, v15
	s_and_b32 s19, s10, 0x60
	s_add_i32 m0, s58, 0x18000
	v_lshl_add_u64 v[6:7], v[6:7], 0, s[36:37]
	s_lshl_b32 s12, s6, 6
	v_lshl_or_b32 v16, v15, 6, v16
	s_lshl_b32 s11, s6, 13
	v_and_b32_e32 v18, 32, v17
	s_lshl_b32 s10, s19, 7
	s_waitcnt vmcnt(0)
	s_barrier
	global_load_lds_dwordx4 v[6:7], off
	v_lshl_add_u64 v[4:5], v[4:5], 0, s[36:37]
	s_add_i32 m0, s58, 0x1a000
	s_add_i32 s70, s58, 0x8000
	s_add_i32 s71, s58, 0xa000
	v_bitop3_b32 v154, v16, s10, v18 bitop3:0xde
	global_load_lds_dwordx4 v[4:5], off
	v_lshl_add_u64 v[2:3], v[2:3], 0, s[36:37]
	s_mov_b32 m0, s70
	s_add_u32 s10, s48, 0x40080
	v_bitop3_b32 v19, v16, s11, v18 bitop3:0xde
	global_load_lds_dwordx4 v[2:3], off
	v_lshl_add_u64 v[0:1], v[0:1], 0, s[36:37]
	s_mov_b32 m0, s71
	s_addc_u32 s11, s49, 0
	global_load_lds_dwordx4 v[0:1], off
	s_add_i32 m0, s58, 0x1c000
	v_lshl_add_u64 v[0:1], s[10:11], 0, v[140:141]
	global_load_lds_dwordx4 v[0:1], off
	v_lshl_add_u64 v[0:1], s[10:11], 0, v[132:133]
	s_add_i32 m0, s58, 0x1e000
	s_lshl_b32 s6, s6, 8
	global_load_lds_dwordx4 v[0:1], off
	v_lshlrev_b32_e32 v0, 14, v9
	v_and_b32_e32 v0, 0xffff8000, v0
	v_lshl_add_u32 v0, v10, 11, v0
	v_and_b32_e32 v1, 1, v9
	v_lshl_or_b32 v0, v1, 6, v0
	v_lshl_add_u32 v136, v11, 1, v0
	v_lshlrev_b32_e32 v0, 14, v12
	v_and_b32_e32 v0, 0xffff8000, v0
	s_add_i32 s6, s6, 0
	v_lshl_add_u32 v0, v13, 11, v0
	v_and_b32_e32 v1, 1, v12
	s_waitcnt vmcnt(6)
	s_add_i32 s6, s6, 0x22000
	v_lshl_or_b32 v0, v1, 6, v0
	v_add_u32_e32 v155, s6, v17
	s_ashr_i32 s6, s12, 31
	v_lshl_add_u32 v138, v14, 1, v0
	v_mov_b32_e32 v0, 0
	v_or_b32_e32 v134, s12, v15
	v_mov_b32_e32 v135, s6
	v_or_b32_e32 v156, s19, v8
	v_mov_b32_e32 v137, v141
	v_mov_b32_e32 v139, v141
	s_mov_b32 s73, 0
	v_add_u32_e32 v157, 0, v19
	v_readlane_b32 s72, v253, 46
	v_readlane_b32 s28, v253, 60
	v_mov_b32_e32 v1, v0
	v_mov_b32_e32 v2, v0
	v_mov_b32_e32 v3, v0
	v_mov_b32_e32 v4, v0
	v_mov_b32_e32 v5, v0
	v_mov_b32_e32 v6, v0
	v_mov_b32_e32 v7, v0
	v_mov_b32_e32 v8, v0
	v_mov_b32_e32 v9, v0
	v_mov_b32_e32 v10, v0
	v_mov_b32_e32 v11, v0
	v_mov_b32_e32 v12, v0
	v_mov_b32_e32 v13, v0
	v_mov_b32_e32 v14, v0
	v_mov_b32_e32 v15, v0
	v_mov_b32_e32 v16, v0
	v_mov_b32_e32 v17, v0
	v_mov_b32_e32 v18, v0
	v_mov_b32_e32 v19, v0
	v_mov_b32_e32 v20, v0
	v_mov_b32_e32 v21, v0
	v_mov_b32_e32 v22, v0
	v_mov_b32_e32 v23, v0
	v_mov_b32_e32 v24, v0
	v_mov_b32_e32 v25, v0
	v_mov_b32_e32 v26, v0
	v_mov_b32_e32 v27, v0
	v_mov_b32_e32 v28, v0
	v_mov_b32_e32 v29, v0
	v_mov_b32_e32 v30, v0
	v_mov_b32_e32 v31, v0
	v_mov_b32_e32 v32, v0
	v_mov_b32_e32 v33, v0
	v_mov_b32_e32 v34, v0
	v_mov_b32_e32 v35, v0
	v_mov_b32_e32 v36, v0
	v_mov_b32_e32 v37, v0
	v_mov_b32_e32 v38, v0
	v_mov_b32_e32 v39, v0
	v_mov_b32_e32 v40, v0
	v_mov_b32_e32 v41, v0
	v_mov_b32_e32 v42, v0
	v_mov_b32_e32 v43, v0
	v_mov_b32_e32 v44, v0
	v_mov_b32_e32 v45, v0
	v_mov_b32_e32 v46, v0
	v_mov_b32_e32 v47, v0
	v_mov_b32_e32 v48, v0
	v_mov_b32_e32 v49, v0
	v_mov_b32_e32 v50, v0
	v_mov_b32_e32 v51, v0
	v_mov_b32_e32 v52, v0
	v_mov_b32_e32 v53, v0
	v_mov_b32_e32 v54, v0
	v_mov_b32_e32 v55, v0
	v_mov_b32_e32 v56, v0
	v_mov_b32_e32 v57, v0
	v_mov_b32_e32 v58, v0
	v_mov_b32_e32 v59, v0
	v_mov_b32_e32 v60, v0
	v_mov_b32_e32 v61, v0
	v_mov_b32_e32 v62, v0
	v_mov_b32_e32 v63, v0
	v_mov_b32_e32 v64, v0
	v_mov_b32_e32 v65, v0
	v_mov_b32_e32 v66, v0
	v_mov_b32_e32 v67, v0
	v_mov_b32_e32 v68, v0
	v_mov_b32_e32 v69, v0
	v_mov_b32_e32 v70, v0
	v_mov_b32_e32 v71, v0
	v_mov_b32_e32 v72, v0
	v_mov_b32_e32 v73, v0
	v_mov_b32_e32 v74, v0
	v_mov_b32_e32 v75, v0
	v_mov_b32_e32 v76, v0
	v_mov_b32_e32 v77, v0
	v_mov_b32_e32 v78, v0
	v_mov_b32_e32 v79, v0
	v_mov_b32_e32 v80, v0
	v_mov_b32_e32 v81, v0
	v_mov_b32_e32 v82, v0
	v_mov_b32_e32 v83, v0
	v_mov_b32_e32 v84, v0
	v_mov_b32_e32 v85, v0
	v_mov_b32_e32 v86, v0
	v_mov_b32_e32 v87, v0
	v_mov_b32_e32 v88, v0
	v_mov_b32_e32 v89, v0
	v_mov_b32_e32 v90, v0
	v_mov_b32_e32 v91, v0
	v_mov_b32_e32 v92, v0
	v_mov_b32_e32 v93, v0
	v_mov_b32_e32 v94, v0
	v_mov_b32_e32 v95, v0
	v_mov_b32_e32 v96, v0
	v_mov_b32_e32 v97, v0
	v_mov_b32_e32 v98, v0
	v_mov_b32_e32 v99, v0
	v_mov_b32_e32 v100, v0
	v_mov_b32_e32 v101, v0
	v_mov_b32_e32 v102, v0
	v_mov_b32_e32 v103, v0
	v_mov_b32_e32 v104, v0
	v_mov_b32_e32 v105, v0
	v_mov_b32_e32 v106, v0
	v_mov_b32_e32 v107, v0
	v_mov_b32_e32 v108, v0
	v_mov_b32_e32 v109, v0
	v_mov_b32_e32 v110, v0
	v_mov_b32_e32 v111, v0
	v_mov_b32_e32 v112, v0
	v_mov_b32_e32 v113, v0
	v_mov_b32_e32 v114, v0
	v_mov_b32_e32 v115, v0
	v_mov_b32_e32 v116, v0
	v_mov_b32_e32 v117, v0
	v_mov_b32_e32 v118, v0
	v_mov_b32_e32 v119, v0
	v_mov_b32_e32 v120, v0
	v_mov_b32_e32 v121, v0
	v_mov_b32_e32 v122, v0
	v_mov_b32_e32 v123, v0
	v_mov_b32_e32 v124, v0
	v_mov_b32_e32 v125, v0
	v_mov_b32_e32 v126, v0
	v_mov_b32_e32 v127, v0
	s_barrier
	v_readlane_b32 s29, v253, 61
	s_mov_b32 s100, 0
	s_branch .LBB0_292

.LBB0_295:
	s_add_u32 s6, s4, s48
	s_addc_u32 s19, s5, s49
	s_add_u32 s6, s6, 0x100
	s_addc_u32 s19, s19, 0
	s_add_u32 s23, s10, s48
	s_addc_u32 s50, s11, s49
	s_add_i32 s80, 0, 0x10000
	v_add_u32_e32 v166, s80, v154
	ds_read_b128 v[146:149], v166
	ds_read_b128 v[158:161], v166 offset:1024
	ds_read_b128 v[162:165], v166 offset:2048
	ds_read_b128 v[166:169], v166 offset:3072
	s_cmpk_eq_i32 s48, 0x700
	s_cselect_b32 s53, s12, s19
	s_cselect_b32 s52, s29, s6
	s_cselect_b32 s51, s31, s50
	s_cselect_b32 s50, s35, s23
	v_lshl_add_u64 v[218:219], v[150:151], 0, s[48:49]
	s_add_i32 m0, s58, 0xc000
	ds_read_b128 v[170:173], v157
	ds_read_b128 v[174:177], v157 offset:1024
	ds_read_b128 v[178:181], v157 offset:2048
	ds_read_b128 v[182:185], v157 offset:3072
	ds_read_b128 v[194:197], v157 offset:4096
	ds_read_b128 v[206:209], v157 offset:5120
	ds_read_b128 v[210:213], v157 offset:6144
	ds_read_b128 v[214:217], v157 offset:7168
	global_load_lds_dwordx4 v[218:219], off
	v_lshl_add_u64 v[218:219], v[152:153], 0, s[48:49]
	s_add_i32 m0, s58, 0xe000
	s_nop 0
	global_load_lds_dwordx4 v[218:219], off
	s_add_i32 s6, 0, 0x14000
	v_add_u32_e32 v192, s6, v154
	ds_read_b128 v[218:221], v192
	ds_read_b128 v[222:225], v192 offset:1024
	ds_read_b128 v[226:229], v192 offset:2048
	ds_read_b128 v[230:233], v192 offset:3072
	s_waitcnt vmcnt(24)
	s_cmp_lg_u32 s100, 0
	s_cbranch_scc1 .Lm4a_295
	s_waitcnt vmcnt(8)
.Lm4a_295:
	s_waitcnt lgkmcnt(0)
	s_barrier
	s_setprio 1
	v_mfma_f32_16x16x32_bf16 v[124:127], v[146:149], v[170:173], v[124:127]
	v_mfma_f32_16x16x32_bf16 v[120:123], v[162:165], v[170:173], v[120:123]
	v_mfma_f32_16x16x32_bf16 v[116:119], v[146:149], v[178:181], v[116:119]
	v_mfma_f32_16x16x32_bf16 v[112:115], v[162:165], v[178:181], v[112:115]
	v_mfma_f32_16x16x32_bf16 v[108:111], v[146:149], v[194:197], v[108:111]
	v_mfma_f32_16x16x32_bf16 v[104:107], v[162:165], v[194:197], v[104:107]
	v_mfma_f32_16x16x32_bf16 v[100:103], v[146:149], v[210:213], v[100:103]
	v_mfma_f32_16x16x32_bf16 v[96:99], v[162:165], v[210:213], v[96:99]
	v_mfma_f32_16x16x32_bf16 v[124:127], v[158:161], v[174:177], v[124:127]
	v_mfma_f32_16x16x32_bf16 v[120:123], v[166:169], v[174:177], v[120:123]
	v_mfma_f32_16x16x32_bf16 v[116:119], v[158:161], v[182:185], v[116:119]
	v_mfma_f32_16x16x32_bf16 v[112:115], v[166:169], v[182:185], v[112:115]
	v_mfma_f32_16x16x32_bf16 v[108:111], v[158:161], v[206:209], v[108:111]
	v_mfma_f32_16x16x32_bf16 v[104:107], v[166:169], v[206:209], v[104:107]
	v_mfma_f32_16x16x32_bf16 v[100:103], v[158:161], v[214:217], v[100:103]
	v_mfma_f32_16x16x32_bf16 v[96:99], v[166:169], v[214:217], v[96:99]
	v_mfma_f32_16x16x32_bf16 v[92:95], v[218:221], v[170:173], v[92:95]
	v_mfma_f32_16x16x32_bf16 v[88:91], v[226:229], v[170:173], v[88:91]
	v_mfma_f32_16x16x32_bf16 v[84:87], v[218:221], v[178:181], v[84:87]
	v_mfma_f32_16x16x32_bf16 v[80:83], v[226:229], v[178:181], v[80:83]
	v_mfma_f32_16x16x32_bf16 v[76:79], v[218:221], v[194:197], v[76:79]
	v_mfma_f32_16x16x32_bf16 v[72:75], v[226:229], v[194:197], v[72:75]
	v_mfma_f32_16x16x32_bf16 v[68:71], v[218:221], v[210:213], v[68:71]
	v_mfma_f32_16x16x32_bf16 v[64:67], v[226:229], v[210:213], v[64:67]
	v_mfma_f32_16x16x32_bf16 v[92:95], v[222:225], v[174:177], v[92:95]
	v_mfma_f32_16x16x32_bf16 v[88:91], v[230:233], v[174:177], v[88:91]
	v_mfma_f32_16x16x32_bf16 v[84:87], v[222:225], v[182:185], v[84:87]
	v_mfma_f32_16x16x32_bf16 v[80:83], v[230:233], v[182:185], v[80:83]
	v_mfma_f32_16x16x32_bf16 v[76:79], v[222:225], v[206:209], v[76:79]
	v_mfma_f32_16x16x32_bf16 v[72:75], v[230:233], v[206:209], v[72:75]
	v_mfma_f32_16x16x32_bf16 v[68:71], v[222:225], v[214:217], v[68:71]
	v_mfma_f32_16x16x32_bf16 v[64:67], v[230:233], v[214:217], v[64:67]
	s_setprio 0
	s_barrier
	s_add_i32 s19, s80, s57
	v_lshl_add_u64 v[234:235], s[50:51], 0, v[140:141]
	s_mov_b32 m0, s19
	s_nop 0
	global_load_lds_dwordx4 v[234:235], off
	v_lshl_add_u64 v[236:237], s[50:51], 0, v[132:133]
	s_add_i32 m0, s19, 0x2000
	s_nop 0
	global_load_lds_dwordx4 v[236:237], off
	s_mov_b32 m0, s58
	v_lshl_add_u64 v[238:239], s[52:53], 0, v[128:129]
	ds_read_b128 v[170:173], v157 offset:16384
	ds_read_b128 v[174:177], v157 offset:17408
	ds_read_b128 v[178:181], v157 offset:18432
	ds_read_b128 v[182:185], v157 offset:19456
	ds_read_b128 v[194:197], v157 offset:20480
	ds_read_b128 v[206:209], v157 offset:21504
	ds_read_b128 v[210:213], v157 offset:22528
	ds_read_b128 v[214:217], v157 offset:23552
	global_load_lds_dwordx4 v[238:239], off
	v_lshl_add_u64 v[240:241], s[52:53], 0, v[130:131]
	s_mov_b32 m0, s59
	s_nop 0
	global_load_lds_dwordx4 v[240:241], off
	s_add_u32 s80, s50, 0x40000
	s_addc_u32 s81, s51, 0
	s_add_i32 s6, s6, s57
	v_lshl_add_u64 v[250:251], s[80:81], 0, v[140:141]
	s_mov_b32 m0, s6
	s_nop 0
	global_load_lds_dwordx4 v[250:251], off
	v_lshl_add_u64 v[250:251], s[80:81], 0, v[132:133]
	s_add_i32 m0, s6, 0x2000
	s_nop 0
	global_load_lds_dwordx4 v[250:251], off
	s_waitcnt vmcnt(24)
	s_cmp_lg_u32 s100, 0
	s_cbranch_scc1 .Lm4b_295
	s_waitcnt vmcnt(8)
.Lm4b_295:
	s_waitcnt lgkmcnt(0)
	s_mov_b32 s100, 0
	s_barrier
	s_setprio 1
	v_mfma_f32_16x16x32_bf16 v[60:63], v[146:149], v[170:173], v[60:63]
	v_mfma_f32_16x16x32_bf16 v[56:59], v[162:165], v[170:173], v[56:59]
	v_mfma_f32_16x16x32_bf16 v[52:55], v[146:149], v[178:181], v[52:55]
	v_mfma_f32_16x16x32_bf16 v[48:51], v[162:165], v[178:181], v[48:51]
	v_mfma_f32_16x16x32_bf16 v[44:47], v[146:149], v[194:197], v[44:47]
	v_mfma_f32_16x16x32_bf16 v[40:43], v[162:165], v[194:197], v[40:43]
	v_mfma_f32_16x16x32_bf16 v[36:39], v[146:149], v[210:213], v[36:39]
	v_mfma_f32_16x16x32_bf16 v[32:35], v[162:165], v[210:213], v[32:35]
	v_mfma_f32_16x16x32_bf16 v[60:63], v[158:161], v[174:177], v[60:63]
	v_mfma_f32_16x16x32_bf16 v[56:59], v[166:169], v[174:177], v[56:59]
	v_mfma_f32_16x16x32_bf16 v[52:55], v[158:161], v[182:185], v[52:55]
	v_mfma_f32_16x16x32_bf16 v[48:51], v[166:169], v[182:185], v[48:51]
	v_mfma_f32_16x16x32_bf16 v[44:47], v[158:161], v[206:209], v[44:47]
	v_mfma_f32_16x16x32_bf16 v[40:43], v[166:169], v[206:209], v[40:43]
	v_mfma_f32_16x16x32_bf16 v[36:39], v[158:161], v[214:217], v[36:39]
	v_mfma_f32_16x16x32_bf16 v[32:35], v[166:169], v[214:217], v[32:35]
	v_mfma_f32_16x16x32_bf16 v[28:31], v[218:221], v[170:173], v[28:31]
	v_mfma_f32_16x16x32_bf16 v[24:27], v[226:229], v[170:173], v[24:27]
	v_mfma_f32_16x16x32_bf16 v[20:23], v[218:221], v[178:181], v[20:23]
	v_mfma_f32_16x16x32_bf16 v[16:19], v[226:229], v[178:181], v[16:19]
	v_mfma_f32_16x16x32_bf16 v[12:15], v[218:221], v[194:197], v[12:15]
	v_mfma_f32_16x16x32_bf16 v[8:11], v[226:229], v[194:197], v[8:11]
	v_mfma_f32_16x16x32_bf16 v[4:7], v[218:221], v[210:213], v[4:7]
	v_mfma_f32_16x16x32_bf16 v[0:3], v[226:229], v[210:213], v[0:3]
	v_mfma_f32_16x16x32_bf16 v[28:31], v[222:225], v[174:177], v[28:31]
	v_mfma_f32_16x16x32_bf16 v[24:27], v[230:233], v[174:177], v[24:27]
	v_mfma_f32_16x16x32_bf16 v[20:23], v[222:225], v[182:185], v[20:23]
	v_mfma_f32_16x16x32_bf16 v[16:19], v[230:233], v[182:185], v[16:19]
	v_mfma_f32_16x16x32_bf16 v[12:15], v[222:225], v[206:209], v[12:15]
	v_mfma_f32_16x16x32_bf16 v[8:11], v[230:233], v[206:209], v[8:11]
	v_mfma_f32_16x16x32_bf16 v[4:7], v[222:225], v[214:217], v[4:7]
	v_mfma_f32_16x16x32_bf16 v[0:3], v[230:233], v[214:217], v[0:3]
	s_setprio 0
	s_barrier
	s_add_i32 s6, 0, 0x18000
	v_add_u32_e32 v166, s6, v154
	ds_read_b128 v[146:149], v166
	ds_read_b128 v[158:161], v166 offset:1024
	ds_read_b128 v[162:165], v166 offset:2048
	ds_read_b128 v[166:169], v166 offset:3072
	s_add_u32 s52, s52, 0x40000
	s_addc_u32 s53, s53, 0
	s_mov_b32 m0, s68
	v_lshl_add_u64 v[218:219], s[52:53], 0, v[128:129]
	ds_read_b128 v[170:173], v157 offset:32768
	ds_read_b128 v[174:177], v157 offset:33792
	ds_read_b128 v[178:181], v157 offset:34816
	ds_read_b128 v[182:185], v157 offset:35840
	ds_read_b128 v[194:197], v157 offset:36864
	ds_read_b128 v[206:209], v157 offset:37888
	ds_read_b128 v[210:213], v157 offset:38912
	ds_read_b128 v[214:217], v157 offset:39936
	global_load_lds_dwordx4 v[218:219], off
	v_lshl_add_u64 v[218:219], s[52:53], 0, v[130:131]
	s_mov_b32 m0, s69
	s_nop 0
	global_load_lds_dwordx4 v[218:219], off
	s_add_i32 s19, 0, 0x1c000
	v_add_u32_e32 v192, s19, v154
	ds_read_b128 v[218:221], v192
	ds_read_b128 v[222:225], v192 offset:1024
	ds_read_b128 v[226:229], v192 offset:2048
	ds_read_b128 v[230:233], v192 offset:3072
	s_waitcnt vmcnt(8)
	s_waitcnt lgkmcnt(0)
	s_barrier
	s_setprio 1
	v_mfma_f32_16x16x32_bf16 v[124:127], v[146:149], v[170:173], v[124:127]
	v_mfma_f32_16x16x32_bf16 v[120:123], v[162:165], v[170:173], v[120:123]
	v_mfma_f32_16x16x32_bf16 v[116:119], v[146:149], v[178:181], v[116:119]
	v_mfma_f32_16x16x32_bf16 v[112:115], v[162:165], v[178:181], v[112:115]
	v_mfma_f32_16x16x32_bf16 v[108:111], v[146:149], v[194:197], v[108:111]
	v_mfma_f32_16x16x32_bf16 v[104:107], v[162:165], v[194:197], v[104:107]
	v_mfma_f32_16x16x32_bf16 v[100:103], v[146:149], v[210:213], v[100:103]
	v_mfma_f32_16x16x32_bf16 v[96:99], v[162:165], v[210:213], v[96:99]
	v_mfma_f32_16x16x32_bf16 v[124:127], v[158:161], v[174:177], v[124:127]
	v_mfma_f32_16x16x32_bf16 v[120:123], v[166:169], v[174:177], v[120:123]
	v_mfma_f32_16x16x32_bf16 v[116:119], v[158:161], v[182:185], v[116:119]
	v_mfma_f32_16x16x32_bf16 v[112:115], v[166:169], v[182:185], v[112:115]
	v_mfma_f32_16x16x32_bf16 v[108:111], v[158:161], v[206:209], v[108:111]
	v_mfma_f32_16x16x32_bf16 v[104:107], v[166:169], v[206:209], v[104:107]
	v_mfma_f32_16x16x32_bf16 v[100:103], v[158:161], v[214:217], v[100:103]
	v_mfma_f32_16x16x32_bf16 v[96:99], v[166:169], v[214:217], v[96:99]
	v_mfma_f32_16x16x32_bf16 v[92:95], v[218:221], v[170:173], v[92:95]
	v_mfma_f32_16x16x32_bf16 v[88:91], v[226:229], v[170:173], v[88:91]
	v_mfma_f32_16x16x32_bf16 v[84:87], v[218:221], v[178:181], v[84:87]
	v_mfma_f32_16x16x32_bf16 v[80:83], v[226:229], v[178:181], v[80:83]
	v_mfma_f32_16x16x32_bf16 v[76:79], v[218:221], v[194:197], v[76:79]
	v_mfma_f32_16x16x32_bf16 v[72:75], v[226:229], v[194:197], v[72:75]
	v_mfma_f32_16x16x32_bf16 v[68:71], v[218:221], v[210:213], v[68:71]
	v_mfma_f32_16x16x32_bf16 v[64:67], v[226:229], v[210:213], v[64:67]
	v_mfma_f32_16x16x32_bf16 v[92:95], v[222:225], v[174:177], v[92:95]
	v_mfma_f32_16x16x32_bf16 v[88:91], v[230:233], v[174:177], v[88:91]
	v_mfma_f32_16x16x32_bf16 v[84:87], v[222:225], v[182:185], v[84:87]
	v_mfma_f32_16x16x32_bf16 v[80:83], v[230:233], v[182:185], v[80:83]
	v_mfma_f32_16x16x32_bf16 v[76:79], v[222:225], v[206:209], v[76:79]
	v_mfma_f32_16x16x32_bf16 v[72:75], v[230:233], v[206:209], v[72:75]
	v_mfma_f32_16x16x32_bf16 v[68:71], v[222:225], v[214:217], v[68:71]
	v_mfma_f32_16x16x32_bf16 v[64:67], v[230:233], v[214:217], v[64:67]
	s_setprio 0
	s_barrier
	s_add_i32 s6, s6, s57
	v_lshl_add_u64 v[234:235], v[234:235], 0, s[36:37]
	s_mov_b32 m0, s6
	s_nop 0
	global_load_lds_dwordx4 v[234:235], off
	v_lshl_add_u64 v[234:235], v[236:237], 0, s[36:37]
	s_add_i32 m0, s6, 0x2000
	s_nop 0
	global_load_lds_dwordx4 v[234:235], off
	s_mov_b32 m0, s70
	v_lshl_add_u64 v[234:235], v[238:239], 0, s[36:37]
	ds_read_b128 v[170:173], v157 offset:49152
	ds_read_b128 v[174:177], v157 offset:50176
	ds_read_b128 v[178:181], v157 offset:51200
	ds_read_b128 v[182:185], v157 offset:52224
	ds_read_b128 v[194:197], v157 offset:53248
	ds_read_b128 v[206:209], v157 offset:54272
	ds_read_b128 v[210:213], v157 offset:55296
	ds_read_b128 v[214:217], v157 offset:56320
	global_load_lds_dwordx4 v[234:235], off
	v_lshl_add_u64 v[234:235], v[240:241], 0, s[36:37]
	s_mov_b32 m0, s71
	s_nop 0
	global_load_lds_dwordx4 v[234:235], off
	s_add_u32 s50, s50, 0x40080
	s_addc_u32 s51, s51, 0
	s_add_i32 s6, s19, s57
	v_lshl_add_u64 v[250:251], s[50:51], 0, v[140:141]
	s_mov_b32 m0, s6
	s_nop 0
	global_load_lds_dwordx4 v[250:251], off
	v_lshl_add_u64 v[250:251], s[50:51], 0, v[132:133]
	s_add_i32 m0, s6, 0x2000
	s_nop 0
	global_load_lds_dwordx4 v[250:251], off
	s_waitcnt vmcnt(8)
	s_waitcnt lgkmcnt(0)
	s_barrier
	s_setprio 1
	v_mfma_f32_16x16x32_bf16 v[60:63], v[146:149], v[170:173], v[60:63]
	v_mfma_f32_16x16x32_bf16 v[56:59], v[162:165], v[170:173], v[56:59]
	v_mfma_f32_16x16x32_bf16 v[52:55], v[146:149], v[178:181], v[52:55]
	v_mfma_f32_16x16x32_bf16 v[48:51], v[162:165], v[178:181], v[48:51]
	v_mfma_f32_16x16x32_bf16 v[44:47], v[146:149], v[194:197], v[44:47]
	v_mfma_f32_16x16x32_bf16 v[40:43], v[162:165], v[194:197], v[40:43]
	v_mfma_f32_16x16x32_bf16 v[36:39], v[146:149], v[210:213], v[36:39]
	v_mfma_f32_16x16x32_bf16 v[32:35], v[162:165], v[210:213], v[32:35]
	v_mfma_f32_16x16x32_bf16 v[60:63], v[158:161], v[174:177], v[60:63]
	v_mfma_f32_16x16x32_bf16 v[56:59], v[166:169], v[174:177], v[56:59]
	v_mfma_f32_16x16x32_bf16 v[52:55], v[158:161], v[182:185], v[52:55]
	v_mfma_f32_16x16x32_bf16 v[48:51], v[166:169], v[182:185], v[48:51]
	v_mfma_f32_16x16x32_bf16 v[44:47], v[158:161], v[206:209], v[44:47]
	v_mfma_f32_16x16x32_bf16 v[40:43], v[166:169], v[206:209], v[40:43]
	v_mfma_f32_16x16x32_bf16 v[36:39], v[158:161], v[214:217], v[36:39]
	v_mfma_f32_16x16x32_bf16 v[32:35], v[166:169], v[214:217], v[32:35]
	v_mfma_f32_16x16x32_bf16 v[28:31], v[218:221], v[170:173], v[28:31]
	v_mfma_f32_16x16x32_bf16 v[24:27], v[226:229], v[170:173], v[24:27]
	v_mfma_f32_16x16x32_bf16 v[20:23], v[218:221], v[178:181], v[20:23]
	v_mfma_f32_16x16x32_bf16 v[16:19], v[226:229], v[178:181], v[16:19]
	v_mfma_f32_16x16x32_bf16 v[12:15], v[218:221], v[194:197], v[12:15]
	v_mfma_f32_16x16x32_bf16 v[8:11], v[226:229], v[194:197], v[8:11]
	v_mfma_f32_16x16x32_bf16 v[4:7], v[218:221], v[210:213], v[4:7]
	v_mfma_f32_16x16x32_bf16 v[0:3], v[226:229], v[210:213], v[0:3]
	v_mfma_f32_16x16x32_bf16 v[28:31], v[222:225], v[174:177], v[28:31]
	v_mfma_f32_16x16x32_bf16 v[24:27], v[230:233], v[174:177], v[24:27]
	v_mfma_f32_16x16x32_bf16 v[20:23], v[222:225], v[182:185], v[20:23]
	v_mfma_f32_16x16x32_bf16 v[16:19], v[230:233], v[182:185], v[16:19]
	v_mfma_f32_16x16x32_bf16 v[12:15], v[222:225], v[206:209], v[12:15]
	v_mfma_f32_16x16x32_bf16 v[8:11], v[230:233], v[206:209], v[8:11]
	v_mfma_f32_16x16x32_bf16 v[4:7], v[222:225], v[214:217], v[4:7]
	v_mfma_f32_16x16x32_bf16 v[0:3], v[230:233], v[214:217], v[0:3]
	s_setprio 0
	s_add_i32 s75, s75, 2
	s_add_u32 s48, s48, 0x100
	s_addc_u32 s49, s49, 0
	s_cmp_gt_u32 s75, 13
	s_barrier
	s_cbranch_scc0 .LBB0_295
	s_mov_b32 s100, 1
	s_add_u32 s48, s10, 0xffffff00
	v_lshl_add_u32 v166, s73, 10, v155
	s_addc_u32 s49, s11, -1
	s_ashr_i32 s29, s28, 31
	v_lshl_or_b32 v146, s72, 8, v156
	ds_read2_b32 v[158:159], v166 offset1:16
	s_lshl_b64 s[10:11], s[28:29], 8
	v_ashrrev_i32_e32 v147, 31, v146
	v_lshl_add_u64 v[148:149], s[10:11], 0, v[134:135]
	v_lshl_add_u64 v[146:147], v[146:147], 1, s[26:27]
	v_mad_u64_u32 v[150:151], s[10:11], v148, s13, v[146:147]
	v_mov_b32_e32 v146, v151
	v_mad_u64_u32 v[152:153], s[10:11], v149, s13, v[146:147]
	s_waitcnt lgkmcnt(0)
	v_pk_mul_f32 v[148:149], v[126:127], v[158:159] op_sel_hi:[1,0]
	v_pk_mul_f32 v[146:147], v[124:125], v[158:159] op_sel_hi:[1,0]
	v_pk_mul_f32 v[160:161], v[122:123], v[158:159] op_sel_hi:[1,0]
	v_pk_mul_f32 v[162:163], v[120:121], v[158:159] op_sel_hi:[1,0]
	v_mov_b32_e32 v151, v152
	v_cvt_pk_bf16_f32 v146, v146, v147
	v_cvt_pk_bf16_f32 v147, v148, v149
	v_cvt_pk_bf16_f32 v148, v162, v163
	v_cvt_pk_bf16_f32 v149, v160, v161
	global_store_dwordx4 v[150:151], v[146:149], off
	v_pk_mul_f32 v[160:161], v[90:91], v[158:159] op_sel_hi:[1,0]
	v_pk_mul_f32 v[162:163], v[88:89], v[158:159] op_sel_hi:[1,0]
	v_pk_mul_f32 v[148:149], v[94:95], v[158:159] op_sel_hi:[1,0]
	v_pk_mul_f32 v[146:147], v[92:93], v[158:159] op_sel_hi:[1,0]
	v_mov_b32_e32 v158, v159
	v_cvt_pk_bf16_f32 v146, v146, v147
	v_cvt_pk_bf16_f32 v147, v148, v149
	v_cvt_pk_bf16_f32 v148, v162, v163
	v_cvt_pk_bf16_f32 v149, v160, v161
	global_store_dwordx4 v[150:151], v[146:149], off offset:256
	v_pk_mul_f32 v[160:161], v[114:115], v[158:159] op_sel_hi:[1,0]
	s_mov_b32 s6, 0x1e000
	v_pk_mul_f32 v[148:149], v[118:119], v[158:159] op_sel_hi:[1,0]
	v_pk_mul_f32 v[146:147], v[116:117], v[158:159] op_sel_hi:[1,0]
	ds_read2_b32 v[164:165], v166 offset0:32 offset1:48
	v_pk_mul_f32 v[162:163], v[112:113], v[158:159] op_sel_hi:[1,0]
	v_cvt_pk_bf16_f32 v146, v146, v147
	v_cvt_pk_bf16_f32 v147, v148, v149
	v_cvt_pk_bf16_f32 v149, v160, v161
	v_add_co_u32_e32 v160, vcc, s6, v150
	v_cvt_pk_bf16_f32 v148, v162, v163
	s_nop 0
	v_addc_co_u32_e32 v161, vcc, 0, v152, vcc
	global_store_dwordx4 v[160:161], v[146:149], off
	v_pk_mul_f32 v[162:163], v[82:83], v[158:159] op_sel_hi:[1,0]
	s_mov_b32 s6, 0x3c000
	v_pk_mul_f32 v[148:149], v[86:87], v[158:159] op_sel_hi:[1,0]
	v_pk_mul_f32 v[146:147], v[84:85], v[158:159] op_sel_hi:[1,0]
	v_pk_mul_f32 v[158:159], v[80:81], v[158:159] op_sel_hi:[1,0]
	v_cvt_pk_bf16_f32 v146, v146, v147
	v_cvt_pk_bf16_f32 v147, v148, v149
	v_cvt_pk_bf16_f32 v148, v158, v159
	v_cvt_pk_bf16_f32 v149, v162, v163
	global_store_dwordx4 v[160:161], v[146:149], off offset:256
	s_waitcnt lgkmcnt(0)
	v_pk_mul_f32 v[158:159], v[106:107], v[164:165] op_sel_hi:[1,0]
	v_pk_mul_f32 v[160:161], v[104:105], v[164:165] op_sel_hi:[1,0]
	v_pk_mul_f32 v[148:149], v[110:111], v[164:165] op_sel_hi:[1,0]
	v_pk_mul_f32 v[146:147], v[108:109], v[164:165] op_sel_hi:[1,0]
	v_pk_mul_f32 v[162:163], v[72:73], v[164:165] op_sel_hi:[1,0]
	v_cvt_pk_bf16_f32 v146, v146, v147
	v_cvt_pk_bf16_f32 v147, v148, v149
	v_cvt_pk_bf16_f32 v149, v158, v159
	v_add_co_u32_e32 v158, vcc, s6, v150
	v_cvt_pk_bf16_f32 v148, v160, v161
	s_nop 0
	v_addc_co_u32_e32 v159, vcc, 0, v152, vcc
	global_store_dwordx4 v[158:159], v[146:149], off
	v_pk_mul_f32 v[160:161], v[74:75], v[164:165] op_sel_hi:[1,0]
	s_mov_b32 s6, 0x5a000
	v_pk_mul_f32 v[148:149], v[78:79], v[164:165] op_sel_hi:[1,0]
	v_pk_mul_f32 v[146:147], v[76:77], v[164:165] op_sel_hi:[1,0]
	s_nop 0
	v_cvt_pk_bf16_f32 v146, v146, v147
	v_cvt_pk_bf16_f32 v147, v148, v149
	v_cvt_pk_bf16_f32 v148, v162, v163
	v_cvt_pk_bf16_f32 v149, v160, v161
	global_store_dwordx4 v[158:159], v[146:149], off offset:256
	v_mov_b32_e32 v158, v165
	v_pk_mul_f32 v[160:161], v[98:99], v[158:159] op_sel_hi:[1,0]
	v_pk_mul_f32 v[148:149], v[102:103], v[158:159] op_sel_hi:[1,0]
	v_pk_mul_f32 v[146:147], v[100:101], v[158:159] op_sel_hi:[1,0]
	ds_read2_b32 v[164:165], v166 offset0:128 offset1:144
	v_pk_mul_f32 v[162:163], v[96:97], v[158:159] op_sel_hi:[1,0]
	v_cvt_pk_bf16_f32 v146, v146, v147
	v_cvt_pk_bf16_f32 v147, v148, v149
	v_cvt_pk_bf16_f32 v149, v160, v161
	v_add_co_u32_e32 v160, vcc, s6, v150
	v_cvt_pk_bf16_f32 v148, v162, v163
	s_nop 0
	v_addc_co_u32_e32 v161, vcc, 0, v152, vcc
	global_store_dwordx4 v[160:161], v[146:149], off
	v_pk_mul_f32 v[162:163], v[66:67], v[158:159] op_sel_hi:[1,0]
	s_mov_b32 s6, 0xf0000
	v_pk_mul_f32 v[148:149], v[70:71], v[158:159] op_sel_hi:[1,0]
	v_pk_mul_f32 v[146:147], v[68:69], v[158:159] op_sel_hi:[1,0]
	v_pk_mul_f32 v[158:159], v[64:65], v[158:159] op_sel_hi:[1,0]
	v_cvt_pk_bf16_f32 v146, v146, v147
	v_cvt_pk_bf16_f32 v147, v148, v149
	v_cvt_pk_bf16_f32 v148, v158, v159
	v_cvt_pk_bf16_f32 v149, v162, v163
	global_store_dwordx4 v[160:161], v[146:149], off offset:256
	s_waitcnt lgkmcnt(0)
	v_pk_mul_f32 v[158:159], v[58:59], v[164:165] op_sel_hi:[1,0]
	v_pk_mul_f32 v[160:161], v[56:57], v[164:165] op_sel_hi:[1,0]
	v_pk_mul_f32 v[148:149], v[62:63], v[164:165] op_sel_hi:[1,0]
	v_pk_mul_f32 v[146:147], v[60:61], v[164:165] op_sel_hi:[1,0]
	v_pk_mul_f32 v[162:163], v[24:25], v[164:165] op_sel_hi:[1,0]
	v_cvt_pk_bf16_f32 v146, v146, v147
	v_cvt_pk_bf16_f32 v147, v148, v149
	v_cvt_pk_bf16_f32 v149, v158, v159
	v_add_co_u32_e32 v158, vcc, s6, v150
	v_cvt_pk_bf16_f32 v148, v160, v161
	s_nop 0
	v_addc_co_u32_e32 v159, vcc, 0, v152, vcc
	global_store_dwordx4 v[158:159], v[146:149], off
	v_pk_mul_f32 v[160:161], v[26:27], v[164:165] op_sel_hi:[1,0]
	s_mov_b32 s6, 0x10e000
	v_pk_mul_f32 v[148:149], v[30:31], v[164:165] op_sel_hi:[1,0]
	v_pk_mul_f32 v[146:147], v[28:29], v[164:165] op_sel_hi:[1,0]
	s_nop 0
	v_cvt_pk_bf16_f32 v146, v146, v147
	v_cvt_pk_bf16_f32 v147, v148, v149
	v_cvt_pk_bf16_f32 v148, v162, v163
	v_cvt_pk_bf16_f32 v149, v160, v161
	global_store_dwordx4 v[158:159], v[146:149], off offset:256
	v_mov_b32_e32 v158, v165
	v_pk_mul_f32 v[160:161], v[50:51], v[158:159] op_sel_hi:[1,0]
	v_pk_mul_f32 v[148:149], v[54:55], v[158:159] op_sel_hi:[1,0]
	v_pk_mul_f32 v[146:147], v[52:53], v[158:159] op_sel_hi:[1,0]
	ds_read2_b32 v[164:165], v166 offset0:160 offset1:176
	v_pk_mul_f32 v[162:163], v[48:49], v[158:159] op_sel_hi:[1,0]
	v_cvt_pk_bf16_f32 v146, v146, v147
	v_cvt_pk_bf16_f32 v147, v148, v149
	v_cvt_pk_bf16_f32 v149, v160, v161
	v_add_co_u32_e32 v160, vcc, s6, v150
	v_cvt_pk_bf16_f32 v148, v162, v163
	s_nop 0
	v_addc_co_u32_e32 v161, vcc, 0, v152, vcc
	global_store_dwordx4 v[160:161], v[146:149], off
	v_pk_mul_f32 v[162:163], v[18:19], v[158:159] op_sel_hi:[1,0]
	s_mov_b32 s6, 0x12c000
	v_pk_mul_f32 v[148:149], v[22:23], v[158:159] op_sel_hi:[1,0]
	v_pk_mul_f32 v[146:147], v[20:21], v[158:159] op_sel_hi:[1,0]
	v_pk_mul_f32 v[158:159], v[16:17], v[158:159] op_sel_hi:[1,0]
	v_cvt_pk_bf16_f32 v146, v146, v147
	v_cvt_pk_bf16_f32 v147, v148, v149
	v_cvt_pk_bf16_f32 v148, v158, v159
	v_cvt_pk_bf16_f32 v149, v162, v163
	global_store_dwordx4 v[160:161], v[146:149], off offset:256
	s_waitcnt lgkmcnt(0)
	v_pk_mul_f32 v[158:159], v[42:43], v[164:165] op_sel_hi:[1,0]
	v_pk_mul_f32 v[160:161], v[40:41], v[164:165] op_sel_hi:[1,0]
	v_pk_mul_f32 v[148:149], v[46:47], v[164:165] op_sel_hi:[1,0]
	v_pk_mul_f32 v[146:147], v[44:45], v[164:165] op_sel_hi:[1,0]
	v_pk_mul_f32 v[162:163], v[8:9], v[164:165] op_sel_hi:[1,0]
	v_cvt_pk_bf16_f32 v146, v146, v147
	v_cvt_pk_bf16_f32 v147, v148, v149
	v_cvt_pk_bf16_f32 v149, v158, v159
	v_add_co_u32_e32 v158, vcc, s6, v150
	v_cvt_pk_bf16_f32 v148, v160, v161
	s_nop 0
	v_addc_co_u32_e32 v159, vcc, 0, v152, vcc
	global_store_dwordx4 v[158:159], v[146:149], off
	v_pk_mul_f32 v[160:161], v[10:11], v[164:165] op_sel_hi:[1,0]
	s_mov_b32 s6, 0x14a000
	v_pk_mul_f32 v[148:149], v[14:15], v[164:165] op_sel_hi:[1,0]
	v_pk_mul_f32 v[146:147], v[12:13], v[164:165] op_sel_hi:[1,0]
	v_add_co_u32_e32 v150, vcc, s6, v150
	v_cvt_pk_bf16_f32 v146, v146, v147
	v_cvt_pk_bf16_f32 v147, v148, v149
	v_cvt_pk_bf16_f32 v148, v162, v163
	v_cvt_pk_bf16_f32 v149, v160, v161
	global_store_dwordx4 v[158:159], v[146:149], off offset:256
	v_mov_b32_e32 v158, v165
	v_pk_mul_f32 v[160:161], v[34:35], v[158:159] op_sel_hi:[1,0]
	v_pk_mul_f32 v[148:149], v[38:39], v[158:159] op_sel_hi:[1,0]
	v_pk_mul_f32 v[146:147], v[36:37], v[158:159] op_sel_hi:[1,0]
	v_pk_mul_f32 v[162:163], v[32:33], v[158:159] op_sel_hi:[1,0]
	v_cvt_pk_bf16_f32 v146, v146, v147
	v_cvt_pk_bf16_f32 v147, v148, v149
	v_cvt_pk_bf16_f32 v148, v162, v163
	v_cvt_pk_bf16_f32 v149, v160, v161
	v_addc_co_u32_e32 v151, vcc, 0, v152, vcc
	global_store_dwordx4 v[150:151], v[146:149], off
	v_pk_mul_f32 v[152:153], v[2:3], v[158:159] op_sel_hi:[1,0]
	s_andn2_b64 vcc, exec, s[44:45]
	v_pk_mul_f32 v[148:149], v[6:7], v[158:159] op_sel_hi:[1,0]
	v_pk_mul_f32 v[146:147], v[4:5], v[158:159] op_sel_hi:[1,0]
	v_pk_mul_f32 v[158:159], v[0:1], v[158:159] op_sel_hi:[1,0]
	v_cvt_pk_bf16_f32 v146, v146, v147
	v_cvt_pk_bf16_f32 v147, v148, v149
	v_cvt_pk_bf16_f32 v148, v158, v159
	v_cvt_pk_bf16_f32 v149, v152, v153
	global_store_dwordx4 v[150:151], v[146:149], off offset:256
	s_cbranch_vccz .LBB0_291
	s_mov_b64 s[38:39], s[48:49]
	s_andn2_b64 vcc, exec, s[42:43]
	s_mov_b64 s[48:49], s[38:39]
	s_cbranch_vccnz .LBB0_292

.LBB0_306:
	v_lshrrev_b32_e32 v16, 1, v10
	v_and_b32_e32 v16, 24, v16
	s_add_u32 s26, s26, 0x1db10000
	v_and_b32_e32 v15, 15, v10
	v_lshlrev_b32_e32 v17, 1, v16
	v_lshlrev_b32_e32 v10, 2, v10
	s_addc_u32 s27, s27, 0
	s_lshl_b32 s12, s6, 6
	v_lshl_or_b32 v17, v15, 6, v17
	s_lshl_b32 s6, s6, 13
	v_and_b32_e32 v10, 32, v10
	v_bitop3_b32 v18, v17, s6, v10 bitop3:0xde
	s_lshl_b32 s6, s10, 5
	s_and_b32 s6, s6, 0x60
	s_add_i32 m0, s58, 0x18000
	v_lshl_add_u64 v[6:7], v[6:7], 0, s[36:37]
	s_lshl_b32 s10, s6, 7
	s_waitcnt vmcnt(0)
	s_barrier
	global_load_lds_dwordx4 v[6:7], off
	v_lshl_add_u64 v[4:5], v[4:5], 0, s[36:37]
	s_add_i32 m0, s58, 0x1a000
	s_add_i32 s71, s58, 0x8000
	s_add_i32 s72, s58, 0xa000
	v_bitop3_b32 v154, v17, s10, v10 bitop3:0xde
	global_load_lds_dwordx4 v[4:5], off
	v_lshl_add_u64 v[2:3], v[2:3], 0, s[36:37]
	s_mov_b32 m0, s71
	s_add_u32 s10, s48, 0x40080
	global_load_lds_dwordx4 v[2:3], off
	v_lshl_add_u64 v[0:1], v[0:1], 0, s[36:37]
	s_mov_b32 m0, s72
	s_addc_u32 s11, s49, 0
	global_load_lds_dwordx4 v[0:1], off
	s_add_i32 m0, s58, 0x1c000
	v_lshl_add_u64 v[0:1], s[10:11], 0, v[140:141]
	global_load_lds_dwordx4 v[0:1], off
	v_lshl_add_u64 v[0:1], s[10:11], 0, v[132:133]
	s_add_i32 m0, s58, 0x1e000
	s_ashr_i32 s10, s12, 31
	global_load_lds_dwordx4 v[0:1], off
	v_or_b32_e32 v0, s12, v15
	v_mov_b32_e32 v1, s10
	v_lshlrev_b64 v[134:135], 12, v[0:1]
	v_lshlrev_b32_e32 v0, 14, v8
	v_and_b32_e32 v0, 0xffff8000, v0
	v_lshl_add_u32 v0, v9, 11, v0
	v_and_b32_e32 v1, 1, v8
	v_lshl_or_b32 v0, v1, 6, v0
	v_lshl_add_u32 v136, v11, 1, v0
	v_lshlrev_b32_e32 v0, 14, v12
	v_and_b32_e32 v0, 0xffff8000, v0
	v_lshl_add_u32 v0, v13, 11, v0
	v_and_b32_e32 v1, 1, v12
	s_waitcnt vmcnt(6)
	v_lshl_or_b32 v0, v1, 6, v0
	v_lshl_add_u32 v138, v14, 1, v0
	v_mov_b32_e32 v0, 0
	s_sext_i32_i8 s28, s28
	s_sext_i32_i8 s70, s30
	v_or_b32_e32 v155, s6, v16
	v_mov_b32_e32 v137, v141
	v_mov_b32_e32 v139, v141
	s_mov_b32 s73, 0
	v_add_u32_e32 v156, 0, v18
	v_mov_b32_e32 v1, v0
	v_mov_b32_e32 v2, v0
	v_mov_b32_e32 v3, v0
	v_mov_b32_e32 v4, v0
	v_mov_b32_e32 v5, v0
	v_mov_b32_e32 v6, v0
	v_mov_b32_e32 v7, v0
	v_mov_b32_e32 v8, v0
	v_mov_b32_e32 v9, v0
	v_mov_b32_e32 v10, v0
	v_mov_b32_e32 v11, v0
	v_mov_b32_e32 v12, v0
	v_mov_b32_e32 v13, v0
	v_mov_b32_e32 v14, v0
	v_mov_b32_e32 v15, v0
	v_mov_b32_e32 v16, v0
	v_mov_b32_e32 v17, v0
	v_mov_b32_e32 v18, v0
	v_mov_b32_e32 v19, v0
	v_mov_b32_e32 v20, v0
	v_mov_b32_e32 v21, v0
	v_mov_b32_e32 v22, v0
	v_mov_b32_e32 v23, v0
	v_mov_b32_e32 v24, v0
	v_mov_b32_e32 v25, v0
	v_mov_b32_e32 v26, v0
	v_mov_b32_e32 v27, v0
	v_mov_b32_e32 v28, v0
	v_mov_b32_e32 v29, v0
	v_mov_b32_e32 v30, v0
	v_mov_b32_e32 v31, v0
	v_mov_b32_e32 v32, v0
	v_mov_b32_e32 v33, v0
	v_mov_b32_e32 v34, v0
	v_mov_b32_e32 v35, v0
	v_mov_b32_e32 v36, v0
	v_mov_b32_e32 v37, v0
	v_mov_b32_e32 v38, v0
	v_mov_b32_e32 v39, v0
	v_mov_b32_e32 v40, v0
	v_mov_b32_e32 v41, v0
	v_mov_b32_e32 v42, v0
	v_mov_b32_e32 v43, v0
	v_mov_b32_e32 v44, v0
	v_mov_b32_e32 v45, v0
	v_mov_b32_e32 v46, v0
	v_mov_b32_e32 v47, v0
	v_mov_b32_e32 v48, v0
	v_mov_b32_e32 v49, v0
	v_mov_b32_e32 v50, v0
	v_mov_b32_e32 v51, v0
	v_mov_b32_e32 v52, v0
	v_mov_b32_e32 v53, v0
	v_mov_b32_e32 v54, v0
	v_mov_b32_e32 v55, v0
	v_mov_b32_e32 v56, v0
	v_mov_b32_e32 v57, v0
	v_mov_b32_e32 v58, v0
	v_mov_b32_e32 v59, v0
	v_mov_b32_e32 v60, v0
	v_mov_b32_e32 v61, v0
	v_mov_b32_e32 v62, v0
	v_mov_b32_e32 v63, v0
	v_mov_b32_e32 v64, v0
	v_mov_b32_e32 v65, v0
	v_mov_b32_e32 v66, v0
	v_mov_b32_e32 v67, v0
	v_mov_b32_e32 v68, v0
	v_mov_b32_e32 v69, v0
	v_mov_b32_e32 v70, v0
	v_mov_b32_e32 v71, v0
	v_mov_b32_e32 v72, v0
	v_mov_b32_e32 v73, v0
	v_mov_b32_e32 v74, v0
	v_mov_b32_e32 v75, v0
	v_mov_b32_e32 v76, v0
	v_mov_b32_e32 v77, v0
	v_mov_b32_e32 v78, v0
	v_mov_b32_e32 v79, v0
	v_mov_b32_e32 v80, v0
	v_mov_b32_e32 v81, v0
	v_mov_b32_e32 v82, v0
	v_mov_b32_e32 v83, v0
	v_mov_b32_e32 v84, v0
	v_mov_b32_e32 v85, v0
	v_mov_b32_e32 v86, v0
	v_mov_b32_e32 v87, v0
	v_mov_b32_e32 v88, v0
	v_mov_b32_e32 v89, v0
	v_mov_b32_e32 v90, v0
	v_mov_b32_e32 v91, v0
	v_mov_b32_e32 v92, v0
	v_mov_b32_e32 v93, v0
	v_mov_b32_e32 v94, v0
	v_mov_b32_e32 v95, v0
	v_mov_b32_e32 v96, v0
	v_mov_b32_e32 v97, v0
	v_mov_b32_e32 v98, v0
	v_mov_b32_e32 v99, v0
	v_mov_b32_e32 v100, v0
	v_mov_b32_e32 v101, v0
	v_mov_b32_e32 v102, v0
	v_mov_b32_e32 v103, v0
	v_mov_b32_e32 v104, v0
	v_mov_b32_e32 v105, v0
	v_mov_b32_e32 v106, v0
	v_mov_b32_e32 v107, v0
	v_mov_b32_e32 v108, v0
	v_mov_b32_e32 v109, v0
	v_mov_b32_e32 v110, v0
	v_mov_b32_e32 v111, v0
	v_mov_b32_e32 v112, v0
	v_mov_b32_e32 v113, v0
	v_mov_b32_e32 v114, v0
	v_mov_b32_e32 v115, v0
	v_mov_b32_e32 v116, v0
	v_mov_b32_e32 v117, v0
	v_mov_b32_e32 v118, v0
	v_mov_b32_e32 v119, v0
	v_mov_b32_e32 v120, v0
	v_mov_b32_e32 v121, v0
	v_mov_b32_e32 v122, v0
	v_mov_b32_e32 v123, v0
	v_mov_b32_e32 v124, v0
	v_mov_b32_e32 v125, v0
	v_mov_b32_e32 v126, v0
	v_mov_b32_e32 v127, v0
	s_barrier
	s_mov_b32 s100, 0
	s_branch .LBB0_308

.LBB0_315:
	s_add_u32 s6, s4, s48
	s_addc_u32 s19, s5, s49
	s_add_u32 s6, s6, 0x100
	s_addc_u32 s19, s19, 0
	s_add_u32 s23, s11, s48
	s_addc_u32 s50, s12, s49
	s_add_i32 s80, 0, 0x10000
	v_add_u32_e32 v157, s80, v154
	ds_read_b128 v[146:149], v157
	ds_read_b128 v[158:161], v157 offset:1024
	ds_read_b128 v[162:165], v157 offset:2048
	ds_read_b128 v[166:169], v157 offset:3072
	s_cmpk_eq_i32 s48, 0x700
	s_cselect_b32 s53, s29, s19
	s_cselect_b32 s52, s31, s6
	s_cselect_b32 s51, s35, s50
	s_cselect_b32 s50, s74, s23
	v_lshl_add_u64 v[218:219], v[150:151], 0, s[48:49]
	s_add_i32 m0, s58, 0xc000
	ds_read_b128 v[170:173], v156
	ds_read_b128 v[174:177], v156 offset:1024
	ds_read_b128 v[178:181], v156 offset:2048
	ds_read_b128 v[182:185], v156 offset:3072
	ds_read_b128 v[194:197], v156 offset:4096
	ds_read_b128 v[206:209], v156 offset:5120
	ds_read_b128 v[210:213], v156 offset:6144
	ds_read_b128 v[214:217], v156 offset:7168
	global_load_lds_dwordx4 v[218:219], off
	v_lshl_add_u64 v[218:219], v[152:153], 0, s[48:49]
	s_add_i32 m0, s58, 0xe000
	s_nop 0
	global_load_lds_dwordx4 v[218:219], off
	s_add_i32 s6, 0, 0x14000
	v_add_u32_e32 v157, s6, v154
	ds_read_b128 v[218:221], v157
	ds_read_b128 v[222:225], v157 offset:1024
	ds_read_b128 v[226:229], v157 offset:2048
	ds_read_b128 v[230:233], v157 offset:3072
	s_waitcnt vmcnt(24)
	s_cmp_lg_u32 s100, 0
	s_cbranch_scc1 .Lm4a_315
	s_waitcnt vmcnt(8)
.Lm4a_315:
	s_waitcnt lgkmcnt(0)
	s_barrier
	s_setprio 1
	v_mfma_f32_16x16x32_bf16 v[124:127], v[146:149], v[170:173], v[124:127]
	v_mfma_f32_16x16x32_bf16 v[120:123], v[162:165], v[170:173], v[120:123]
	v_mfma_f32_16x16x32_bf16 v[116:119], v[146:149], v[178:181], v[116:119]
	v_mfma_f32_16x16x32_bf16 v[112:115], v[162:165], v[178:181], v[112:115]
	v_mfma_f32_16x16x32_bf16 v[108:111], v[146:149], v[194:197], v[108:111]
	v_mfma_f32_16x16x32_bf16 v[104:107], v[162:165], v[194:197], v[104:107]
	v_mfma_f32_16x16x32_bf16 v[100:103], v[146:149], v[210:213], v[100:103]
	v_mfma_f32_16x16x32_bf16 v[96:99], v[162:165], v[210:213], v[96:99]
	v_mfma_f32_16x16x32_bf16 v[124:127], v[158:161], v[174:177], v[124:127]
	v_mfma_f32_16x16x32_bf16 v[120:123], v[166:169], v[174:177], v[120:123]
	v_mfma_f32_16x16x32_bf16 v[116:119], v[158:161], v[182:185], v[116:119]
	v_mfma_f32_16x16x32_bf16 v[112:115], v[166:169], v[182:185], v[112:115]
	v_mfma_f32_16x16x32_bf16 v[108:111], v[158:161], v[206:209], v[108:111]
	v_mfma_f32_16x16x32_bf16 v[104:107], v[166:169], v[206:209], v[104:107]
	v_mfma_f32_16x16x32_bf16 v[100:103], v[158:161], v[214:217], v[100:103]
	v_mfma_f32_16x16x32_bf16 v[96:99], v[166:169], v[214:217], v[96:99]
	v_mfma_f32_16x16x32_bf16 v[92:95], v[218:221], v[170:173], v[92:95]
	v_mfma_f32_16x16x32_bf16 v[88:91], v[226:229], v[170:173], v[88:91]
	v_mfma_f32_16x16x32_bf16 v[84:87], v[218:221], v[178:181], v[84:87]
	v_mfma_f32_16x16x32_bf16 v[80:83], v[226:229], v[178:181], v[80:83]
	v_mfma_f32_16x16x32_bf16 v[76:79], v[218:221], v[194:197], v[76:79]
	v_mfma_f32_16x16x32_bf16 v[72:75], v[226:229], v[194:197], v[72:75]
	v_mfma_f32_16x16x32_bf16 v[68:71], v[218:221], v[210:213], v[68:71]
	v_mfma_f32_16x16x32_bf16 v[64:67], v[226:229], v[210:213], v[64:67]
	v_mfma_f32_16x16x32_bf16 v[92:95], v[222:225], v[174:177], v[92:95]
	v_mfma_f32_16x16x32_bf16 v[88:91], v[230:233], v[174:177], v[88:91]
	v_mfma_f32_16x16x32_bf16 v[84:87], v[222:225], v[182:185], v[84:87]
	v_mfma_f32_16x16x32_bf16 v[80:83], v[230:233], v[182:185], v[80:83]
	v_mfma_f32_16x16x32_bf16 v[76:79], v[222:225], v[206:209], v[76:79]
	v_mfma_f32_16x16x32_bf16 v[72:75], v[230:233], v[206:209], v[72:75]
	v_mfma_f32_16x16x32_bf16 v[68:71], v[222:225], v[214:217], v[68:71]
	v_mfma_f32_16x16x32_bf16 v[64:67], v[230:233], v[214:217], v[64:67]
	s_setprio 0
	s_barrier
	s_add_i32 s19, s80, s57
	v_lshl_add_u64 v[234:235], s[50:51], 0, v[140:141]
	s_mov_b32 m0, s19
	s_nop 0
	global_load_lds_dwordx4 v[234:235], off
	v_lshl_add_u64 v[236:237], s[50:51], 0, v[132:133]
	s_add_i32 m0, s19, 0x2000
	s_nop 0
	global_load_lds_dwordx4 v[236:237], off
	s_mov_b32 m0, s58
	v_lshl_add_u64 v[238:239], s[52:53], 0, v[128:129]
	ds_read_b128 v[170:173], v156 offset:16384
	ds_read_b128 v[174:177], v156 offset:17408
	ds_read_b128 v[178:181], v156 offset:18432
	ds_read_b128 v[182:185], v156 offset:19456
	ds_read_b128 v[194:197], v156 offset:20480
	ds_read_b128 v[206:209], v156 offset:21504
	ds_read_b128 v[210:213], v156 offset:22528
	ds_read_b128 v[214:217], v156 offset:23552
	global_load_lds_dwordx4 v[238:239], off
	v_lshl_add_u64 v[240:241], s[52:53], 0, v[130:131]
	s_mov_b32 m0, s59
	s_nop 0
	global_load_lds_dwordx4 v[240:241], off
	s_add_u32 s80, s50, 0x40000
	s_addc_u32 s81, s51, 0
	s_add_i32 s6, s6, s57
	v_lshl_add_u64 v[250:251], s[80:81], 0, v[140:141]
	s_mov_b32 m0, s6
	s_nop 0
	global_load_lds_dwordx4 v[250:251], off
	v_lshl_add_u64 v[250:251], s[80:81], 0, v[132:133]
	s_add_i32 m0, s6, 0x2000
	s_nop 0
	global_load_lds_dwordx4 v[250:251], off
	s_waitcnt vmcnt(24)
	s_cmp_lg_u32 s100, 0
	s_cbranch_scc1 .Lm4b_315
	s_waitcnt vmcnt(8)
.Lm4b_315:
	s_waitcnt lgkmcnt(0)
	s_mov_b32 s100, 0
	s_barrier
	s_setprio 1
	v_mfma_f32_16x16x32_bf16 v[60:63], v[146:149], v[170:173], v[60:63]
	v_mfma_f32_16x16x32_bf16 v[56:59], v[162:165], v[170:173], v[56:59]
	v_mfma_f32_16x16x32_bf16 v[52:55], v[146:149], v[178:181], v[52:55]
	v_mfma_f32_16x16x32_bf16 v[48:51], v[162:165], v[178:181], v[48:51]
	v_mfma_f32_16x16x32_bf16 v[44:47], v[146:149], v[194:197], v[44:47]
	v_mfma_f32_16x16x32_bf16 v[40:43], v[162:165], v[194:197], v[40:43]
	v_mfma_f32_16x16x32_bf16 v[36:39], v[146:149], v[210:213], v[36:39]
	v_mfma_f32_16x16x32_bf16 v[32:35], v[162:165], v[210:213], v[32:35]
	v_mfma_f32_16x16x32_bf16 v[60:63], v[158:161], v[174:177], v[60:63]
	v_mfma_f32_16x16x32_bf16 v[56:59], v[166:169], v[174:177], v[56:59]
	v_mfma_f32_16x16x32_bf16 v[52:55], v[158:161], v[182:185], v[52:55]
	v_mfma_f32_16x16x32_bf16 v[48:51], v[166:169], v[182:185], v[48:51]
	v_mfma_f32_16x16x32_bf16 v[44:47], v[158:161], v[206:209], v[44:47]
	v_mfma_f32_16x16x32_bf16 v[40:43], v[166:169], v[206:209], v[40:43]
	v_mfma_f32_16x16x32_bf16 v[36:39], v[158:161], v[214:217], v[36:39]
	v_mfma_f32_16x16x32_bf16 v[32:35], v[166:169], v[214:217], v[32:35]
	v_mfma_f32_16x16x32_bf16 v[28:31], v[218:221], v[170:173], v[28:31]
	v_mfma_f32_16x16x32_bf16 v[24:27], v[226:229], v[170:173], v[24:27]
	v_mfma_f32_16x16x32_bf16 v[20:23], v[218:221], v[178:181], v[20:23]
	v_mfma_f32_16x16x32_bf16 v[16:19], v[226:229], v[178:181], v[16:19]
	v_mfma_f32_16x16x32_bf16 v[12:15], v[218:221], v[194:197], v[12:15]
	v_mfma_f32_16x16x32_bf16 v[8:11], v[226:229], v[194:197], v[8:11]
	v_mfma_f32_16x16x32_bf16 v[4:7], v[218:221], v[210:213], v[4:7]
	v_mfma_f32_16x16x32_bf16 v[0:3], v[226:229], v[210:213], v[0:3]
	v_mfma_f32_16x16x32_bf16 v[28:31], v[222:225], v[174:177], v[28:31]
	v_mfma_f32_16x16x32_bf16 v[24:27], v[230:233], v[174:177], v[24:27]
	v_mfma_f32_16x16x32_bf16 v[20:23], v[222:225], v[182:185], v[20:23]
	v_mfma_f32_16x16x32_bf16 v[16:19], v[230:233], v[182:185], v[16:19]
	v_mfma_f32_16x16x32_bf16 v[12:15], v[222:225], v[206:209], v[12:15]
	v_mfma_f32_16x16x32_bf16 v[8:11], v[230:233], v[206:209], v[8:11]
	v_mfma_f32_16x16x32_bf16 v[4:7], v[222:225], v[214:217], v[4:7]
	v_mfma_f32_16x16x32_bf16 v[0:3], v[230:233], v[214:217], v[0:3]
	s_setprio 0
	s_barrier
	s_add_i32 s6, 0, 0x18000
	v_add_u32_e32 v157, s6, v154
	ds_read_b128 v[146:149], v157
	ds_read_b128 v[158:161], v157 offset:1024
	ds_read_b128 v[162:165], v157 offset:2048
	ds_read_b128 v[166:169], v157 offset:3072
	s_add_u32 s52, s52, 0x40000
	s_addc_u32 s53, s53, 0
	s_mov_b32 m0, s68
	v_lshl_add_u64 v[218:219], s[52:53], 0, v[128:129]
	ds_read_b128 v[170:173], v156 offset:32768
	ds_read_b128 v[174:177], v156 offset:33792
	ds_read_b128 v[178:181], v156 offset:34816
	ds_read_b128 v[182:185], v156 offset:35840
	ds_read_b128 v[194:197], v156 offset:36864
	ds_read_b128 v[206:209], v156 offset:37888
	ds_read_b128 v[210:213], v156 offset:38912
	ds_read_b128 v[214:217], v156 offset:39936
	global_load_lds_dwordx4 v[218:219], off
	v_lshl_add_u64 v[218:219], s[52:53], 0, v[130:131]
	s_mov_b32 m0, s69
	s_nop 0
	global_load_lds_dwordx4 v[218:219], off
	s_add_i32 s19, 0, 0x1c000
	v_add_u32_e32 v157, s19, v154
	ds_read_b128 v[218:221], v157
	ds_read_b128 v[222:225], v157 offset:1024
	ds_read_b128 v[226:229], v157 offset:2048
	ds_read_b128 v[230:233], v157 offset:3072
	s_waitcnt vmcnt(8)
	s_waitcnt lgkmcnt(0)
	s_barrier
	s_setprio 1
	v_mfma_f32_16x16x32_bf16 v[124:127], v[146:149], v[170:173], v[124:127]
	v_mfma_f32_16x16x32_bf16 v[120:123], v[162:165], v[170:173], v[120:123]
	v_mfma_f32_16x16x32_bf16 v[116:119], v[146:149], v[178:181], v[116:119]
	v_mfma_f32_16x16x32_bf16 v[112:115], v[162:165], v[178:181], v[112:115]
	v_mfma_f32_16x16x32_bf16 v[108:111], v[146:149], v[194:197], v[108:111]
	v_mfma_f32_16x16x32_bf16 v[104:107], v[162:165], v[194:197], v[104:107]
	v_mfma_f32_16x16x32_bf16 v[100:103], v[146:149], v[210:213], v[100:103]
	v_mfma_f32_16x16x32_bf16 v[96:99], v[162:165], v[210:213], v[96:99]
	v_mfma_f32_16x16x32_bf16 v[124:127], v[158:161], v[174:177], v[124:127]
	v_mfma_f32_16x16x32_bf16 v[120:123], v[166:169], v[174:177], v[120:123]
	v_mfma_f32_16x16x32_bf16 v[116:119], v[158:161], v[182:185], v[116:119]
	v_mfma_f32_16x16x32_bf16 v[112:115], v[166:169], v[182:185], v[112:115]
	v_mfma_f32_16x16x32_bf16 v[108:111], v[158:161], v[206:209], v[108:111]
	v_mfma_f32_16x16x32_bf16 v[104:107], v[166:169], v[206:209], v[104:107]
	v_mfma_f32_16x16x32_bf16 v[100:103], v[158:161], v[214:217], v[100:103]
	v_mfma_f32_16x16x32_bf16 v[96:99], v[166:169], v[214:217], v[96:99]
	v_mfma_f32_16x16x32_bf16 v[92:95], v[218:221], v[170:173], v[92:95]
	v_mfma_f32_16x16x32_bf16 v[88:91], v[226:229], v[170:173], v[88:91]
	v_mfma_f32_16x16x32_bf16 v[84:87], v[218:221], v[178:181], v[84:87]
	v_mfma_f32_16x16x32_bf16 v[80:83], v[226:229], v[178:181], v[80:83]
	v_mfma_f32_16x16x32_bf16 v[76:79], v[218:221], v[194:197], v[76:79]
	v_mfma_f32_16x16x32_bf16 v[72:75], v[226:229], v[194:197], v[72:75]
	v_mfma_f32_16x16x32_bf16 v[68:71], v[218:221], v[210:213], v[68:71]
	v_mfma_f32_16x16x32_bf16 v[64:67], v[226:229], v[210:213], v[64:67]
	v_mfma_f32_16x16x32_bf16 v[92:95], v[222:225], v[174:177], v[92:95]
	v_mfma_f32_16x16x32_bf16 v[88:91], v[230:233], v[174:177], v[88:91]
	v_mfma_f32_16x16x32_bf16 v[84:87], v[222:225], v[182:185], v[84:87]
	v_mfma_f32_16x16x32_bf16 v[80:83], v[230:233], v[182:185], v[80:83]
	v_mfma_f32_16x16x32_bf16 v[76:79], v[222:225], v[206:209], v[76:79]
	v_mfma_f32_16x16x32_bf16 v[72:75], v[230:233], v[206:209], v[72:75]
	v_mfma_f32_16x16x32_bf16 v[68:71], v[222:225], v[214:217], v[68:71]
	v_mfma_f32_16x16x32_bf16 v[64:67], v[230:233], v[214:217], v[64:67]
	s_setprio 0
	s_barrier
	s_add_i32 s6, s6, s57
	v_lshl_add_u64 v[234:235], v[234:235], 0, s[36:37]
	s_mov_b32 m0, s6
	s_nop 0
	global_load_lds_dwordx4 v[234:235], off
	v_lshl_add_u64 v[234:235], v[236:237], 0, s[36:37]
	s_add_i32 m0, s6, 0x2000
	s_nop 0
	global_load_lds_dwordx4 v[234:235], off
	s_mov_b32 m0, s71
	v_lshl_add_u64 v[234:235], v[238:239], 0, s[36:37]
	ds_read_b128 v[170:173], v156 offset:49152
	ds_read_b128 v[174:177], v156 offset:50176
	ds_read_b128 v[178:181], v156 offset:51200
	ds_read_b128 v[182:185], v156 offset:52224
	ds_read_b128 v[194:197], v156 offset:53248
	ds_read_b128 v[206:209], v156 offset:54272
	ds_read_b128 v[210:213], v156 offset:55296
	ds_read_b128 v[214:217], v156 offset:56320
	global_load_lds_dwordx4 v[234:235], off
	v_lshl_add_u64 v[234:235], v[240:241], 0, s[36:37]
	s_mov_b32 m0, s72
	s_nop 0
	global_load_lds_dwordx4 v[234:235], off
	s_add_u32 s50, s50, 0x40080
	s_addc_u32 s51, s51, 0
	s_add_i32 s6, s19, s57
	v_lshl_add_u64 v[250:251], s[50:51], 0, v[140:141]
	s_mov_b32 m0, s6
	s_nop 0
	global_load_lds_dwordx4 v[250:251], off
	v_lshl_add_u64 v[250:251], s[50:51], 0, v[132:133]
	s_add_i32 m0, s6, 0x2000
	s_nop 0
	global_load_lds_dwordx4 v[250:251], off
	s_waitcnt vmcnt(8)
	s_waitcnt lgkmcnt(0)
	s_barrier
	s_setprio 1
	v_mfma_f32_16x16x32_bf16 v[60:63], v[146:149], v[170:173], v[60:63]
	v_mfma_f32_16x16x32_bf16 v[56:59], v[162:165], v[170:173], v[56:59]
	v_mfma_f32_16x16x32_bf16 v[52:55], v[146:149], v[178:181], v[52:55]
	v_mfma_f32_16x16x32_bf16 v[48:51], v[162:165], v[178:181], v[48:51]
	v_mfma_f32_16x16x32_bf16 v[44:47], v[146:149], v[194:197], v[44:47]
	v_mfma_f32_16x16x32_bf16 v[40:43], v[162:165], v[194:197], v[40:43]
	v_mfma_f32_16x16x32_bf16 v[36:39], v[146:149], v[210:213], v[36:39]
	v_mfma_f32_16x16x32_bf16 v[32:35], v[162:165], v[210:213], v[32:35]
	v_mfma_f32_16x16x32_bf16 v[60:63], v[158:161], v[174:177], v[60:63]
	v_mfma_f32_16x16x32_bf16 v[56:59], v[166:169], v[174:177], v[56:59]
	v_mfma_f32_16x16x32_bf16 v[52:55], v[158:161], v[182:185], v[52:55]
	v_mfma_f32_16x16x32_bf16 v[48:51], v[166:169], v[182:185], v[48:51]
	v_mfma_f32_16x16x32_bf16 v[44:47], v[158:161], v[206:209], v[44:47]
	v_mfma_f32_16x16x32_bf16 v[40:43], v[166:169], v[206:209], v[40:43]
	v_mfma_f32_16x16x32_bf16 v[36:39], v[158:161], v[214:217], v[36:39]
	v_mfma_f32_16x16x32_bf16 v[32:35], v[166:169], v[214:217], v[32:35]
	v_mfma_f32_16x16x32_bf16 v[28:31], v[218:221], v[170:173], v[28:31]
	v_mfma_f32_16x16x32_bf16 v[24:27], v[226:229], v[170:173], v[24:27]
	v_mfma_f32_16x16x32_bf16 v[20:23], v[218:221], v[178:181], v[20:23]
	v_mfma_f32_16x16x32_bf16 v[16:19], v[226:229], v[178:181], v[16:19]
	v_mfma_f32_16x16x32_bf16 v[12:15], v[218:221], v[194:197], v[12:15]
	v_mfma_f32_16x16x32_bf16 v[8:11], v[226:229], v[194:197], v[8:11]
	v_mfma_f32_16x16x32_bf16 v[4:7], v[218:221], v[210:213], v[4:7]
	v_mfma_f32_16x16x32_bf16 v[0:3], v[226:229], v[210:213], v[0:3]
	v_mfma_f32_16x16x32_bf16 v[28:31], v[222:225], v[174:177], v[28:31]
	v_mfma_f32_16x16x32_bf16 v[24:27], v[230:233], v[174:177], v[24:27]
	v_mfma_f32_16x16x32_bf16 v[20:23], v[222:225], v[182:185], v[20:23]
	v_mfma_f32_16x16x32_bf16 v[16:19], v[230:233], v[182:185], v[16:19]
	v_mfma_f32_16x16x32_bf16 v[12:15], v[222:225], v[206:209], v[12:15]
	v_mfma_f32_16x16x32_bf16 v[8:11], v[230:233], v[206:209], v[8:11]
	v_mfma_f32_16x16x32_bf16 v[4:7], v[222:225], v[214:217], v[4:7]
	v_mfma_f32_16x16x32_bf16 v[0:3], v[230:233], v[214:217], v[0:3]
	s_setprio 0
	s_add_i32 s75, s75, 2
	s_add_u32 s48, s48, 0x100
	s_addc_u32 s49, s49, 0
	s_cmp_gt_u32 s75, 13
	s_barrier
	s_cbranch_scc0 .LBB0_315
	s_mov_b32 s100, 1
	s_add_u32 s48, s11, 0xffffff00
	v_lshl_or_b32 v146, s70, 8, v155
	s_addc_u32 s49, s12, -1
	s_ashr_i32 s29, s28, 31
	v_ashrrev_i32_e32 v147, 31, v146
	v_lshl_add_u64 v[146:147], v[146:147], 1, s[26:27]
	s_lshl_b64 s[50:51], s[28:29], 20
	v_lshl_add_u64 v[146:147], v[146:147], 0, s[50:51]
	v_lshl_add_u64 v[150:151], v[146:147], 0, v[134:135]
	v_cvt_pk_bf16_f32 v146, v124, v125
	v_cvt_pk_bf16_f32 v147, v126, v127
	v_cvt_pk_bf16_f32 v148, v120, v121
	v_cvt_pk_bf16_f32 v149, v122, v123
	global_store_dwordx4 v[150:151], v[146:149], off
	v_add_co_u32_e32 v152, vcc, s66, v150
	s_nop 0
	v_cvt_pk_bf16_f32 v146, v92, v93
	v_cvt_pk_bf16_f32 v147, v94, v95
	v_cvt_pk_bf16_f32 v148, v88, v89
	v_cvt_pk_bf16_f32 v149, v90, v91
	global_store_dwordx4 v[150:151], v[146:149], off offset:256
	v_addc_co_u32_e32 v153, vcc, 0, v151, vcc
	s_nop 0
	v_cvt_pk_bf16_f32 v146, v116, v117
	v_cvt_pk_bf16_f32 v147, v118, v119
	v_cvt_pk_bf16_f32 v148, v112, v113
	v_cvt_pk_bf16_f32 v149, v114, v115
	global_store_dwordx4 v[152:153], v[146:149], off
	s_mov_b32 s6, 0x20000
	s_nop 0
	v_cvt_pk_bf16_f32 v146, v84, v85
	v_cvt_pk_bf16_f32 v147, v86, v87
	v_cvt_pk_bf16_f32 v148, v80, v81
	v_cvt_pk_bf16_f32 v149, v82, v83
	global_store_dwordx4 v[152:153], v[146:149], off offset:256
	v_add_co_u32_e32 v152, vcc, s6, v150
	s_nop 0
	v_cvt_pk_bf16_f32 v146, v108, v109
	v_cvt_pk_bf16_f32 v147, v110, v111
	v_cvt_pk_bf16_f32 v148, v104, v105
	v_cvt_pk_bf16_f32 v149, v106, v107
	v_addc_co_u32_e32 v153, vcc, 0, v151, vcc
	global_store_dwordx4 v[152:153], v[146:149], off
	s_mov_b32 s6, 0x30000
	s_nop 0
	v_cvt_pk_bf16_f32 v146, v76, v77
	v_cvt_pk_bf16_f32 v147, v78, v79
	v_cvt_pk_bf16_f32 v148, v72, v73
	v_cvt_pk_bf16_f32 v149, v74, v75
	global_store_dwordx4 v[152:153], v[146:149], off offset:256
	v_add_co_u32_e32 v152, vcc, s6, v150
	s_nop 0
	v_cvt_pk_bf16_f32 v146, v100, v101
	v_cvt_pk_bf16_f32 v147, v102, v103
	v_cvt_pk_bf16_f32 v148, v96, v97
	v_cvt_pk_bf16_f32 v149, v98, v99
	v_addc_co_u32_e32 v153, vcc, 0, v151, vcc
	global_store_dwordx4 v[152:153], v[146:149], off
	s_mov_b32 s6, 0x80000
	s_nop 0
	v_cvt_pk_bf16_f32 v146, v68, v69
	v_cvt_pk_bf16_f32 v147, v70, v71
	v_cvt_pk_bf16_f32 v148, v64, v65
	v_cvt_pk_bf16_f32 v149, v66, v67
	global_store_dwordx4 v[152:153], v[146:149], off offset:256
	v_add_co_u32_e32 v152, vcc, s6, v150
	s_nop 0
	v_cvt_pk_bf16_f32 v146, v60, v61
	v_cvt_pk_bf16_f32 v147, v62, v63
	v_cvt_pk_bf16_f32 v148, v56, v57
	v_cvt_pk_bf16_f32 v149, v58, v59
	v_addc_co_u32_e32 v153, vcc, 0, v151, vcc
	global_store_dwordx4 v[152:153], v[146:149], off
	s_mov_b32 s6, 0x90000
	s_nop 0
	v_cvt_pk_bf16_f32 v146, v28, v29
	v_cvt_pk_bf16_f32 v147, v30, v31
	v_cvt_pk_bf16_f32 v148, v24, v25
	v_cvt_pk_bf16_f32 v149, v26, v27
	global_store_dwordx4 v[152:153], v[146:149], off offset:256
	v_add_co_u32_e32 v152, vcc, s6, v150
	s_nop 0
	v_cvt_pk_bf16_f32 v146, v52, v53
	v_cvt_pk_bf16_f32 v147, v54, v55
	v_cvt_pk_bf16_f32 v148, v48, v49
	v_cvt_pk_bf16_f32 v149, v50, v51
	v_addc_co_u32_e32 v153, vcc, 0, v151, vcc
	global_store_dwordx4 v[152:153], v[146:149], off
	s_mov_b32 s6, 0xa0000
	s_nop 0
	v_cvt_pk_bf16_f32 v146, v20, v21
	v_cvt_pk_bf16_f32 v147, v22, v23
	v_cvt_pk_bf16_f32 v148, v16, v17
	v_cvt_pk_bf16_f32 v149, v18, v19
	global_store_dwordx4 v[152:153], v[146:149], off offset:256
	v_add_co_u32_e32 v152, vcc, s6, v150
	s_nop 0
	v_cvt_pk_bf16_f32 v146, v44, v45
	v_cvt_pk_bf16_f32 v147, v46, v47
	v_cvt_pk_bf16_f32 v148, v40, v41
	v_cvt_pk_bf16_f32 v149, v42, v43
	v_addc_co_u32_e32 v153, vcc, 0, v151, vcc
	s_mov_b32 s6, 0xb0000
	global_store_dwordx4 v[152:153], v[146:149], off
	v_add_co_u32_e32 v150, vcc, s6, v150
	s_nop 0
	v_cvt_pk_bf16_f32 v146, v12, v13
	v_cvt_pk_bf16_f32 v147, v14, v15
	v_cvt_pk_bf16_f32 v148, v8, v9
	v_cvt_pk_bf16_f32 v149, v10, v11
	global_store_dwordx4 v[152:153], v[146:149], off offset:256
	v_addc_co_u32_e32 v151, vcc, 0, v151, vcc
	s_nop 0
	v_cvt_pk_bf16_f32 v146, v36, v37
	v_cvt_pk_bf16_f32 v147, v38, v39
	v_cvt_pk_bf16_f32 v148, v32, v33
	v_cvt_pk_bf16_f32 v149, v34, v35
	global_store_dwordx4 v[150:151], v[146:149], off
	s_andn2_b64 vcc, exec, s[44:45]
	s_nop 0
	v_cvt_pk_bf16_f32 v146, v4, v5
	v_cvt_pk_bf16_f32 v147, v6, v7
	v_cvt_pk_bf16_f32 v148, v0, v1
	v_cvt_pk_bf16_f32 v149, v2, v3
	global_store_dwordx4 v[150:151], v[146:149], off offset:256
	s_cbranch_vccz .LBB0_307
	s_mov_b64 s[42:43], s[48:49]
	s_andn2_b64 vcc, exec, s[38:39]
	s_mov_b64 s[48:49], s[42:43]
	s_cbranch_vccnz .LBB0_308

.LBB0_328:
	s_waitcnt lgkmcnt(0)
	s_add_u32 s26, s26, 0x12290000
	s_addc_u32 s27, s27, 0
	s_add_u32 s28, s28, 0x12290000
	s_addc_u32 s29, s29, 0
	s_and_b32 s12, s10, 3
	s_add_i32 m0, s58, 0x18000
	v_lshl_add_u64 v[6:7], v[6:7], 0, s[36:37]
	s_lshl_b32 s19, s6, 6
	s_lshl_b32 s6, s6, 13
	s_lshl_b32 s23, s12, 12
	s_waitcnt vmcnt(0)
	s_barrier
	global_load_lds_dwordx4 v[6:7], off
	v_lshl_add_u64 v[4:5], v[4:5], 0, s[36:37]
	s_add_i32 m0, s58, 0x1a000
	s_add_i32 s70, s58, 0x8000
	s_add_i32 s71, s58, 0xa000
	global_load_lds_dwordx4 v[4:5], off
	v_lshl_add_u64 v[2:3], v[2:3], 0, s[36:37]
	s_mov_b32 m0, s70
	s_add_u32 s10, s52, 0xb0080
	global_load_lds_dwordx4 v[2:3], off
	v_lshl_add_u64 v[0:1], v[0:1], 0, s[36:37]
	s_mov_b32 m0, s71
	s_addc_u32 s11, s53, 0
	global_load_lds_dwordx4 v[0:1], off
	s_add_i32 m0, s58, 0x1c000
	v_lshl_add_u64 v[0:1], s[10:11], 0, v[140:141]
	global_load_lds_dwordx4 v[0:1], off
	v_lshl_add_u64 v[0:1], s[10:11], 0, v[150:151]
	s_add_i32 m0, s58, 0x1e000
	v_lshlrev_b32_e32 v4, 2, v8
	global_load_lds_dwordx4 v[0:1], off
	v_bfe_u32 v1, v8, 4, 2
	v_and_b32_e32 v0, 15, v8
	v_lshlrev_b32_e32 v3, 4, v1
	v_lshl_or_b32 v3, v0, 6, v3
	v_and_b32_e32 v4, 32, v4
	v_bitop3_b32 v5, v3, s6, v4 bitop3:0xde
	s_ashr_i32 s6, s19, 31
	v_mov_b32_e32 v157, s6
	s_lshl_b32 s6, s12, 2
	s_add_u32 s6, s34, s6
	s_addc_u32 s10, s35, 0
	v_lshlrev_b32_e32 v2, 3, v1
	s_add_u32 s73, s6, 0x1e114000
	s_movk_i32 s6, 0xb00
	v_lshl_or_b32 v207, s12, 5, v2
	v_or_b32_e32 v156, s19, v0
	v_cmp_eq_u32_e64 s[42:43], 0, v1
	v_lshrrev_b32_e32 v1, 1, v14
	v_mul_lo_u32 v0, v13, s6
	s_mov_b32 s12, 0xb000
	s_addc_u32 s74, s10, 0
	v_mad_u64_u32 v[0:1], s[10:11], v1, s12, v[0:1]
	v_or_b32_e32 v0, v0, v15
	v_add_lshl_u32 v0, v0, v16, 1
	v_mov_b32_e32 v1, v141
	s_mov_b64 s[30:31], 0xb0080
	v_lshl_add_u64 v[158:159], v[0:1], 0, s[30:31]
	v_lshrrev_b32_e32 v1, 1, v9
	v_mul_lo_u32 v0, v10, s6
	v_mad_u64_u32 v[0:1], s[10:11], v1, s12, v[0:1]
	s_waitcnt vmcnt(6)
	v_or_b32_e32 v0, v0, v11
	v_add_lshl_u32 v0, v0, v12, 1
	v_mov_b32_e32 v1, v141
	v_bitop3_b32 v206, v3, s23, v4 bitop3:0xde
	s_mov_b32 s72, 0
	v_lshl_add_u64 v[160:161], v[0:1], 0, s[30:31]
	v_add_u32_e32 v208, 0, v5
	v_readlane_b32 s81, v254, 52
	v_readlane_b32 s38, v254, 55
	s_barrier
	v_readlane_b32 s39, v254, 56
	s_mov_b32 s100, 0
	s_branch .LBB0_330

.Lm4b_341:
	s_waitcnt lgkmcnt(0)
	s_mov_b32 s100, 0
	s_barrier
	s_setprio 1
	v_mfma_f32_16x16x32_bf16 v[60:63], v[128:131], v[162:165], v[60:63]
	v_mfma_f32_16x16x32_bf16 v[56:59], v[136:139], v[162:165], v[56:59]
	v_mfma_f32_16x16x32_bf16 v[48:51], v[128:131], v[170:173], v[48:51]
	v_mfma_f32_16x16x32_bf16 v[40:43], v[136:139], v[170:173], v[40:43]
	v_mfma_f32_16x16x32_bf16 v[32:35], v[128:131], v[178:181], v[32:35]
	v_mfma_f32_16x16x32_bf16 v[24:27], v[136:139], v[178:181], v[24:27]
	v_mfma_f32_16x16x32_bf16 v[16:19], v[128:131], v[194:197], v[16:19]
	v_mfma_f32_16x16x32_bf16 v[8:11], v[136:139], v[194:197], v[8:11]
	v_mfma_f32_16x16x32_bf16 v[60:63], v[132:135], v[166:169], v[60:63]
	v_mfma_f32_16x16x32_bf16 v[56:59], v[146:149], v[166:169], v[56:59]
	v_mfma_f32_16x16x32_bf16 v[48:51], v[132:135], v[174:177], v[48:51]
	v_mfma_f32_16x16x32_bf16 v[40:43], v[146:149], v[174:177], v[40:43]
	v_mfma_f32_16x16x32_bf16 v[32:35], v[132:135], v[182:185], v[32:35]
	v_mfma_f32_16x16x32_bf16 v[24:27], v[146:149], v[182:185], v[24:27]
	v_mfma_f32_16x16x32_bf16 v[16:19], v[132:135], v[210:213], v[16:19]
	v_mfma_f32_16x16x32_bf16 v[8:11], v[146:149], v[210:213], v[8:11]
	v_mfma_f32_16x16x32_bf16 v[52:55], v[214:217], v[162:165], v[52:55]
	v_mfma_f32_16x16x32_bf16 v[44:47], v[222:225], v[162:165], v[44:47]
	v_mfma_f32_16x16x32_bf16 v[36:39], v[214:217], v[170:173], v[36:39]
	v_mfma_f32_16x16x32_bf16 v[28:31], v[222:225], v[170:173], v[28:31]
	v_mfma_f32_16x16x32_bf16 v[20:23], v[214:217], v[178:181], v[20:23]
	v_mfma_f32_16x16x32_bf16 v[12:15], v[222:225], v[178:181], v[12:15]
	v_mfma_f32_16x16x32_bf16 v[4:7], v[214:217], v[194:197], v[4:7]
	v_mfma_f32_16x16x32_bf16 v[0:3], v[222:225], v[194:197], v[0:3]
	v_mfma_f32_16x16x32_bf16 v[52:55], v[218:221], v[166:169], v[52:55]
	v_mfma_f32_16x16x32_bf16 v[44:47], v[226:229], v[166:169], v[44:47]
	v_mfma_f32_16x16x32_bf16 v[36:39], v[218:221], v[174:177], v[36:39]
	v_mfma_f32_16x16x32_bf16 v[28:31], v[226:229], v[174:177], v[28:31]
	v_mfma_f32_16x16x32_bf16 v[20:23], v[218:221], v[182:185], v[20:23]
	v_mfma_f32_16x16x32_bf16 v[12:15], v[226:229], v[182:185], v[12:15]
	v_mfma_f32_16x16x32_bf16 v[4:7], v[218:221], v[210:213], v[4:7]
	v_mfma_f32_16x16x32_bf16 v[0:3], v[226:229], v[210:213], v[0:3]
	s_setprio 0
	s_barrier
	s_add_i32 s6, 0, 0x18000
	v_add_u32_e32 v146, s6, v206
	ds_read_b128 v[128:131], v146
	ds_read_b128 v[132:135], v146 offset:1024
	ds_read_b128 v[136:139], v146 offset:2048
	ds_read_b128 v[146:149], v146 offset:3072
	s_add_u32 s50, s52, 0xb0000
	s_addc_u32 s51, s53, 0
	s_mov_b32 m0, s68
	v_lshl_add_u64 v[214:215], s[50:51], 0, v[154:155]
	ds_read_b128 v[162:165], v208 offset:32768
	ds_read_b128 v[166:169], v208 offset:33792
	ds_read_b128 v[170:173], v208 offset:34816
	ds_read_b128 v[174:177], v208 offset:35840
	ds_read_b128 v[178:181], v208 offset:36864
	ds_read_b128 v[182:185], v208 offset:37888
	ds_read_b128 v[194:197], v208 offset:38912
	ds_read_b128 v[210:213], v208 offset:39936
	global_load_lds_dwordx4 v[214:215], off
	v_lshl_add_u64 v[214:215], s[50:51], 0, v[152:153]
	s_mov_b32 m0, s69
	s_nop 0
	global_load_lds_dwordx4 v[214:215], off
	s_add_i32 s19, 0, 0x1c000
	v_add_u32_e32 v192, s19, v206
	ds_read_b128 v[214:217], v192
	ds_read_b128 v[218:221], v192 offset:1024
	ds_read_b128 v[222:225], v192 offset:2048
	ds_read_b128 v[226:229], v192 offset:3072
	s_waitcnt vmcnt(8)
	s_waitcnt lgkmcnt(0)
	s_barrier
	s_setprio 1
	v_mfma_f32_16x16x32_bf16 v[124:127], v[128:131], v[162:165], v[124:127]
	v_mfma_f32_16x16x32_bf16 v[120:123], v[136:139], v[162:165], v[120:123]
	v_mfma_f32_16x16x32_bf16 v[108:111], v[128:131], v[170:173], v[108:111]
	v_mfma_f32_16x16x32_bf16 v[104:107], v[136:139], v[170:173], v[104:107]
	v_mfma_f32_16x16x32_bf16 v[96:99], v[128:131], v[178:181], v[96:99]
	v_mfma_f32_16x16x32_bf16 v[88:91], v[136:139], v[178:181], v[88:91]
	v_mfma_f32_16x16x32_bf16 v[84:87], v[128:131], v[194:197], v[84:87]
	v_mfma_f32_16x16x32_bf16 v[80:83], v[136:139], v[194:197], v[80:83]
	v_mfma_f32_16x16x32_bf16 v[124:127], v[132:135], v[166:169], v[124:127]
	v_mfma_f32_16x16x32_bf16 v[120:123], v[146:149], v[166:169], v[120:123]
	v_mfma_f32_16x16x32_bf16 v[108:111], v[132:135], v[174:177], v[108:111]
	v_mfma_f32_16x16x32_bf16 v[104:107], v[146:149], v[174:177], v[104:107]
	v_mfma_f32_16x16x32_bf16 v[96:99], v[132:135], v[182:185], v[96:99]
	v_mfma_f32_16x16x32_bf16 v[88:91], v[146:149], v[182:185], v[88:91]
	v_mfma_f32_16x16x32_bf16 v[84:87], v[132:135], v[210:213], v[84:87]
	v_mfma_f32_16x16x32_bf16 v[80:83], v[146:149], v[210:213], v[80:83]
	v_mfma_f32_16x16x32_bf16 v[116:119], v[214:217], v[162:165], v[116:119]
	v_mfma_f32_16x16x32_bf16 v[112:115], v[222:225], v[162:165], v[112:115]
	v_mfma_f32_16x16x32_bf16 v[100:103], v[214:217], v[170:173], v[100:103]
	v_mfma_f32_16x16x32_bf16 v[92:95], v[222:225], v[170:173], v[92:95]
	v_mfma_f32_16x16x32_bf16 v[76:79], v[214:217], v[178:181], v[76:79]
	v_mfma_f32_16x16x32_bf16 v[72:75], v[222:225], v[178:181], v[72:75]
	v_mfma_f32_16x16x32_bf16 v[68:71], v[214:217], v[194:197], v[68:71]
	v_mfma_f32_16x16x32_bf16 v[64:67], v[222:225], v[194:197], v[64:67]
	v_mfma_f32_16x16x32_bf16 v[116:119], v[218:221], v[166:169], v[116:119]
	v_mfma_f32_16x16x32_bf16 v[112:115], v[226:229], v[166:169], v[112:115]
	v_mfma_f32_16x16x32_bf16 v[100:103], v[218:221], v[174:177], v[100:103]
	v_mfma_f32_16x16x32_bf16 v[92:95], v[226:229], v[174:177], v[92:95]
	v_mfma_f32_16x16x32_bf16 v[76:79], v[218:221], v[182:185], v[76:79]
	v_mfma_f32_16x16x32_bf16 v[72:75], v[226:229], v[182:185], v[72:75]
	v_mfma_f32_16x16x32_bf16 v[68:71], v[218:221], v[210:213], v[68:71]
	v_mfma_f32_16x16x32_bf16 v[64:67], v[226:229], v[210:213], v[64:67]
	s_setprio 0
	s_barrier
	s_add_i32 s6, s6, s57
	v_lshl_add_u64 v[230:231], v[230:231], 0, s[36:37]
	s_mov_b32 m0, s6
	s_nop 0
	global_load_lds_dwordx4 v[230:231], off
	v_lshl_add_u64 v[230:231], v[232:233], 0, s[36:37]
	s_add_i32 m0, s6, 0x2000
	s_nop 0
	global_load_lds_dwordx4 v[230:231], off
	s_mov_b32 m0, s70
	v_lshl_add_u64 v[230:231], v[234:235], 0, s[36:37]
	ds_read_b128 v[162:165], v208 offset:49152
	ds_read_b128 v[166:169], v208 offset:50176
	ds_read_b128 v[170:173], v208 offset:51200
	ds_read_b128 v[174:177], v208 offset:52224
	ds_read_b128 v[178:181], v208 offset:53248
	ds_read_b128 v[182:185], v208 offset:54272
	ds_read_b128 v[194:197], v208 offset:55296
	ds_read_b128 v[210:213], v208 offset:56320
	global_load_lds_dwordx4 v[230:231], off
	v_lshl_add_u64 v[230:231], v[236:237], 0, s[36:37]
	s_mov_b32 m0, s71
	s_nop 0
	global_load_lds_dwordx4 v[230:231], off
	s_add_u32 s48, s48, 0xb0080
	s_addc_u32 s49, s49, 0
	s_add_i32 s6, s19, s57
	v_lshl_add_u64 v[250:251], s[48:49], 0, v[140:141]
	s_mov_b32 m0, s6
	s_nop 0
	global_load_lds_dwordx4 v[250:251], off
	v_lshl_add_u64 v[250:251], s[48:49], 0, v[150:151]
	s_add_i32 m0, s6, 0x2000
	s_nop 0
	global_load_lds_dwordx4 v[250:251], off
	s_waitcnt vmcnt(8)
	s_waitcnt lgkmcnt(0)
	s_barrier
	s_setprio 1
	v_mfma_f32_16x16x32_bf16 v[60:63], v[128:131], v[162:165], v[60:63]
	v_mfma_f32_16x16x32_bf16 v[56:59], v[136:139], v[162:165], v[56:59]
	v_mfma_f32_16x16x32_bf16 v[48:51], v[128:131], v[170:173], v[48:51]
	v_mfma_f32_16x16x32_bf16 v[40:43], v[136:139], v[170:173], v[40:43]
	v_mfma_f32_16x16x32_bf16 v[32:35], v[128:131], v[178:181], v[32:35]
	v_mfma_f32_16x16x32_bf16 v[24:27], v[136:139], v[178:181], v[24:27]
	v_mfma_f32_16x16x32_bf16 v[16:19], v[128:131], v[194:197], v[16:19]
	v_mfma_f32_16x16x32_bf16 v[8:11], v[136:139], v[194:197], v[8:11]
	v_mfma_f32_16x16x32_bf16 v[60:63], v[132:135], v[166:169], v[60:63]
	v_mfma_f32_16x16x32_bf16 v[56:59], v[146:149], v[166:169], v[56:59]
	v_mfma_f32_16x16x32_bf16 v[48:51], v[132:135], v[174:177], v[48:51]
	v_mfma_f32_16x16x32_bf16 v[40:43], v[146:149], v[174:177], v[40:43]
	v_mfma_f32_16x16x32_bf16 v[32:35], v[132:135], v[182:185], v[32:35]
	v_mfma_f32_16x16x32_bf16 v[24:27], v[146:149], v[182:185], v[24:27]
	v_mfma_f32_16x16x32_bf16 v[16:19], v[132:135], v[210:213], v[16:19]
	v_mfma_f32_16x16x32_bf16 v[8:11], v[146:149], v[210:213], v[8:11]
	v_mfma_f32_16x16x32_bf16 v[52:55], v[214:217], v[162:165], v[52:55]
	v_mfma_f32_16x16x32_bf16 v[44:47], v[222:225], v[162:165], v[44:47]
	v_mfma_f32_16x16x32_bf16 v[36:39], v[214:217], v[170:173], v[36:39]
	v_mfma_f32_16x16x32_bf16 v[28:31], v[222:225], v[170:173], v[28:31]
	v_mfma_f32_16x16x32_bf16 v[20:23], v[214:217], v[178:181], v[20:23]
	v_mfma_f32_16x16x32_bf16 v[12:15], v[222:225], v[178:181], v[12:15]
	v_mfma_f32_16x16x32_bf16 v[4:7], v[214:217], v[194:197], v[4:7]
	v_mfma_f32_16x16x32_bf16 v[0:3], v[222:225], v[194:197], v[0:3]
	v_mfma_f32_16x16x32_bf16 v[52:55], v[218:221], v[166:169], v[52:55]
	v_mfma_f32_16x16x32_bf16 v[44:47], v[226:229], v[166:169], v[44:47]
	v_mfma_f32_16x16x32_bf16 v[36:39], v[218:221], v[174:177], v[36:39]
	v_mfma_f32_16x16x32_bf16 v[28:31], v[226:229], v[174:177], v[28:31]
	v_mfma_f32_16x16x32_bf16 v[20:23], v[218:221], v[182:185], v[20:23]
	v_mfma_f32_16x16x32_bf16 v[12:15], v[226:229], v[182:185], v[12:15]
	v_mfma_f32_16x16x32_bf16 v[4:7], v[218:221], v[210:213], v[4:7]
	v_mfma_f32_16x16x32_bf16 v[0:3], v[226:229], v[210:213], v[0:3]
	s_setprio 0
	s_add_i32 s12, s12, 2
	s_add_u32 s10, s10, 0x100
	s_addc_u32 s11, s11, 0
	s_cmp_gt_u32 s12, 41
	s_mov_b64 s[50:51], s[46:47]
	s_barrier
	s_cbranch_scc0 .LBB0_341
	s_mov_b32 s100, 1
	s_ashr_i32 s39, s38, 31
	v_lshl_or_b32 v128, s81, 8, v207
	s_lshl_b64 s[10:11], s[38:39], 8
	v_ashrrev_i32_e32 v129, 31, v128
	v_lshl_add_u64 v[168:169], s[10:11], 0, v[156:157]
	v_lshlrev_b64 v[170:171], 1, v[128:129]
	v_lshl_add_u64 v[174:175], s[26:27], 0, v[170:171]
	v_lshlrev_b64 v[172:173], 11, v[168:169]
	v_lshl_add_u64 v[128:129], v[174:175], 0, v[172:173]
	global_load_dwordx4 v[182:185], v[128:129], off
	global_load_dwordx4 v[210:213], v[128:129], off offset:256
	v_or_b32_e32 v166, 16, v168
	v_mov_b32_e32 v167, v169
	v_lshlrev_b64 v[176:177], 11, v[166:167]
	v_lshl_add_u64 v[128:129], v[174:175], 0, v[176:177]
	global_load_dwordx4 v[214:217], v[128:129], off
	global_load_dwordx4 v[218:221], v[128:129], off offset:256
	v_or_b32_e32 v164, 32, v168
	v_mov_b32_e32 v165, v169
	v_or_b32_e32 v162, 48, v168
	v_mov_b32_e32 v163, v169
	v_lshlrev_b64 v[180:181], 11, v[164:165]
	v_lshlrev_b64 v[178:179], 11, v[162:163]
	v_lshl_add_u64 v[128:129], v[174:175], 0, v[180:181]
	v_lshl_add_u64 v[130:131], v[174:175], 0, v[178:179]
	global_load_dwordx4 v[222:225], v[128:129], off
	global_load_dwordx4 v[136:139], v[128:129], off offset:256
	global_load_dwordx4 v[132:135], v[130:131], off
	s_nop 0
	global_load_dwordx4 v[128:131], v[130:131], off offset:256
	s_mov_b64 s[10:11], 0x90
	v_lshl_add_u64 v[172:173], s[28:29], 0, v[172:173]
	v_lshl_add_u64 v[172:173], v[172:173], 0, v[170:171]
	s_waitcnt vmcnt(0)
	v_lshlrev_b32_e32 v146, 16, v182
	v_and_b32_e32 v147, 0xffff0000, v182
	v_lshlrev_b32_e32 v148, 16, v184
	v_and_b32_e32 v149, 0xffff0000, v184
	v_lshlrev_b32_e32 v182, 16, v183
	v_and_b32_e32 v183, 0xffff0000, v183
	v_lshlrev_b32_e32 v194, 16, v210
	v_and_b32_e32 v195, 0xffff0000, v210
	v_lshlrev_b32_e32 v196, 16, v212
	v_and_b32_e32 v197, 0xffff0000, v212
	v_lshlrev_b32_e32 v210, 16, v211
	v_and_b32_e32 v211, 0xffff0000, v211
	v_lshlrev_b32_e32 v212, 16, v213
	v_and_b32_e32 v213, 0xffff0000, v213
	v_pk_fma_f32 v[124:125], v[124:125], 0.5, v[146:147] op_sel_hi:[1,0,1]
	v_pk_fma_f32 v[120:121], v[120:121], 0.5, v[148:149] op_sel_hi:[1,0,1]
	v_pk_fma_f32 v[126:127], v[126:127], 0.5, v[182:183] op_sel_hi:[1,0,1]
	v_pk_fma_f32 v[116:117], v[116:117], 0.5, v[194:195] op_sel_hi:[1,0,1]
	v_pk_fma_f32 v[146:147], v[112:113], 0.5, v[196:197] op_sel_hi:[1,0,1]
	v_pk_fma_f32 v[118:119], v[118:119], 0.5, v[210:211] op_sel_hi:[1,0,1]
	v_pk_fma_f32 v[148:149], v[114:115], 0.5, v[212:213] op_sel_hi:[1,0,1]
	v_pk_mul_f32 v[212:213], v[124:125], v[124:125]
	v_lshlrev_b32_e32 v182, 16, v214
	v_and_b32_e32 v183, 0xffff0000, v214
	v_lshlrev_b32_e32 v194, 16, v215
	v_and_b32_e32 v195, 0xffff0000, v215
	v_pk_mul_f32 v[214:215], v[126:127], v[126:127]
	v_cvt_pk_bf16_f32 v112, v124, v125
	v_cvt_pk_bf16_f32 v113, v126, v127
	v_pk_mul_f32 v[124:125], v[116:117], v[116:117]
	v_pk_mul_f32 v[126:127], v[118:119], v[118:119]
	v_pk_mul_f32 v[228:229], v[146:147], v[146:147]
	v_cvt_pk_bf16_f32 v116, v116, v117
	v_cvt_pk_bf16_f32 v117, v118, v119
	v_cvt_pk_bf16_f32 v118, v146, v147
	v_add_f32_e32 v146, v212, v213
	v_lshlrev_b32_e32 v184, 16, v185
	v_and_b32_e32 v185, 0xffff0000, v185
	v_add_f32_e32 v146, v214, v146
	v_pk_fma_f32 v[122:123], v[122:123], 0.5, v[184:185] op_sel_hi:[1,0,1]
	v_lshlrev_b32_e32 v184, 16, v216
	v_and_b32_e32 v185, 0xffff0000, v216
	v_lshlrev_b32_e32 v196, 16, v217
	v_and_b32_e32 v197, 0xffff0000, v217
	v_pk_mul_f32 v[216:217], v[120:121], v[120:121]
	v_add_f32_e32 v146, v215, v146
	v_add_f32_e32 v146, v216, v146
	v_pk_mul_f32 v[226:227], v[122:123], v[122:123]
	v_add_f32_e32 v146, v217, v146
	v_add_f32_e32 v146, v226, v146
	v_add_f32_e32 v146, v227, v146
	v_add_f32_e32 v124, v124, v146
	v_add_f32_e32 v124, v125, v124
	v_add_f32_e32 v124, v126, v124
	v_add_f32_e32 v124, v127, v124
	v_add_f32_e32 v124, v228, v124
	v_pk_mul_f32 v[230:231], v[148:149], v[148:149]
	v_add_f32_e32 v124, v229, v124
	v_add_f32_e32 v124, v230, v124
	v_add_f32_e32 v209, v231, v124
	v_lshlrev_b32_e32 v124, 16, v220
	v_and_b32_e32 v125, 0xffff0000, v220
	v_pk_fma_f32 v[124:125], v[92:93], 0.5, v[124:125] op_sel_hi:[1,0,1]
	v_lshlrev_b32_e32 v92, 16, v219
	v_and_b32_e32 v93, 0xffff0000, v219
	v_pk_fma_f32 v[102:103], v[102:103], 0.5, v[92:93] op_sel_hi:[1,0,1]
	v_lshlrev_b32_e32 v92, 16, v221
	v_and_b32_e32 v93, 0xffff0000, v221
	v_pk_fma_f32 v[126:127], v[94:95], 0.5, v[92:93] op_sel_hi:[1,0,1]
	v_lshlrev_b32_e32 v92, 16, v222
	v_and_b32_e32 v93, 0xffff0000, v222
	v_pk_fma_f32 v[92:93], v[96:97], 0.5, v[92:93] op_sel_hi:[1,0,1]
	v_lshlrev_b32_e32 v96, 16, v225
	v_and_b32_e32 v97, 0xffff0000, v225
	v_lshlrev_b32_e32 v94, 16, v224
	v_and_b32_e32 v95, 0xffff0000, v224
	v_pk_fma_f32 v[90:91], v[90:91], 0.5, v[96:97] op_sel_hi:[1,0,1]
	v_lshlrev_b32_e32 v96, 16, v136
	v_and_b32_e32 v97, 0xffff0000, v136
	v_pk_fma_f32 v[88:89], v[88:89], 0.5, v[94:95] op_sel_hi:[1,0,1]
	v_lshlrev_b32_e32 v94, 16, v223
	v_and_b32_e32 v95, 0xffff0000, v223
	v_pk_fma_f32 v[96:97], v[76:77], 0.5, v[96:97] op_sel_hi:[1,0,1]
	v_lshl_add_u64 v[76:77], v[168:169], 0, s[36:37]
	v_cvt_pk_bf16_f32 v114, v120, v121
	v_pk_fma_f32 v[120:121], v[108:109], 0.5, v[182:183] op_sel_hi:[1,0,1]
	v_pk_fma_f32 v[94:95], v[98:99], 0.5, v[94:95] op_sel_hi:[1,0,1]
	v_lshlrev_b64 v[182:183], 11, v[76:77]
	v_lshlrev_b32_e32 v98, 16, v138
	v_and_b32_e32 v99, 0xffff0000, v138
	v_lshl_add_u64 v[146:147], v[174:175], 0, v[182:183]
	v_pk_fma_f32 v[98:99], v[72:73], 0.5, v[98:99] op_sel_hi:[1,0,1]
	v_lshlrev_b32_e32 v72, 16, v137
	v_and_b32_e32 v73, 0xffff0000, v137
	v_lshlrev_b32_e32 v210, 16, v218
	v_and_b32_e32 v211, 0xffff0000, v218
	global_load_dwordx4 v[218:221], v[146:147], off
	global_load_dwordx4 v[226:229], v[146:147], off offset:256
	v_pk_fma_f32 v[136:137], v[78:79], 0.5, v[72:73] op_sel_hi:[1,0,1]
	v_lshlrev_b32_e32 v72, 16, v139
	v_and_b32_e32 v73, 0xffff0000, v139
	v_pk_fma_f32 v[138:139], v[74:75], 0.5, v[72:73] op_sel_hi:[1,0,1]
	v_lshlrev_b32_e32 v72, 16, v132
	v_and_b32_e32 v73, 0xffff0000, v132
	v_pk_fma_f32 v[74:75], v[84:85], 0.5, v[72:73] op_sel_hi:[1,0,1]
	v_lshlrev_b32_e32 v72, 16, v134
	v_and_b32_e32 v73, 0xffff0000, v134
	v_pk_fma_f32 v[78:79], v[80:81], 0.5, v[72:73] op_sel_hi:[1,0,1]
	v_lshlrev_b32_e32 v72, 16, v133
	v_and_b32_e32 v73, 0xffff0000, v133
	v_pk_fma_f32 v[80:81], v[86:87], 0.5, v[72:73] op_sel_hi:[1,0,1]
	v_lshlrev_b32_e32 v72, 16, v135
	v_and_b32_e32 v73, 0xffff0000, v135
	v_pk_fma_f32 v[82:83], v[82:83], 0.5, v[72:73] op_sel_hi:[1,0,1]
	v_lshl_add_u64 v[72:73], v[168:169], 0, s[10:11]
	v_lshlrev_b64 v[132:133], 11, v[72:73]
	v_lshl_add_u64 v[134:135], v[174:175], 0, v[132:133]
	global_load_dwordx4 v[234:237], v[134:135], off
	global_load_dwordx4 v[242:245], v[134:135], off offset:256
	v_lshlrev_b32_e32 v84, 16, v128
	v_and_b32_e32 v85, 0xffff0000, v128
	v_pk_fma_f32 v[84:85], v[68:69], 0.5, v[84:85] op_sel_hi:[1,0,1]
	v_lshlrev_b32_e32 v68, 16, v130
	v_and_b32_e32 v69, 0xffff0000, v130
	v_pk_fma_f32 v[86:87], v[64:65], 0.5, v[68:69] op_sel_hi:[1,0,1]
	v_lshlrev_b32_e32 v64, 16, v129
	v_and_b32_e32 v65, 0xffff0000, v129
	s_mov_b64 s[10:11], 0xa0
	v_pk_fma_f32 v[128:129], v[70:71], 0.5, v[64:65] op_sel_hi:[1,0,1]
	v_lshl_add_u64 v[70:71], v[168:169], 0, s[10:11]
	v_lshlrev_b32_e32 v64, 16, v131
	v_and_b32_e32 v65, 0xffff0000, v131
	v_lshlrev_b64 v[134:135], 11, v[70:71]
	v_pk_fma_f32 v[130:131], v[66:67], 0.5, v[64:65] op_sel_hi:[1,0,1]
	v_lshl_add_u64 v[64:65], v[174:175], 0, v[134:135]
	v_cvt_pk_bf16_f32 v115, v122, v123
	v_pk_fma_f32 v[122:123], v[110:111], 0.5, v[194:195] op_sel_hi:[1,0,1]
	v_pk_fma_f32 v[110:111], v[106:107], 0.5, v[196:197] op_sel_hi:[1,0,1]
	global_load_dwordx4 v[246:249], v[64:65], off
	global_load_dwordx4 v[194:197], v[64:65], off offset:256
	s_mov_b64 s[10:11], 0xb0
	v_lshl_add_u64 v[68:69], v[168:169], 0, s[10:11]
	v_pk_fma_f32 v[108:109], v[104:105], 0.5, v[184:185] op_sel_hi:[1,0,1]
	v_lshlrev_b64 v[184:185], 11, v[68:69]
	v_lshl_add_u64 v[64:65], v[174:175], 0, v[184:185]
	v_cvt_pk_bf16_f32 v119, v148, v149
	global_load_dwordx4 v[146:149], v[64:65], off
	s_nop 0
	global_load_dwordx4 v[64:67], v[64:65], off offset:256
	global_store_dwordx4 v[172:173], v[112:115], off
	global_store_dwordx4 v[172:173], v[116:119], off offset:256
	v_cvt_pk_bf16_f32 v104, v120, v121
	v_lshl_add_u64 v[112:113], s[28:29], 0, v[176:177]
	v_cvt_pk_bf16_f32 v105, v122, v123
	v_cvt_pk_bf16_f32 v106, v108, v109
	v_cvt_pk_bf16_f32 v107, v110, v111
	v_pk_fma_f32 v[100:101], v[100:101], 0.5, v[210:211] op_sel_hi:[1,0,1]
	v_lshl_add_u64 v[112:113], v[112:113], 0, v[170:171]
	v_cvt_pk_bf16_f32 v210, v100, v101
	v_cvt_pk_bf16_f32 v211, v102, v103
	v_cvt_pk_bf16_f32 v212, v124, v125
	v_cvt_pk_bf16_f32 v213, v126, v127
	global_store_dwordx4 v[112:113], v[104:107], off
	global_store_dwordx4 v[112:113], v[210:213], off offset:256
	v_cvt_pk_bf16_f32 v214, v92, v93
	v_lshl_add_u64 v[104:105], s[28:29], 0, v[180:181]
	v_cvt_pk_bf16_f32 v215, v94, v95
	v_cvt_pk_bf16_f32 v216, v88, v89
	v_cvt_pk_bf16_f32 v217, v90, v91
	v_lshl_add_u64 v[104:105], v[104:105], 0, v[170:171]
	v_cvt_pk_bf16_f32 v222, v96, v97
	v_cvt_pk_bf16_f32 v223, v136, v137
	v_cvt_pk_bf16_f32 v224, v98, v99
	v_cvt_pk_bf16_f32 v225, v138, v139
	global_store_dwordx4 v[104:105], v[214:217], off
	global_store_dwordx4 v[104:105], v[222:225], off offset:256
	v_lshl_add_u64 v[104:105], s[28:29], 0, v[178:179]
	v_cvt_pk_bf16_f32 v230, v74, v75
	v_cvt_pk_bf16_f32 v231, v80, v81
	v_cvt_pk_bf16_f32 v232, v78, v79
	v_cvt_pk_bf16_f32 v233, v82, v83
	v_lshl_add_u64 v[104:105], v[104:105], 0, v[170:171]
	v_cvt_pk_bf16_f32 v238, v84, v85
	v_cvt_pk_bf16_f32 v239, v128, v129
	v_cvt_pk_bf16_f32 v240, v86, v87
	v_cvt_pk_bf16_f32 v241, v130, v131
	global_store_dwordx4 v[104:105], v[230:233], off
	global_store_dwordx4 v[104:105], v[238:241], off offset:256
	s_waitcnt vmcnt(0)
	v_lshlrev_b32_e32 v104, 16, v218
	v_and_b32_e32 v105, 0xffff0000, v218
	v_pk_fma_f32 v[60:61], v[60:61], 0.5, v[104:105] op_sel_hi:[1,0,1]
	v_lshlrev_b32_e32 v104, 16, v220
	v_and_b32_e32 v105, 0xffff0000, v220
	v_pk_fma_f32 v[56:57], v[56:57], 0.5, v[104:105] op_sel_hi:[1,0,1]
	v_lshlrev_b32_e32 v104, 16, v219
	v_and_b32_e32 v105, 0xffff0000, v219
	v_pk_fma_f32 v[62:63], v[62:63], 0.5, v[104:105] op_sel_hi:[1,0,1]
	v_lshlrev_b32_e32 v104, 16, v221
	v_and_b32_e32 v105, 0xffff0000, v221
	v_pk_fma_f32 v[58:59], v[58:59], 0.5, v[104:105] op_sel_hi:[1,0,1]
	v_lshlrev_b32_e32 v104, 16, v226
	v_and_b32_e32 v105, 0xffff0000, v226
	v_pk_fma_f32 v[52:53], v[52:53], 0.5, v[104:105] op_sel_hi:[1,0,1]
	v_lshlrev_b32_e32 v104, 16, v228
	v_and_b32_e32 v105, 0xffff0000, v228
	v_pk_fma_f32 v[104:105], v[44:45], 0.5, v[104:105] op_sel_hi:[1,0,1]
	v_lshlrev_b32_e32 v44, 16, v227
	v_and_b32_e32 v45, 0xffff0000, v227
	v_pk_fma_f32 v[54:55], v[54:55], 0.5, v[44:45] op_sel_hi:[1,0,1]
	v_lshlrev_b32_e32 v44, 16, v229
	v_and_b32_e32 v45, 0xffff0000, v229
	v_pk_fma_f32 v[106:107], v[46:47], 0.5, v[44:45] op_sel_hi:[1,0,1]
	v_lshlrev_b32_e32 v44, 16, v234
	v_and_b32_e32 v45, 0xffff0000, v234
	v_pk_fma_f32 v[44:45], v[48:49], 0.5, v[44:45] op_sel_hi:[1,0,1]
	v_lshlrev_b32_e32 v48, 16, v237
	v_and_b32_e32 v49, 0xffff0000, v237
	v_pk_fma_f32 v[42:43], v[42:43], 0.5, v[48:49] op_sel_hi:[1,0,1]
	v_lshlrev_b32_e32 v48, 16, v242
	v_and_b32_e32 v49, 0xffff0000, v242
	v_pk_fma_f32 v[36:37], v[36:37], 0.5, v[48:49] op_sel_hi:[1,0,1]
	v_lshlrev_b32_e32 v48, 16, v244
	v_and_b32_e32 v49, 0xffff0000, v244
	v_lshlrev_b32_e32 v46, 16, v236
	v_and_b32_e32 v47, 0xffff0000, v236
	v_pk_fma_f32 v[48:49], v[28:29], 0.5, v[48:49] op_sel_hi:[1,0,1]
	v_lshlrev_b32_e32 v28, 16, v243
	v_and_b32_e32 v29, 0xffff0000, v243
	v_pk_fma_f32 v[40:41], v[40:41], 0.5, v[46:47] op_sel_hi:[1,0,1]
	v_lshlrev_b32_e32 v46, 16, v235
	v_and_b32_e32 v47, 0xffff0000, v235
	v_pk_fma_f32 v[38:39], v[38:39], 0.5, v[28:29] op_sel_hi:[1,0,1]
	v_lshlrev_b32_e32 v28, 16, v245
	v_and_b32_e32 v29, 0xffff0000, v245
	v_pk_fma_f32 v[46:47], v[50:51], 0.5, v[46:47] op_sel_hi:[1,0,1]
	v_pk_fma_f32 v[50:51], v[30:31], 0.5, v[28:29] op_sel_hi:[1,0,1]
	v_lshlrev_b32_e32 v28, 16, v246
	v_and_b32_e32 v29, 0xffff0000, v246
	v_pk_fma_f32 v[28:29], v[32:33], 0.5, v[28:29] op_sel_hi:[1,0,1]
	v_lshlrev_b32_e32 v32, 16, v249
	v_and_b32_e32 v33, 0xffff0000, v249
	v_pk_fma_f32 v[26:27], v[26:27], 0.5, v[32:33] op_sel_hi:[1,0,1]
	v_lshlrev_b32_e32 v32, 16, v194
	v_and_b32_e32 v33, 0xffff0000, v194
	v_pk_fma_f32 v[20:21], v[20:21], 0.5, v[32:33] op_sel_hi:[1,0,1]
	v_lshlrev_b32_e32 v32, 16, v196
	v_and_b32_e32 v33, 0xffff0000, v196
	v_lshlrev_b32_e32 v30, 16, v248
	v_and_b32_e32 v31, 0xffff0000, v248
	v_pk_fma_f32 v[32:33], v[12:13], 0.5, v[32:33] op_sel_hi:[1,0,1]
	v_lshlrev_b32_e32 v12, 16, v195
	v_and_b32_e32 v13, 0xffff0000, v195
	v_pk_fma_f32 v[24:25], v[24:25], 0.5, v[30:31] op_sel_hi:[1,0,1]
	v_lshlrev_b32_e32 v30, 16, v247
	v_and_b32_e32 v31, 0xffff0000, v247
	v_pk_fma_f32 v[22:23], v[22:23], 0.5, v[12:13] op_sel_hi:[1,0,1]
	v_lshlrev_b32_e32 v12, 16, v197
	v_and_b32_e32 v13, 0xffff0000, v197
	v_pk_fma_f32 v[30:31], v[34:35], 0.5, v[30:31] op_sel_hi:[1,0,1]
	v_pk_fma_f32 v[34:35], v[14:15], 0.5, v[12:13] op_sel_hi:[1,0,1]
	v_lshlrev_b32_e32 v14, 16, v148
	v_and_b32_e32 v15, 0xffff0000, v148
	v_lshlrev_b32_e32 v12, 16, v146
	v_and_b32_e32 v13, 0xffff0000, v146
	v_pk_fma_f32 v[8:9], v[8:9], 0.5, v[14:15] op_sel_hi:[1,0,1]
	v_lshlrev_b32_e32 v14, 16, v147
	v_and_b32_e32 v15, 0xffff0000, v147
	v_lshlrev_b32_e32 v146, 16, v64
	v_and_b32_e32 v147, 0xffff0000, v64
	v_pk_fma_f32 v[4:5], v[4:5], 0.5, v[146:147] op_sel_hi:[1,0,1]
	v_lshlrev_b32_e32 v146, 16, v66
	v_and_b32_e32 v147, 0xffff0000, v66
	v_pk_fma_f32 v[0:1], v[0:1], 0.5, v[146:147] op_sel_hi:[1,0,1]
	v_lshl_add_u64 v[146:147], s[28:29], 0, v[182:183]
	v_cvt_pk_bf16_f32 v112, v60, v61
	v_cvt_pk_bf16_f32 v113, v62, v63
	v_cvt_pk_bf16_f32 v114, v56, v57
	v_cvt_pk_bf16_f32 v115, v58, v59
	v_lshl_add_u64 v[146:147], v[146:147], 0, v[170:171]
	v_cvt_pk_bf16_f32 v116, v52, v53
	v_cvt_pk_bf16_f32 v117, v54, v55
	v_cvt_pk_bf16_f32 v118, v104, v105
	v_cvt_pk_bf16_f32 v119, v106, v107
	global_store_dwordx4 v[146:147], v[112:115], off
	global_store_dwordx4 v[146:147], v[116:119], off offset:256
	v_cvt_pk_bf16_f32 v172, v44, v45
	v_lshl_add_u64 v[112:113], s[28:29], 0, v[132:133]
	v_cvt_pk_bf16_f32 v173, v46, v47
	v_cvt_pk_bf16_f32 v174, v40, v41
	v_cvt_pk_bf16_f32 v175, v42, v43
	v_lshl_add_u64 v[112:113], v[112:113], 0, v[170:171]
	v_cvt_pk_bf16_f32 v176, v36, v37
	v_cvt_pk_bf16_f32 v177, v38, v39
	v_cvt_pk_bf16_f32 v178, v48, v49
	v_cvt_pk_bf16_f32 v179, v50, v51
	global_store_dwordx4 v[112:113], v[172:175], off
	global_store_dwordx4 v[112:113], v[176:179], off offset:256
	v_lshl_add_u64 v[112:113], s[28:29], 0, v[134:135]
	v_cvt_pk_bf16_f32 v210, v28, v29
	v_cvt_pk_bf16_f32 v211, v30, v31
	v_cvt_pk_bf16_f32 v212, v24, v25
	v_cvt_pk_bf16_f32 v213, v26, v27
	v_pk_fma_f32 v[12:13], v[16:17], 0.5, v[12:13] op_sel_hi:[1,0,1]
	v_lshlrev_b32_e32 v16, 16, v149
	v_and_b32_e32 v17, 0xffff0000, v149
	v_lshlrev_b32_e32 v64, 16, v65
	v_and_b32_e32 v65, 0xffff0000, v65
	v_lshl_add_u64 v[112:113], v[112:113], 0, v[170:171]
	v_cvt_pk_bf16_f32 v194, v20, v21
	v_cvt_pk_bf16_f32 v195, v22, v23
	v_cvt_pk_bf16_f32 v196, v32, v33
	v_cvt_pk_bf16_f32 v197, v34, v35
	v_pk_fma_f32 v[14:15], v[18:19], 0.5, v[14:15] op_sel_hi:[1,0,1]
	v_pk_fma_f32 v[10:11], v[10:11], 0.5, v[16:17] op_sel_hi:[1,0,1]
	v_pk_fma_f32 v[6:7], v[6:7], 0.5, v[64:65] op_sel_hi:[1,0,1]
	v_lshlrev_b32_e32 v64, 16, v67
	v_and_b32_e32 v65, 0xffff0000, v67
	global_store_dwordx4 v[112:113], v[210:213], off
	global_store_dwordx4 v[112:113], v[194:197], off offset:256
	v_lshl_add_u64 v[112:113], s[28:29], 0, v[184:185]
	v_cvt_pk_bf16_f32 v16, v12, v13
	v_cvt_pk_bf16_f32 v17, v14, v15
	v_cvt_pk_bf16_f32 v18, v8, v9
	v_cvt_pk_bf16_f32 v19, v10, v11
	v_pk_fma_f32 v[2:3], v[2:3], 0.5, v[64:65] op_sel_hi:[1,0,1]
	v_lshl_add_u64 v[112:113], v[112:113], 0, v[170:171]
	v_cvt_pk_bf16_f32 v64, v4, v5
	v_cvt_pk_bf16_f32 v65, v6, v7
	v_cvt_pk_bf16_f32 v66, v0, v1
	v_cvt_pk_bf16_f32 v67, v2, v3
	global_store_dwordx4 v[112:113], v[16:19], off
	global_store_dwordx4 v[112:113], v[64:67], off offset:256
	s_lshl_b32 s10, s81, 2
	v_and_b32_e32 v17, 64, v188
	v_xor_b32_e32 v16, 16, v188
	v_add_u32_e32 v17, 64, v17
	v_cmp_lt_i32_e32 vcc, v16, v17
	v_xor_b32_e32 v18, 32, v188
	s_ashr_i32 s11, s10, 31
	v_cndmask_b32_e32 v16, v188, v16, vcc
	v_lshlrev_b32_e32 v16, 2, v16
	ds_bpermute_b32 v19, v16, v209
	v_cmp_lt_i32_e32 vcc, v18, v17
	s_lshl_b64 s[10:11], s[10:11], 2
	s_add_u32 s38, s73, s10
	v_cndmask_b32_e32 v17, v188, v18, vcc
	v_lshlrev_b32_e32 v17, 2, v17
	s_waitcnt lgkmcnt(0)
	v_add_f32_e32 v18, v209, v19
	ds_bpermute_b32 v19, v17, v18
	s_addc_u32 s39, s74, s11
	s_and_saveexec_b64 s[46:47], s[42:43]
	s_cbranch_execz .LBB0_344
	s_waitcnt lgkmcnt(0)
	v_add_f32_e32 v64, v18, v19
	v_lshlrev_b64 v[18:19], 6, v[168:169]
	v_lshl_add_u64 v[18:19], s[38:39], 0, v[18:19]
	global_store_dword v[18:19], v64, off

.LBB0_381:
	s_add_u32 s30, s30, 0x3290000
	v_and_b32_e32 v15, 15, v8
	v_lshrrev_b32_e32 v8, 1, v8
	s_addc_u32 s31, s31, 0
	v_and_b32_e32 v8, 24, v8
	s_lshl_b32 s10, s10, 5
	v_lshlrev_b32_e32 v16, 1, v8
	v_lshlrev_b32_e32 v17, 2, v15
	s_and_b32 s19, s10, 0x60
	s_add_i32 m0, s68, 0x18000
	v_lshl_add_u64 v[6:7], v[6:7], 0, s[36:37]
	s_lshl_b32 s12, s6, 6
	v_lshl_or_b32 v16, v15, 6, v16
	s_lshl_b32 s11, s6, 13
	v_and_b32_e32 v18, 32, v17
	s_lshl_b32 s10, s19, 7
	s_waitcnt vmcnt(0)
	s_barrier
	global_load_lds_dwordx4 v[6:7], off
	v_lshl_add_u64 v[4:5], v[4:5], 0, s[36:37]
	s_add_i32 m0, s68, 0x1a000
	s_add_i32 s72, s68, 0x8000
	s_add_i32 s73, s68, 0xa000
	v_bitop3_b32 v154, v16, s10, v18 bitop3:0xde
	global_load_lds_dwordx4 v[4:5], off
	v_lshl_add_u64 v[2:3], v[2:3], 0, s[36:37]
	s_mov_b32 m0, s72
	s_add_u32 s10, s52, 0x40080
	v_bitop3_b32 v19, v16, s11, v18 bitop3:0xde
	global_load_lds_dwordx4 v[2:3], off
	v_lshl_add_u64 v[0:1], v[0:1], 0, s[36:37]
	s_mov_b32 m0, s73
	s_addc_u32 s11, s53, 0
	global_load_lds_dwordx4 v[0:1], off
	s_add_i32 m0, s68, 0x1c000
	v_lshl_add_u64 v[0:1], s[10:11], 0, v[140:141]
	global_load_lds_dwordx4 v[0:1], off
	v_lshl_add_u64 v[0:1], s[10:11], 0, v[132:133]
	s_add_i32 m0, s68, 0x1e000
	s_lshl_b32 s6, s6, 8
	global_load_lds_dwordx4 v[0:1], off
	v_lshlrev_b32_e32 v0, 14, v9
	v_and_b32_e32 v0, 0xffff8000, v0
	v_lshl_add_u32 v0, v10, 11, v0
	v_and_b32_e32 v1, 1, v9
	v_lshl_or_b32 v0, v1, 6, v0
	v_lshl_add_u32 v136, v11, 1, v0
	v_lshlrev_b32_e32 v0, 14, v12
	v_and_b32_e32 v0, 0xffff8000, v0
	s_add_i32 s6, s6, 0
	v_lshl_add_u32 v0, v13, 11, v0
	v_and_b32_e32 v1, 1, v12
	s_waitcnt vmcnt(6)
	s_add_i32 s6, s6, 0x22000
	v_lshl_or_b32 v0, v1, 6, v0
	v_add_u32_e32 v155, s6, v17
	s_ashr_i32 s6, s12, 31
	v_lshl_add_u32 v138, v14, 1, v0
	v_mov_b32_e32 v0, 0
	v_or_b32_e32 v134, s12, v15
	v_mov_b32_e32 v135, s6
	v_or_b32_e32 v156, s19, v8
	v_mov_b32_e32 v137, v141
	v_mov_b32_e32 v139, v141
	s_mov_b32 s75, 0
	v_add_u32_e32 v157, 0, v19
	v_readlane_b32 s74, v253, 49
	v_readlane_b32 s34, v254, 0
	v_mov_b32_e32 v1, v0
	v_mov_b32_e32 v2, v0
	v_mov_b32_e32 v3, v0
	v_mov_b32_e32 v4, v0
	v_mov_b32_e32 v5, v0
	v_mov_b32_e32 v6, v0
	v_mov_b32_e32 v7, v0
	v_mov_b32_e32 v8, v0
	v_mov_b32_e32 v9, v0
	v_mov_b32_e32 v10, v0
	v_mov_b32_e32 v11, v0
	v_mov_b32_e32 v12, v0
	v_mov_b32_e32 v13, v0
	v_mov_b32_e32 v14, v0
	v_mov_b32_e32 v15, v0
	v_mov_b32_e32 v16, v0
	v_mov_b32_e32 v17, v0
	v_mov_b32_e32 v18, v0
	v_mov_b32_e32 v19, v0
	v_mov_b32_e32 v20, v0
	v_mov_b32_e32 v21, v0
	v_mov_b32_e32 v22, v0
	v_mov_b32_e32 v23, v0
	v_mov_b32_e32 v24, v0
	v_mov_b32_e32 v25, v0
	v_mov_b32_e32 v26, v0
	v_mov_b32_e32 v27, v0
	v_mov_b32_e32 v28, v0
	v_mov_b32_e32 v29, v0
	v_mov_b32_e32 v30, v0
	v_mov_b32_e32 v31, v0
	v_mov_b32_e32 v32, v0
	v_mov_b32_e32 v33, v0
	v_mov_b32_e32 v34, v0
	v_mov_b32_e32 v35, v0
	v_mov_b32_e32 v36, v0
	v_mov_b32_e32 v37, v0
	v_mov_b32_e32 v38, v0
	v_mov_b32_e32 v39, v0
	v_mov_b32_e32 v40, v0
	v_mov_b32_e32 v41, v0
	v_mov_b32_e32 v42, v0
	v_mov_b32_e32 v43, v0
	v_mov_b32_e32 v44, v0
	v_mov_b32_e32 v45, v0
	v_mov_b32_e32 v46, v0
	v_mov_b32_e32 v47, v0
	v_mov_b32_e32 v48, v0
	v_mov_b32_e32 v49, v0
	v_mov_b32_e32 v50, v0
	v_mov_b32_e32 v51, v0
	v_mov_b32_e32 v52, v0
	v_mov_b32_e32 v53, v0
	v_mov_b32_e32 v54, v0
	v_mov_b32_e32 v55, v0
	v_mov_b32_e32 v56, v0
	v_mov_b32_e32 v57, v0
	v_mov_b32_e32 v58, v0
	v_mov_b32_e32 v59, v0
	v_mov_b32_e32 v60, v0
	v_mov_b32_e32 v61, v0
	v_mov_b32_e32 v62, v0
	v_mov_b32_e32 v63, v0
	v_mov_b32_e32 v64, v0
	v_mov_b32_e32 v65, v0
	v_mov_b32_e32 v66, v0
	v_mov_b32_e32 v67, v0
	v_mov_b32_e32 v68, v0
	v_mov_b32_e32 v69, v0
	v_mov_b32_e32 v70, v0
	v_mov_b32_e32 v71, v0
	v_mov_b32_e32 v72, v0
	v_mov_b32_e32 v73, v0
	v_mov_b32_e32 v74, v0
	v_mov_b32_e32 v75, v0
	v_mov_b32_e32 v76, v0
	v_mov_b32_e32 v77, v0
	v_mov_b32_e32 v78, v0
	v_mov_b32_e32 v79, v0
	v_mov_b32_e32 v80, v0
	v_mov_b32_e32 v81, v0
	v_mov_b32_e32 v82, v0
	v_mov_b32_e32 v83, v0
	v_mov_b32_e32 v84, v0
	v_mov_b32_e32 v85, v0
	v_mov_b32_e32 v86, v0
	v_mov_b32_e32 v87, v0
	v_mov_b32_e32 v88, v0
	v_mov_b32_e32 v89, v0
	v_mov_b32_e32 v90, v0
	v_mov_b32_e32 v91, v0
	v_mov_b32_e32 v92, v0
	v_mov_b32_e32 v93, v0
	v_mov_b32_e32 v94, v0
	v_mov_b32_e32 v95, v0
	v_mov_b32_e32 v96, v0
	v_mov_b32_e32 v97, v0
	v_mov_b32_e32 v98, v0
	v_mov_b32_e32 v99, v0
	v_mov_b32_e32 v100, v0
	v_mov_b32_e32 v101, v0
	v_mov_b32_e32 v102, v0
	v_mov_b32_e32 v103, v0
	v_mov_b32_e32 v104, v0
	v_mov_b32_e32 v105, v0
	v_mov_b32_e32 v106, v0
	v_mov_b32_e32 v107, v0
	v_mov_b32_e32 v108, v0
	v_mov_b32_e32 v109, v0
	v_mov_b32_e32 v110, v0
	v_mov_b32_e32 v111, v0
	v_mov_b32_e32 v112, v0
	v_mov_b32_e32 v113, v0
	v_mov_b32_e32 v114, v0
	v_mov_b32_e32 v115, v0
	v_mov_b32_e32 v116, v0
	v_mov_b32_e32 v117, v0
	v_mov_b32_e32 v118, v0
	v_mov_b32_e32 v119, v0
	v_mov_b32_e32 v120, v0
	v_mov_b32_e32 v121, v0
	v_mov_b32_e32 v122, v0
	v_mov_b32_e32 v123, v0
	v_mov_b32_e32 v124, v0
	v_mov_b32_e32 v125, v0
	v_mov_b32_e32 v126, v0
	v_mov_b32_e32 v127, v0
	s_barrier
	v_readlane_b32 s35, v254, 1
	s_mov_b32 s100, 0
	s_branch .LBB0_383

.LBB0_386:
	s_add_u32 s6, s28, s52
	s_addc_u32 s19, s29, s53
	s_add_u32 s6, s6, 0x100
	s_addc_u32 s19, s19, 0
	s_add_u32 s23, s10, s52
	s_addc_u32 s54, s11, s53
	s_add_i32 s82, 0, 0x10000
	v_add_u32_e32 v146, s82, v154
	ds_read_b128 v[158:161], v146
	ds_read_b128 v[162:165], v146 offset:1024
	ds_read_b128 v[166:169], v146 offset:2048
	ds_read_b128 v[170:173], v146 offset:3072
	s_cmpk_eq_i32 s52, 0x700
	s_cselect_b32 s59, s12, s19
	s_cselect_b32 s58, s35, s6
	s_cselect_b32 s55, s39, s54
	s_cselect_b32 s54, s47, s23
	v_lshl_add_u64 v[146:147], v[150:151], 0, s[52:53]
	s_add_i32 m0, s68, 0xc000
	ds_read_b128 v[174:177], v157
	ds_read_b128 v[178:181], v157 offset:1024
	ds_read_b128 v[182:185], v157 offset:2048
	ds_read_b128 v[206:209], v157 offset:3072
	ds_read_b128 v[210:213], v157 offset:4096
	ds_read_b128 v[214:217], v157 offset:5120
	ds_read_b128 v[218:221], v157 offset:6144
	ds_read_b128 v[222:225], v157 offset:7168
	global_load_lds_dwordx4 v[146:147], off
	v_lshl_add_u64 v[146:147], v[152:153], 0, s[52:53]
	s_add_i32 m0, s68, 0xe000
	s_nop 0
	global_load_lds_dwordx4 v[146:147], off
	s_add_i32 s6, 0, 0x14000
	v_add_u32_e32 v146, s6, v154
	ds_read_b128 v[226:229], v146
	ds_read_b128 v[230:233], v146 offset:1024
	ds_read_b128 v[234:237], v146 offset:2048
	ds_read_b128 v[238:241], v146 offset:3072
	s_waitcnt vmcnt(16)
	s_cmp_lg_u32 s100, 0
	s_cbranch_scc1 .Lm4a_386
	s_waitcnt vmcnt(8)
.Lm4a_386:
	s_waitcnt lgkmcnt(0)
	s_barrier
	s_setprio 1
	v_mfma_f32_16x16x32_bf16 v[124:127], v[158:161], v[174:177], v[124:127]
	v_mfma_f32_16x16x32_bf16 v[120:123], v[166:169], v[174:177], v[120:123]
	v_mfma_f32_16x16x32_bf16 v[116:119], v[158:161], v[182:185], v[116:119]
	v_mfma_f32_16x16x32_bf16 v[112:115], v[166:169], v[182:185], v[112:115]
	v_mfma_f32_16x16x32_bf16 v[108:111], v[158:161], v[210:213], v[108:111]
	v_mfma_f32_16x16x32_bf16 v[104:107], v[166:169], v[210:213], v[104:107]
	v_mfma_f32_16x16x32_bf16 v[100:103], v[158:161], v[218:221], v[100:103]
	v_mfma_f32_16x16x32_bf16 v[96:99], v[166:169], v[218:221], v[96:99]
	v_mfma_f32_16x16x32_bf16 v[124:127], v[162:165], v[178:181], v[124:127]
	v_mfma_f32_16x16x32_bf16 v[120:123], v[170:173], v[178:181], v[120:123]
	v_mfma_f32_16x16x32_bf16 v[116:119], v[162:165], v[206:209], v[116:119]
	v_mfma_f32_16x16x32_bf16 v[112:115], v[170:173], v[206:209], v[112:115]
	v_mfma_f32_16x16x32_bf16 v[108:111], v[162:165], v[214:217], v[108:111]
	v_mfma_f32_16x16x32_bf16 v[104:107], v[170:173], v[214:217], v[104:107]
	v_mfma_f32_16x16x32_bf16 v[100:103], v[162:165], v[222:225], v[100:103]
	v_mfma_f32_16x16x32_bf16 v[96:99], v[170:173], v[222:225], v[96:99]
	v_mfma_f32_16x16x32_bf16 v[92:95], v[226:229], v[174:177], v[92:95]
	v_mfma_f32_16x16x32_bf16 v[88:91], v[234:237], v[174:177], v[88:91]
	v_mfma_f32_16x16x32_bf16 v[84:87], v[226:229], v[182:185], v[84:87]
	v_mfma_f32_16x16x32_bf16 v[80:83], v[234:237], v[182:185], v[80:83]
	v_mfma_f32_16x16x32_bf16 v[76:79], v[226:229], v[210:213], v[76:79]
	v_mfma_f32_16x16x32_bf16 v[72:75], v[234:237], v[210:213], v[72:75]
	v_mfma_f32_16x16x32_bf16 v[68:71], v[226:229], v[218:221], v[68:71]
	v_mfma_f32_16x16x32_bf16 v[64:67], v[234:237], v[218:221], v[64:67]
	v_mfma_f32_16x16x32_bf16 v[92:95], v[230:233], v[178:181], v[92:95]
	v_mfma_f32_16x16x32_bf16 v[88:91], v[238:241], v[178:181], v[88:91]
	v_mfma_f32_16x16x32_bf16 v[84:87], v[230:233], v[206:209], v[84:87]
	v_mfma_f32_16x16x32_bf16 v[80:83], v[238:241], v[206:209], v[80:83]
	v_mfma_f32_16x16x32_bf16 v[76:79], v[230:233], v[214:217], v[76:79]
	v_mfma_f32_16x16x32_bf16 v[72:75], v[238:241], v[214:217], v[72:75]
	v_mfma_f32_16x16x32_bf16 v[68:71], v[230:233], v[222:225], v[68:71]
	v_mfma_f32_16x16x32_bf16 v[64:67], v[238:241], v[222:225], v[64:67]
	s_setprio 0
	s_barrier
	s_add_i32 s19, s82, s57
	v_lshl_add_u64 v[146:147], s[54:55], 0, v[140:141]
	s_mov_b32 m0, s19
	v_lshl_add_u64 v[148:149], s[54:55], 0, v[132:133]
	global_load_lds_dwordx4 v[146:147], off
	s_add_i32 m0, s19, 0x2000
	s_nop 0
	global_load_lds_dwordx4 v[148:149], off
	s_mov_b32 m0, s68
	v_lshl_add_u64 v[194:195], s[58:59], 0, v[128:129]
	ds_read_b128 v[174:177], v157 offset:16384
	ds_read_b128 v[178:181], v157 offset:17408
	ds_read_b128 v[182:185], v157 offset:18432
	ds_read_b128 v[206:209], v157 offset:19456
	ds_read_b128 v[210:213], v157 offset:20480
	ds_read_b128 v[214:217], v157 offset:21504
	ds_read_b128 v[218:221], v157 offset:22528
	ds_read_b128 v[222:225], v157 offset:23552
	global_load_lds_dwordx4 v[194:195], off
	v_lshl_add_u64 v[196:197], s[58:59], 0, v[130:131]
	s_mov_b32 m0, s69
	s_nop 0
	global_load_lds_dwordx4 v[196:197], off
	s_add_u32 s82, s54, 0x40000
	s_addc_u32 s83, s55, 0
	s_add_i32 s6, s6, s57
	v_lshl_add_u64 v[250:251], s[82:83], 0, v[140:141]
	s_mov_b32 m0, s6
	s_nop 0
	global_load_lds_dwordx4 v[250:251], off
	v_lshl_add_u64 v[250:251], s[82:83], 0, v[132:133]
	s_add_i32 m0, s6, 0x2000
	s_nop 0
	global_load_lds_dwordx4 v[250:251], off
	s_waitcnt vmcnt(16)
	s_cmp_lg_u32 s100, 0
	s_cbranch_scc1 .Lm4b_386
	s_waitcnt vmcnt(8)
.Lm4b_386:
	s_waitcnt lgkmcnt(0)
	s_mov_b32 s100, 0
	s_barrier
	s_setprio 1
	v_mfma_f32_16x16x32_bf16 v[60:63], v[158:161], v[174:177], v[60:63]
	v_mfma_f32_16x16x32_bf16 v[56:59], v[166:169], v[174:177], v[56:59]
	v_mfma_f32_16x16x32_bf16 v[52:55], v[158:161], v[182:185], v[52:55]
	v_mfma_f32_16x16x32_bf16 v[48:51], v[166:169], v[182:185], v[48:51]
	v_mfma_f32_16x16x32_bf16 v[44:47], v[158:161], v[210:213], v[44:47]
	v_mfma_f32_16x16x32_bf16 v[40:43], v[166:169], v[210:213], v[40:43]
	v_mfma_f32_16x16x32_bf16 v[36:39], v[158:161], v[218:221], v[36:39]
	v_mfma_f32_16x16x32_bf16 v[32:35], v[166:169], v[218:221], v[32:35]
	v_mfma_f32_16x16x32_bf16 v[60:63], v[162:165], v[178:181], v[60:63]
	v_mfma_f32_16x16x32_bf16 v[56:59], v[170:173], v[178:181], v[56:59]
	v_mfma_f32_16x16x32_bf16 v[52:55], v[162:165], v[206:209], v[52:55]
	v_mfma_f32_16x16x32_bf16 v[48:51], v[170:173], v[206:209], v[48:51]
	v_mfma_f32_16x16x32_bf16 v[44:47], v[162:165], v[214:217], v[44:47]
	v_mfma_f32_16x16x32_bf16 v[40:43], v[170:173], v[214:217], v[40:43]
	v_mfma_f32_16x16x32_bf16 v[36:39], v[162:165], v[222:225], v[36:39]
	v_mfma_f32_16x16x32_bf16 v[32:35], v[170:173], v[222:225], v[32:35]
	v_mfma_f32_16x16x32_bf16 v[28:31], v[226:229], v[174:177], v[28:31]
	v_mfma_f32_16x16x32_bf16 v[24:27], v[234:237], v[174:177], v[24:27]
	v_mfma_f32_16x16x32_bf16 v[20:23], v[226:229], v[182:185], v[20:23]
	v_mfma_f32_16x16x32_bf16 v[16:19], v[234:237], v[182:185], v[16:19]
	v_mfma_f32_16x16x32_bf16 v[12:15], v[226:229], v[210:213], v[12:15]
	v_mfma_f32_16x16x32_bf16 v[8:11], v[234:237], v[210:213], v[8:11]
	v_mfma_f32_16x16x32_bf16 v[4:7], v[226:229], v[218:221], v[4:7]
	v_mfma_f32_16x16x32_bf16 v[0:3], v[234:237], v[218:221], v[0:3]
	v_mfma_f32_16x16x32_bf16 v[28:31], v[230:233], v[178:181], v[28:31]
	v_mfma_f32_16x16x32_bf16 v[24:27], v[238:241], v[178:181], v[24:27]
	v_mfma_f32_16x16x32_bf16 v[20:23], v[230:233], v[206:209], v[20:23]
	v_mfma_f32_16x16x32_bf16 v[16:19], v[238:241], v[206:209], v[16:19]
	v_mfma_f32_16x16x32_bf16 v[12:15], v[230:233], v[214:217], v[12:15]
	v_mfma_f32_16x16x32_bf16 v[8:11], v[238:241], v[214:217], v[8:11]
	v_mfma_f32_16x16x32_bf16 v[4:7], v[230:233], v[222:225], v[4:7]
	v_mfma_f32_16x16x32_bf16 v[0:3], v[238:241], v[222:225], v[0:3]
	s_setprio 0
	s_barrier
	s_add_i32 s6, 0, 0x18000
	v_add_u32_e32 v170, s6, v154
	ds_read_b128 v[158:161], v170
	ds_read_b128 v[162:165], v170 offset:1024
	ds_read_b128 v[166:169], v170 offset:2048
	ds_read_b128 v[170:173], v170 offset:3072
	s_add_u32 s58, s58, 0x40000
	s_addc_u32 s59, s59, 0
	s_mov_b32 m0, s70
	v_lshl_add_u64 v[226:227], s[58:59], 0, v[128:129]
	ds_read_b128 v[174:177], v157 offset:32768
	ds_read_b128 v[178:181], v157 offset:33792
	ds_read_b128 v[182:185], v157 offset:34816
	ds_read_b128 v[206:209], v157 offset:35840
	ds_read_b128 v[210:213], v157 offset:36864
	ds_read_b128 v[214:217], v157 offset:37888
	ds_read_b128 v[218:221], v157 offset:38912
	ds_read_b128 v[222:225], v157 offset:39936
	global_load_lds_dwordx4 v[226:227], off
	v_lshl_add_u64 v[226:227], s[58:59], 0, v[130:131]
	s_mov_b32 m0, s71
	s_nop 0
	global_load_lds_dwordx4 v[226:227], off
	s_add_i32 s19, 0, 0x1c000
	v_add_u32_e32 v192, s19, v154
	ds_read_b128 v[226:229], v192
	ds_read_b128 v[230:233], v192 offset:1024
	ds_read_b128 v[234:237], v192 offset:2048
	ds_read_b128 v[238:241], v192 offset:3072
	s_waitcnt vmcnt(8)
	s_waitcnt lgkmcnt(0)
	s_barrier
	s_setprio 1
	v_mfma_f32_16x16x32_bf16 v[124:127], v[158:161], v[174:177], v[124:127]
	v_mfma_f32_16x16x32_bf16 v[120:123], v[166:169], v[174:177], v[120:123]
	v_mfma_f32_16x16x32_bf16 v[116:119], v[158:161], v[182:185], v[116:119]
	v_mfma_f32_16x16x32_bf16 v[112:115], v[166:169], v[182:185], v[112:115]
	v_mfma_f32_16x16x32_bf16 v[108:111], v[158:161], v[210:213], v[108:111]
	v_mfma_f32_16x16x32_bf16 v[104:107], v[166:169], v[210:213], v[104:107]
	v_mfma_f32_16x16x32_bf16 v[100:103], v[158:161], v[218:221], v[100:103]
	v_mfma_f32_16x16x32_bf16 v[96:99], v[166:169], v[218:221], v[96:99]
	v_mfma_f32_16x16x32_bf16 v[124:127], v[162:165], v[178:181], v[124:127]
	v_mfma_f32_16x16x32_bf16 v[120:123], v[170:173], v[178:181], v[120:123]
	v_mfma_f32_16x16x32_bf16 v[116:119], v[162:165], v[206:209], v[116:119]
	v_mfma_f32_16x16x32_bf16 v[112:115], v[170:173], v[206:209], v[112:115]
	v_mfma_f32_16x16x32_bf16 v[108:111], v[162:165], v[214:217], v[108:111]
	v_mfma_f32_16x16x32_bf16 v[104:107], v[170:173], v[214:217], v[104:107]
	v_mfma_f32_16x16x32_bf16 v[100:103], v[162:165], v[222:225], v[100:103]
	v_mfma_f32_16x16x32_bf16 v[96:99], v[170:173], v[222:225], v[96:99]
	v_mfma_f32_16x16x32_bf16 v[92:95], v[226:229], v[174:177], v[92:95]
	v_mfma_f32_16x16x32_bf16 v[88:91], v[234:237], v[174:177], v[88:91]
	v_mfma_f32_16x16x32_bf16 v[84:87], v[226:229], v[182:185], v[84:87]
	v_mfma_f32_16x16x32_bf16 v[80:83], v[234:237], v[182:185], v[80:83]
	v_mfma_f32_16x16x32_bf16 v[76:79], v[226:229], v[210:213], v[76:79]
	v_mfma_f32_16x16x32_bf16 v[72:75], v[234:237], v[210:213], v[72:75]
	v_mfma_f32_16x16x32_bf16 v[68:71], v[226:229], v[218:221], v[68:71]
	v_mfma_f32_16x16x32_bf16 v[64:67], v[234:237], v[218:221], v[64:67]
	v_mfma_f32_16x16x32_bf16 v[92:95], v[230:233], v[178:181], v[92:95]
	v_mfma_f32_16x16x32_bf16 v[88:91], v[238:241], v[178:181], v[88:91]
	v_mfma_f32_16x16x32_bf16 v[84:87], v[230:233], v[206:209], v[84:87]
	v_mfma_f32_16x16x32_bf16 v[80:83], v[238:241], v[206:209], v[80:83]
	v_mfma_f32_16x16x32_bf16 v[76:79], v[230:233], v[214:217], v[76:79]
	v_mfma_f32_16x16x32_bf16 v[72:75], v[238:241], v[214:217], v[72:75]
	v_mfma_f32_16x16x32_bf16 v[68:71], v[230:233], v[222:225], v[68:71]
	v_mfma_f32_16x16x32_bf16 v[64:67], v[238:241], v[222:225], v[64:67]
	s_setprio 0
	s_barrier
	s_add_i32 s6, s6, s57
	v_lshl_add_u64 v[146:147], v[146:147], 0, s[36:37]
	s_mov_b32 m0, s6
	s_nop 0
	global_load_lds_dwordx4 v[146:147], off
	v_lshl_add_u64 v[146:147], v[148:149], 0, s[36:37]
	s_add_i32 m0, s6, 0x2000
	s_nop 0
	global_load_lds_dwordx4 v[146:147], off
	s_mov_b32 m0, s72
	v_lshl_add_u64 v[146:147], v[194:195], 0, s[36:37]
	ds_read_b128 v[174:177], v157 offset:49152
	ds_read_b128 v[178:181], v157 offset:50176
	ds_read_b128 v[182:185], v157 offset:51200
	ds_read_b128 v[206:209], v157 offset:52224
	ds_read_b128 v[210:213], v157 offset:53248
	ds_read_b128 v[214:217], v157 offset:54272
	ds_read_b128 v[218:221], v157 offset:55296
	ds_read_b128 v[222:225], v157 offset:56320
	global_load_lds_dwordx4 v[146:147], off
	v_lshl_add_u64 v[146:147], v[196:197], 0, s[36:37]
	s_mov_b32 m0, s73
	s_nop 0
	global_load_lds_dwordx4 v[146:147], off
	s_add_u32 s54, s54, 0x40080
	s_addc_u32 s55, s55, 0
	s_add_i32 s6, s19, s57
	v_lshl_add_u64 v[146:147], s[54:55], 0, v[140:141]
	s_mov_b32 m0, s6
	s_nop 0
	global_load_lds_dwordx4 v[146:147], off
	v_lshl_add_u64 v[146:147], s[54:55], 0, v[132:133]
	s_add_i32 m0, s6, 0x2000
	s_nop 0
	global_load_lds_dwordx4 v[146:147], off
	s_waitcnt vmcnt(8)
	s_waitcnt lgkmcnt(0)
	s_barrier
	s_setprio 1
	v_mfma_f32_16x16x32_bf16 v[60:63], v[158:161], v[174:177], v[60:63]
	v_mfma_f32_16x16x32_bf16 v[56:59], v[166:169], v[174:177], v[56:59]
	v_mfma_f32_16x16x32_bf16 v[52:55], v[158:161], v[182:185], v[52:55]
	v_mfma_f32_16x16x32_bf16 v[48:51], v[166:169], v[182:185], v[48:51]
	v_mfma_f32_16x16x32_bf16 v[44:47], v[158:161], v[210:213], v[44:47]
	v_mfma_f32_16x16x32_bf16 v[40:43], v[166:169], v[210:213], v[40:43]
	v_mfma_f32_16x16x32_bf16 v[36:39], v[158:161], v[218:221], v[36:39]
	v_mfma_f32_16x16x32_bf16 v[32:35], v[166:169], v[218:221], v[32:35]
	v_mfma_f32_16x16x32_bf16 v[60:63], v[162:165], v[178:181], v[60:63]
	v_mfma_f32_16x16x32_bf16 v[56:59], v[170:173], v[178:181], v[56:59]
	v_mfma_f32_16x16x32_bf16 v[52:55], v[162:165], v[206:209], v[52:55]
	v_mfma_f32_16x16x32_bf16 v[48:51], v[170:173], v[206:209], v[48:51]
	v_mfma_f32_16x16x32_bf16 v[44:47], v[162:165], v[214:217], v[44:47]
	v_mfma_f32_16x16x32_bf16 v[40:43], v[170:173], v[214:217], v[40:43]
	v_mfma_f32_16x16x32_bf16 v[36:39], v[162:165], v[222:225], v[36:39]
	v_mfma_f32_16x16x32_bf16 v[32:35], v[170:173], v[222:225], v[32:35]
	v_mfma_f32_16x16x32_bf16 v[28:31], v[226:229], v[174:177], v[28:31]
	v_mfma_f32_16x16x32_bf16 v[24:27], v[234:237], v[174:177], v[24:27]
	v_mfma_f32_16x16x32_bf16 v[20:23], v[226:229], v[182:185], v[20:23]
	v_mfma_f32_16x16x32_bf16 v[16:19], v[234:237], v[182:185], v[16:19]
	v_mfma_f32_16x16x32_bf16 v[12:15], v[226:229], v[210:213], v[12:15]
	v_mfma_f32_16x16x32_bf16 v[8:11], v[234:237], v[210:213], v[8:11]
	v_mfma_f32_16x16x32_bf16 v[4:7], v[226:229], v[218:221], v[4:7]
	v_mfma_f32_16x16x32_bf16 v[0:3], v[234:237], v[218:221], v[0:3]
	v_mfma_f32_16x16x32_bf16 v[28:31], v[230:233], v[178:181], v[28:31]
	v_mfma_f32_16x16x32_bf16 v[24:27], v[238:241], v[178:181], v[24:27]
	v_mfma_f32_16x16x32_bf16 v[20:23], v[230:233], v[206:209], v[20:23]
	v_mfma_f32_16x16x32_bf16 v[16:19], v[238:241], v[206:209], v[16:19]
	v_mfma_f32_16x16x32_bf16 v[12:15], v[230:233], v[214:217], v[12:15]
	v_mfma_f32_16x16x32_bf16 v[8:11], v[238:241], v[214:217], v[8:11]
	v_mfma_f32_16x16x32_bf16 v[4:7], v[230:233], v[222:225], v[4:7]
	v_mfma_f32_16x16x32_bf16 v[0:3], v[238:241], v[222:225], v[0:3]
	s_setprio 0
	s_add_i32 s81, s81, 2
	s_add_u32 s52, s52, 0x100
	s_addc_u32 s53, s53, 0
	s_cmp_gt_u32 s81, 13
	s_barrier
	s_cbranch_scc0 .LBB0_386
	s_mov_b32 s100, 1
	v_lshl_add_u32 v158, s75, 10, v155
	ds_read2_b32 v[146:147], v158 offset1:16
	s_add_u32 s52, s10, 0xffffff00
	s_addc_u32 s53, s11, -1
	s_ashr_i32 s35, s34, 31
	s_lshl_b64 s[10:11], s[34:35], 8
	s_waitcnt lgkmcnt(0)
	v_pk_mul_f32 v[148:149], v[124:125], v[146:147] op_sel_hi:[1,0]
	v_lshl_add_u64 v[152:153], v[134:135], 0, s[10:11]
	v_mul_f32_e32 v159, 0xbfb8aa3b, v148
	v_exp_f32_e32 v159, v159
	s_movk_i32 s6, 0x1600
	v_lshl_or_b32 v150, s74, 7, v156
	v_ashrrev_i32_e32 v151, 31, v150
	v_add_f32_e32 v159, 1.0, v159
	v_rcp_f32_e32 v160, v159
	v_mul_f32_e32 v159, 0xbfb8aa3b, v149
	v_exp_f32_e32 v159, v159
	s_nop 0
	v_add_f32_e32 v159, 1.0, v159
	v_rcp_f32_e32 v161, v159
	s_nop 0
	v_pk_mul_f32 v[148:149], v[148:149], v[160:161]
	v_pk_mul_f32 v[160:161], v[92:93], v[146:147] op_sel_hi:[1,0]
	s_nop 0
	v_pk_mul_f32 v[148:149], v[160:161], v[148:149]
	v_pk_mul_f32 v[160:161], v[126:127], v[146:147] op_sel_hi:[1,0]
	s_nop 0
	v_mul_f32_e32 v159, 0xbfb8aa3b, v160
	v_exp_f32_e32 v159, v159
	s_nop 0
	v_add_f32_e32 v159, 1.0, v159
	v_rcp_f32_e32 v162, v159
	v_mul_f32_e32 v159, 0xbfb8aa3b, v161
	v_exp_f32_e32 v159, v159
	s_nop 0
	v_add_f32_e32 v159, 1.0, v159
	v_rcp_f32_e32 v163, v159
	s_nop 0
	v_pk_mul_f32 v[160:161], v[160:161], v[162:163]
	v_pk_mul_f32 v[162:163], v[94:95], v[146:147] op_sel_hi:[1,0]
	s_nop 0
	v_pk_mul_f32 v[162:163], v[162:163], v[160:161]
	v_pk_mul_f32 v[160:161], v[120:121], v[146:147] op_sel_hi:[1,0]
	s_nop 0
	v_mul_f32_e32 v159, 0xbfb8aa3b, v160
	v_exp_f32_e32 v159, v159
	s_nop 0
	v_add_f32_e32 v159, 1.0, v159
	v_rcp_f32_e32 v164, v159
	v_mul_f32_e32 v159, 0xbfb8aa3b, v161
	v_exp_f32_e32 v159, v159
	s_nop 0
	v_add_f32_e32 v159, 1.0, v159
	v_rcp_f32_e32 v165, v159
	s_nop 0
	v_pk_mul_f32 v[160:161], v[160:161], v[164:165]
	v_pk_mul_f32 v[164:165], v[88:89], v[146:147] op_sel_hi:[1,0]
	s_nop 0
	v_pk_mul_f32 v[164:165], v[164:165], v[160:161]
	v_pk_mul_f32 v[160:161], v[122:123], v[146:147] op_sel_hi:[1,0]
	s_nop 0
	v_mul_f32_e32 v159, 0xbfb8aa3b, v160
	v_exp_f32_e32 v159, v159
	s_nop 0
	v_add_f32_e32 v159, 1.0, v159
	v_rcp_f32_e32 v166, v159
	v_mul_f32_e32 v159, 0xbfb8aa3b, v161
	v_exp_f32_e32 v159, v159
	s_nop 0
	v_add_f32_e32 v159, 1.0, v159
	v_rcp_f32_e32 v167, v159
	s_nop 0
	v_pk_mul_f32 v[160:161], v[160:161], v[166:167]
	v_pk_mul_f32 v[166:167], v[90:91], v[146:147] op_sel_hi:[1,0]
	s_nop 0
	v_pk_mul_f32 v[166:167], v[166:167], v[160:161]
	v_cvt_pk_bf16_f32 v160, v148, v149
	v_mov_b64_e32 v[148:149], s[30:31]
	v_mad_u64_u32 v[148:149], s[10:11], v152, s6, v[148:149]
	v_mov_b32_e32 v146, v149
	v_mad_u64_u32 v[152:153], s[10:11], v153, s6, v[146:147]
	v_mov_b32_e32 v149, v152
	v_mov_b32_e32 v146, v147
	v_lshl_add_u64 v[150:151], v[150:151], 1, v[148:149]
	v_pk_mul_f32 v[148:149], v[116:117], v[146:147] op_sel_hi:[1,0]
	v_cvt_pk_bf16_f32 v161, v162, v163
	v_mul_f32_e32 v147, 0xbfb8aa3b, v148
	v_exp_f32_e32 v147, v147
	v_cvt_pk_bf16_f32 v162, v164, v165
	v_cvt_pk_bf16_f32 v163, v166, v167
	global_store_dwordx4 v[150:151], v[160:163], off
	v_add_f32_e32 v147, 1.0, v147
	v_rcp_f32_e32 v152, v147
	v_mul_f32_e32 v147, 0xbfb8aa3b, v149
	v_exp_f32_e32 v147, v147
	s_mov_b32 s6, 0x16000
	v_add_f32_e32 v147, 1.0, v147
	v_rcp_f32_e32 v153, v147
	s_nop 0
	v_pk_mul_f32 v[148:149], v[148:149], v[152:153]
	v_pk_mul_f32 v[152:153], v[84:85], v[146:147] op_sel_hi:[1,0]
	s_nop 0
	v_pk_mul_f32 v[148:149], v[152:153], v[148:149]
	v_pk_mul_f32 v[152:153], v[118:119], v[146:147] op_sel_hi:[1,0]
	s_nop 0
	v_mul_f32_e32 v147, 0xbfb8aa3b, v152
	v_exp_f32_e32 v147, v147
	s_nop 0
	v_add_f32_e32 v147, 1.0, v147
	v_rcp_f32_e32 v160, v147
	v_mul_f32_e32 v147, 0xbfb8aa3b, v153
	v_exp_f32_e32 v147, v147
	s_nop 0
	v_add_f32_e32 v147, 1.0, v147
	v_rcp_f32_e32 v161, v147
	s_nop 0
	v_pk_mul_f32 v[152:153], v[152:153], v[160:161]
	v_pk_mul_f32 v[160:161], v[86:87], v[146:147] op_sel_hi:[1,0]
	s_nop 0
	v_pk_mul_f32 v[152:153], v[160:161], v[152:153]
	v_pk_mul_f32 v[160:161], v[112:113], v[146:147] op_sel_hi:[1,0]
	s_nop 0
	v_mul_f32_e32 v147, 0xbfb8aa3b, v160
	v_exp_f32_e32 v147, v147
	s_nop 0
	v_add_f32_e32 v147, 1.0, v147
	v_rcp_f32_e32 v162, v147
	v_mul_f32_e32 v147, 0xbfb8aa3b, v161
	v_exp_f32_e32 v147, v147
	s_nop 0
	v_add_f32_e32 v147, 1.0, v147
	v_rcp_f32_e32 v163, v147
	s_nop 0
	v_pk_mul_f32 v[160:161], v[160:161], v[162:163]
	v_pk_mul_f32 v[162:163], v[80:81], v[146:147] op_sel_hi:[1,0]
	s_nop 0
	v_pk_mul_f32 v[162:163], v[162:163], v[160:161]
	v_pk_mul_f32 v[160:161], v[114:115], v[146:147] op_sel_hi:[1,0]
	v_cvt_pk_bf16_f32 v162, v162, v163
	v_mul_f32_e32 v147, 0xbfb8aa3b, v160
	v_exp_f32_e32 v147, v147
	s_nop 0
	v_add_f32_e32 v147, 1.0, v147
	v_rcp_f32_e32 v164, v147
	v_mul_f32_e32 v147, 0xbfb8aa3b, v161
	v_exp_f32_e32 v147, v147
	s_nop 0
	v_add_f32_e32 v147, 1.0, v147
	v_rcp_f32_e32 v165, v147
	v_pk_mul_f32 v[146:147], v[82:83], v[146:147] op_sel_hi:[1,0]
	v_pk_mul_f32 v[160:161], v[160:161], v[164:165]
	s_nop 0
	v_pk_mul_f32 v[146:147], v[146:147], v[160:161]
	v_cvt_pk_bf16_f32 v160, v148, v149
	v_cvt_pk_bf16_f32 v163, v146, v147
	v_add_co_u32_e32 v146, vcc, s6, v150
	v_cvt_pk_bf16_f32 v161, v152, v153
	s_nop 0
	v_addc_co_u32_e32 v147, vcc, 0, v151, vcc
	global_store_dwordx4 v[146:147], v[160:163], off
	ds_read2_b32 v[146:147], v158 offset0:32 offset1:48
	s_mov_b32 s6, 0x2c000
	s_waitcnt lgkmcnt(0)
	v_pk_mul_f32 v[148:149], v[108:109], v[146:147] op_sel_hi:[1,0]
	s_nop 0
	v_mul_f32_e32 v152, 0xbfb8aa3b, v148
	v_mul_f32_e32 v153, 0xbfb8aa3b, v149
	v_exp_f32_e32 v152, v152
	v_exp_f32_e32 v153, v153
	v_add_f32_e32 v152, 1.0, v152
	v_add_f32_e32 v153, 1.0, v153
	v_rcp_f32_e32 v152, v152
	v_rcp_f32_e32 v153, v153
	s_nop 0
	v_pk_mul_f32 v[148:149], v[148:149], v[152:153]
	v_pk_mul_f32 v[152:153], v[76:77], v[146:147] op_sel_hi:[1,0]
	s_nop 0
	v_pk_mul_f32 v[148:149], v[152:153], v[148:149]
	v_pk_mul_f32 v[152:153], v[110:111], v[146:147] op_sel_hi:[1,0]
	s_nop 0
	v_mul_f32_e32 v159, 0xbfb8aa3b, v152
	v_exp_f32_e32 v159, v159
	s_nop 0
	v_add_f32_e32 v159, 1.0, v159
	v_rcp_f32_e32 v160, v159
	v_mul_f32_e32 v159, 0xbfb8aa3b, v153
	v_exp_f32_e32 v159, v159
	s_nop 0
	v_add_f32_e32 v159, 1.0, v159
	v_rcp_f32_e32 v161, v159
	s_nop 0
	v_pk_mul_f32 v[152:153], v[152:153], v[160:161]
	v_pk_mul_f32 v[160:161], v[78:79], v[146:147] op_sel_hi:[1,0]
	s_nop 0
	v_pk_mul_f32 v[152:153], v[160:161], v[152:153]
	v_pk_mul_f32 v[160:161], v[104:105], v[146:147] op_sel_hi:[1,0]
	s_nop 0
	v_mul_f32_e32 v159, 0xbfb8aa3b, v160
	v_exp_f32_e32 v159, v159
	s_nop 0
	v_add_f32_e32 v159, 1.0, v159
	v_rcp_f32_e32 v162, v159
	v_mul_f32_e32 v159, 0xbfb8aa3b, v161
	v_exp_f32_e32 v159, v159
	s_nop 0
	v_add_f32_e32 v159, 1.0, v159
	v_rcp_f32_e32 v163, v159
	s_nop 0
	v_pk_mul_f32 v[160:161], v[160:161], v[162:163]
	v_pk_mul_f32 v[162:163], v[72:73], v[146:147] op_sel_hi:[1,0]
	s_nop 0
	v_pk_mul_f32 v[162:163], v[162:163], v[160:161]
	v_pk_mul_f32 v[160:161], v[106:107], v[146:147] op_sel_hi:[1,0]
	v_cvt_pk_bf16_f32 v162, v162, v163
	v_mul_f32_e32 v159, 0xbfb8aa3b, v160
	v_exp_f32_e32 v159, v159
	s_nop 0
	v_add_f32_e32 v159, 1.0, v159
	v_rcp_f32_e32 v164, v159
	v_mul_f32_e32 v159, 0xbfb8aa3b, v161
	v_exp_f32_e32 v159, v159
	s_nop 0
	v_add_f32_e32 v159, 1.0, v159
	v_rcp_f32_e32 v165, v159
	s_nop 0
	v_pk_mul_f32 v[160:161], v[160:161], v[164:165]
	v_pk_mul_f32 v[164:165], v[74:75], v[146:147] op_sel_hi:[1,0]
	v_mov_b32_e32 v146, v147
	v_pk_mul_f32 v[164:165], v[164:165], v[160:161]
	v_cvt_pk_bf16_f32 v160, v148, v149
	v_add_co_u32_e32 v148, vcc, s6, v150
	v_cvt_pk_bf16_f32 v161, v152, v153
	v_cvt_pk_bf16_f32 v163, v164, v165
	v_addc_co_u32_e32 v149, vcc, 0, v151, vcc
	global_store_dwordx4 v[148:149], v[160:163], off
	v_pk_mul_f32 v[148:149], v[100:101], v[146:147] op_sel_hi:[1,0]
	s_mov_b32 s6, 0x42000
	v_mul_f32_e32 v147, 0xbfb8aa3b, v148
	v_exp_f32_e32 v147, v147
	s_nop 0
	v_add_f32_e32 v147, 1.0, v147
	v_rcp_f32_e32 v152, v147
	v_mul_f32_e32 v147, 0xbfb8aa3b, v149
	v_exp_f32_e32 v147, v147
	s_nop 0
	v_add_f32_e32 v147, 1.0, v147
	v_rcp_f32_e32 v153, v147
	s_nop 0
	v_pk_mul_f32 v[148:149], v[148:149], v[152:153]
	v_pk_mul_f32 v[152:153], v[68:69], v[146:147] op_sel_hi:[1,0]
	s_nop 0
	v_pk_mul_f32 v[148:149], v[152:153], v[148:149]
	v_pk_mul_f32 v[152:153], v[102:103], v[146:147] op_sel_hi:[1,0]
	s_nop 0
	v_mul_f32_e32 v147, 0xbfb8aa3b, v152
	v_exp_f32_e32 v147, v147
	s_nop 0
	v_add_f32_e32 v147, 1.0, v147
	v_rcp_f32_e32 v160, v147
	v_mul_f32_e32 v147, 0xbfb8aa3b, v153
	v_exp_f32_e32 v147, v147
	s_nop 0
	v_add_f32_e32 v147, 1.0, v147
	v_rcp_f32_e32 v161, v147
	s_nop 0
	v_pk_mul_f32 v[152:153], v[152:153], v[160:161]
	v_pk_mul_f32 v[160:161], v[70:71], v[146:147] op_sel_hi:[1,0]
	s_nop 0
	v_pk_mul_f32 v[152:153], v[160:161], v[152:153]
	v_pk_mul_f32 v[160:161], v[96:97], v[146:147] op_sel_hi:[1,0]
	s_nop 0
	v_mul_f32_e32 v147, 0xbfb8aa3b, v160
	v_exp_f32_e32 v147, v147
	s_nop 0
	v_add_f32_e32 v147, 1.0, v147
	v_rcp_f32_e32 v162, v147
	v_mul_f32_e32 v147, 0xbfb8aa3b, v161
	v_exp_f32_e32 v147, v147
	s_nop 0
	v_add_f32_e32 v147, 1.0, v147
	v_rcp_f32_e32 v163, v147
	s_nop 0
	v_pk_mul_f32 v[160:161], v[160:161], v[162:163]
	v_pk_mul_f32 v[162:163], v[64:65], v[146:147] op_sel_hi:[1,0]
	s_nop 0
	v_pk_mul_f32 v[162:163], v[162:163], v[160:161]
	v_pk_mul_f32 v[160:161], v[98:99], v[146:147] op_sel_hi:[1,0]
	v_cvt_pk_bf16_f32 v162, v162, v163
	v_mul_f32_e32 v147, 0xbfb8aa3b, v160
	v_exp_f32_e32 v147, v147
	s_nop 0
	v_add_f32_e32 v147, 1.0, v147
	v_rcp_f32_e32 v164, v147
	v_mul_f32_e32 v147, 0xbfb8aa3b, v161
	v_exp_f32_e32 v147, v147
	s_nop 0
	v_add_f32_e32 v147, 1.0, v147
	v_rcp_f32_e32 v165, v147
	v_pk_mul_f32 v[146:147], v[66:67], v[146:147] op_sel_hi:[1,0]
	v_pk_mul_f32 v[160:161], v[160:161], v[164:165]
	s_nop 0
	v_pk_mul_f32 v[146:147], v[146:147], v[160:161]
	v_cvt_pk_bf16_f32 v160, v148, v149
	v_cvt_pk_bf16_f32 v163, v146, v147
	v_add_co_u32_e32 v146, vcc, s6, v150
	v_cvt_pk_bf16_f32 v161, v152, v153
	s_nop 0
	v_addc_co_u32_e32 v147, vcc, 0, v151, vcc
	global_store_dwordx4 v[146:147], v[160:163], off
	ds_read2_b32 v[146:147], v158 offset0:128 offset1:144
	s_mov_b32 s6, 0xb0000
	s_waitcnt lgkmcnt(0)
	v_pk_mul_f32 v[148:149], v[60:61], v[146:147] op_sel_hi:[1,0]
	s_nop 0
	v_mul_f32_e32 v152, 0xbfb8aa3b, v148
	v_mul_f32_e32 v153, 0xbfb8aa3b, v149
	v_exp_f32_e32 v152, v152
	v_exp_f32_e32 v153, v153
	v_add_f32_e32 v152, 1.0, v152
	v_add_f32_e32 v153, 1.0, v153
	v_rcp_f32_e32 v152, v152
	v_rcp_f32_e32 v153, v153
	s_nop 0
	v_pk_mul_f32 v[148:149], v[148:149], v[152:153]
	v_pk_mul_f32 v[152:153], v[28:29], v[146:147] op_sel_hi:[1,0]
	s_nop 0
	v_pk_mul_f32 v[148:149], v[152:153], v[148:149]
	v_pk_mul_f32 v[152:153], v[62:63], v[146:147] op_sel_hi:[1,0]
	s_nop 0
	v_mul_f32_e32 v159, 0xbfb8aa3b, v152
	v_exp_f32_e32 v159, v159
	s_nop 0
	v_add_f32_e32 v159, 1.0, v159
	v_rcp_f32_e32 v160, v159
	v_mul_f32_e32 v159, 0xbfb8aa3b, v153
	v_exp_f32_e32 v159, v159
	s_nop 0
	v_add_f32_e32 v159, 1.0, v159
	v_rcp_f32_e32 v161, v159
	s_nop 0
	v_pk_mul_f32 v[152:153], v[152:153], v[160:161]
	v_pk_mul_f32 v[160:161], v[30:31], v[146:147] op_sel_hi:[1,0]
	s_nop 0
	v_pk_mul_f32 v[152:153], v[160:161], v[152:153]
	v_pk_mul_f32 v[160:161], v[56:57], v[146:147] op_sel_hi:[1,0]
	s_nop 0
	v_mul_f32_e32 v159, 0xbfb8aa3b, v160
	v_exp_f32_e32 v159, v159
	s_nop 0
	v_add_f32_e32 v159, 1.0, v159
	v_rcp_f32_e32 v162, v159
	v_mul_f32_e32 v159, 0xbfb8aa3b, v161
	v_exp_f32_e32 v159, v159
	s_nop 0
	v_add_f32_e32 v159, 1.0, v159
	v_rcp_f32_e32 v163, v159
	s_nop 0
	v_pk_mul_f32 v[160:161], v[160:161], v[162:163]
	v_pk_mul_f32 v[162:163], v[24:25], v[146:147] op_sel_hi:[1,0]
	s_nop 0
	v_pk_mul_f32 v[162:163], v[162:163], v[160:161]
	v_pk_mul_f32 v[160:161], v[58:59], v[146:147] op_sel_hi:[1,0]
	v_cvt_pk_bf16_f32 v162, v162, v163
	v_mul_f32_e32 v159, 0xbfb8aa3b, v160
	v_exp_f32_e32 v159, v159
	s_nop 0
	v_add_f32_e32 v159, 1.0, v159
	v_rcp_f32_e32 v164, v159
	v_mul_f32_e32 v159, 0xbfb8aa3b, v161
	v_exp_f32_e32 v159, v159
	s_nop 0
	v_add_f32_e32 v159, 1.0, v159
	v_rcp_f32_e32 v165, v159
	s_nop 0
	v_pk_mul_f32 v[160:161], v[160:161], v[164:165]
	v_pk_mul_f32 v[164:165], v[26:27], v[146:147] op_sel_hi:[1,0]
	v_mov_b32_e32 v146, v147
	v_pk_mul_f32 v[164:165], v[164:165], v[160:161]
	v_cvt_pk_bf16_f32 v160, v148, v149
	v_add_co_u32_e32 v148, vcc, s6, v150
	v_cvt_pk_bf16_f32 v161, v152, v153
	v_cvt_pk_bf16_f32 v163, v164, v165
	v_addc_co_u32_e32 v149, vcc, 0, v151, vcc
	global_store_dwordx4 v[148:149], v[160:163], off
	v_pk_mul_f32 v[148:149], v[52:53], v[146:147] op_sel_hi:[1,0]
	s_mov_b32 s6, 0xc6000
	v_mul_f32_e32 v147, 0xbfb8aa3b, v148
	v_exp_f32_e32 v147, v147
	s_nop 0
	v_add_f32_e32 v147, 1.0, v147
	v_rcp_f32_e32 v152, v147
	v_mul_f32_e32 v147, 0xbfb8aa3b, v149
	v_exp_f32_e32 v147, v147
	s_nop 0
	v_add_f32_e32 v147, 1.0, v147
	v_rcp_f32_e32 v153, v147
	s_nop 0
	v_pk_mul_f32 v[148:149], v[148:149], v[152:153]
	v_pk_mul_f32 v[152:153], v[20:21], v[146:147] op_sel_hi:[1,0]
	s_nop 0
	v_pk_mul_f32 v[148:149], v[152:153], v[148:149]
	v_pk_mul_f32 v[152:153], v[54:55], v[146:147] op_sel_hi:[1,0]
	s_nop 0
	v_mul_f32_e32 v147, 0xbfb8aa3b, v152
	v_exp_f32_e32 v147, v147
	s_nop 0
	v_add_f32_e32 v147, 1.0, v147
	v_rcp_f32_e32 v160, v147
	v_mul_f32_e32 v147, 0xbfb8aa3b, v153
	v_exp_f32_e32 v147, v147
	s_nop 0
	v_add_f32_e32 v147, 1.0, v147
	v_rcp_f32_e32 v161, v147
	s_nop 0
	v_pk_mul_f32 v[152:153], v[152:153], v[160:161]
	v_pk_mul_f32 v[160:161], v[22:23], v[146:147] op_sel_hi:[1,0]
	s_nop 0
	v_pk_mul_f32 v[152:153], v[160:161], v[152:153]
	v_pk_mul_f32 v[160:161], v[48:49], v[146:147] op_sel_hi:[1,0]
	s_nop 0
	v_mul_f32_e32 v147, 0xbfb8aa3b, v160
	v_exp_f32_e32 v147, v147
	s_nop 0
	v_add_f32_e32 v147, 1.0, v147
	v_rcp_f32_e32 v162, v147
	v_mul_f32_e32 v147, 0xbfb8aa3b, v161
	v_exp_f32_e32 v147, v147
	s_nop 0
	v_add_f32_e32 v147, 1.0, v147
	v_rcp_f32_e32 v163, v147
	s_nop 0
	v_pk_mul_f32 v[160:161], v[160:161], v[162:163]
	v_pk_mul_f32 v[162:163], v[16:17], v[146:147] op_sel_hi:[1,0]
	s_nop 0
	v_pk_mul_f32 v[162:163], v[162:163], v[160:161]
	v_pk_mul_f32 v[160:161], v[50:51], v[146:147] op_sel_hi:[1,0]
	v_cvt_pk_bf16_f32 v162, v162, v163
	v_mul_f32_e32 v147, 0xbfb8aa3b, v160
	v_exp_f32_e32 v147, v147
	s_nop 0
	v_add_f32_e32 v147, 1.0, v147
	v_rcp_f32_e32 v164, v147
	v_mul_f32_e32 v147, 0xbfb8aa3b, v161
	v_exp_f32_e32 v147, v147
	s_nop 0
	v_add_f32_e32 v147, 1.0, v147
	v_rcp_f32_e32 v165, v147
	v_pk_mul_f32 v[146:147], v[18:19], v[146:147] op_sel_hi:[1,0]
	v_pk_mul_f32 v[160:161], v[160:161], v[164:165]
	s_nop 0
	v_pk_mul_f32 v[146:147], v[146:147], v[160:161]
	v_cvt_pk_bf16_f32 v160, v148, v149
	v_cvt_pk_bf16_f32 v163, v146, v147
	v_add_co_u32_e32 v146, vcc, s6, v150
	v_cvt_pk_bf16_f32 v161, v152, v153
	s_nop 0
	v_addc_co_u32_e32 v147, vcc, 0, v151, vcc
	global_store_dwordx4 v[146:147], v[160:163], off
	ds_read2_b32 v[146:147], v158 offset0:160 offset1:176
	s_mov_b32 s6, 0xdc000
	s_waitcnt lgkmcnt(0)
	v_pk_mul_f32 v[148:149], v[44:45], v[146:147] op_sel_hi:[1,0]
	s_nop 0
	v_mul_f32_e32 v152, 0xbfb8aa3b, v148
	v_mul_f32_e32 v153, 0xbfb8aa3b, v149
	v_exp_f32_e32 v152, v152
	v_exp_f32_e32 v153, v153
	v_add_f32_e32 v152, 1.0, v152
	v_add_f32_e32 v153, 1.0, v153
	v_rcp_f32_e32 v152, v152
	v_rcp_f32_e32 v153, v153
	s_nop 0
	v_pk_mul_f32 v[148:149], v[148:149], v[152:153]
	v_pk_mul_f32 v[152:153], v[12:13], v[146:147] op_sel_hi:[1,0]
	s_nop 0
	v_pk_mul_f32 v[148:149], v[152:153], v[148:149]
	v_pk_mul_f32 v[152:153], v[46:47], v[146:147] op_sel_hi:[1,0]
	s_nop 0
	v_mul_f32_e32 v158, 0xbfb8aa3b, v152
	v_mul_f32_e32 v159, 0xbfb8aa3b, v153
	v_exp_f32_e32 v158, v158
	v_exp_f32_e32 v159, v159
	v_add_f32_e32 v158, 1.0, v158
	v_add_f32_e32 v159, 1.0, v159
	v_rcp_f32_e32 v158, v158
	v_rcp_f32_e32 v159, v159
	s_nop 0
	v_pk_mul_f32 v[152:153], v[152:153], v[158:159]
	v_pk_mul_f32 v[158:159], v[14:15], v[146:147] op_sel_hi:[1,0]
	s_nop 0
	v_pk_mul_f32 v[152:153], v[158:159], v[152:153]
	v_pk_mul_f32 v[158:159], v[40:41], v[146:147] op_sel_hi:[1,0]
	s_nop 0
	v_mul_f32_e32 v160, 0xbfb8aa3b, v158
	v_mul_f32_e32 v161, 0xbfb8aa3b, v159
	v_exp_f32_e32 v160, v160
	v_exp_f32_e32 v161, v161
	v_add_f32_e32 v160, 1.0, v160
	v_add_f32_e32 v161, 1.0, v161
	v_rcp_f32_e32 v160, v160
	v_rcp_f32_e32 v161, v161
	s_nop 0
	v_pk_mul_f32 v[158:159], v[158:159], v[160:161]
	v_pk_mul_f32 v[160:161], v[8:9], v[146:147] op_sel_hi:[1,0]
	s_nop 0
	v_pk_mul_f32 v[160:161], v[160:161], v[158:159]
	v_pk_mul_f32 v[158:159], v[42:43], v[146:147] op_sel_hi:[1,0]
	v_cvt_pk_bf16_f32 v160, v160, v161
	v_mul_f32_e32 v162, 0xbfb8aa3b, v158
	v_mul_f32_e32 v163, 0xbfb8aa3b, v159
	v_exp_f32_e32 v162, v162
	v_exp_f32_e32 v163, v163
	v_add_f32_e32 v162, 1.0, v162
	v_add_f32_e32 v163, 1.0, v163
	v_rcp_f32_e32 v162, v162
	v_rcp_f32_e32 v163, v163
	s_nop 0
	v_pk_mul_f32 v[158:159], v[158:159], v[162:163]
	v_pk_mul_f32 v[162:163], v[10:11], v[146:147] op_sel_hi:[1,0]
	v_mov_b32_e32 v146, v147
	v_pk_mul_f32 v[162:163], v[162:163], v[158:159]
	v_cvt_pk_bf16_f32 v158, v148, v149
	v_add_co_u32_e32 v148, vcc, s6, v150
	v_cvt_pk_bf16_f32 v159, v152, v153
	v_cvt_pk_bf16_f32 v161, v162, v163
	v_addc_co_u32_e32 v149, vcc, 0, v151, vcc
	global_store_dwordx4 v[148:149], v[158:161], off
	v_pk_mul_f32 v[148:149], v[36:37], v[146:147] op_sel_hi:[1,0]
	s_nop 0
	v_mul_f32_e32 v147, 0xbfb8aa3b, v148
	v_exp_f32_e32 v147, v147
	s_nop 0
	v_add_f32_e32 v147, 1.0, v147
	v_rcp_f32_e32 v152, v147
	v_mul_f32_e32 v147, 0xbfb8aa3b, v149
	v_exp_f32_e32 v147, v147
	s_nop 0
	v_add_f32_e32 v147, 1.0, v147
	v_rcp_f32_e32 v153, v147
	s_nop 0
	v_pk_mul_f32 v[148:149], v[148:149], v[152:153]
	v_pk_mul_f32 v[152:153], v[4:5], v[146:147] op_sel_hi:[1,0]
	s_nop 0
	v_pk_mul_f32 v[148:149], v[152:153], v[148:149]
	v_pk_mul_f32 v[152:153], v[38:39], v[146:147] op_sel_hi:[1,0]
	s_nop 0
	v_mul_f32_e32 v147, 0xbfb8aa3b, v152
	v_exp_f32_e32 v147, v147
	s_nop 0
	v_add_f32_e32 v147, 1.0, v147
	v_rcp_f32_e32 v158, v147
	v_mul_f32_e32 v147, 0xbfb8aa3b, v153
	v_exp_f32_e32 v147, v147
	s_nop 0
	v_add_f32_e32 v147, 1.0, v147
	v_rcp_f32_e32 v159, v147
	s_nop 0
	v_pk_mul_f32 v[152:153], v[152:153], v[158:159]
	v_pk_mul_f32 v[158:159], v[6:7], v[146:147] op_sel_hi:[1,0]
	s_nop 0
	v_pk_mul_f32 v[152:153], v[158:159], v[152:153]
	v_pk_mul_f32 v[158:159], v[32:33], v[146:147] op_sel_hi:[1,0]
	s_nop 0
	v_mul_f32_e32 v147, 0xbfb8aa3b, v158
	v_exp_f32_e32 v147, v147
	s_nop 0
	v_add_f32_e32 v147, 1.0, v147
	v_rcp_f32_e32 v160, v147
	v_mul_f32_e32 v147, 0xbfb8aa3b, v159
	v_exp_f32_e32 v147, v147
	s_nop 0
	v_add_f32_e32 v147, 1.0, v147
	v_rcp_f32_e32 v161, v147
	s_nop 0
	v_pk_mul_f32 v[158:159], v[158:159], v[160:161]
	v_pk_mul_f32 v[160:161], v[0:1], v[146:147] op_sel_hi:[1,0]
	s_nop 0
	v_pk_mul_f32 v[160:161], v[160:161], v[158:159]
	v_pk_mul_f32 v[158:159], v[34:35], v[146:147] op_sel_hi:[1,0]
	v_cvt_pk_bf16_f32 v160, v160, v161
	v_mul_f32_e32 v147, 0xbfb8aa3b, v158
	v_exp_f32_e32 v147, v147
	s_nop 0
	v_add_f32_e32 v147, 1.0, v147
	v_rcp_f32_e32 v162, v147
	v_mul_f32_e32 v147, 0xbfb8aa3b, v159
	v_exp_f32_e32 v147, v147
	s_nop 0
	v_add_f32_e32 v147, 1.0, v147
	v_rcp_f32_e32 v163, v147
	v_pk_mul_f32 v[146:147], v[2:3], v[146:147] op_sel_hi:[1,0]
	v_pk_mul_f32 v[158:159], v[158:159], v[162:163]
	s_nop 0
	v_pk_mul_f32 v[146:147], v[146:147], v[158:159]
	v_cvt_pk_bf16_f32 v158, v148, v149
	v_cvt_pk_bf16_f32 v161, v146, v147
	v_add_co_u32_e32 v146, vcc, 0xf2000, v150
	v_cvt_pk_bf16_f32 v159, v152, v153
	s_nop 0
	v_addc_co_u32_e32 v147, vcc, 0, v151, vcc
	s_andn2_b64 vcc, exec, s[44:45]
	global_store_dwordx4 v[146:147], v[158:161], off
	s_cbranch_vccz .LBB0_382
	s_mov_b64 s[48:49], s[52:53]
	s_andn2_b64 vcc, exec, s[42:43]
	s_mov_b64 s[52:53], s[48:49]
	s_cbranch_vccnz .LBB0_383

	.amdhsa_kernel _Z4mega6Params
		.amdhsa_group_segment_fixed_size 0
		.amdhsa_private_segment_fixed_size 0
		.amdhsa_kernarg_size 512
		.amdhsa_user_sgpr_count 2
		.amdhsa_user_sgpr_dispatch_ptr 0
		.amdhsa_user_sgpr_queue_ptr 0
		.amdhsa_user_sgpr_kernarg_segment_ptr 1
		.amdhsa_user_sgpr_dispatch_id 0
		.amdhsa_user_sgpr_kernarg_preload_length 0
		.amdhsa_user_sgpr_kernarg_preload_offset 0
		.amdhsa_user_sgpr_private_segment_size 0
		.amdhsa_uses_dynamic_stack 0
		.amdhsa_enable_private_segment 0
		.amdhsa_system_sgpr_workgroup_id_x 1
		.amdhsa_system_sgpr_workgroup_id_y 0
		.amdhsa_system_sgpr_workgroup_id_z 0
		.amdhsa_system_sgpr_workgroup_info 0
		.amdhsa_system_vgpr_workitem_id 2
		.amdhsa_next_free_vgpr 256
		.amdhsa_next_free_sgpr 102
		.amdhsa_accum_offset 256
		.amdhsa_reserve_vcc 1
		.amdhsa_float_round_mode_32 0
		.amdhsa_float_round_mode_16_64 0
		.amdhsa_float_denorm_mode_32 3
		.amdhsa_float_denorm_mode_16_64 3
		.amdhsa_dx10_clamp 1
		.amdhsa_ieee_mode 1
		.amdhsa_fp16_overflow 0
		.amdhsa_tg_split 0
		.amdhsa_exception_fp_ieee_invalid_op 0
		.amdhsa_exception_fp_denorm_src 0
		.amdhsa_exception_fp_ieee_div_zero 0
		.amdhsa_exception_fp_ieee_overflow 0
		.amdhsa_exception_fp_ieee_underflow 0
		.amdhsa_exception_fp_ieee_inexact 0
		.amdhsa_exception_int_div_zero 0
	.end_amdhsa_kernel

amdhsa.kernels:
  - .agpr_count:     0
    .args:
      - .offset:         0
        .size:           256
        .value_kind:     by_value
      - .offset:         256
        .size:           4
        .value_kind:     hidden_block_count_x
      - .offset:         260
        .size:           4
        .value_kind:     hidden_block_count_y
      - .offset:         264
        .size:           4
        .value_kind:     hidden_block_count_z
      - .offset:         268
        .size:           2
        .value_kind:     hidden_group_size_x
      - .offset:         270
        .size:           2
        .value_kind:     hidden_group_size_y
      - .offset:         272
        .size:           2
        .value_kind:     hidden_group_size_z
      - .offset:         274
        .size:           2
        .value_kind:     hidden_remainder_x
      - .offset:         276
        .size:           2
        .value_kind:     hidden_remainder_y
      - .offset:         278
        .size:           2
        .value_kind:     hidden_remainder_z
      - .offset:         296
        .size:           8
        .value_kind:     hidden_global_offset_x
      - .offset:         304
        .size:           8
        .value_kind:     hidden_global_offset_y
      - .offset:         312
        .size:           8
        .value_kind:     hidden_global_offset_z
      - .offset:         320
        .size:           2
        .value_kind:     hidden_grid_dims
      - .offset:         344
        .size:           8
        .value_kind:     hidden_multigrid_sync_arg
      - .offset:         376
        .size:           4
        .value_kind:     hidden_dynamic_lds_size
    .group_segment_fixed_size: 0
    .kernarg_segment_align: 8
    .kernarg_segment_size: 512
    .language:       OpenCL C
    .language_version:
      - 2
      - 0
    .max_flat_workgroup_size: 512
    .name:           _Z4mega6Params
    .private_segment_fixed_size: 0
    .sgpr_count:     108
    .sgpr_spill_count: 226
    .symbol:         _Z4mega6Params.kd
    .uniform_work_group_size: 1
    .uses_dynamic_stack: false
    .vgpr_count:     256
    .vgpr_spill_count: 0
    .wavefront_size: 64
